# GEMM MMA blocks: snake source order with both K-halves of each accumulator issued back-to-back
# speedup vs baseline: 1.0096x; 1.0096x over previous
; #define PG8_STAGE(bufoff, gbase, voff) do { _Pragma("unroll") for (int _i = 0; _i < 2; ++_i) \
;         __builtin_amdgcn_global_load_lds((const unsigned*)((const char*)(gbase) + (voff)[_i]), (LAS unsigned*)(lds + (bufoff) + ldsw + _i * 8192), 16, 0, 0); } while (0)
; #define PG8_LDA(dst, b, h) do { _Pragma("unroll") for (int m = 0; m < 4; ++m) _Pragma("unroll") for (int k = 0; k < 2; ++k) dst[m][k] = *(const LAS bf16x8*)(lds + PG8_SA(b, h) + aoff + m * 2048 + k * 1024); } while (0)
; #define PG8_LDB(dst, b, h) do { _Pragma("unroll") for (int n = 0; n < 2; ++n) _Pragma("unroll") for (int k = 0; k < 2; ++k) dst[n][k] = *(const LAS bf16x8*)(lds + PG8_SB(b, h) + boff + n * 2048 + k * 1024); } while (0)
; #define PG8_MMA(ai, bj, At, Bt) do { __builtin_amdgcn_s_setprio(1); _Pragma("unroll") for (int m = 0; m < 4; ++m) _Pragma("unroll") for (int n = 0; n < 2; ++n) _Pragma("unroll") for (int k = 0; k < 2; ++k) \
;         acc[ai][bj][m][n] = __builtin_amdgcn_mfma_f32_16x16x32_bf16(Bt[n][k], At[m][k], acc[ai][bj][m][n], 0, 0, 0); __builtin_amdgcn_s_setprio(0); } while (0)
; #define PG8_WAIT_L(n) asm volatile("s_waitcnt lgkmcnt(" #n ")" ::: "memory")
; #define PG8_BAR __builtin_amdgcn_s_barrier()
; #define PG8_SCHED __builtin_amdgcn_sched_barrier(0)
; template <class Epi>
; DEVINL void gemm_phase(LAS unsigned char* lds, const Gemm g, const Order& S, const Epi& E) {
;     ...
;         for (int t = 0; t < nt; t += 2) {
;             const bool last = (t == nt - 2);
;             const char* a1 = cA + (size_t)(t + 1) * kstep;
;             const char* a2 = last ? nA : cA + (size_t)(t + 2) * kstep; const char* b2 = last ? nB : cB + (size_t)(t + 2) * kstep;
;             const char* a3 = a2 + kstep; const char* b3 = b2 + kstep;
;             PG8_LDB(B0, 0, 0); PG8_SCHED; PG8_LDA(At, 0, 0); PG8_STAGE(PG8_SA(1, 1), a1 + hstepA, voffA);
;             PG8_WAIT_L(8); PG8_BAR; PG8_WAIT_L(0); PG8_MMA(0, 0, At, B0); PG8_BAR; PG8_SCHED;
;             PG8_LDB(B1, 0, 1); PG8_STAGE(PG8_SB(0, 0), b2, voffB);
;             PG8_BAR; PG8_WAIT_L(0); PG8_MMA(0, 1, At, B1); PG8_BAR;
;             PG8_LDA(At, 0, 1); PG8_STAGE(PG8_SA(0, 0), a2, voffA);
;             PG8_BAR; PG8_WAIT_L(0); PG8_MMA(1, 0, At, B0); PG8_BAR; PG8_SCHED;
.LBB0_340:
	ds_read_b128 v[152:155], v149
	ds_read_b128 v[156:159], v149 offset:1024
	ds_read_b128 v[160:163], v149 offset:2048
	ds_read_b128 v[164:167], v149 offset:3072
	s_add_i32 s93, s10, 2
	s_add_u32 s2, s12, 0xfff80080
	s_addc_u32 s3, s13, -1
	s_cmp_eq_u32 s76, s10
	s_cselect_b32 s10, s85, s86
	s_cselect_b32 s15, s17, s3
	s_cselect_b32 s14, s61, s2
	s_cselect_b32 s11, s84, s87
	v_lshl_add_u64 v[144:145], s[12:13], 0, v[136:137]
	s_add_i32 m0, s67, 0xc000
	ds_read_b128 v[168:171], v150
	ds_read_b128 v[172:175], v150 offset:1024
	ds_read_b128 v[176:179], v150 offset:2048
	ds_read_b128 v[180:183], v150 offset:3072
	ds_read_b128 v[184:187], v150 offset:4096
	ds_read_b128 v[188:191], v150 offset:5120
	ds_read_b128 v[192:195], v150 offset:6144
	ds_read_b128 v[196:199], v150 offset:7168
	global_load_lds_dwordx4 v[144:145], off
	v_lshl_add_u64 v[144:145], s[12:13], 0, v[138:139]
	s_add_i32 m0, s67, 0xe000
	s_nop 0
	global_load_lds_dwordx4 v[144:145], off
	s_waitcnt lgkmcnt(8)
	s_barrier
	s_waitcnt lgkmcnt(0)
	s_setprio 1
	s_waitcnt lgkmcnt(0)
	v_mfma_f32_16x16x32_bf16 v[124:127], v[152:155], v[168:171], v[124:127]
	v_mfma_f32_16x16x32_bf16 v[124:127], v[156:159], v[172:175], v[124:127]
	v_mfma_f32_16x16x32_bf16 v[116:119], v[160:163], v[168:171], v[116:119]
	v_mfma_f32_16x16x32_bf16 v[116:119], v[164:167], v[172:175], v[116:119]
	v_mfma_f32_16x16x32_bf16 v[100:103], v[160:163], v[176:179], v[100:103]
	v_mfma_f32_16x16x32_bf16 v[100:103], v[164:167], v[180:183], v[100:103]
	v_mfma_f32_16x16x32_bf16 v[108:111], v[152:155], v[176:179], v[108:111]
	v_mfma_f32_16x16x32_bf16 v[108:111], v[156:159], v[180:183], v[108:111]
	v_mfma_f32_16x16x32_bf16 v[92:95], v[152:155], v[184:187], v[92:95]
	v_mfma_f32_16x16x32_bf16 v[92:95], v[156:159], v[188:191], v[92:95]
	v_mfma_f32_16x16x32_bf16 v[84:87], v[160:163], v[184:187], v[84:87]
	v_mfma_f32_16x16x32_bf16 v[84:87], v[164:167], v[188:191], v[84:87]
	v_mfma_f32_16x16x32_bf16 v[68:71], v[160:163], v[192:195], v[68:71]
	v_mfma_f32_16x16x32_bf16 v[68:71], v[164:167], v[196:199], v[68:71]
	v_mfma_f32_16x16x32_bf16 v[76:79], v[152:155], v[192:195], v[76:79]
	v_mfma_f32_16x16x32_bf16 v[76:79], v[156:159], v[196:199], v[76:79]
	s_setprio 0
	s_barrier
	s_add_i32 s2, s80, s38
	v_lshl_add_u64 v[144:145], s[10:11], 0, v[132:133]
	s_mov_b32 m0, s2
	ds_read_b128 v[200:203], v151
	ds_read_b128 v[204:207], v151 offset:1024
	ds_read_b128 v[208:211], v151 offset:2048
	ds_read_b128 v[218:221], v151 offset:3072
	global_load_lds_dwordx4 v[144:145], off
	v_lshl_add_u64 v[212:213], s[10:11], 0, v[128:129]
	s_add_i32 m0, s2, 0x2000
	s_nop 0
	global_load_lds_dwordx4 v[212:213], off
	s_barrier
	s_waitcnt lgkmcnt(0)
	s_setprio 1
	s_waitcnt lgkmcnt(0)
	v_mfma_f32_16x16x32_bf16 v[120:123], v[200:203], v[168:171], v[120:123]
	v_mfma_f32_16x16x32_bf16 v[120:123], v[204:207], v[172:175], v[120:123]
	v_mfma_f32_16x16x32_bf16 v[112:115], v[208:211], v[168:171], v[112:115]
	v_mfma_f32_16x16x32_bf16 v[112:115], v[218:221], v[172:175], v[112:115]
	v_mfma_f32_16x16x32_bf16 v[96:99], v[208:211], v[176:179], v[96:99]
	v_mfma_f32_16x16x32_bf16 v[96:99], v[218:221], v[180:183], v[96:99]
	v_mfma_f32_16x16x32_bf16 v[104:107], v[200:203], v[176:179], v[104:107]
	v_mfma_f32_16x16x32_bf16 v[104:107], v[204:207], v[180:183], v[104:107]
	v_mfma_f32_16x16x32_bf16 v[88:91], v[200:203], v[184:187], v[88:91]
	v_mfma_f32_16x16x32_bf16 v[88:91], v[204:207], v[188:191], v[88:91]
	v_mfma_f32_16x16x32_bf16 v[80:83], v[208:211], v[184:187], v[80:83]
	v_mfma_f32_16x16x32_bf16 v[80:83], v[218:221], v[188:191], v[80:83]
	v_mfma_f32_16x16x32_bf16 v[64:67], v[208:211], v[192:195], v[64:67]
	v_mfma_f32_16x16x32_bf16 v[64:67], v[218:221], v[196:199], v[64:67]
	v_mfma_f32_16x16x32_bf16 v[72:75], v[200:203], v[192:195], v[72:75]
	v_mfma_f32_16x16x32_bf16 v[72:75], v[204:207], v[196:199], v[72:75]
	s_setprio 0
	s_mov_b32 m0, s67
	v_lshl_add_u64 v[222:223], s[14:15], 0, v[134:135]
	s_barrier
	ds_read_b128 v[168:171], v150 offset:16384
	ds_read_b128 v[172:175], v150 offset:17408
	ds_read_b128 v[176:179], v150 offset:18432
	ds_read_b128 v[180:183], v150 offset:19456
	ds_read_b128 v[184:187], v150 offset:20480
	ds_read_b128 v[188:191], v150 offset:21504
	ds_read_b128 v[192:195], v150 offset:22528
	ds_read_b128 v[196:199], v150 offset:23552
	global_load_lds_dwordx4 v[222:223], off
	v_lshl_add_u64 v[224:225], s[14:15], 0, v[130:131]
	s_mov_b32 m0, s68
	s_nop 0
	global_load_lds_dwordx4 v[224:225], off
	s_barrier
	s_waitcnt lgkmcnt(0)
	s_setprio 1
	s_waitcnt lgkmcnt(0)
	v_mfma_f32_16x16x32_bf16 v[60:63], v[152:155], v[168:171], v[60:63]
	v_mfma_f32_16x16x32_bf16 v[60:63], v[156:159], v[172:175], v[60:63]
	v_mfma_f32_16x16x32_bf16 v[52:55], v[160:163], v[168:171], v[52:55]
	v_mfma_f32_16x16x32_bf16 v[52:55], v[164:167], v[172:175], v[52:55]
	v_mfma_f32_16x16x32_bf16 v[36:39], v[160:163], v[176:179], v[36:39]
	v_mfma_f32_16x16x32_bf16 v[36:39], v[164:167], v[180:183], v[36:39]
	v_mfma_f32_16x16x32_bf16 v[44:47], v[152:155], v[176:179], v[44:47]
	v_mfma_f32_16x16x32_bf16 v[44:47], v[156:159], v[180:183], v[44:47]
	v_mfma_f32_16x16x32_bf16 v[28:31], v[152:155], v[184:187], v[28:31]
	v_mfma_f32_16x16x32_bf16 v[28:31], v[156:159], v[188:191], v[28:31]
	v_mfma_f32_16x16x32_bf16 v[20:23], v[160:163], v[184:187], v[20:23]
	v_mfma_f32_16x16x32_bf16 v[20:23], v[164:167], v[188:191], v[20:23]
	v_mfma_f32_16x16x32_bf16 v[4:7], v[160:163], v[192:195], v[4:7]
	v_mfma_f32_16x16x32_bf16 v[4:7], v[164:167], v[196:199], v[4:7]
	v_mfma_f32_16x16x32_bf16 v[12:15], v[152:155], v[192:195], v[12:15]
	v_mfma_f32_16x16x32_bf16 v[12:15], v[156:159], v[196:199], v[12:15]
	s_setprio 0
	s_barrier
; #define PG8_STAGE(bufoff, gbase, voff) do { _Pragma("unroll") for (int _i = 0; _i < 2; ++_i) \
;         __builtin_amdgcn_global_load_lds((const unsigned*)((const char*)(gbase) + (voff)[_i]), (LAS unsigned*)(lds + (bufoff) + ldsw + _i * 8192), 16, 0, 0); } while (0)
; #define PG8_LDA(dst, b, h) do { _Pragma("unroll") for (int m = 0; m < 4; ++m) _Pragma("unroll") for (int k = 0; k < 2; ++k) dst[m][k] = *(const LAS bf16x8*)(lds + PG8_SA(b, h) + aoff + m * 2048 + k * 1024); } while (0)
; #define PG8_LDB(dst, b, h) do { _Pragma("unroll") for (int n = 0; n < 2; ++n) _Pragma("unroll") for (int k = 0; k < 2; ++k) dst[n][k] = *(const LAS bf16x8*)(lds + PG8_SB(b, h) + boff + n * 2048 + k * 1024); } while (0)
; #define PG8_MMA(ai, bj, At, Bt) do { __builtin_amdgcn_s_setprio(1); _Pragma("unroll") for (int m = 0; m < 4; ++m) _Pragma("unroll") for (int n = 0; n < 2; ++n) _Pragma("unroll") for (int k = 0; k < 2; ++k) \
;         acc[ai][bj][m][n] = __builtin_amdgcn_mfma_f32_16x16x32_bf16(Bt[n][k], At[m][k], acc[ai][bj][m][n], 0, 0, 0); __builtin_amdgcn_s_setprio(0); } while (0)
; #define PG8_WAIT_V(n) asm volatile("s_waitcnt vmcnt(" #n ")" ::: "memory")
; #define PG8_WAIT_L(n) asm volatile("s_waitcnt lgkmcnt(" #n ")" ::: "memory")
; #define PG8_BAR __builtin_amdgcn_s_barrier()
; #define PG8_SCHED __builtin_amdgcn_sched_barrier(0)
; template <class Epi>
; DEVINL void gemm_phase(LAS unsigned char* lds, const Gemm g, const Order& S, const Epi& E) {
;     ...
;             PG8_STAGE(PG8_SB(0, 1), b2 + hstepB, voffB);
;             PG8_WAIT_V(6); PG8_BAR; PG8_MMA(1, 1, At, B1); PG8_BAR;
;             PG8_LDB(B0, 1, 0); PG8_SCHED; PG8_LDA(At, 1, 0); PG8_STAGE(PG8_SA(0, 1), a2 + hstepA, voffA);
;             PG8_WAIT_L(8); PG8_BAR; PG8_WAIT_L(0); PG8_MMA(0, 0, At, B0); PG8_BAR; PG8_SCHED;
;             PG8_LDB(B1, 1, 1); PG8_STAGE(PG8_SB(1, 0), b3, voffB);
	s_add_u32 s96, s10, 0x80000
	s_addc_u32 s97, s11, 0
	s_add_i32 s2, s81, s38
	v_lshl_add_u64 v[152:153], s[96:97], 0, v[132:133]
	s_mov_b32 m0, s2
	s_nop 0
	global_load_lds_dwordx4 v[152:153], off
	v_lshl_add_u64 v[152:153], s[96:97], 0, v[128:129]
	s_add_i32 m0, s2, 0x2000
	s_nop 0
	global_load_lds_dwordx4 v[152:153], off
	s_waitcnt vmcnt(6)
	s_barrier
	s_setprio 1
	v_mfma_f32_16x16x32_bf16 v[56:59], v[200:203], v[168:171], v[56:59]
	v_mfma_f32_16x16x32_bf16 v[56:59], v[204:207], v[172:175], v[56:59]
	v_mfma_f32_16x16x32_bf16 v[48:51], v[208:211], v[168:171], v[48:51]
	v_mfma_f32_16x16x32_bf16 v[48:51], v[218:221], v[172:175], v[48:51]
	v_mfma_f32_16x16x32_bf16 v[32:35], v[208:211], v[176:179], v[32:35]
	v_mfma_f32_16x16x32_bf16 v[32:35], v[218:221], v[180:183], v[32:35]
	v_mfma_f32_16x16x32_bf16 v[40:43], v[200:203], v[176:179], v[40:43]
	v_mfma_f32_16x16x32_bf16 v[40:43], v[204:207], v[180:183], v[40:43]
	v_mfma_f32_16x16x32_bf16 v[24:27], v[200:203], v[184:187], v[24:27]
	v_mfma_f32_16x16x32_bf16 v[24:27], v[204:207], v[188:191], v[24:27]
	v_mfma_f32_16x16x32_bf16 v[16:19], v[208:211], v[184:187], v[16:19]
	v_mfma_f32_16x16x32_bf16 v[16:19], v[218:221], v[188:191], v[16:19]
	v_mfma_f32_16x16x32_bf16 v[0:3], v[208:211], v[192:195], v[0:3]
	v_mfma_f32_16x16x32_bf16 v[0:3], v[218:221], v[196:199], v[0:3]
	v_mfma_f32_16x16x32_bf16 v[8:11], v[200:203], v[192:195], v[8:11]
	v_mfma_f32_16x16x32_bf16 v[8:11], v[204:207], v[196:199], v[8:11]
	s_setprio 0
	s_add_i32 s2, 16, 0x18000
	v_add_u32_e32 v164, s2, v147
	s_barrier
	ds_read_b128 v[152:155], v164
	ds_read_b128 v[156:159], v164 offset:1024
	ds_read_b128 v[160:163], v164 offset:2048
	ds_read_b128 v[164:167], v164 offset:3072
	s_add_u32 s14, s14, 0x80000
	s_addc_u32 s15, s15, 0
	s_mov_b32 m0, s69
	v_lshl_add_u64 v[200:201], s[14:15], 0, v[134:135]
	ds_read_b128 v[168:171], v150 offset:32768
	ds_read_b128 v[172:175], v150 offset:33792
	ds_read_b128 v[176:179], v150 offset:34816
	ds_read_b128 v[180:183], v150 offset:35840
	ds_read_b128 v[184:187], v150 offset:36864
	ds_read_b128 v[188:191], v150 offset:37888
	ds_read_b128 v[192:195], v150 offset:38912
	ds_read_b128 v[196:199], v150 offset:39936
	global_load_lds_dwordx4 v[200:201], off
	v_lshl_add_u64 v[200:201], s[14:15], 0, v[130:131]
	s_mov_b32 m0, s72
	s_nop 0
	global_load_lds_dwordx4 v[200:201], off
	s_waitcnt lgkmcnt(8)
	s_barrier
	s_waitcnt lgkmcnt(0)
	s_setprio 1
	s_waitcnt lgkmcnt(0)
	v_mfma_f32_16x16x32_bf16 v[124:127], v[152:155], v[168:171], v[124:127]
	v_mfma_f32_16x16x32_bf16 v[124:127], v[156:159], v[172:175], v[124:127]
	v_mfma_f32_16x16x32_bf16 v[116:119], v[160:163], v[168:171], v[116:119]
	v_mfma_f32_16x16x32_bf16 v[116:119], v[164:167], v[172:175], v[116:119]
	v_mfma_f32_16x16x32_bf16 v[100:103], v[160:163], v[176:179], v[100:103]
	v_mfma_f32_16x16x32_bf16 v[100:103], v[164:167], v[180:183], v[100:103]
	v_mfma_f32_16x16x32_bf16 v[108:111], v[152:155], v[176:179], v[108:111]
	v_mfma_f32_16x16x32_bf16 v[108:111], v[156:159], v[180:183], v[108:111]
	v_mfma_f32_16x16x32_bf16 v[92:95], v[152:155], v[184:187], v[92:95]
	v_mfma_f32_16x16x32_bf16 v[92:95], v[156:159], v[188:191], v[92:95]
	v_mfma_f32_16x16x32_bf16 v[84:87], v[160:163], v[184:187], v[84:87]
	v_mfma_f32_16x16x32_bf16 v[84:87], v[164:167], v[188:191], v[84:87]
	v_mfma_f32_16x16x32_bf16 v[68:71], v[160:163], v[192:195], v[68:71]
	v_mfma_f32_16x16x32_bf16 v[68:71], v[164:167], v[196:199], v[68:71]
	v_mfma_f32_16x16x32_bf16 v[76:79], v[152:155], v[192:195], v[76:79]
	v_mfma_f32_16x16x32_bf16 v[76:79], v[156:159], v[196:199], v[76:79]
	s_setprio 0
	s_barrier
	s_add_i32 s3, 16, 0x1c000
	s_add_i32 s2, s2, s38
	v_add_u32_e32 v214, s3, v147
	v_lshl_add_u64 v[144:145], v[144:145], 0, s[6:7]
	s_mov_b32 m0, s2
	ds_read_b128 v[200:203], v214
	ds_read_b128 v[204:207], v214 offset:1024
	ds_read_b128 v[208:211], v214 offset:2048
	ds_read_b128 v[218:221], v214 offset:3072
	global_load_lds_dwordx4 v[144:145], off
	v_lshl_add_u64 v[144:145], v[212:213], 0, s[6:7]
	s_add_i32 m0, s2, 0x2000
	s_nop 0
	global_load_lds_dwordx4 v[144:145], off
	s_barrier
; #define PG8_STAGE(bufoff, gbase, voff) do { _Pragma("unroll") for (int _i = 0; _i < 2; ++_i) \
;         __builtin_amdgcn_global_load_lds((const unsigned*)((const char*)(gbase) + (voff)[_i]), (LAS unsigned*)(lds + (bufoff) + ldsw + _i * 8192), 16, 0, 0); } while (0)
; #define PG8_LDA(dst, b, h) do { _Pragma("unroll") for (int m = 0; m < 4; ++m) _Pragma("unroll") for (int k = 0; k < 2; ++k) dst[m][k] = *(const LAS bf16x8*)(lds + PG8_SA(b, h) + aoff + m * 2048 + k * 1024); } while (0)
; #define PG8_MMA(ai, bj, At, Bt) do { __builtin_amdgcn_s_setprio(1); _Pragma("unroll") for (int m = 0; m < 4; ++m) _Pragma("unroll") for (int n = 0; n < 2; ++n) _Pragma("unroll") for (int k = 0; k < 2; ++k) \
;         acc[ai][bj][m][n] = __builtin_amdgcn_mfma_f32_16x16x32_bf16(Bt[n][k], At[m][k], acc[ai][bj][m][n], 0, 0, 0); __builtin_amdgcn_s_setprio(0); } while (0)
; #define PG8_WAIT_V(n) asm volatile("s_waitcnt vmcnt(" #n ")" ::: "memory")
; #define PG8_WAIT_L(n) asm volatile("s_waitcnt lgkmcnt(" #n ")" ::: "memory")
; #define PG8_BAR __builtin_amdgcn_s_barrier()
; #define PG8_SCHED __builtin_amdgcn_sched_barrier(0)
; template <class Epi>
; DEVINL void gemm_phase(LAS unsigned char* lds, const Gemm g, const Order& S, const Epi& E) {
;     ...
;             PG8_BAR; PG8_WAIT_L(0); PG8_MMA(0, 1, At, B1); PG8_BAR;
;             PG8_LDA(At, 1, 1); PG8_STAGE(PG8_SA(1, 0), a3, voffA);
;             PG8_BAR; PG8_WAIT_L(0); PG8_MMA(1, 0, At, B0); PG8_BAR; PG8_SCHED;
;             PG8_STAGE(PG8_SB(1, 1), b3 + hstepB, voffB);
;             PG8_WAIT_V(6); PG8_BAR; PG8_MMA(1, 1, At, B1); PG8_BAR;
	s_waitcnt lgkmcnt(0)
	s_setprio 1
	s_waitcnt lgkmcnt(0)
	v_mfma_f32_16x16x32_bf16 v[120:123], v[200:203], v[168:171], v[120:123]
	v_mfma_f32_16x16x32_bf16 v[120:123], v[204:207], v[172:175], v[120:123]
	v_mfma_f32_16x16x32_bf16 v[112:115], v[208:211], v[168:171], v[112:115]
	v_mfma_f32_16x16x32_bf16 v[112:115], v[218:221], v[172:175], v[112:115]
	v_mfma_f32_16x16x32_bf16 v[96:99], v[208:211], v[176:179], v[96:99]
	v_mfma_f32_16x16x32_bf16 v[96:99], v[218:221], v[180:183], v[96:99]
	v_mfma_f32_16x16x32_bf16 v[104:107], v[200:203], v[176:179], v[104:107]
	v_mfma_f32_16x16x32_bf16 v[104:107], v[204:207], v[180:183], v[104:107]
	v_mfma_f32_16x16x32_bf16 v[88:91], v[200:203], v[184:187], v[88:91]
	v_mfma_f32_16x16x32_bf16 v[88:91], v[204:207], v[188:191], v[88:91]
	v_mfma_f32_16x16x32_bf16 v[80:83], v[208:211], v[184:187], v[80:83]
	v_mfma_f32_16x16x32_bf16 v[80:83], v[218:221], v[188:191], v[80:83]
	v_mfma_f32_16x16x32_bf16 v[64:67], v[208:211], v[192:195], v[64:67]
	v_mfma_f32_16x16x32_bf16 v[64:67], v[218:221], v[196:199], v[64:67]
	v_mfma_f32_16x16x32_bf16 v[72:75], v[200:203], v[192:195], v[72:75]
	v_mfma_f32_16x16x32_bf16 v[72:75], v[204:207], v[196:199], v[72:75]
	s_setprio 0
	s_mov_b32 m0, s74
	v_lshl_add_u64 v[144:145], v[222:223], 0, s[6:7]
	s_barrier
	ds_read_b128 v[168:171], v150 offset:49152
	ds_read_b128 v[172:175], v150 offset:50176
	ds_read_b128 v[176:179], v150 offset:51200
	ds_read_b128 v[180:183], v150 offset:52224
	ds_read_b128 v[184:187], v150 offset:53248
	ds_read_b128 v[188:191], v150 offset:54272
	ds_read_b128 v[192:195], v150 offset:55296
	ds_read_b128 v[196:199], v150 offset:56320
	global_load_lds_dwordx4 v[144:145], off
	v_lshl_add_u64 v[144:145], v[224:225], 0, s[6:7]
	s_mov_b32 m0, s75
	s_nop 0
	global_load_lds_dwordx4 v[144:145], off
	s_barrier
	s_waitcnt lgkmcnt(0)
	s_setprio 1
	s_waitcnt lgkmcnt(0)
	v_mfma_f32_16x16x32_bf16 v[60:63], v[152:155], v[168:171], v[60:63]
	v_mfma_f32_16x16x32_bf16 v[60:63], v[156:159], v[172:175], v[60:63]
	v_mfma_f32_16x16x32_bf16 v[52:55], v[160:163], v[168:171], v[52:55]
	v_mfma_f32_16x16x32_bf16 v[52:55], v[164:167], v[172:175], v[52:55]
	v_mfma_f32_16x16x32_bf16 v[36:39], v[160:163], v[176:179], v[36:39]
	v_mfma_f32_16x16x32_bf16 v[36:39], v[164:167], v[180:183], v[36:39]
	v_mfma_f32_16x16x32_bf16 v[44:47], v[152:155], v[176:179], v[44:47]
	v_mfma_f32_16x16x32_bf16 v[44:47], v[156:159], v[180:183], v[44:47]
	v_mfma_f32_16x16x32_bf16 v[28:31], v[152:155], v[184:187], v[28:31]
	v_mfma_f32_16x16x32_bf16 v[28:31], v[156:159], v[188:191], v[28:31]
	v_mfma_f32_16x16x32_bf16 v[20:23], v[160:163], v[184:187], v[20:23]
	v_mfma_f32_16x16x32_bf16 v[20:23], v[164:167], v[188:191], v[20:23]
	v_mfma_f32_16x16x32_bf16 v[4:7], v[160:163], v[192:195], v[4:7]
	v_mfma_f32_16x16x32_bf16 v[4:7], v[164:167], v[196:199], v[4:7]
	v_mfma_f32_16x16x32_bf16 v[12:15], v[152:155], v[192:195], v[12:15]
	v_mfma_f32_16x16x32_bf16 v[12:15], v[156:159], v[196:199], v[12:15]
	s_setprio 0
	s_barrier
	s_add_u32 s10, s10, 0x80080
	s_addc_u32 s11, s11, 0
	s_add_i32 s2, s3, s38
	v_lshl_add_u64 v[144:145], s[10:11], 0, v[132:133]
	s_mov_b32 m0, s2
	s_nop 0
	global_load_lds_dwordx4 v[144:145], off
	v_lshl_add_u64 v[144:145], s[10:11], 0, v[128:129]
	s_add_i32 m0, s2, 0x2000
	s_nop 0
	global_load_lds_dwordx4 v[144:145], off
	s_waitcnt vmcnt(6)
	s_barrier
	s_setprio 1
	v_mfma_f32_16x16x32_bf16 v[56:59], v[200:203], v[168:171], v[56:59]
	v_mfma_f32_16x16x32_bf16 v[56:59], v[204:207], v[172:175], v[56:59]
	v_mfma_f32_16x16x32_bf16 v[48:51], v[208:211], v[168:171], v[48:51]
	v_mfma_f32_16x16x32_bf16 v[48:51], v[218:221], v[172:175], v[48:51]
	v_mfma_f32_16x16x32_bf16 v[32:35], v[208:211], v[176:179], v[32:35]
	v_mfma_f32_16x16x32_bf16 v[32:35], v[218:221], v[180:183], v[32:35]
	v_mfma_f32_16x16x32_bf16 v[40:43], v[200:203], v[176:179], v[40:43]
	v_mfma_f32_16x16x32_bf16 v[40:43], v[204:207], v[180:183], v[40:43]
	v_mfma_f32_16x16x32_bf16 v[24:27], v[200:203], v[184:187], v[24:27]
	v_mfma_f32_16x16x32_bf16 v[24:27], v[204:207], v[188:191], v[24:27]
	v_mfma_f32_16x16x32_bf16 v[16:19], v[208:211], v[184:187], v[16:19]
	v_mfma_f32_16x16x32_bf16 v[16:19], v[218:221], v[188:191], v[16:19]
	v_mfma_f32_16x16x32_bf16 v[0:3], v[208:211], v[192:195], v[0:3]
	v_mfma_f32_16x16x32_bf16 v[0:3], v[218:221], v[196:199], v[0:3]
	v_mfma_f32_16x16x32_bf16 v[8:11], v[200:203], v[192:195], v[8:11]
	v_mfma_f32_16x16x32_bf16 v[8:11], v[204:207], v[196:199], v[8:11]
	s_setprio 0
	s_add_u32 s12, s12, 0x100
	s_addc_u32 s13, s13, 0
	s_add_u32 s86, s86, 0x100
	s_addc_u32 s87, s87, 0
	s_cmp_ge_i32 s93, s73
	s_mov_b32 s10, s93
	s_barrier
	s_cbranch_scc0 .LBB0_340
	s_branch .LBB0_335

; #define PG8_STAGE(bufoff, gbase, voff) do { _Pragma("unroll") for (int _i = 0; _i < 2; ++_i) \
;         __builtin_amdgcn_global_load_lds((const unsigned*)((const char*)(gbase) + (voff)[_i]), (LAS unsigned*)(lds + (bufoff) + ldsw + _i * 8192), 16, 0, 0); } while (0)
; #define PG8_LDA(dst, b, h) do { _Pragma("unroll") for (int m = 0; m < 4; ++m) _Pragma("unroll") for (int k = 0; k < 2; ++k) dst[m][k] = *(const LAS bf16x8*)(lds + PG8_SA(b, h) + aoff + m * 2048 + k * 1024); } while (0)
; #define PG8_LDB(dst, b, h) do { _Pragma("unroll") for (int n = 0; n < 2; ++n) _Pragma("unroll") for (int k = 0; k < 2; ++k) dst[n][k] = *(const LAS bf16x8*)(lds + PG8_SB(b, h) + boff + n * 2048 + k * 1024); } while (0)
; #define PG8_MMA(ai, bj, At, Bt) do { __builtin_amdgcn_s_setprio(1); _Pragma("unroll") for (int m = 0; m < 4; ++m) _Pragma("unroll") for (int n = 0; n < 2; ++n) _Pragma("unroll") for (int k = 0; k < 2; ++k) \
;         acc[ai][bj][m][n] = __builtin_amdgcn_mfma_f32_16x16x32_bf16(Bt[n][k], At[m][k], acc[ai][bj][m][n], 0, 0, 0); __builtin_amdgcn_s_setprio(0); } while (0)
; #define PG8_WAIT_L(n) asm volatile("s_waitcnt lgkmcnt(" #n ")" ::: "memory")
; #define PG8_BAR __builtin_amdgcn_s_barrier()
; #define PG8_SCHED __builtin_amdgcn_sched_barrier(0)
; template <class Epi>
; DEVINL void gemm_phase(LAS unsigned char* lds, const Gemm g, const Order& S, const Epi& E) {
;     ...
;         for (int t = 0; t < nt; t += 2) {
;             const bool last = (t == nt - 2);
;             const char* a1 = cA + (size_t)(t + 1) * kstep;
;             const char* a2 = last ? nA : cA + (size_t)(t + 2) * kstep; const char* b2 = last ? nB : cB + (size_t)(t + 2) * kstep;
;             const char* a3 = a2 + kstep; const char* b3 = b2 + kstep;
;             PG8_LDB(B0, 0, 0); PG8_SCHED; PG8_LDA(At, 0, 0); PG8_STAGE(PG8_SA(1, 1), a1 + hstepA, voffA);
;             PG8_WAIT_L(8); PG8_BAR; PG8_WAIT_L(0); PG8_MMA(0, 0, At, B0); PG8_BAR; PG8_SCHED;
;             PG8_LDB(B1, 0, 1); PG8_STAGE(PG8_SB(0, 0), b2, voffB);
;             PG8_BAR; PG8_WAIT_L(0); PG8_MMA(0, 1, At, B1); PG8_BAR;
;             PG8_LDA(At, 0, 1); PG8_STAGE(PG8_SA(0, 0), a2, voffA);
;             PG8_BAR; PG8_WAIT_L(0); PG8_MMA(1, 0, At, B0); PG8_BAR; PG8_SCHED;
.LBB0_361:
	ds_read_b128 v[146:149], v143
	ds_read_b128 v[150:153], v143 offset:1024
	ds_read_b128 v[154:157], v143 offset:2048
	ds_read_b128 v[158:161], v143 offset:3072
	s_add_i32 s87, s10, 2
	s_add_u32 s2, s12, 0xfff80080
	s_addc_u32 s3, s13, -1
	s_cmp_eq_u32 s36, s10
	s_cselect_b32 s10, s84, s85
	s_cselect_b32 s15, s63, s3
	s_cselect_b32 s14, s65, s2
	s_cselect_b32 s11, s83, s86
	v_lshl_add_u64 v[194:195], s[12:13], 0, v[136:137]
	s_add_i32 m0, s5, 0xc000
	ds_read_b128 v[162:165], v144
	ds_read_b128 v[166:169], v144 offset:1024
	ds_read_b128 v[170:173], v144 offset:2048
	ds_read_b128 v[174:177], v144 offset:3072
	ds_read_b128 v[178:181], v144 offset:4096
	ds_read_b128 v[182:185], v144 offset:5120
	ds_read_b128 v[186:189], v144 offset:6144
	ds_read_b128 v[190:193], v144 offset:7168
	global_load_lds_dwordx4 v[194:195], off
	v_lshl_add_u64 v[194:195], s[12:13], 0, v[138:139]
	s_add_i32 m0, s5, 0xe000
	s_nop 0
	global_load_lds_dwordx4 v[194:195], off
	s_waitcnt lgkmcnt(8)
	s_barrier
	s_waitcnt lgkmcnt(0)
	s_setprio 1
	s_waitcnt lgkmcnt(0)
	v_mfma_f32_16x16x32_bf16 v[120:123], v[146:149], v[162:165], v[120:123]
	v_mfma_f32_16x16x32_bf16 v[120:123], v[150:153], v[166:169], v[120:123]
	v_mfma_f32_16x16x32_bf16 v[124:127], v[154:157], v[162:165], v[124:127]
	v_mfma_f32_16x16x32_bf16 v[124:127], v[158:161], v[166:169], v[124:127]
	v_mfma_f32_16x16x32_bf16 v[104:107], v[154:157], v[170:173], v[104:107]
	v_mfma_f32_16x16x32_bf16 v[104:107], v[158:161], v[174:177], v[104:107]
	v_mfma_f32_16x16x32_bf16 v[108:111], v[146:149], v[170:173], v[108:111]
	v_mfma_f32_16x16x32_bf16 v[108:111], v[150:153], v[174:177], v[108:111]
	v_mfma_f32_16x16x32_bf16 v[92:95], v[146:149], v[178:181], v[92:95]
	v_mfma_f32_16x16x32_bf16 v[92:95], v[150:153], v[182:185], v[92:95]
	v_mfma_f32_16x16x32_bf16 v[88:91], v[154:157], v[178:181], v[88:91]
	v_mfma_f32_16x16x32_bf16 v[88:91], v[158:161], v[182:185], v[88:91]
	v_mfma_f32_16x16x32_bf16 v[72:75], v[154:157], v[186:189], v[72:75]
	v_mfma_f32_16x16x32_bf16 v[72:75], v[158:161], v[190:193], v[72:75]
	v_mfma_f32_16x16x32_bf16 v[76:79], v[146:149], v[186:189], v[76:79]
	v_mfma_f32_16x16x32_bf16 v[76:79], v[150:153], v[190:193], v[76:79]
	s_setprio 0
	s_barrier
	s_add_i32 s2, s80, s68
	v_lshl_add_u64 v[210:211], s[10:11], 0, v[130:131]
	s_mov_b32 m0, s2
	ds_read_b128 v[194:197], v145
	ds_read_b128 v[198:201], v145 offset:1024
	ds_read_b128 v[202:205], v145 offset:2048
	ds_read_b128 v[206:209], v145 offset:3072
	global_load_lds_dwordx4 v[210:211], off
	v_lshl_add_u64 v[212:213], s[10:11], 0, v[134:135]
	s_add_i32 m0, s2, 0x2000
	s_nop 0
	global_load_lds_dwordx4 v[212:213], off
	s_barrier
	s_waitcnt lgkmcnt(0)
	s_setprio 1
	s_waitcnt lgkmcnt(0)
	v_mfma_f32_16x16x32_bf16 v[116:119], v[194:197], v[162:165], v[116:119]
	v_mfma_f32_16x16x32_bf16 v[116:119], v[198:201], v[166:169], v[116:119]
	v_mfma_f32_16x16x32_bf16 v[112:115], v[202:205], v[162:165], v[112:115]
	v_mfma_f32_16x16x32_bf16 v[112:115], v[206:209], v[166:169], v[112:115]
	v_mfma_f32_16x16x32_bf16 v[96:99], v[202:205], v[170:173], v[96:99]
	v_mfma_f32_16x16x32_bf16 v[96:99], v[206:209], v[174:177], v[96:99]
	v_mfma_f32_16x16x32_bf16 v[100:103], v[194:197], v[170:173], v[100:103]
	v_mfma_f32_16x16x32_bf16 v[100:103], v[198:201], v[174:177], v[100:103]
	v_mfma_f32_16x16x32_bf16 v[84:87], v[194:197], v[178:181], v[84:87]
	v_mfma_f32_16x16x32_bf16 v[84:87], v[198:201], v[182:185], v[84:87]
	v_mfma_f32_16x16x32_bf16 v[80:83], v[202:205], v[178:181], v[80:83]
	v_mfma_f32_16x16x32_bf16 v[80:83], v[206:209], v[182:185], v[80:83]
	v_mfma_f32_16x16x32_bf16 v[64:67], v[202:205], v[186:189], v[64:67]
	v_mfma_f32_16x16x32_bf16 v[64:67], v[206:209], v[190:193], v[64:67]
	v_mfma_f32_16x16x32_bf16 v[68:71], v[194:197], v[186:189], v[68:71]
	v_mfma_f32_16x16x32_bf16 v[68:71], v[198:201], v[190:193], v[68:71]
	s_setprio 0
	s_mov_b32 m0, s5
	v_lshl_add_u64 v[218:219], s[14:15], 0, v[128:129]
	s_barrier
	ds_read_b128 v[162:165], v144 offset:16384
	ds_read_b128 v[166:169], v144 offset:17408
	ds_read_b128 v[170:173], v144 offset:18432
	ds_read_b128 v[174:177], v144 offset:19456
	ds_read_b128 v[178:181], v144 offset:20480
	ds_read_b128 v[182:185], v144 offset:21504
	ds_read_b128 v[186:189], v144 offset:22528
	ds_read_b128 v[190:193], v144 offset:23552
	global_load_lds_dwordx4 v[218:219], off
	v_lshl_add_u64 v[220:221], s[14:15], 0, v[132:133]
	s_mov_b32 m0, s69
	s_nop 0
	global_load_lds_dwordx4 v[220:221], off
	s_barrier
	s_waitcnt lgkmcnt(0)
	s_setprio 1
	s_waitcnt lgkmcnt(0)
	v_mfma_f32_16x16x32_bf16 v[60:63], v[146:149], v[162:165], v[60:63]
	v_mfma_f32_16x16x32_bf16 v[60:63], v[150:153], v[166:169], v[60:63]
	v_mfma_f32_16x16x32_bf16 v[56:59], v[154:157], v[162:165], v[56:59]
	v_mfma_f32_16x16x32_bf16 v[56:59], v[158:161], v[166:169], v[56:59]
	v_mfma_f32_16x16x32_bf16 v[40:43], v[154:157], v[170:173], v[40:43]
	v_mfma_f32_16x16x32_bf16 v[40:43], v[158:161], v[174:177], v[40:43]
	v_mfma_f32_16x16x32_bf16 v[44:47], v[146:149], v[170:173], v[44:47]
	v_mfma_f32_16x16x32_bf16 v[44:47], v[150:153], v[174:177], v[44:47]
	v_mfma_f32_16x16x32_bf16 v[28:31], v[146:149], v[178:181], v[28:31]
	v_mfma_f32_16x16x32_bf16 v[28:31], v[150:153], v[182:185], v[28:31]
	v_mfma_f32_16x16x32_bf16 v[24:27], v[154:157], v[178:181], v[24:27]
	v_mfma_f32_16x16x32_bf16 v[24:27], v[158:161], v[182:185], v[24:27]
	v_mfma_f32_16x16x32_bf16 v[8:11], v[154:157], v[186:189], v[8:11]
	v_mfma_f32_16x16x32_bf16 v[8:11], v[158:161], v[190:193], v[8:11]
	v_mfma_f32_16x16x32_bf16 v[12:15], v[146:149], v[186:189], v[12:15]
	v_mfma_f32_16x16x32_bf16 v[12:15], v[150:153], v[190:193], v[12:15]
	s_setprio 0
	s_barrier
; #define PG8_STAGE(bufoff, gbase, voff) do { _Pragma("unroll") for (int _i = 0; _i < 2; ++_i) \
;         __builtin_amdgcn_global_load_lds((const unsigned*)((const char*)(gbase) + (voff)[_i]), (LAS unsigned*)(lds + (bufoff) + ldsw + _i * 8192), 16, 0, 0); } while (0)
; #define PG8_LDA(dst, b, h) do { _Pragma("unroll") for (int m = 0; m < 4; ++m) _Pragma("unroll") for (int k = 0; k < 2; ++k) dst[m][k] = *(const LAS bf16x8*)(lds + PG8_SA(b, h) + aoff + m * 2048 + k * 1024); } while (0)
; #define PG8_LDB(dst, b, h) do { _Pragma("unroll") for (int n = 0; n < 2; ++n) _Pragma("unroll") for (int k = 0; k < 2; ++k) dst[n][k] = *(const LAS bf16x8*)(lds + PG8_SB(b, h) + boff + n * 2048 + k * 1024); } while (0)
; #define PG8_MMA(ai, bj, At, Bt) do { __builtin_amdgcn_s_setprio(1); _Pragma("unroll") for (int m = 0; m < 4; ++m) _Pragma("unroll") for (int n = 0; n < 2; ++n) _Pragma("unroll") for (int k = 0; k < 2; ++k) \
;         acc[ai][bj][m][n] = __builtin_amdgcn_mfma_f32_16x16x32_bf16(Bt[n][k], At[m][k], acc[ai][bj][m][n], 0, 0, 0); __builtin_amdgcn_s_setprio(0); } while (0)
; #define PG8_WAIT_V(n) asm volatile("s_waitcnt vmcnt(" #n ")" ::: "memory")
; #define PG8_WAIT_L(n) asm volatile("s_waitcnt lgkmcnt(" #n ")" ::: "memory")
; #define PG8_BAR __builtin_amdgcn_s_barrier()
; #define PG8_SCHED __builtin_amdgcn_sched_barrier(0)
; template <class Epi>
; DEVINL void gemm_phase(LAS unsigned char* lds, const Gemm g, const Order& S, const Epi& E) {
;     ...
;             PG8_STAGE(PG8_SB(0, 1), b2 + hstepB, voffB);
;             PG8_WAIT_V(6); PG8_BAR; PG8_MMA(1, 1, At, B1); PG8_BAR;
;             PG8_LDB(B0, 1, 0); PG8_SCHED; PG8_LDA(At, 1, 0); PG8_STAGE(PG8_SA(0, 1), a2 + hstepA, voffA);
;             PG8_WAIT_L(8); PG8_BAR; PG8_WAIT_L(0); PG8_MMA(0, 0, At, B0); PG8_BAR; PG8_SCHED;
;             PG8_LDB(B1, 1, 1); PG8_STAGE(PG8_SB(1, 0), b3, voffB);
	s_add_u32 vcc_lo, s10, 0x80000
	s_addc_u32 vcc_hi, s11, 0
	s_add_i32 s2, s81, s68
	v_lshl_add_u64 v[146:147], vcc, 0, v[130:131]
	s_mov_b32 m0, s2
	s_nop 0
	global_load_lds_dwordx4 v[146:147], off
	v_lshl_add_u64 v[146:147], vcc, 0, v[134:135]
	s_add_i32 m0, s2, 0x2000
	s_nop 0
	global_load_lds_dwordx4 v[146:147], off
	s_waitcnt vmcnt(6)
	s_barrier
	s_setprio 1
	v_mfma_f32_16x16x32_bf16 v[52:55], v[194:197], v[162:165], v[52:55]
	v_mfma_f32_16x16x32_bf16 v[52:55], v[198:201], v[166:169], v[52:55]
	v_mfma_f32_16x16x32_bf16 v[48:51], v[202:205], v[162:165], v[48:51]
	v_mfma_f32_16x16x32_bf16 v[48:51], v[206:209], v[166:169], v[48:51]
	v_mfma_f32_16x16x32_bf16 v[32:35], v[202:205], v[170:173], v[32:35]
	v_mfma_f32_16x16x32_bf16 v[32:35], v[206:209], v[174:177], v[32:35]
	v_mfma_f32_16x16x32_bf16 v[36:39], v[194:197], v[170:173], v[36:39]
	v_mfma_f32_16x16x32_bf16 v[36:39], v[198:201], v[174:177], v[36:39]
	v_mfma_f32_16x16x32_bf16 v[20:23], v[194:197], v[178:181], v[20:23]
	v_mfma_f32_16x16x32_bf16 v[20:23], v[198:201], v[182:185], v[20:23]
	v_mfma_f32_16x16x32_bf16 v[16:19], v[202:205], v[178:181], v[16:19]
	v_mfma_f32_16x16x32_bf16 v[16:19], v[206:209], v[182:185], v[16:19]
	v_mfma_f32_16x16x32_bf16 v[0:3], v[202:205], v[186:189], v[0:3]
	v_mfma_f32_16x16x32_bf16 v[0:3], v[206:209], v[190:193], v[0:3]
	v_mfma_f32_16x16x32_bf16 v[4:7], v[194:197], v[186:189], v[4:7]
	v_mfma_f32_16x16x32_bf16 v[4:7], v[198:201], v[190:193], v[4:7]
	s_setprio 0
	s_add_i32 s2, 16, 0x18000
	v_add_u32_e32 v158, s2, v141
	s_barrier
	ds_read_b128 v[146:149], v158
	ds_read_b128 v[150:153], v158 offset:1024
	ds_read_b128 v[154:157], v158 offset:2048
	ds_read_b128 v[158:161], v158 offset:3072
	s_add_u32 s14, s14, 0x80000
	s_addc_u32 s15, s15, 0
	s_mov_b32 m0, s72
	v_lshl_add_u64 v[194:195], s[14:15], 0, v[128:129]
	ds_read_b128 v[162:165], v144 offset:32768
	ds_read_b128 v[166:169], v144 offset:33792
	ds_read_b128 v[170:173], v144 offset:34816
	ds_read_b128 v[174:177], v144 offset:35840
	ds_read_b128 v[178:181], v144 offset:36864
	ds_read_b128 v[182:185], v144 offset:37888
	ds_read_b128 v[186:189], v144 offset:38912
	ds_read_b128 v[190:193], v144 offset:39936
	global_load_lds_dwordx4 v[194:195], off
	v_lshl_add_u64 v[194:195], s[14:15], 0, v[132:133]
	s_mov_b32 m0, s73
	s_nop 0
	global_load_lds_dwordx4 v[194:195], off
	s_waitcnt lgkmcnt(8)
	s_barrier
	s_waitcnt lgkmcnt(0)
	s_setprio 1
	s_waitcnt lgkmcnt(0)
	v_mfma_f32_16x16x32_bf16 v[120:123], v[146:149], v[162:165], v[120:123]
	v_mfma_f32_16x16x32_bf16 v[120:123], v[150:153], v[166:169], v[120:123]
	v_mfma_f32_16x16x32_bf16 v[124:127], v[154:157], v[162:165], v[124:127]
	v_mfma_f32_16x16x32_bf16 v[124:127], v[158:161], v[166:169], v[124:127]
	v_mfma_f32_16x16x32_bf16 v[104:107], v[154:157], v[170:173], v[104:107]
	v_mfma_f32_16x16x32_bf16 v[104:107], v[158:161], v[174:177], v[104:107]
	v_mfma_f32_16x16x32_bf16 v[108:111], v[146:149], v[170:173], v[108:111]
	v_mfma_f32_16x16x32_bf16 v[108:111], v[150:153], v[174:177], v[108:111]
	v_mfma_f32_16x16x32_bf16 v[92:95], v[146:149], v[178:181], v[92:95]
	v_mfma_f32_16x16x32_bf16 v[92:95], v[150:153], v[182:185], v[92:95]
	v_mfma_f32_16x16x32_bf16 v[88:91], v[154:157], v[178:181], v[88:91]
	v_mfma_f32_16x16x32_bf16 v[88:91], v[158:161], v[182:185], v[88:91]
	v_mfma_f32_16x16x32_bf16 v[72:75], v[154:157], v[186:189], v[72:75]
	v_mfma_f32_16x16x32_bf16 v[72:75], v[158:161], v[190:193], v[72:75]
	v_mfma_f32_16x16x32_bf16 v[76:79], v[146:149], v[186:189], v[76:79]
	v_mfma_f32_16x16x32_bf16 v[76:79], v[150:153], v[190:193], v[76:79]
	s_setprio 0
	s_barrier
	s_add_i32 s3, 16, 0x1c000
	s_add_i32 s2, s2, s68
	v_add_u32_e32 v206, s3, v141
	v_lshl_add_u64 v[210:211], v[210:211], 0, s[0:1]
	s_mov_b32 m0, s2
	ds_read_b128 v[194:197], v206
	ds_read_b128 v[198:201], v206 offset:1024
	ds_read_b128 v[202:205], v206 offset:2048
	ds_read_b128 v[206:209], v206 offset:3072
	global_load_lds_dwordx4 v[210:211], off
	v_lshl_add_u64 v[210:211], v[212:213], 0, s[0:1]
	s_add_i32 m0, s2, 0x2000
	s_nop 0
	global_load_lds_dwordx4 v[210:211], off
	s_barrier
; #define PG8_STAGE(bufoff, gbase, voff) do { _Pragma("unroll") for (int _i = 0; _i < 2; ++_i) \
;         __builtin_amdgcn_global_load_lds((const unsigned*)((const char*)(gbase) + (voff)[_i]), (LAS unsigned*)(lds + (bufoff) + ldsw + _i * 8192), 16, 0, 0); } while (0)
; #define PG8_LDA(dst, b, h) do { _Pragma("unroll") for (int m = 0; m < 4; ++m) _Pragma("unroll") for (int k = 0; k < 2; ++k) dst[m][k] = *(const LAS bf16x8*)(lds + PG8_SA(b, h) + aoff + m * 2048 + k * 1024); } while (0)
; #define PG8_MMA(ai, bj, At, Bt) do { __builtin_amdgcn_s_setprio(1); _Pragma("unroll") for (int m = 0; m < 4; ++m) _Pragma("unroll") for (int n = 0; n < 2; ++n) _Pragma("unroll") for (int k = 0; k < 2; ++k) \
;         acc[ai][bj][m][n] = __builtin_amdgcn_mfma_f32_16x16x32_bf16(Bt[n][k], At[m][k], acc[ai][bj][m][n], 0, 0, 0); __builtin_amdgcn_s_setprio(0); } while (0)
; #define PG8_WAIT_V(n) asm volatile("s_waitcnt vmcnt(" #n ")" ::: "memory")
; #define PG8_WAIT_L(n) asm volatile("s_waitcnt lgkmcnt(" #n ")" ::: "memory")
; #define PG8_BAR __builtin_amdgcn_s_barrier()
; #define PG8_SCHED __builtin_amdgcn_sched_barrier(0)
; template <class Epi>
; DEVINL void gemm_phase(LAS unsigned char* lds, const Gemm g, const Order& S, const Epi& E) {
;     ...
;             PG8_BAR; PG8_WAIT_L(0); PG8_MMA(0, 1, At, B1); PG8_BAR;
;             PG8_LDA(At, 1, 1); PG8_STAGE(PG8_SA(1, 0), a3, voffA);
;             PG8_BAR; PG8_WAIT_L(0); PG8_MMA(1, 0, At, B0); PG8_BAR; PG8_SCHED;
;             PG8_STAGE(PG8_SB(1, 1), b3 + hstepB, voffB);
;             PG8_WAIT_V(6); PG8_BAR; PG8_MMA(1, 1, At, B1); PG8_BAR;
	s_waitcnt lgkmcnt(0)
	s_setprio 1
	s_waitcnt lgkmcnt(0)
	v_mfma_f32_16x16x32_bf16 v[116:119], v[194:197], v[162:165], v[116:119]
	v_mfma_f32_16x16x32_bf16 v[116:119], v[198:201], v[166:169], v[116:119]
	v_mfma_f32_16x16x32_bf16 v[112:115], v[202:205], v[162:165], v[112:115]
	v_mfma_f32_16x16x32_bf16 v[112:115], v[206:209], v[166:169], v[112:115]
	v_mfma_f32_16x16x32_bf16 v[96:99], v[202:205], v[170:173], v[96:99]
	v_mfma_f32_16x16x32_bf16 v[96:99], v[206:209], v[174:177], v[96:99]
	v_mfma_f32_16x16x32_bf16 v[100:103], v[194:197], v[170:173], v[100:103]
	v_mfma_f32_16x16x32_bf16 v[100:103], v[198:201], v[174:177], v[100:103]
	v_mfma_f32_16x16x32_bf16 v[84:87], v[194:197], v[178:181], v[84:87]
	v_mfma_f32_16x16x32_bf16 v[84:87], v[198:201], v[182:185], v[84:87]
	v_mfma_f32_16x16x32_bf16 v[80:83], v[202:205], v[178:181], v[80:83]
	v_mfma_f32_16x16x32_bf16 v[80:83], v[206:209], v[182:185], v[80:83]
	v_mfma_f32_16x16x32_bf16 v[64:67], v[202:205], v[186:189], v[64:67]
	v_mfma_f32_16x16x32_bf16 v[64:67], v[206:209], v[190:193], v[64:67]
	v_mfma_f32_16x16x32_bf16 v[68:71], v[194:197], v[186:189], v[68:71]
	v_mfma_f32_16x16x32_bf16 v[68:71], v[198:201], v[190:193], v[68:71]
	s_setprio 0
	s_mov_b32 m0, s75
	v_lshl_add_u64 v[210:211], v[218:219], 0, s[0:1]
	s_barrier
	ds_read_b128 v[162:165], v144 offset:49152
	ds_read_b128 v[166:169], v144 offset:50176
	ds_read_b128 v[170:173], v144 offset:51200
	ds_read_b128 v[174:177], v144 offset:52224
	ds_read_b128 v[178:181], v144 offset:53248
	ds_read_b128 v[182:185], v144 offset:54272
	ds_read_b128 v[186:189], v144 offset:55296
	ds_read_b128 v[190:193], v144 offset:56320
	global_load_lds_dwordx4 v[210:211], off
	v_lshl_add_u64 v[210:211], v[220:221], 0, s[0:1]
	s_mov_b32 m0, s76
	s_nop 0
	global_load_lds_dwordx4 v[210:211], off
	s_barrier
	s_waitcnt lgkmcnt(0)
	s_setprio 1
	s_waitcnt lgkmcnt(0)
	v_mfma_f32_16x16x32_bf16 v[60:63], v[146:149], v[162:165], v[60:63]
	v_mfma_f32_16x16x32_bf16 v[60:63], v[150:153], v[166:169], v[60:63]
	v_mfma_f32_16x16x32_bf16 v[56:59], v[154:157], v[162:165], v[56:59]
	v_mfma_f32_16x16x32_bf16 v[56:59], v[158:161], v[166:169], v[56:59]
	v_mfma_f32_16x16x32_bf16 v[40:43], v[154:157], v[170:173], v[40:43]
	v_mfma_f32_16x16x32_bf16 v[40:43], v[158:161], v[174:177], v[40:43]
	v_mfma_f32_16x16x32_bf16 v[44:47], v[146:149], v[170:173], v[44:47]
	v_mfma_f32_16x16x32_bf16 v[44:47], v[150:153], v[174:177], v[44:47]
	v_mfma_f32_16x16x32_bf16 v[28:31], v[146:149], v[178:181], v[28:31]
	v_mfma_f32_16x16x32_bf16 v[28:31], v[150:153], v[182:185], v[28:31]
	v_mfma_f32_16x16x32_bf16 v[24:27], v[154:157], v[178:181], v[24:27]
	v_mfma_f32_16x16x32_bf16 v[24:27], v[158:161], v[182:185], v[24:27]
	v_mfma_f32_16x16x32_bf16 v[8:11], v[154:157], v[186:189], v[8:11]
	v_mfma_f32_16x16x32_bf16 v[8:11], v[158:161], v[190:193], v[8:11]
	v_mfma_f32_16x16x32_bf16 v[12:15], v[146:149], v[186:189], v[12:15]
	v_mfma_f32_16x16x32_bf16 v[12:15], v[150:153], v[190:193], v[12:15]
	s_setprio 0
	s_barrier
	s_add_u32 s10, s10, 0x80080
	s_addc_u32 s11, s11, 0
	s_add_i32 s2, s3, s68
	v_lshl_add_u64 v[146:147], s[10:11], 0, v[130:131]
	s_mov_b32 m0, s2
	s_nop 0
	global_load_lds_dwordx4 v[146:147], off
	v_lshl_add_u64 v[146:147], s[10:11], 0, v[134:135]
	s_add_i32 m0, s2, 0x2000
	s_nop 0
	global_load_lds_dwordx4 v[146:147], off
	s_waitcnt vmcnt(6)
	s_barrier
	s_setprio 1
	v_mfma_f32_16x16x32_bf16 v[52:55], v[194:197], v[162:165], v[52:55]
	v_mfma_f32_16x16x32_bf16 v[52:55], v[198:201], v[166:169], v[52:55]
	v_mfma_f32_16x16x32_bf16 v[48:51], v[202:205], v[162:165], v[48:51]
	v_mfma_f32_16x16x32_bf16 v[48:51], v[206:209], v[166:169], v[48:51]
	v_mfma_f32_16x16x32_bf16 v[32:35], v[202:205], v[170:173], v[32:35]
	v_mfma_f32_16x16x32_bf16 v[32:35], v[206:209], v[174:177], v[32:35]
	v_mfma_f32_16x16x32_bf16 v[36:39], v[194:197], v[170:173], v[36:39]
	v_mfma_f32_16x16x32_bf16 v[36:39], v[198:201], v[174:177], v[36:39]
	v_mfma_f32_16x16x32_bf16 v[20:23], v[194:197], v[178:181], v[20:23]
	v_mfma_f32_16x16x32_bf16 v[20:23], v[198:201], v[182:185], v[20:23]
	v_mfma_f32_16x16x32_bf16 v[16:19], v[202:205], v[178:181], v[16:19]
	v_mfma_f32_16x16x32_bf16 v[16:19], v[206:209], v[182:185], v[16:19]
	v_mfma_f32_16x16x32_bf16 v[0:3], v[202:205], v[186:189], v[0:3]
	v_mfma_f32_16x16x32_bf16 v[0:3], v[206:209], v[190:193], v[0:3]
	v_mfma_f32_16x16x32_bf16 v[4:7], v[194:197], v[186:189], v[4:7]
	v_mfma_f32_16x16x32_bf16 v[4:7], v[198:201], v[190:193], v[4:7]
	s_setprio 0
	s_add_u32 s12, s12, 0x100
	s_addc_u32 s13, s13, 0
	s_add_u32 s85, s85, 0x100
	s_addc_u32 s86, s86, 0
	s_cmp_ge_i32 s87, s74
	s_mov_b32 s10, s87
	s_barrier
	s_cbranch_scc0 .LBB0_361
	s_branch .LBB0_352

; #define PG8_STAGE(bufoff, gbase, voff) do { _Pragma("unroll") for (int _i = 0; _i < 2; ++_i) \
;         __builtin_amdgcn_global_load_lds((const unsigned*)((const char*)(gbase) + (voff)[_i]), (LAS unsigned*)(lds + (bufoff) + ldsw + _i * 8192), 16, 0, 0); } while (0)
; #define PG8_LDA(dst, b, h) do { _Pragma("unroll") for (int m = 0; m < 4; ++m) _Pragma("unroll") for (int k = 0; k < 2; ++k) dst[m][k] = *(const LAS bf16x8*)(lds + PG8_SA(b, h) + aoff + m * 2048 + k * 1024); } while (0)
; #define PG8_LDB(dst, b, h) do { _Pragma("unroll") for (int n = 0; n < 2; ++n) _Pragma("unroll") for (int k = 0; k < 2; ++k) dst[n][k] = *(const LAS bf16x8*)(lds + PG8_SB(b, h) + boff + n * 2048 + k * 1024); } while (0)
; #define PG8_MMA(ai, bj, At, Bt) do { __builtin_amdgcn_s_setprio(1); _Pragma("unroll") for (int m = 0; m < 4; ++m) _Pragma("unroll") for (int n = 0; n < 2; ++n) _Pragma("unroll") for (int k = 0; k < 2; ++k) \
;         acc[ai][bj][m][n] = __builtin_amdgcn_mfma_f32_16x16x32_bf16(Bt[n][k], At[m][k], acc[ai][bj][m][n], 0, 0, 0); __builtin_amdgcn_s_setprio(0); } while (0)
; #define PG8_WAIT_L(n) asm volatile("s_waitcnt lgkmcnt(" #n ")" ::: "memory")
; #define PG8_BAR __builtin_amdgcn_s_barrier()
; #define PG8_SCHED __builtin_amdgcn_sched_barrier(0)
; template <class Epi>
; DEVINL void gemm_phase(LAS unsigned char* lds, const Gemm g, const Order& S, const Epi& E) {
;     ...
;         for (int t = 0; t < nt; t += 2) {
;             const bool last = (t == nt - 2);
;             const char* a1 = cA + (size_t)(t + 1) * kstep;
;             const char* a2 = last ? nA : cA + (size_t)(t + 2) * kstep; const char* b2 = last ? nB : cB + (size_t)(t + 2) * kstep;
;             const char* a3 = a2 + kstep; const char* b3 = b2 + kstep;
;             PG8_LDB(B0, 0, 0); PG8_SCHED; PG8_LDA(At, 0, 0); PG8_STAGE(PG8_SA(1, 1), a1 + hstepA, voffA);
;             PG8_WAIT_L(8); PG8_BAR; PG8_WAIT_L(0); PG8_MMA(0, 0, At, B0); PG8_BAR; PG8_SCHED;
;             PG8_LDB(B1, 0, 1); PG8_STAGE(PG8_SB(0, 0), b2, voffB);
;             PG8_BAR; PG8_WAIT_L(0); PG8_MMA(0, 1, At, B1); PG8_BAR;
;             PG8_LDA(At, 0, 1); PG8_STAGE(PG8_SA(0, 0), a2, voffA);
;             PG8_BAR; PG8_WAIT_L(0); PG8_MMA(1, 0, At, B0); PG8_BAR; PG8_SCHED;
.LBB0_382:
	ds_read_b128 v[146:149], v143
	ds_read_b128 v[150:153], v143 offset:1024
	ds_read_b128 v[154:157], v143 offset:2048
	ds_read_b128 v[158:161], v143 offset:3072
	s_add_i32 s87, s12, 2
	s_add_u32 s2, s14, 0xfff80080
	s_addc_u32 s3, s15, -1
	s_cmp_eq_u32 s78, s12
	s_cselect_b32 s12, s84, s85
	s_cselect_b32 vcc_hi, s65, s3
	s_cselect_b32 vcc_lo, s66, s2
	s_cselect_b32 s13, s67, s86
	v_lshl_add_u64 v[194:195], s[14:15], 0, v[136:137]
	s_add_i32 m0, s5, 0xc000
	ds_read_b128 v[162:165], v144
	ds_read_b128 v[166:169], v144 offset:1024
	ds_read_b128 v[170:173], v144 offset:2048
	ds_read_b128 v[174:177], v144 offset:3072
	ds_read_b128 v[178:181], v144 offset:4096
	ds_read_b128 v[182:185], v144 offset:5120
	ds_read_b128 v[186:189], v144 offset:6144
	ds_read_b128 v[190:193], v144 offset:7168
	global_load_lds_dwordx4 v[194:195], off
	v_lshl_add_u64 v[194:195], s[14:15], 0, v[138:139]
	s_add_i32 m0, s5, 0xe000
	s_nop 0
	global_load_lds_dwordx4 v[194:195], off
	s_waitcnt lgkmcnt(8)
	s_barrier
	s_waitcnt lgkmcnt(0)
	s_setprio 1
	s_waitcnt lgkmcnt(0)
	v_mfma_f32_16x16x32_bf16 v[120:123], v[146:149], v[162:165], v[120:123]
	v_mfma_f32_16x16x32_bf16 v[120:123], v[150:153], v[166:169], v[120:123]
	v_mfma_f32_16x16x32_bf16 v[124:127], v[154:157], v[162:165], v[124:127]
	v_mfma_f32_16x16x32_bf16 v[124:127], v[158:161], v[166:169], v[124:127]
	v_mfma_f32_16x16x32_bf16 v[104:107], v[154:157], v[170:173], v[104:107]
	v_mfma_f32_16x16x32_bf16 v[104:107], v[158:161], v[174:177], v[104:107]
	v_mfma_f32_16x16x32_bf16 v[108:111], v[146:149], v[170:173], v[108:111]
	v_mfma_f32_16x16x32_bf16 v[108:111], v[150:153], v[174:177], v[108:111]
	v_mfma_f32_16x16x32_bf16 v[92:95], v[146:149], v[178:181], v[92:95]
	v_mfma_f32_16x16x32_bf16 v[92:95], v[150:153], v[182:185], v[92:95]
	v_mfma_f32_16x16x32_bf16 v[88:91], v[154:157], v[178:181], v[88:91]
	v_mfma_f32_16x16x32_bf16 v[88:91], v[158:161], v[182:185], v[88:91]
	v_mfma_f32_16x16x32_bf16 v[72:75], v[154:157], v[186:189], v[72:75]
	v_mfma_f32_16x16x32_bf16 v[72:75], v[158:161], v[190:193], v[72:75]
	v_mfma_f32_16x16x32_bf16 v[76:79], v[146:149], v[186:189], v[76:79]
	v_mfma_f32_16x16x32_bf16 v[76:79], v[150:153], v[190:193], v[76:79]
	s_setprio 0
	s_barrier
	s_add_i32 s2, s81, s68
	v_lshl_add_u64 v[210:211], s[12:13], 0, v[130:131]
	s_mov_b32 m0, s2
	ds_read_b128 v[194:197], v145
	ds_read_b128 v[198:201], v145 offset:1024
	ds_read_b128 v[202:205], v145 offset:2048
	ds_read_b128 v[206:209], v145 offset:3072
	global_load_lds_dwordx4 v[210:211], off
	v_lshl_add_u64 v[212:213], s[12:13], 0, v[134:135]
	s_add_i32 m0, s2, 0x2000
	s_nop 0
	global_load_lds_dwordx4 v[212:213], off
	s_barrier
	s_waitcnt lgkmcnt(0)
	s_setprio 1
	s_waitcnt lgkmcnt(0)
	v_mfma_f32_16x16x32_bf16 v[116:119], v[194:197], v[162:165], v[116:119]
	v_mfma_f32_16x16x32_bf16 v[116:119], v[198:201], v[166:169], v[116:119]
	v_mfma_f32_16x16x32_bf16 v[112:115], v[202:205], v[162:165], v[112:115]
	v_mfma_f32_16x16x32_bf16 v[112:115], v[206:209], v[166:169], v[112:115]
	v_mfma_f32_16x16x32_bf16 v[96:99], v[202:205], v[170:173], v[96:99]
	v_mfma_f32_16x16x32_bf16 v[96:99], v[206:209], v[174:177], v[96:99]
	v_mfma_f32_16x16x32_bf16 v[100:103], v[194:197], v[170:173], v[100:103]
	v_mfma_f32_16x16x32_bf16 v[100:103], v[198:201], v[174:177], v[100:103]
	v_mfma_f32_16x16x32_bf16 v[84:87], v[194:197], v[178:181], v[84:87]
	v_mfma_f32_16x16x32_bf16 v[84:87], v[198:201], v[182:185], v[84:87]
	v_mfma_f32_16x16x32_bf16 v[80:83], v[202:205], v[178:181], v[80:83]
	v_mfma_f32_16x16x32_bf16 v[80:83], v[206:209], v[182:185], v[80:83]
	v_mfma_f32_16x16x32_bf16 v[64:67], v[202:205], v[186:189], v[64:67]
	v_mfma_f32_16x16x32_bf16 v[64:67], v[206:209], v[190:193], v[64:67]
	v_mfma_f32_16x16x32_bf16 v[68:71], v[194:197], v[186:189], v[68:71]
	v_mfma_f32_16x16x32_bf16 v[68:71], v[198:201], v[190:193], v[68:71]
	s_setprio 0
	s_mov_b32 m0, s5
	v_lshl_add_u64 v[218:219], vcc, 0, v[128:129]
	s_barrier
	ds_read_b128 v[162:165], v144 offset:16384
	ds_read_b128 v[166:169], v144 offset:17408
	ds_read_b128 v[170:173], v144 offset:18432
	ds_read_b128 v[174:177], v144 offset:19456
	ds_read_b128 v[178:181], v144 offset:20480
	ds_read_b128 v[182:185], v144 offset:21504
	ds_read_b128 v[186:189], v144 offset:22528
	ds_read_b128 v[190:193], v144 offset:23552
	global_load_lds_dwordx4 v[218:219], off
	v_lshl_add_u64 v[220:221], vcc, 0, v[132:133]
	s_mov_b32 m0, s69
	s_nop 0
	global_load_lds_dwordx4 v[220:221], off
	s_barrier
	s_waitcnt lgkmcnt(0)
	s_setprio 1
	s_waitcnt lgkmcnt(0)
	v_mfma_f32_16x16x32_bf16 v[60:63], v[146:149], v[162:165], v[60:63]
	v_mfma_f32_16x16x32_bf16 v[60:63], v[150:153], v[166:169], v[60:63]
	v_mfma_f32_16x16x32_bf16 v[56:59], v[154:157], v[162:165], v[56:59]
	v_mfma_f32_16x16x32_bf16 v[56:59], v[158:161], v[166:169], v[56:59]
	v_mfma_f32_16x16x32_bf16 v[40:43], v[154:157], v[170:173], v[40:43]
	v_mfma_f32_16x16x32_bf16 v[40:43], v[158:161], v[174:177], v[40:43]
	v_mfma_f32_16x16x32_bf16 v[44:47], v[146:149], v[170:173], v[44:47]
	v_mfma_f32_16x16x32_bf16 v[44:47], v[150:153], v[174:177], v[44:47]
	v_mfma_f32_16x16x32_bf16 v[28:31], v[146:149], v[178:181], v[28:31]
	v_mfma_f32_16x16x32_bf16 v[28:31], v[150:153], v[182:185], v[28:31]
	v_mfma_f32_16x16x32_bf16 v[24:27], v[154:157], v[178:181], v[24:27]
	v_mfma_f32_16x16x32_bf16 v[24:27], v[158:161], v[182:185], v[24:27]
	v_mfma_f32_16x16x32_bf16 v[8:11], v[154:157], v[186:189], v[8:11]
	v_mfma_f32_16x16x32_bf16 v[8:11], v[158:161], v[190:193], v[8:11]
	v_mfma_f32_16x16x32_bf16 v[12:15], v[146:149], v[186:189], v[12:15]
	v_mfma_f32_16x16x32_bf16 v[12:15], v[150:153], v[190:193], v[12:15]
	s_setprio 0
	s_barrier
; #define PG8_STAGE(bufoff, gbase, voff) do { _Pragma("unroll") for (int _i = 0; _i < 2; ++_i) \
;         __builtin_amdgcn_global_load_lds((const unsigned*)((const char*)(gbase) + (voff)[_i]), (LAS unsigned*)(lds + (bufoff) + ldsw + _i * 8192), 16, 0, 0); } while (0)
; #define PG8_LDA(dst, b, h) do { _Pragma("unroll") for (int m = 0; m < 4; ++m) _Pragma("unroll") for (int k = 0; k < 2; ++k) dst[m][k] = *(const LAS bf16x8*)(lds + PG8_SA(b, h) + aoff + m * 2048 + k * 1024); } while (0)
; #define PG8_LDB(dst, b, h) do { _Pragma("unroll") for (int n = 0; n < 2; ++n) _Pragma("unroll") for (int k = 0; k < 2; ++k) dst[n][k] = *(const LAS bf16x8*)(lds + PG8_SB(b, h) + boff + n * 2048 + k * 1024); } while (0)
; #define PG8_MMA(ai, bj, At, Bt) do { __builtin_amdgcn_s_setprio(1); _Pragma("unroll") for (int m = 0; m < 4; ++m) _Pragma("unroll") for (int n = 0; n < 2; ++n) _Pragma("unroll") for (int k = 0; k < 2; ++k) \
;         acc[ai][bj][m][n] = __builtin_amdgcn_mfma_f32_16x16x32_bf16(Bt[n][k], At[m][k], acc[ai][bj][m][n], 0, 0, 0); __builtin_amdgcn_s_setprio(0); } while (0)
; #define PG8_WAIT_V(n) asm volatile("s_waitcnt vmcnt(" #n ")" ::: "memory")
; #define PG8_WAIT_L(n) asm volatile("s_waitcnt lgkmcnt(" #n ")" ::: "memory")
; #define PG8_BAR __builtin_amdgcn_s_barrier()
; #define PG8_SCHED __builtin_amdgcn_sched_barrier(0)
; template <class Epi>
; DEVINL void gemm_phase(LAS unsigned char* lds, const Gemm g, const Order& S, const Epi& E) {
;     ...
;             PG8_STAGE(PG8_SB(0, 1), b2 + hstepB, voffB);
;             PG8_WAIT_V(6); PG8_BAR; PG8_MMA(1, 1, At, B1); PG8_BAR;
;             PG8_LDB(B0, 1, 0); PG8_SCHED; PG8_LDA(At, 1, 0); PG8_STAGE(PG8_SA(0, 1), a2 + hstepA, voffA);
;             PG8_WAIT_L(8); PG8_BAR; PG8_WAIT_L(0); PG8_MMA(0, 0, At, B0); PG8_BAR; PG8_SCHED;
;             PG8_LDB(B1, 1, 1); PG8_STAGE(PG8_SB(1, 0), b3, voffB);
	s_add_u32 s2, s12, 0x80000
	s_addc_u32 s3, s13, 0
	s_add_i32 s93, s82, s68
	v_lshl_add_u64 v[146:147], s[2:3], 0, v[130:131]
	s_mov_b32 m0, s93
	s_nop 0
	global_load_lds_dwordx4 v[146:147], off
	v_lshl_add_u64 v[146:147], s[2:3], 0, v[134:135]
	s_add_i32 m0, s93, 0x2000
	s_nop 0
	global_load_lds_dwordx4 v[146:147], off
	s_waitcnt vmcnt(6)
	s_barrier
	s_setprio 1
	v_mfma_f32_16x16x32_bf16 v[52:55], v[194:197], v[162:165], v[52:55]
	v_mfma_f32_16x16x32_bf16 v[52:55], v[198:201], v[166:169], v[52:55]
	v_mfma_f32_16x16x32_bf16 v[48:51], v[202:205], v[162:165], v[48:51]
	v_mfma_f32_16x16x32_bf16 v[48:51], v[206:209], v[166:169], v[48:51]
	v_mfma_f32_16x16x32_bf16 v[32:35], v[202:205], v[170:173], v[32:35]
	v_mfma_f32_16x16x32_bf16 v[32:35], v[206:209], v[174:177], v[32:35]
	v_mfma_f32_16x16x32_bf16 v[36:39], v[194:197], v[170:173], v[36:39]
	v_mfma_f32_16x16x32_bf16 v[36:39], v[198:201], v[174:177], v[36:39]
	v_mfma_f32_16x16x32_bf16 v[20:23], v[194:197], v[178:181], v[20:23]
	v_mfma_f32_16x16x32_bf16 v[20:23], v[198:201], v[182:185], v[20:23]
	v_mfma_f32_16x16x32_bf16 v[16:19], v[202:205], v[178:181], v[16:19]
	v_mfma_f32_16x16x32_bf16 v[16:19], v[206:209], v[182:185], v[16:19]
	v_mfma_f32_16x16x32_bf16 v[0:3], v[202:205], v[186:189], v[0:3]
	v_mfma_f32_16x16x32_bf16 v[0:3], v[206:209], v[190:193], v[0:3]
	v_mfma_f32_16x16x32_bf16 v[4:7], v[194:197], v[186:189], v[4:7]
	v_mfma_f32_16x16x32_bf16 v[4:7], v[198:201], v[190:193], v[4:7]
	s_setprio 0
	s_add_i32 s93, 16, 0x18000
	v_add_u32_e32 v158, s93, v141
	s_barrier
	ds_read_b128 v[146:149], v158
	ds_read_b128 v[150:153], v158 offset:1024
	ds_read_b128 v[154:157], v158 offset:2048
	ds_read_b128 v[158:161], v158 offset:3072
	s_add_u32 s2, vcc_lo, 0x80000
	s_addc_u32 s3, vcc_hi, 0
	s_mov_b32 m0, s72
	v_lshl_add_u64 v[194:195], s[2:3], 0, v[128:129]
	ds_read_b128 v[162:165], v144 offset:32768
	ds_read_b128 v[166:169], v144 offset:33792
	ds_read_b128 v[170:173], v144 offset:34816
	ds_read_b128 v[174:177], v144 offset:35840
	ds_read_b128 v[178:181], v144 offset:36864
	ds_read_b128 v[182:185], v144 offset:37888
	ds_read_b128 v[186:189], v144 offset:38912
	ds_read_b128 v[190:193], v144 offset:39936
	global_load_lds_dwordx4 v[194:195], off
	v_lshl_add_u64 v[194:195], s[2:3], 0, v[132:133]
	s_mov_b32 m0, s73
	s_nop 0
	global_load_lds_dwordx4 v[194:195], off
	s_waitcnt lgkmcnt(8)
	s_barrier
	s_waitcnt lgkmcnt(0)
	s_setprio 1
	s_waitcnt lgkmcnt(0)
	v_mfma_f32_16x16x32_bf16 v[120:123], v[146:149], v[162:165], v[120:123]
	v_mfma_f32_16x16x32_bf16 v[120:123], v[150:153], v[166:169], v[120:123]
	v_mfma_f32_16x16x32_bf16 v[124:127], v[154:157], v[162:165], v[124:127]
	v_mfma_f32_16x16x32_bf16 v[124:127], v[158:161], v[166:169], v[124:127]
	v_mfma_f32_16x16x32_bf16 v[104:107], v[154:157], v[170:173], v[104:107]
	v_mfma_f32_16x16x32_bf16 v[104:107], v[158:161], v[174:177], v[104:107]
	v_mfma_f32_16x16x32_bf16 v[108:111], v[146:149], v[170:173], v[108:111]
	v_mfma_f32_16x16x32_bf16 v[108:111], v[150:153], v[174:177], v[108:111]
	v_mfma_f32_16x16x32_bf16 v[92:95], v[146:149], v[178:181], v[92:95]
	v_mfma_f32_16x16x32_bf16 v[92:95], v[150:153], v[182:185], v[92:95]
	v_mfma_f32_16x16x32_bf16 v[88:91], v[154:157], v[178:181], v[88:91]
	v_mfma_f32_16x16x32_bf16 v[88:91], v[158:161], v[182:185], v[88:91]
	v_mfma_f32_16x16x32_bf16 v[72:75], v[154:157], v[186:189], v[72:75]
	v_mfma_f32_16x16x32_bf16 v[72:75], v[158:161], v[190:193], v[72:75]
	v_mfma_f32_16x16x32_bf16 v[76:79], v[146:149], v[186:189], v[76:79]
	v_mfma_f32_16x16x32_bf16 v[76:79], v[150:153], v[190:193], v[76:79]
	s_setprio 0
	s_barrier
	s_add_i32 vcc_lo, 16, 0x1c000
	s_add_i32 s2, s93, s68
	v_add_u32_e32 v206, vcc_lo, v141
	v_lshl_add_u64 v[210:211], v[210:211], 0, s[0:1]
	s_mov_b32 m0, s2
	ds_read_b128 v[194:197], v206
	ds_read_b128 v[198:201], v206 offset:1024
	ds_read_b128 v[202:205], v206 offset:2048
	ds_read_b128 v[206:209], v206 offset:3072
	global_load_lds_dwordx4 v[210:211], off
	v_lshl_add_u64 v[210:211], v[212:213], 0, s[0:1]
	s_add_i32 m0, s2, 0x2000
	s_nop 0
	global_load_lds_dwordx4 v[210:211], off
	s_barrier
; #define PG8_STAGE(bufoff, gbase, voff) do { _Pragma("unroll") for (int _i = 0; _i < 2; ++_i) \
;         __builtin_amdgcn_global_load_lds((const unsigned*)((const char*)(gbase) + (voff)[_i]), (LAS unsigned*)(lds + (bufoff) + ldsw + _i * 8192), 16, 0, 0); } while (0)
; #define PG8_LDA(dst, b, h) do { _Pragma("unroll") for (int m = 0; m < 4; ++m) _Pragma("unroll") for (int k = 0; k < 2; ++k) dst[m][k] = *(const LAS bf16x8*)(lds + PG8_SA(b, h) + aoff + m * 2048 + k * 1024); } while (0)
; #define PG8_MMA(ai, bj, At, Bt) do { __builtin_amdgcn_s_setprio(1); _Pragma("unroll") for (int m = 0; m < 4; ++m) _Pragma("unroll") for (int n = 0; n < 2; ++n) _Pragma("unroll") for (int k = 0; k < 2; ++k) \
;         acc[ai][bj][m][n] = __builtin_amdgcn_mfma_f32_16x16x32_bf16(Bt[n][k], At[m][k], acc[ai][bj][m][n], 0, 0, 0); __builtin_amdgcn_s_setprio(0); } while (0)
; #define PG8_WAIT_V(n) asm volatile("s_waitcnt vmcnt(" #n ")" ::: "memory")
; #define PG8_WAIT_L(n) asm volatile("s_waitcnt lgkmcnt(" #n ")" ::: "memory")
; #define PG8_BAR __builtin_amdgcn_s_barrier()
; #define PG8_SCHED __builtin_amdgcn_sched_barrier(0)
; template <class Epi>
; DEVINL void gemm_phase(LAS unsigned char* lds, const Gemm g, const Order& S, const Epi& E) {
;     ...
;             PG8_BAR; PG8_WAIT_L(0); PG8_MMA(0, 1, At, B1); PG8_BAR;
;             PG8_LDA(At, 1, 1); PG8_STAGE(PG8_SA(1, 0), a3, voffA);
;             PG8_BAR; PG8_WAIT_L(0); PG8_MMA(1, 0, At, B0); PG8_BAR; PG8_SCHED;
;             PG8_STAGE(PG8_SB(1, 1), b3 + hstepB, voffB);
;             PG8_WAIT_V(6); PG8_BAR; PG8_MMA(1, 1, At, B1); PG8_BAR;
	s_waitcnt lgkmcnt(0)
	s_setprio 1
	s_waitcnt lgkmcnt(0)
	v_mfma_f32_16x16x32_bf16 v[116:119], v[194:197], v[162:165], v[116:119]
	v_mfma_f32_16x16x32_bf16 v[116:119], v[198:201], v[166:169], v[116:119]
	v_mfma_f32_16x16x32_bf16 v[112:115], v[202:205], v[162:165], v[112:115]
	v_mfma_f32_16x16x32_bf16 v[112:115], v[206:209], v[166:169], v[112:115]
	v_mfma_f32_16x16x32_bf16 v[96:99], v[202:205], v[170:173], v[96:99]
	v_mfma_f32_16x16x32_bf16 v[96:99], v[206:209], v[174:177], v[96:99]
	v_mfma_f32_16x16x32_bf16 v[100:103], v[194:197], v[170:173], v[100:103]
	v_mfma_f32_16x16x32_bf16 v[100:103], v[198:201], v[174:177], v[100:103]
	v_mfma_f32_16x16x32_bf16 v[84:87], v[194:197], v[178:181], v[84:87]
	v_mfma_f32_16x16x32_bf16 v[84:87], v[198:201], v[182:185], v[84:87]
	v_mfma_f32_16x16x32_bf16 v[80:83], v[202:205], v[178:181], v[80:83]
	v_mfma_f32_16x16x32_bf16 v[80:83], v[206:209], v[182:185], v[80:83]
	v_mfma_f32_16x16x32_bf16 v[64:67], v[202:205], v[186:189], v[64:67]
	v_mfma_f32_16x16x32_bf16 v[64:67], v[206:209], v[190:193], v[64:67]
	v_mfma_f32_16x16x32_bf16 v[68:71], v[194:197], v[186:189], v[68:71]
	v_mfma_f32_16x16x32_bf16 v[68:71], v[198:201], v[190:193], v[68:71]
	s_setprio 0
	s_mov_b32 m0, s76
	v_lshl_add_u64 v[210:211], v[218:219], 0, s[0:1]
	s_barrier
	ds_read_b128 v[162:165], v144 offset:49152
	ds_read_b128 v[166:169], v144 offset:50176
	ds_read_b128 v[170:173], v144 offset:51200
	ds_read_b128 v[174:177], v144 offset:52224
	ds_read_b128 v[178:181], v144 offset:53248
	ds_read_b128 v[182:185], v144 offset:54272
	ds_read_b128 v[186:189], v144 offset:55296
	ds_read_b128 v[190:193], v144 offset:56320
	global_load_lds_dwordx4 v[210:211], off
	v_lshl_add_u64 v[210:211], v[220:221], 0, s[0:1]
	s_mov_b32 m0, s77
	s_nop 0
	global_load_lds_dwordx4 v[210:211], off
	s_barrier
	s_waitcnt lgkmcnt(0)
	s_setprio 1
	s_waitcnt lgkmcnt(0)
	v_mfma_f32_16x16x32_bf16 v[60:63], v[146:149], v[162:165], v[60:63]
	v_mfma_f32_16x16x32_bf16 v[60:63], v[150:153], v[166:169], v[60:63]
	v_mfma_f32_16x16x32_bf16 v[56:59], v[154:157], v[162:165], v[56:59]
	v_mfma_f32_16x16x32_bf16 v[56:59], v[158:161], v[166:169], v[56:59]
	v_mfma_f32_16x16x32_bf16 v[40:43], v[154:157], v[170:173], v[40:43]
	v_mfma_f32_16x16x32_bf16 v[40:43], v[158:161], v[174:177], v[40:43]
	v_mfma_f32_16x16x32_bf16 v[44:47], v[146:149], v[170:173], v[44:47]
	v_mfma_f32_16x16x32_bf16 v[44:47], v[150:153], v[174:177], v[44:47]
	v_mfma_f32_16x16x32_bf16 v[28:31], v[146:149], v[178:181], v[28:31]
	v_mfma_f32_16x16x32_bf16 v[28:31], v[150:153], v[182:185], v[28:31]
	v_mfma_f32_16x16x32_bf16 v[24:27], v[154:157], v[178:181], v[24:27]
	v_mfma_f32_16x16x32_bf16 v[24:27], v[158:161], v[182:185], v[24:27]
	v_mfma_f32_16x16x32_bf16 v[8:11], v[154:157], v[186:189], v[8:11]
	v_mfma_f32_16x16x32_bf16 v[8:11], v[158:161], v[190:193], v[8:11]
	v_mfma_f32_16x16x32_bf16 v[12:15], v[146:149], v[186:189], v[12:15]
	v_mfma_f32_16x16x32_bf16 v[12:15], v[150:153], v[190:193], v[12:15]
	s_setprio 0
	s_barrier
	s_add_u32 s2, s12, 0x80080
	s_addc_u32 s3, s13, 0
	s_add_i32 s12, vcc_lo, s68
	v_lshl_add_u64 v[146:147], s[2:3], 0, v[130:131]
	s_mov_b32 m0, s12
	s_nop 0
	global_load_lds_dwordx4 v[146:147], off
	v_lshl_add_u64 v[146:147], s[2:3], 0, v[134:135]
	s_add_i32 m0, s12, 0x2000
	s_nop 0
	global_load_lds_dwordx4 v[146:147], off
	s_waitcnt vmcnt(6)
	s_barrier
	s_setprio 1
	v_mfma_f32_16x16x32_bf16 v[52:55], v[194:197], v[162:165], v[52:55]
	v_mfma_f32_16x16x32_bf16 v[52:55], v[198:201], v[166:169], v[52:55]
	v_mfma_f32_16x16x32_bf16 v[48:51], v[202:205], v[162:165], v[48:51]
	v_mfma_f32_16x16x32_bf16 v[48:51], v[206:209], v[166:169], v[48:51]
	v_mfma_f32_16x16x32_bf16 v[32:35], v[202:205], v[170:173], v[32:35]
	v_mfma_f32_16x16x32_bf16 v[32:35], v[206:209], v[174:177], v[32:35]
	v_mfma_f32_16x16x32_bf16 v[36:39], v[194:197], v[170:173], v[36:39]
	v_mfma_f32_16x16x32_bf16 v[36:39], v[198:201], v[174:177], v[36:39]
	v_mfma_f32_16x16x32_bf16 v[20:23], v[194:197], v[178:181], v[20:23]
	v_mfma_f32_16x16x32_bf16 v[20:23], v[198:201], v[182:185], v[20:23]
	v_mfma_f32_16x16x32_bf16 v[16:19], v[202:205], v[178:181], v[16:19]
	v_mfma_f32_16x16x32_bf16 v[16:19], v[206:209], v[182:185], v[16:19]
	v_mfma_f32_16x16x32_bf16 v[0:3], v[202:205], v[186:189], v[0:3]
	v_mfma_f32_16x16x32_bf16 v[0:3], v[206:209], v[190:193], v[0:3]
	v_mfma_f32_16x16x32_bf16 v[4:7], v[194:197], v[186:189], v[4:7]
	v_mfma_f32_16x16x32_bf16 v[4:7], v[198:201], v[190:193], v[4:7]
	s_setprio 0
	s_add_u32 s14, s14, 0x100
	s_addc_u32 s15, s15, 0
	s_add_u32 s85, s85, 0x100
	s_addc_u32 s86, s86, 0
	s_cmp_ge_i32 s87, s75
	s_mov_b32 s12, s87
	s_barrier
	s_cbranch_scc0 .LBB0_382
	s_branch .LBB0_373

; #define PG8_STAGE(bufoff, gbase, voff) do { _Pragma("unroll") for (int _i = 0; _i < 2; ++_i) \
;         __builtin_amdgcn_global_load_lds((const unsigned*)((const char*)(gbase) + (voff)[_i]), (LAS unsigned*)(lds + (bufoff) + ldsw + _i * 8192), 16, 0, 0); } while (0)
; #define PG8_LDA(dst, b, h) do { _Pragma("unroll") for (int m = 0; m < 4; ++m) _Pragma("unroll") for (int k = 0; k < 2; ++k) dst[m][k] = *(const LAS bf16x8*)(lds + PG8_SA(b, h) + aoff + m * 2048 + k * 1024); } while (0)
; #define PG8_LDB(dst, b, h) do { _Pragma("unroll") for (int n = 0; n < 2; ++n) _Pragma("unroll") for (int k = 0; k < 2; ++k) dst[n][k] = *(const LAS bf16x8*)(lds + PG8_SB(b, h) + boff + n * 2048 + k * 1024); } while (0)
; #define PG8_MMA(ai, bj, At, Bt) do { __builtin_amdgcn_s_setprio(1); _Pragma("unroll") for (int m = 0; m < 4; ++m) _Pragma("unroll") for (int n = 0; n < 2; ++n) _Pragma("unroll") for (int k = 0; k < 2; ++k) \
;         acc[ai][bj][m][n] = __builtin_amdgcn_mfma_f32_16x16x32_bf16(Bt[n][k], At[m][k], acc[ai][bj][m][n], 0, 0, 0); __builtin_amdgcn_s_setprio(0); } while (0)
; #define PG8_WAIT_L(n) asm volatile("s_waitcnt lgkmcnt(" #n ")" ::: "memory")
; #define PG8_BAR __builtin_amdgcn_s_barrier()
; #define PG8_SCHED __builtin_amdgcn_sched_barrier(0)
; template <class Epi>
; DEVINL void gemm_phase(LAS unsigned char* lds, const Gemm g, const Order& S, const Epi& E) {
;     ...
;         for (int t = 0; t < nt; t += 2) {
;             const bool last = (t == nt - 2);
;             const char* a1 = cA + (size_t)(t + 1) * kstep;
;             const char* a2 = last ? nA : cA + (size_t)(t + 2) * kstep; const char* b2 = last ? nB : cB + (size_t)(t + 2) * kstep;
;             const char* a3 = a2 + kstep; const char* b3 = b2 + kstep;
;             PG8_LDB(B0, 0, 0); PG8_SCHED; PG8_LDA(At, 0, 0); PG8_STAGE(PG8_SA(1, 1), a1 + hstepA, voffA);
;             PG8_WAIT_L(8); PG8_BAR; PG8_WAIT_L(0); PG8_MMA(0, 0, At, B0); PG8_BAR; PG8_SCHED;
;             PG8_LDB(B1, 0, 1); PG8_STAGE(PG8_SB(0, 0), b2, voffB);
;             PG8_BAR; PG8_WAIT_L(0); PG8_MMA(0, 1, At, B1); PG8_BAR;
;             PG8_LDA(At, 0, 1); PG8_STAGE(PG8_SA(0, 0), a2, voffA);
;             PG8_BAR; PG8_WAIT_L(0); PG8_MMA(1, 0, At, B0); PG8_BAR; PG8_SCHED;
.LBB0_459:
	ds_read_b128 v[150:153], v147
	ds_read_b128 v[154:157], v147 offset:1024
	ds_read_b128 v[158:161], v147 offset:2048
	ds_read_b128 v[162:165], v147 offset:3072
	s_add_i32 s85, s14, 2
	s_add_u32 s10, s12, 0x100
	s_addc_u32 s11, s13, 0
	s_cmp_eq_u32 s74, s14
	s_cselect_b32 s14, s4, s83
	s_cselect_b32 s65, s9, s11
	s_cselect_b32 s64, s8, s10
	s_cselect_b32 s15, s5, s84
	v_lshl_add_u64 v[198:199], s[12:13], 0, v[136:137]
	s_add_i32 m0, s38, 0xc000
	ds_read_b128 v[166:169], v148
	ds_read_b128 v[170:173], v148 offset:1024
	ds_read_b128 v[174:177], v148 offset:2048
	ds_read_b128 v[178:181], v148 offset:3072
	ds_read_b128 v[182:185], v148 offset:4096
	ds_read_b128 v[186:189], v148 offset:5120
	ds_read_b128 v[190:193], v148 offset:6144
	ds_read_b128 v[194:197], v148 offset:7168
	global_load_lds_dwordx4 v[198:199], off
	v_lshl_add_u64 v[198:199], s[12:13], 0, v[138:139]
	s_add_i32 m0, s38, 0xe000
	s_nop 0
	global_load_lds_dwordx4 v[198:199], off
	s_waitcnt lgkmcnt(8)
	s_barrier
	s_waitcnt lgkmcnt(0)
	s_setprio 1
	s_waitcnt lgkmcnt(0)
	v_mfma_f32_16x16x32_bf16 v[120:123], v[150:153], v[166:169], v[120:123]
	v_mfma_f32_16x16x32_bf16 v[120:123], v[154:157], v[170:173], v[120:123]
	v_mfma_f32_16x16x32_bf16 v[124:127], v[158:161], v[166:169], v[124:127]
	v_mfma_f32_16x16x32_bf16 v[124:127], v[162:165], v[170:173], v[124:127]
	v_mfma_f32_16x16x32_bf16 v[104:107], v[158:161], v[174:177], v[104:107]
	v_mfma_f32_16x16x32_bf16 v[104:107], v[162:165], v[178:181], v[104:107]
	v_mfma_f32_16x16x32_bf16 v[108:111], v[150:153], v[174:177], v[108:111]
	v_mfma_f32_16x16x32_bf16 v[108:111], v[154:157], v[178:181], v[108:111]
	v_mfma_f32_16x16x32_bf16 v[92:95], v[150:153], v[182:185], v[92:95]
	v_mfma_f32_16x16x32_bf16 v[92:95], v[154:157], v[186:189], v[92:95]
	v_mfma_f32_16x16x32_bf16 v[88:91], v[158:161], v[182:185], v[88:91]
	v_mfma_f32_16x16x32_bf16 v[88:91], v[162:165], v[186:189], v[88:91]
	v_mfma_f32_16x16x32_bf16 v[72:75], v[158:161], v[190:193], v[72:75]
	v_mfma_f32_16x16x32_bf16 v[72:75], v[162:165], v[194:197], v[72:75]
	v_mfma_f32_16x16x32_bf16 v[76:79], v[150:153], v[190:193], v[76:79]
	v_mfma_f32_16x16x32_bf16 v[76:79], v[154:157], v[194:197], v[76:79]
	s_setprio 0
	s_barrier
	s_add_i32 s2, s78, s37
	v_lshl_add_u64 v[218:219], s[14:15], 0, v[130:131]
	s_mov_b32 m0, s2
	ds_read_b128 v[198:201], v149
	ds_read_b128 v[202:205], v149 offset:1024
	ds_read_b128 v[206:209], v149 offset:2048
	ds_read_b128 v[210:213], v149 offset:3072
	global_load_lds_dwordx4 v[218:219], off
	v_lshl_add_u64 v[220:221], s[14:15], 0, v[134:135]
	s_add_i32 m0, s2, 0x2000
	s_nop 0
	global_load_lds_dwordx4 v[220:221], off
	s_barrier
	s_waitcnt lgkmcnt(0)
	s_setprio 1
	s_waitcnt lgkmcnt(0)
	v_mfma_f32_16x16x32_bf16 v[116:119], v[198:201], v[166:169], v[116:119]
	v_mfma_f32_16x16x32_bf16 v[116:119], v[202:205], v[170:173], v[116:119]
	v_mfma_f32_16x16x32_bf16 v[112:115], v[206:209], v[166:169], v[112:115]
	v_mfma_f32_16x16x32_bf16 v[112:115], v[210:213], v[170:173], v[112:115]
	v_mfma_f32_16x16x32_bf16 v[96:99], v[206:209], v[174:177], v[96:99]
	v_mfma_f32_16x16x32_bf16 v[96:99], v[210:213], v[178:181], v[96:99]
	v_mfma_f32_16x16x32_bf16 v[100:103], v[198:201], v[174:177], v[100:103]
	v_mfma_f32_16x16x32_bf16 v[100:103], v[202:205], v[178:181], v[100:103]
	v_mfma_f32_16x16x32_bf16 v[84:87], v[198:201], v[182:185], v[84:87]
	v_mfma_f32_16x16x32_bf16 v[84:87], v[202:205], v[186:189], v[84:87]
	v_mfma_f32_16x16x32_bf16 v[80:83], v[206:209], v[182:185], v[80:83]
	v_mfma_f32_16x16x32_bf16 v[80:83], v[210:213], v[186:189], v[80:83]
	v_mfma_f32_16x16x32_bf16 v[64:67], v[206:209], v[190:193], v[64:67]
	v_mfma_f32_16x16x32_bf16 v[64:67], v[210:213], v[194:197], v[64:67]
	v_mfma_f32_16x16x32_bf16 v[68:71], v[198:201], v[190:193], v[68:71]
	v_mfma_f32_16x16x32_bf16 v[68:71], v[202:205], v[194:197], v[68:71]
	s_setprio 0
	s_mov_b32 m0, s38
	v_lshl_add_u64 v[222:223], s[64:65], 0, v[128:129]
	s_barrier
	ds_read_b128 v[166:169], v148 offset:16384
	ds_read_b128 v[170:173], v148 offset:17408
	ds_read_b128 v[174:177], v148 offset:18432
	ds_read_b128 v[178:181], v148 offset:19456
	ds_read_b128 v[182:185], v148 offset:20480
	ds_read_b128 v[186:189], v148 offset:21504
	ds_read_b128 v[190:193], v148 offset:22528
	ds_read_b128 v[194:197], v148 offset:23552
	global_load_lds_dwordx4 v[222:223], off
	v_lshl_add_u64 v[224:225], s[64:65], 0, v[132:133]
	s_mov_b32 m0, s39
	s_nop 0
	global_load_lds_dwordx4 v[224:225], off
	s_barrier
	s_waitcnt lgkmcnt(0)
	s_setprio 1
	s_waitcnt lgkmcnt(0)
	v_mfma_f32_16x16x32_bf16 v[60:63], v[150:153], v[166:169], v[60:63]
	v_mfma_f32_16x16x32_bf16 v[60:63], v[154:157], v[170:173], v[60:63]
	v_mfma_f32_16x16x32_bf16 v[56:59], v[158:161], v[166:169], v[56:59]
	v_mfma_f32_16x16x32_bf16 v[56:59], v[162:165], v[170:173], v[56:59]
	v_mfma_f32_16x16x32_bf16 v[40:43], v[158:161], v[174:177], v[40:43]
	v_mfma_f32_16x16x32_bf16 v[40:43], v[162:165], v[178:181], v[40:43]
	v_mfma_f32_16x16x32_bf16 v[44:47], v[150:153], v[174:177], v[44:47]
	v_mfma_f32_16x16x32_bf16 v[44:47], v[154:157], v[178:181], v[44:47]
	v_mfma_f32_16x16x32_bf16 v[28:31], v[150:153], v[182:185], v[28:31]
	v_mfma_f32_16x16x32_bf16 v[28:31], v[154:157], v[186:189], v[28:31]
	v_mfma_f32_16x16x32_bf16 v[24:27], v[158:161], v[182:185], v[24:27]
	v_mfma_f32_16x16x32_bf16 v[24:27], v[162:165], v[186:189], v[24:27]
	v_mfma_f32_16x16x32_bf16 v[8:11], v[158:161], v[190:193], v[8:11]
	v_mfma_f32_16x16x32_bf16 v[8:11], v[162:165], v[194:197], v[8:11]
	v_mfma_f32_16x16x32_bf16 v[12:15], v[150:153], v[190:193], v[12:15]
	v_mfma_f32_16x16x32_bf16 v[12:15], v[154:157], v[194:197], v[12:15]
	s_setprio 0
	s_barrier
; #define PG8_STAGE(bufoff, gbase, voff) do { _Pragma("unroll") for (int _i = 0; _i < 2; ++_i) \
;         __builtin_amdgcn_global_load_lds((const unsigned*)((const char*)(gbase) + (voff)[_i]), (LAS unsigned*)(lds + (bufoff) + ldsw + _i * 8192), 16, 0, 0); } while (0)
; #define PG8_LDA(dst, b, h) do { _Pragma("unroll") for (int m = 0; m < 4; ++m) _Pragma("unroll") for (int k = 0; k < 2; ++k) dst[m][k] = *(const LAS bf16x8*)(lds + PG8_SA(b, h) + aoff + m * 2048 + k * 1024); } while (0)
; #define PG8_LDB(dst, b, h) do { _Pragma("unroll") for (int n = 0; n < 2; ++n) _Pragma("unroll") for (int k = 0; k < 2; ++k) dst[n][k] = *(const LAS bf16x8*)(lds + PG8_SB(b, h) + boff + n * 2048 + k * 1024); } while (0)
; #define PG8_MMA(ai, bj, At, Bt) do { __builtin_amdgcn_s_setprio(1); _Pragma("unroll") for (int m = 0; m < 4; ++m) _Pragma("unroll") for (int n = 0; n < 2; ++n) _Pragma("unroll") for (int k = 0; k < 2; ++k) \
;         acc[ai][bj][m][n] = __builtin_amdgcn_mfma_f32_16x16x32_bf16(Bt[n][k], At[m][k], acc[ai][bj][m][n], 0, 0, 0); __builtin_amdgcn_s_setprio(0); } while (0)
; #define PG8_WAIT_V(n) asm volatile("s_waitcnt vmcnt(" #n ")" ::: "memory")
; #define PG8_WAIT_L(n) asm volatile("s_waitcnt lgkmcnt(" #n ")" ::: "memory")
; #define PG8_BAR __builtin_amdgcn_s_barrier()
; #define PG8_SCHED __builtin_amdgcn_sched_barrier(0)
; template <class Epi>
; DEVINL void gemm_phase(LAS unsigned char* lds, const Gemm g, const Order& S, const Epi& E) {
;     ...
;             PG8_STAGE(PG8_SB(0, 1), b2 + hstepB, voffB);
;             PG8_WAIT_V(6); PG8_BAR; PG8_MMA(1, 1, At, B1); PG8_BAR;
;             PG8_LDB(B0, 1, 0); PG8_SCHED; PG8_LDA(At, 1, 0); PG8_STAGE(PG8_SA(0, 1), a2 + hstepA, voffA);
;             PG8_WAIT_L(8); PG8_BAR; PG8_WAIT_L(0); PG8_MMA(0, 0, At, B0); PG8_BAR; PG8_SCHED;
;             PG8_LDB(B1, 1, 1); PG8_STAGE(PG8_SB(1, 0), b3, voffB);
	s_add_u32 s2, s14, 0x158000
	s_addc_u32 s3, s15, 0
	s_add_i32 s12, s79, s37
	v_lshl_add_u64 v[150:151], s[2:3], 0, v[130:131]
	s_mov_b32 m0, s12
	s_nop 0
	global_load_lds_dwordx4 v[150:151], off
	v_lshl_add_u64 v[150:151], s[2:3], 0, v[134:135]
	s_add_i32 m0, s12, 0x2000
	s_nop 0
	global_load_lds_dwordx4 v[150:151], off
	s_waitcnt vmcnt(6)
	s_barrier
	s_setprio 1
	v_mfma_f32_16x16x32_bf16 v[52:55], v[198:201], v[166:169], v[52:55]
	v_mfma_f32_16x16x32_bf16 v[52:55], v[202:205], v[170:173], v[52:55]
	v_mfma_f32_16x16x32_bf16 v[48:51], v[206:209], v[166:169], v[48:51]
	v_mfma_f32_16x16x32_bf16 v[48:51], v[210:213], v[170:173], v[48:51]
	v_mfma_f32_16x16x32_bf16 v[32:35], v[206:209], v[174:177], v[32:35]
	v_mfma_f32_16x16x32_bf16 v[32:35], v[210:213], v[178:181], v[32:35]
	v_mfma_f32_16x16x32_bf16 v[36:39], v[198:201], v[174:177], v[36:39]
	v_mfma_f32_16x16x32_bf16 v[36:39], v[202:205], v[178:181], v[36:39]
	v_mfma_f32_16x16x32_bf16 v[20:23], v[198:201], v[182:185], v[20:23]
	v_mfma_f32_16x16x32_bf16 v[20:23], v[202:205], v[186:189], v[20:23]
	v_mfma_f32_16x16x32_bf16 v[16:19], v[206:209], v[182:185], v[16:19]
	v_mfma_f32_16x16x32_bf16 v[16:19], v[210:213], v[186:189], v[16:19]
	v_mfma_f32_16x16x32_bf16 v[0:3], v[206:209], v[190:193], v[0:3]
	v_mfma_f32_16x16x32_bf16 v[0:3], v[210:213], v[194:197], v[0:3]
	v_mfma_f32_16x16x32_bf16 v[4:7], v[198:201], v[190:193], v[4:7]
	v_mfma_f32_16x16x32_bf16 v[4:7], v[202:205], v[194:197], v[4:7]
	s_setprio 0
	s_add_i32 s12, 16, 0x18000
	v_add_u32_e32 v162, s12, v145
	s_barrier
	ds_read_b128 v[150:153], v162
	ds_read_b128 v[154:157], v162 offset:1024
	ds_read_b128 v[158:161], v162 offset:2048
	ds_read_b128 v[162:165], v162 offset:3072
	s_add_u32 s2, s64, 0x158000
	s_addc_u32 s3, s65, 0
	s_mov_b32 m0, s66
	v_lshl_add_u64 v[198:199], s[2:3], 0, v[128:129]
	ds_read_b128 v[166:169], v148 offset:32768
	ds_read_b128 v[170:173], v148 offset:33792
	ds_read_b128 v[174:177], v148 offset:34816
	ds_read_b128 v[178:181], v148 offset:35840
	ds_read_b128 v[182:185], v148 offset:36864
	ds_read_b128 v[186:189], v148 offset:37888
	ds_read_b128 v[190:193], v148 offset:38912
	ds_read_b128 v[194:197], v148 offset:39936
	global_load_lds_dwordx4 v[198:199], off
	v_lshl_add_u64 v[198:199], s[2:3], 0, v[132:133]
	s_mov_b32 m0, s67
	s_nop 0
	global_load_lds_dwordx4 v[198:199], off
	s_waitcnt lgkmcnt(8)
	s_barrier
	s_waitcnt lgkmcnt(0)
	s_setprio 1
	s_waitcnt lgkmcnt(0)
	v_mfma_f32_16x16x32_bf16 v[120:123], v[150:153], v[166:169], v[120:123]
	v_mfma_f32_16x16x32_bf16 v[120:123], v[154:157], v[170:173], v[120:123]
	v_mfma_f32_16x16x32_bf16 v[124:127], v[158:161], v[166:169], v[124:127]
	v_mfma_f32_16x16x32_bf16 v[124:127], v[162:165], v[170:173], v[124:127]
	v_mfma_f32_16x16x32_bf16 v[104:107], v[158:161], v[174:177], v[104:107]
	v_mfma_f32_16x16x32_bf16 v[104:107], v[162:165], v[178:181], v[104:107]
	v_mfma_f32_16x16x32_bf16 v[108:111], v[150:153], v[174:177], v[108:111]
	v_mfma_f32_16x16x32_bf16 v[108:111], v[154:157], v[178:181], v[108:111]
	v_mfma_f32_16x16x32_bf16 v[92:95], v[150:153], v[182:185], v[92:95]
	v_mfma_f32_16x16x32_bf16 v[92:95], v[154:157], v[186:189], v[92:95]
	v_mfma_f32_16x16x32_bf16 v[88:91], v[158:161], v[182:185], v[88:91]
	v_mfma_f32_16x16x32_bf16 v[88:91], v[162:165], v[186:189], v[88:91]
	v_mfma_f32_16x16x32_bf16 v[72:75], v[158:161], v[190:193], v[72:75]
	v_mfma_f32_16x16x32_bf16 v[72:75], v[162:165], v[194:197], v[72:75]
	v_mfma_f32_16x16x32_bf16 v[76:79], v[150:153], v[190:193], v[76:79]
	v_mfma_f32_16x16x32_bf16 v[76:79], v[154:157], v[194:197], v[76:79]
	s_setprio 0
	s_barrier
	s_add_i32 s13, 16, 0x1c000
	s_add_i32 s2, s12, s37
	v_add_u32_e32 v210, s13, v145
	v_lshl_add_u64 v[218:219], v[218:219], 0, s[6:7]
	s_mov_b32 m0, s2
	ds_read_b128 v[198:201], v210
	ds_read_b128 v[202:205], v210 offset:1024
	ds_read_b128 v[206:209], v210 offset:2048
	ds_read_b128 v[210:213], v210 offset:3072
	global_load_lds_dwordx4 v[218:219], off
	v_lshl_add_u64 v[218:219], v[220:221], 0, s[6:7]
	s_add_i32 m0, s2, 0x2000
	s_nop 0
	global_load_lds_dwordx4 v[218:219], off
	s_barrier
; #define PG8_STAGE(bufoff, gbase, voff) do { _Pragma("unroll") for (int _i = 0; _i < 2; ++_i) \
;         __builtin_amdgcn_global_load_lds((const unsigned*)((const char*)(gbase) + (voff)[_i]), (LAS unsigned*)(lds + (bufoff) + ldsw + _i * 8192), 16, 0, 0); } while (0)
; #define PG8_LDA(dst, b, h) do { _Pragma("unroll") for (int m = 0; m < 4; ++m) _Pragma("unroll") for (int k = 0; k < 2; ++k) dst[m][k] = *(const LAS bf16x8*)(lds + PG8_SA(b, h) + aoff + m * 2048 + k * 1024); } while (0)
; #define PG8_MMA(ai, bj, At, Bt) do { __builtin_amdgcn_s_setprio(1); _Pragma("unroll") for (int m = 0; m < 4; ++m) _Pragma("unroll") for (int n = 0; n < 2; ++n) _Pragma("unroll") for (int k = 0; k < 2; ++k) \
;         acc[ai][bj][m][n] = __builtin_amdgcn_mfma_f32_16x16x32_bf16(Bt[n][k], At[m][k], acc[ai][bj][m][n], 0, 0, 0); __builtin_amdgcn_s_setprio(0); } while (0)
; #define PG8_WAIT_V(n) asm volatile("s_waitcnt vmcnt(" #n ")" ::: "memory")
; #define PG8_WAIT_L(n) asm volatile("s_waitcnt lgkmcnt(" #n ")" ::: "memory")
; #define PG8_BAR __builtin_amdgcn_s_barrier()
; #define PG8_SCHED __builtin_amdgcn_sched_barrier(0)
; template <class Epi>
; DEVINL void gemm_phase(LAS unsigned char* lds, const Gemm g, const Order& S, const Epi& E) {
;     ...
;             PG8_BAR; PG8_WAIT_L(0); PG8_MMA(0, 1, At, B1); PG8_BAR;
;             PG8_LDA(At, 1, 1); PG8_STAGE(PG8_SA(1, 0), a3, voffA);
;             PG8_BAR; PG8_WAIT_L(0); PG8_MMA(1, 0, At, B0); PG8_BAR; PG8_SCHED;
;             PG8_STAGE(PG8_SB(1, 1), b3 + hstepB, voffB);
;             PG8_WAIT_V(6); PG8_BAR; PG8_MMA(1, 1, At, B1); PG8_BAR;
	s_waitcnt lgkmcnt(0)
	s_setprio 1
	s_waitcnt lgkmcnt(0)
	v_mfma_f32_16x16x32_bf16 v[116:119], v[198:201], v[166:169], v[116:119]
	v_mfma_f32_16x16x32_bf16 v[116:119], v[202:205], v[170:173], v[116:119]
	v_mfma_f32_16x16x32_bf16 v[112:115], v[206:209], v[166:169], v[112:115]
	v_mfma_f32_16x16x32_bf16 v[112:115], v[210:213], v[170:173], v[112:115]
	v_mfma_f32_16x16x32_bf16 v[96:99], v[206:209], v[174:177], v[96:99]
	v_mfma_f32_16x16x32_bf16 v[96:99], v[210:213], v[178:181], v[96:99]
	v_mfma_f32_16x16x32_bf16 v[100:103], v[198:201], v[174:177], v[100:103]
	v_mfma_f32_16x16x32_bf16 v[100:103], v[202:205], v[178:181], v[100:103]
	v_mfma_f32_16x16x32_bf16 v[84:87], v[198:201], v[182:185], v[84:87]
	v_mfma_f32_16x16x32_bf16 v[84:87], v[202:205], v[186:189], v[84:87]
	v_mfma_f32_16x16x32_bf16 v[80:83], v[206:209], v[182:185], v[80:83]
	v_mfma_f32_16x16x32_bf16 v[80:83], v[210:213], v[186:189], v[80:83]
	v_mfma_f32_16x16x32_bf16 v[64:67], v[206:209], v[190:193], v[64:67]
	v_mfma_f32_16x16x32_bf16 v[64:67], v[210:213], v[194:197], v[64:67]
	v_mfma_f32_16x16x32_bf16 v[68:71], v[198:201], v[190:193], v[68:71]
	v_mfma_f32_16x16x32_bf16 v[68:71], v[202:205], v[194:197], v[68:71]
	s_setprio 0
	s_mov_b32 m0, s69
	v_lshl_add_u64 v[218:219], v[222:223], 0, s[6:7]
	s_barrier
	ds_read_b128 v[166:169], v148 offset:49152
	ds_read_b128 v[170:173], v148 offset:50176
	ds_read_b128 v[174:177], v148 offset:51200
	ds_read_b128 v[178:181], v148 offset:52224
	ds_read_b128 v[182:185], v148 offset:53248
	ds_read_b128 v[186:189], v148 offset:54272
	ds_read_b128 v[190:193], v148 offset:55296
	ds_read_b128 v[194:197], v148 offset:56320
	global_load_lds_dwordx4 v[218:219], off
	v_lshl_add_u64 v[218:219], v[224:225], 0, s[6:7]
	s_mov_b32 m0, s72
	s_nop 0
	global_load_lds_dwordx4 v[218:219], off
	s_barrier
	s_waitcnt lgkmcnt(0)
	s_setprio 1
	s_waitcnt lgkmcnt(0)
	v_mfma_f32_16x16x32_bf16 v[60:63], v[150:153], v[166:169], v[60:63]
	v_mfma_f32_16x16x32_bf16 v[60:63], v[154:157], v[170:173], v[60:63]
	v_mfma_f32_16x16x32_bf16 v[56:59], v[158:161], v[166:169], v[56:59]
	v_mfma_f32_16x16x32_bf16 v[56:59], v[162:165], v[170:173], v[56:59]
	v_mfma_f32_16x16x32_bf16 v[40:43], v[158:161], v[174:177], v[40:43]
	v_mfma_f32_16x16x32_bf16 v[40:43], v[162:165], v[178:181], v[40:43]
	v_mfma_f32_16x16x32_bf16 v[44:47], v[150:153], v[174:177], v[44:47]
	v_mfma_f32_16x16x32_bf16 v[44:47], v[154:157], v[178:181], v[44:47]
	v_mfma_f32_16x16x32_bf16 v[28:31], v[150:153], v[182:185], v[28:31]
	v_mfma_f32_16x16x32_bf16 v[28:31], v[154:157], v[186:189], v[28:31]
	v_mfma_f32_16x16x32_bf16 v[24:27], v[158:161], v[182:185], v[24:27]
	v_mfma_f32_16x16x32_bf16 v[24:27], v[162:165], v[186:189], v[24:27]
	v_mfma_f32_16x16x32_bf16 v[8:11], v[158:161], v[190:193], v[8:11]
	v_mfma_f32_16x16x32_bf16 v[8:11], v[162:165], v[194:197], v[8:11]
	v_mfma_f32_16x16x32_bf16 v[12:15], v[150:153], v[190:193], v[12:15]
	v_mfma_f32_16x16x32_bf16 v[12:15], v[154:157], v[194:197], v[12:15]
	s_setprio 0
	s_barrier
	s_add_u32 s2, s14, 0x158080
	s_addc_u32 s3, s15, 0
	s_add_i32 s12, s13, s37
	v_lshl_add_u64 v[150:151], s[2:3], 0, v[130:131]
	s_mov_b32 m0, s12
	s_nop 0
	global_load_lds_dwordx4 v[150:151], off
	v_lshl_add_u64 v[150:151], s[2:3], 0, v[134:135]
	s_add_i32 m0, s12, 0x2000
	s_nop 0
	global_load_lds_dwordx4 v[150:151], off
	s_waitcnt vmcnt(6)
	s_barrier
	s_setprio 1
	v_mfma_f32_16x16x32_bf16 v[52:55], v[198:201], v[166:169], v[52:55]
	v_mfma_f32_16x16x32_bf16 v[52:55], v[202:205], v[170:173], v[52:55]
	v_mfma_f32_16x16x32_bf16 v[48:51], v[206:209], v[166:169], v[48:51]
	v_mfma_f32_16x16x32_bf16 v[48:51], v[210:213], v[170:173], v[48:51]
	v_mfma_f32_16x16x32_bf16 v[32:35], v[206:209], v[174:177], v[32:35]
	v_mfma_f32_16x16x32_bf16 v[32:35], v[210:213], v[178:181], v[32:35]
	v_mfma_f32_16x16x32_bf16 v[36:39], v[198:201], v[174:177], v[36:39]
	v_mfma_f32_16x16x32_bf16 v[36:39], v[202:205], v[178:181], v[36:39]
	v_mfma_f32_16x16x32_bf16 v[20:23], v[198:201], v[182:185], v[20:23]
	v_mfma_f32_16x16x32_bf16 v[20:23], v[202:205], v[186:189], v[20:23]
	v_mfma_f32_16x16x32_bf16 v[16:19], v[206:209], v[182:185], v[16:19]
	v_mfma_f32_16x16x32_bf16 v[16:19], v[210:213], v[186:189], v[16:19]
	v_mfma_f32_16x16x32_bf16 v[0:3], v[206:209], v[190:193], v[0:3]
	v_mfma_f32_16x16x32_bf16 v[0:3], v[210:213], v[194:197], v[0:3]
	v_mfma_f32_16x16x32_bf16 v[4:7], v[198:201], v[190:193], v[4:7]
	v_mfma_f32_16x16x32_bf16 v[4:7], v[202:205], v[194:197], v[4:7]
	s_setprio 0
	s_add_u32 s83, s83, 0x100
	s_addc_u32 s84, s84, 0
	s_cmp_ge_i32 s85, s68
	s_mov_b64 s[12:13], s[10:11]
	s_mov_b32 s14, s85
	s_barrier
	s_cbranch_scc0 .LBB0_459
	s_branch .LBB0_446

; #define PG8_STAGE(bufoff, gbase, voff) do { _Pragma("unroll") for (int _i = 0; _i < 2; ++_i) \
;         __builtin_amdgcn_global_load_lds((const unsigned*)((const char*)(gbase) + (voff)[_i]), (LAS unsigned*)(lds + (bufoff) + ldsw + _i * 8192), 16, 0, 0); } while (0)
; #define PG8_LDA(dst, b, h) do { _Pragma("unroll") for (int m = 0; m < 4; ++m) _Pragma("unroll") for (int k = 0; k < 2; ++k) dst[m][k] = *(const LAS bf16x8*)(lds + PG8_SA(b, h) + aoff + m * 2048 + k * 1024); } while (0)
; #define PG8_LDB(dst, b, h) do { _Pragma("unroll") for (int n = 0; n < 2; ++n) _Pragma("unroll") for (int k = 0; k < 2; ++k) dst[n][k] = *(const LAS bf16x8*)(lds + PG8_SB(b, h) + boff + n * 2048 + k * 1024); } while (0)
; #define PG8_MMA(ai, bj, At, Bt) do { __builtin_amdgcn_s_setprio(1); _Pragma("unroll") for (int m = 0; m < 4; ++m) _Pragma("unroll") for (int n = 0; n < 2; ++n) _Pragma("unroll") for (int k = 0; k < 2; ++k) \
;         acc[ai][bj][m][n] = __builtin_amdgcn_mfma_f32_16x16x32_bf16(Bt[n][k], At[m][k], acc[ai][bj][m][n], 0, 0, 0); __builtin_amdgcn_s_setprio(0); } while (0)
; #define PG8_WAIT_L(n) asm volatile("s_waitcnt lgkmcnt(" #n ")" ::: "memory")
; #define PG8_BAR __builtin_amdgcn_s_barrier()
; #define PG8_SCHED __builtin_amdgcn_sched_barrier(0)
; template <class Epi>
; DEVINL void gemm_phase(LAS unsigned char* lds, const Gemm g, const Order& S, const Epi& E) {
;     ...
;         for (int t = 0; t < nt; t += 2) {
;             const bool last = (t == nt - 2);
;             const char* a1 = cA + (size_t)(t + 1) * kstep;
;             const char* a2 = last ? nA : cA + (size_t)(t + 2) * kstep; const char* b2 = last ? nB : cB + (size_t)(t + 2) * kstep;
;             const char* a3 = a2 + kstep; const char* b3 = b2 + kstep;
;             PG8_LDB(B0, 0, 0); PG8_SCHED; PG8_LDA(At, 0, 0); PG8_STAGE(PG8_SA(1, 1), a1 + hstepA, voffA);
;             PG8_WAIT_L(8); PG8_BAR; PG8_WAIT_L(0); PG8_MMA(0, 0, At, B0); PG8_BAR; PG8_SCHED;
;             PG8_LDB(B1, 0, 1); PG8_STAGE(PG8_SB(0, 0), b2, voffB);
;             PG8_BAR; PG8_WAIT_L(0); PG8_MMA(0, 1, At, B1); PG8_BAR;
;             PG8_LDA(At, 0, 1); PG8_STAGE(PG8_SA(0, 0), a2, voffA);
;             PG8_BAR; PG8_WAIT_L(0); PG8_MMA(1, 0, At, B0); PG8_BAR; PG8_SCHED;
.LBB0_650:
	ds_read_b128 v[128:131], v175
	ds_read_b128 v[132:135], v175 offset:1024
	ds_read_b128 v[136:139], v175 offset:2048
	ds_read_b128 v[140:143], v175 offset:3072
	s_add_i32 s64, s14, 2
	s_add_u32 s2, s12, 0xfff80080
	s_addc_u32 s3, s13, -1
	s_cmp_eq_u32 s49, s14
	s_cselect_b32 s14, s57, s58
	s_cselect_b32 s45, s11, s3
	s_cselect_b32 s44, s17, s2
	s_cselect_b32 s15, s56, s59
	v_lshl_add_u64 v[170:171], s[12:13], 0, v[156:157]
	s_add_i32 m0, s29, 0xc000
	ds_read_b128 v[166:169], v176
	ds_read_b128 v[178:181], v176 offset:1024
	ds_read_b128 v[182:185], v176 offset:2048
	ds_read_b128 v[186:189], v176 offset:3072
	ds_read_b128 v[190:193], v176 offset:4096
	ds_read_b128 v[194:197], v176 offset:5120
	ds_read_b128 v[198:201], v176 offset:6144
	ds_read_b128 v[202:205], v176 offset:7168
	global_load_lds_dwordx4 v[170:171], off
	v_lshl_add_u64 v[170:171], s[12:13], 0, v[158:159]
	s_add_i32 m0, s29, 0xe000
	s_nop 0
	global_load_lds_dwordx4 v[170:171], off
	s_waitcnt lgkmcnt(8)
	s_barrier
	s_waitcnt lgkmcnt(0)
	s_setprio 1
	s_waitcnt lgkmcnt(0)
	v_mfma_f32_16x16x32_bf16 v[124:127], v[128:131], v[166:169], v[124:127]
	v_mfma_f32_16x16x32_bf16 v[124:127], v[132:135], v[178:181], v[124:127]
	v_mfma_f32_16x16x32_bf16 v[120:123], v[136:139], v[166:169], v[120:123]
	v_mfma_f32_16x16x32_bf16 v[120:123], v[140:143], v[178:181], v[120:123]
	v_mfma_f32_16x16x32_bf16 v[104:107], v[136:139], v[182:185], v[104:107]
	v_mfma_f32_16x16x32_bf16 v[104:107], v[140:143], v[186:189], v[104:107]
	v_mfma_f32_16x16x32_bf16 v[108:111], v[128:131], v[182:185], v[108:111]
	v_mfma_f32_16x16x32_bf16 v[108:111], v[132:135], v[186:189], v[108:111]
	v_mfma_f32_16x16x32_bf16 v[92:95], v[128:131], v[190:193], v[92:95]
	v_mfma_f32_16x16x32_bf16 v[92:95], v[132:135], v[194:197], v[92:95]
	v_mfma_f32_16x16x32_bf16 v[88:91], v[136:139], v[190:193], v[88:91]
	v_mfma_f32_16x16x32_bf16 v[88:91], v[140:143], v[194:197], v[88:91]
	v_mfma_f32_16x16x32_bf16 v[72:75], v[136:139], v[198:201], v[72:75]
	v_mfma_f32_16x16x32_bf16 v[72:75], v[140:143], v[202:205], v[72:75]
	v_mfma_f32_16x16x32_bf16 v[76:79], v[128:131], v[198:201], v[76:79]
	v_mfma_f32_16x16x32_bf16 v[76:79], v[132:135], v[202:205], v[76:79]
	s_setprio 0
	s_barrier
	s_add_i32 s2, s52, s26
	v_lshl_add_u64 v[170:171], s[14:15], 0, v[148:149]
	s_mov_b32 m0, s2
	ds_read_b128 v[206:209], v177
	ds_read_b128 v[210:213], v177 offset:1024
	ds_read_b128 v[218:221], v177 offset:2048
	ds_read_b128 v[222:225], v177 offset:3072
	global_load_lds_dwordx4 v[170:171], off
	v_lshl_add_u64 v[226:227], s[14:15], 0, v[144:145]
	s_add_i32 m0, s2, 0x2000
	s_nop 0
	global_load_lds_dwordx4 v[226:227], off
	s_barrier
	s_waitcnt lgkmcnt(0)
	s_setprio 1
	s_waitcnt lgkmcnt(0)
	v_mfma_f32_16x16x32_bf16 v[116:119], v[206:209], v[166:169], v[116:119]
	v_mfma_f32_16x16x32_bf16 v[116:119], v[210:213], v[178:181], v[116:119]
	v_mfma_f32_16x16x32_bf16 v[112:115], v[218:221], v[166:169], v[112:115]
	v_mfma_f32_16x16x32_bf16 v[112:115], v[222:225], v[178:181], v[112:115]
	v_mfma_f32_16x16x32_bf16 v[96:99], v[218:221], v[182:185], v[96:99]
	v_mfma_f32_16x16x32_bf16 v[96:99], v[222:225], v[186:189], v[96:99]
	v_mfma_f32_16x16x32_bf16 v[100:103], v[206:209], v[182:185], v[100:103]
	v_mfma_f32_16x16x32_bf16 v[100:103], v[210:213], v[186:189], v[100:103]
	v_mfma_f32_16x16x32_bf16 v[84:87], v[206:209], v[190:193], v[84:87]
	v_mfma_f32_16x16x32_bf16 v[84:87], v[210:213], v[194:197], v[84:87]
	v_mfma_f32_16x16x32_bf16 v[80:83], v[218:221], v[190:193], v[80:83]
	v_mfma_f32_16x16x32_bf16 v[80:83], v[222:225], v[194:197], v[80:83]
	v_mfma_f32_16x16x32_bf16 v[64:67], v[218:221], v[198:201], v[64:67]
	v_mfma_f32_16x16x32_bf16 v[64:67], v[222:225], v[202:205], v[64:67]
	v_mfma_f32_16x16x32_bf16 v[68:71], v[206:209], v[198:201], v[68:71]
	v_mfma_f32_16x16x32_bf16 v[68:71], v[210:213], v[202:205], v[68:71]
	s_setprio 0
	s_mov_b32 m0, s29
	v_lshl_add_u64 v[228:229], s[44:45], 0, v[150:151]
	s_barrier
	ds_read_b128 v[166:169], v176 offset:16384
	ds_read_b128 v[178:181], v176 offset:17408
	ds_read_b128 v[182:185], v176 offset:18432
	ds_read_b128 v[186:189], v176 offset:19456
	ds_read_b128 v[190:193], v176 offset:20480
	ds_read_b128 v[194:197], v176 offset:21504
	ds_read_b128 v[198:201], v176 offset:22528
	ds_read_b128 v[202:205], v176 offset:23552
	global_load_lds_dwordx4 v[228:229], off
	v_lshl_add_u64 v[230:231], s[44:45], 0, v[146:147]
	s_mov_b32 m0, s30
	s_nop 0
	global_load_lds_dwordx4 v[230:231], off
	s_barrier
	s_waitcnt lgkmcnt(0)
	s_setprio 1
	s_waitcnt lgkmcnt(0)
	v_mfma_f32_16x16x32_bf16 v[60:63], v[128:131], v[166:169], v[60:63]
	v_mfma_f32_16x16x32_bf16 v[60:63], v[132:135], v[178:181], v[60:63]
	v_mfma_f32_16x16x32_bf16 v[56:59], v[136:139], v[166:169], v[56:59]
	v_mfma_f32_16x16x32_bf16 v[56:59], v[140:143], v[178:181], v[56:59]
	v_mfma_f32_16x16x32_bf16 v[40:43], v[136:139], v[182:185], v[40:43]
	v_mfma_f32_16x16x32_bf16 v[40:43], v[140:143], v[186:189], v[40:43]
	v_mfma_f32_16x16x32_bf16 v[44:47], v[128:131], v[182:185], v[44:47]
	v_mfma_f32_16x16x32_bf16 v[44:47], v[132:135], v[186:189], v[44:47]
	v_mfma_f32_16x16x32_bf16 v[28:31], v[128:131], v[190:193], v[28:31]
	v_mfma_f32_16x16x32_bf16 v[28:31], v[132:135], v[194:197], v[28:31]
	v_mfma_f32_16x16x32_bf16 v[24:27], v[136:139], v[190:193], v[24:27]
	v_mfma_f32_16x16x32_bf16 v[24:27], v[140:143], v[194:197], v[24:27]
	v_mfma_f32_16x16x32_bf16 v[8:11], v[136:139], v[198:201], v[8:11]
	v_mfma_f32_16x16x32_bf16 v[8:11], v[140:143], v[202:205], v[8:11]
	v_mfma_f32_16x16x32_bf16 v[12:15], v[128:131], v[198:201], v[12:15]
	v_mfma_f32_16x16x32_bf16 v[12:15], v[132:135], v[202:205], v[12:15]
	s_setprio 0
	s_barrier
; #define PG8_STAGE(bufoff, gbase, voff) do { _Pragma("unroll") for (int _i = 0; _i < 2; ++_i) \
;         __builtin_amdgcn_global_load_lds((const unsigned*)((const char*)(gbase) + (voff)[_i]), (LAS unsigned*)(lds + (bufoff) + ldsw + _i * 8192), 16, 0, 0); } while (0)
; #define PG8_LDA(dst, b, h) do { _Pragma("unroll") for (int m = 0; m < 4; ++m) _Pragma("unroll") for (int k = 0; k < 2; ++k) dst[m][k] = *(const LAS bf16x8*)(lds + PG8_SA(b, h) + aoff + m * 2048 + k * 1024); } while (0)
; #define PG8_LDB(dst, b, h) do { _Pragma("unroll") for (int n = 0; n < 2; ++n) _Pragma("unroll") for (int k = 0; k < 2; ++k) dst[n][k] = *(const LAS bf16x8*)(lds + PG8_SB(b, h) + boff + n * 2048 + k * 1024); } while (0)
; #define PG8_MMA(ai, bj, At, Bt) do { __builtin_amdgcn_s_setprio(1); _Pragma("unroll") for (int m = 0; m < 4; ++m) _Pragma("unroll") for (int n = 0; n < 2; ++n) _Pragma("unroll") for (int k = 0; k < 2; ++k) \
;         acc[ai][bj][m][n] = __builtin_amdgcn_mfma_f32_16x16x32_bf16(Bt[n][k], At[m][k], acc[ai][bj][m][n], 0, 0, 0); __builtin_amdgcn_s_setprio(0); } while (0)
; #define PG8_WAIT_V(n) asm volatile("s_waitcnt vmcnt(" #n ")" ::: "memory")
; #define PG8_WAIT_L(n) asm volatile("s_waitcnt lgkmcnt(" #n ")" ::: "memory")
; #define PG8_BAR __builtin_amdgcn_s_barrier()
; #define PG8_SCHED __builtin_amdgcn_sched_barrier(0)
; template <class Epi>
; DEVINL void gemm_phase(LAS unsigned char* lds, const Gemm g, const Order& S, const Epi& E) {
;     ...
;             PG8_STAGE(PG8_SB(0, 1), b2 + hstepB, voffB);
;             PG8_WAIT_V(6); PG8_BAR; PG8_MMA(1, 1, At, B1); PG8_BAR;
;             PG8_LDB(B0, 1, 0); PG8_SCHED; PG8_LDA(At, 1, 0); PG8_STAGE(PG8_SA(0, 1), a2 + hstepA, voffA);
;             PG8_WAIT_L(8); PG8_BAR; PG8_WAIT_L(0); PG8_MMA(0, 0, At, B0); PG8_BAR; PG8_SCHED;
;             PG8_LDB(B1, 1, 1); PG8_STAGE(PG8_SB(1, 0), b3, voffB);
	s_add_u32 s2, s14, 0x80000
	s_addc_u32 s3, s15, 0
	s_add_i32 s65, s53, s26
	v_lshl_add_u64 v[128:129], s[2:3], 0, v[148:149]
	s_mov_b32 m0, s65
	s_nop 0
	global_load_lds_dwordx4 v[128:129], off
	v_lshl_add_u64 v[128:129], s[2:3], 0, v[144:145]
	s_add_i32 m0, s65, 0x2000
	s_nop 0
	global_load_lds_dwordx4 v[128:129], off
	s_waitcnt vmcnt(6)
	s_barrier
	s_setprio 1
	v_mfma_f32_16x16x32_bf16 v[52:55], v[206:209], v[166:169], v[52:55]
	v_mfma_f32_16x16x32_bf16 v[52:55], v[210:213], v[178:181], v[52:55]
	v_mfma_f32_16x16x32_bf16 v[48:51], v[218:221], v[166:169], v[48:51]
	v_mfma_f32_16x16x32_bf16 v[48:51], v[222:225], v[178:181], v[48:51]
	v_mfma_f32_16x16x32_bf16 v[32:35], v[218:221], v[182:185], v[32:35]
	v_mfma_f32_16x16x32_bf16 v[32:35], v[222:225], v[186:189], v[32:35]
	v_mfma_f32_16x16x32_bf16 v[36:39], v[206:209], v[182:185], v[36:39]
	v_mfma_f32_16x16x32_bf16 v[36:39], v[210:213], v[186:189], v[36:39]
	v_mfma_f32_16x16x32_bf16 v[20:23], v[206:209], v[190:193], v[20:23]
	v_mfma_f32_16x16x32_bf16 v[20:23], v[210:213], v[194:197], v[20:23]
	v_mfma_f32_16x16x32_bf16 v[16:19], v[218:221], v[190:193], v[16:19]
	v_mfma_f32_16x16x32_bf16 v[16:19], v[222:225], v[194:197], v[16:19]
	v_mfma_f32_16x16x32_bf16 v[0:3], v[218:221], v[198:201], v[0:3]
	v_mfma_f32_16x16x32_bf16 v[0:3], v[222:225], v[202:205], v[0:3]
	v_mfma_f32_16x16x32_bf16 v[4:7], v[206:209], v[198:201], v[4:7]
	v_mfma_f32_16x16x32_bf16 v[4:7], v[210:213], v[202:205], v[4:7]
	s_setprio 0
	s_add_i32 s65, 16, 0x18000
	v_add_u32_e32 v140, s65, v173
	s_barrier
	ds_read_b128 v[128:131], v140
	ds_read_b128 v[132:135], v140 offset:1024
	ds_read_b128 v[136:139], v140 offset:2048
	ds_read_b128 v[140:143], v140 offset:3072
	s_add_u32 s2, s44, 0x80000
	s_addc_u32 s3, s45, 0
	s_mov_b32 m0, s31
	v_lshl_add_u64 v[206:207], s[2:3], 0, v[150:151]
	ds_read_b128 v[166:169], v176 offset:32768
	ds_read_b128 v[178:181], v176 offset:33792
	ds_read_b128 v[182:185], v176 offset:34816
	ds_read_b128 v[186:189], v176 offset:35840
	ds_read_b128 v[190:193], v176 offset:36864
	ds_read_b128 v[194:197], v176 offset:37888
	ds_read_b128 v[198:201], v176 offset:38912
	ds_read_b128 v[202:205], v176 offset:39936
	global_load_lds_dwordx4 v[206:207], off
	v_lshl_add_u64 v[206:207], s[2:3], 0, v[146:147]
	s_mov_b32 m0, s43
	s_nop 0
	global_load_lds_dwordx4 v[206:207], off
	s_waitcnt lgkmcnt(8)
	s_barrier
	s_waitcnt lgkmcnt(0)
	s_setprio 1
	s_waitcnt lgkmcnt(0)
	v_mfma_f32_16x16x32_bf16 v[124:127], v[128:131], v[166:169], v[124:127]
	v_mfma_f32_16x16x32_bf16 v[124:127], v[132:135], v[178:181], v[124:127]
	v_mfma_f32_16x16x32_bf16 v[120:123], v[136:139], v[166:169], v[120:123]
	v_mfma_f32_16x16x32_bf16 v[120:123], v[140:143], v[178:181], v[120:123]
	v_mfma_f32_16x16x32_bf16 v[104:107], v[136:139], v[182:185], v[104:107]
	v_mfma_f32_16x16x32_bf16 v[104:107], v[140:143], v[186:189], v[104:107]
	v_mfma_f32_16x16x32_bf16 v[108:111], v[128:131], v[182:185], v[108:111]
	v_mfma_f32_16x16x32_bf16 v[108:111], v[132:135], v[186:189], v[108:111]
	v_mfma_f32_16x16x32_bf16 v[92:95], v[128:131], v[190:193], v[92:95]
	v_mfma_f32_16x16x32_bf16 v[92:95], v[132:135], v[194:197], v[92:95]
	v_mfma_f32_16x16x32_bf16 v[88:91], v[136:139], v[190:193], v[88:91]
	v_mfma_f32_16x16x32_bf16 v[88:91], v[140:143], v[194:197], v[88:91]
	v_mfma_f32_16x16x32_bf16 v[72:75], v[136:139], v[198:201], v[72:75]
	v_mfma_f32_16x16x32_bf16 v[72:75], v[140:143], v[202:205], v[72:75]
	v_mfma_f32_16x16x32_bf16 v[76:79], v[128:131], v[198:201], v[76:79]
	v_mfma_f32_16x16x32_bf16 v[76:79], v[132:135], v[202:205], v[76:79]
	s_setprio 0
	s_barrier
	s_add_i32 s44, 16, 0x1c000
	s_add_i32 s2, s65, s26
	v_add_u32_e32 v152, s44, v173
	v_lshl_add_u64 v[170:171], v[170:171], 0, s[4:5]
	s_mov_b32 m0, s2
	ds_read_b128 v[206:209], v152
	ds_read_b128 v[210:213], v152 offset:1024
	ds_read_b128 v[218:221], v152 offset:2048
	ds_read_b128 v[222:225], v152 offset:3072
	global_load_lds_dwordx4 v[170:171], off
	v_lshl_add_u64 v[170:171], v[226:227], 0, s[4:5]
	s_add_i32 m0, s2, 0x2000
	s_nop 0
	global_load_lds_dwordx4 v[170:171], off
	s_barrier
; #define PG8_STAGE(bufoff, gbase, voff) do { _Pragma("unroll") for (int _i = 0; _i < 2; ++_i) \
;         __builtin_amdgcn_global_load_lds((const unsigned*)((const char*)(gbase) + (voff)[_i]), (LAS unsigned*)(lds + (bufoff) + ldsw + _i * 8192), 16, 0, 0); } while (0)
; #define PG8_LDA(dst, b, h) do { _Pragma("unroll") for (int m = 0; m < 4; ++m) _Pragma("unroll") for (int k = 0; k < 2; ++k) dst[m][k] = *(const LAS bf16x8*)(lds + PG8_SA(b, h) + aoff + m * 2048 + k * 1024); } while (0)
; #define PG8_MMA(ai, bj, At, Bt) do { __builtin_amdgcn_s_setprio(1); _Pragma("unroll") for (int m = 0; m < 4; ++m) _Pragma("unroll") for (int n = 0; n < 2; ++n) _Pragma("unroll") for (int k = 0; k < 2; ++k) \
;         acc[ai][bj][m][n] = __builtin_amdgcn_mfma_f32_16x16x32_bf16(Bt[n][k], At[m][k], acc[ai][bj][m][n], 0, 0, 0); __builtin_amdgcn_s_setprio(0); } while (0)
; #define PG8_WAIT_V(n) asm volatile("s_waitcnt vmcnt(" #n ")" ::: "memory")
; #define PG8_WAIT_L(n) asm volatile("s_waitcnt lgkmcnt(" #n ")" ::: "memory")
; #define PG8_BAR __builtin_amdgcn_s_barrier()
; #define PG8_SCHED __builtin_amdgcn_sched_barrier(0)
; template <class Epi>
; DEVINL void gemm_phase(LAS unsigned char* lds, const Gemm g, const Order& S, const Epi& E) {
;     ...
;             PG8_BAR; PG8_WAIT_L(0); PG8_MMA(0, 1, At, B1); PG8_BAR;
;             PG8_LDA(At, 1, 1); PG8_STAGE(PG8_SA(1, 0), a3, voffA);
;             PG8_BAR; PG8_WAIT_L(0); PG8_MMA(1, 0, At, B0); PG8_BAR; PG8_SCHED;
;             PG8_STAGE(PG8_SB(1, 1), b3 + hstepB, voffB);
;             PG8_WAIT_V(6); PG8_BAR; PG8_MMA(1, 1, At, B1); PG8_BAR;
	s_waitcnt lgkmcnt(0)
	s_setprio 1
	s_waitcnt lgkmcnt(0)
	v_mfma_f32_16x16x32_bf16 v[116:119], v[206:209], v[166:169], v[116:119]
	v_mfma_f32_16x16x32_bf16 v[116:119], v[210:213], v[178:181], v[116:119]
	v_mfma_f32_16x16x32_bf16 v[112:115], v[218:221], v[166:169], v[112:115]
	v_mfma_f32_16x16x32_bf16 v[112:115], v[222:225], v[178:181], v[112:115]
	v_mfma_f32_16x16x32_bf16 v[96:99], v[218:221], v[182:185], v[96:99]
	v_mfma_f32_16x16x32_bf16 v[96:99], v[222:225], v[186:189], v[96:99]
	v_mfma_f32_16x16x32_bf16 v[100:103], v[206:209], v[182:185], v[100:103]
	v_mfma_f32_16x16x32_bf16 v[100:103], v[210:213], v[186:189], v[100:103]
	v_mfma_f32_16x16x32_bf16 v[84:87], v[206:209], v[190:193], v[84:87]
	v_mfma_f32_16x16x32_bf16 v[84:87], v[210:213], v[194:197], v[84:87]
	v_mfma_f32_16x16x32_bf16 v[80:83], v[218:221], v[190:193], v[80:83]
	v_mfma_f32_16x16x32_bf16 v[80:83], v[222:225], v[194:197], v[80:83]
	v_mfma_f32_16x16x32_bf16 v[64:67], v[218:221], v[198:201], v[64:67]
	v_mfma_f32_16x16x32_bf16 v[64:67], v[222:225], v[202:205], v[64:67]
	v_mfma_f32_16x16x32_bf16 v[68:71], v[206:209], v[198:201], v[68:71]
	v_mfma_f32_16x16x32_bf16 v[68:71], v[210:213], v[202:205], v[68:71]
	s_setprio 0
	s_mov_b32 m0, s47
	v_lshl_add_u64 v[170:171], v[228:229], 0, s[4:5]
	s_barrier
	ds_read_b128 v[166:169], v176 offset:49152
	ds_read_b128 v[178:181], v176 offset:50176
	ds_read_b128 v[182:185], v176 offset:51200
	ds_read_b128 v[186:189], v176 offset:52224
	ds_read_b128 v[190:193], v176 offset:53248
	ds_read_b128 v[194:197], v176 offset:54272
	ds_read_b128 v[198:201], v176 offset:55296
	ds_read_b128 v[202:205], v176 offset:56320
	global_load_lds_dwordx4 v[170:171], off
	v_lshl_add_u64 v[170:171], v[230:231], 0, s[4:5]
	s_mov_b32 m0, s48
	s_nop 0
	global_load_lds_dwordx4 v[170:171], off
	s_barrier
	s_waitcnt lgkmcnt(0)
	s_setprio 1
	s_waitcnt lgkmcnt(0)
	v_mfma_f32_16x16x32_bf16 v[60:63], v[128:131], v[166:169], v[60:63]
	v_mfma_f32_16x16x32_bf16 v[60:63], v[132:135], v[178:181], v[60:63]
	v_mfma_f32_16x16x32_bf16 v[56:59], v[136:139], v[166:169], v[56:59]
	v_mfma_f32_16x16x32_bf16 v[56:59], v[140:143], v[178:181], v[56:59]
	v_mfma_f32_16x16x32_bf16 v[40:43], v[136:139], v[182:185], v[40:43]
	v_mfma_f32_16x16x32_bf16 v[40:43], v[140:143], v[186:189], v[40:43]
	v_mfma_f32_16x16x32_bf16 v[44:47], v[128:131], v[182:185], v[44:47]
	v_mfma_f32_16x16x32_bf16 v[44:47], v[132:135], v[186:189], v[44:47]
	v_mfma_f32_16x16x32_bf16 v[28:31], v[128:131], v[190:193], v[28:31]
	v_mfma_f32_16x16x32_bf16 v[28:31], v[132:135], v[194:197], v[28:31]
	v_mfma_f32_16x16x32_bf16 v[24:27], v[136:139], v[190:193], v[24:27]
	v_mfma_f32_16x16x32_bf16 v[24:27], v[140:143], v[194:197], v[24:27]
	v_mfma_f32_16x16x32_bf16 v[8:11], v[136:139], v[198:201], v[8:11]
	v_mfma_f32_16x16x32_bf16 v[8:11], v[140:143], v[202:205], v[8:11]
	v_mfma_f32_16x16x32_bf16 v[12:15], v[128:131], v[198:201], v[12:15]
	v_mfma_f32_16x16x32_bf16 v[12:15], v[132:135], v[202:205], v[12:15]
	s_setprio 0
	s_barrier
	s_add_u32 s2, s14, 0x80080
	s_addc_u32 s3, s15, 0
	s_add_i32 s14, s44, s26
	v_lshl_add_u64 v[128:129], s[2:3], 0, v[148:149]
	s_mov_b32 m0, s14
	s_nop 0
	global_load_lds_dwordx4 v[128:129], off
	v_lshl_add_u64 v[128:129], s[2:3], 0, v[144:145]
	s_add_i32 m0, s14, 0x2000
	s_nop 0
	global_load_lds_dwordx4 v[128:129], off
	s_waitcnt vmcnt(6)
	s_barrier
	s_setprio 1
	v_mfma_f32_16x16x32_bf16 v[52:55], v[206:209], v[166:169], v[52:55]
	v_mfma_f32_16x16x32_bf16 v[52:55], v[210:213], v[178:181], v[52:55]
	v_mfma_f32_16x16x32_bf16 v[48:51], v[218:221], v[166:169], v[48:51]
	v_mfma_f32_16x16x32_bf16 v[48:51], v[222:225], v[178:181], v[48:51]
	v_mfma_f32_16x16x32_bf16 v[32:35], v[218:221], v[182:185], v[32:35]
	v_mfma_f32_16x16x32_bf16 v[32:35], v[222:225], v[186:189], v[32:35]
	v_mfma_f32_16x16x32_bf16 v[36:39], v[206:209], v[182:185], v[36:39]
	v_mfma_f32_16x16x32_bf16 v[36:39], v[210:213], v[186:189], v[36:39]
	v_mfma_f32_16x16x32_bf16 v[20:23], v[206:209], v[190:193], v[20:23]
	v_mfma_f32_16x16x32_bf16 v[20:23], v[210:213], v[194:197], v[20:23]
	v_mfma_f32_16x16x32_bf16 v[16:19], v[218:221], v[190:193], v[16:19]
	v_mfma_f32_16x16x32_bf16 v[16:19], v[222:225], v[194:197], v[16:19]
	v_mfma_f32_16x16x32_bf16 v[0:3], v[218:221], v[198:201], v[0:3]
	v_mfma_f32_16x16x32_bf16 v[0:3], v[222:225], v[202:205], v[0:3]
	v_mfma_f32_16x16x32_bf16 v[4:7], v[206:209], v[198:201], v[4:7]
	v_mfma_f32_16x16x32_bf16 v[4:7], v[210:213], v[202:205], v[4:7]
	s_setprio 0
	s_add_u32 s12, s12, 0x100
	s_addc_u32 s13, s13, 0
	s_add_u32 s58, s58, 0x100
	s_addc_u32 s59, s59, 0
	s_cmp_ge_i32 s64, s46
	s_mov_b32 s14, s64
	s_barrier
	s_cbranch_scc0 .LBB0_650

; #define PG8_STAGE(bufoff, gbase, voff) do { _Pragma("unroll") for (int _i = 0; _i < 2; ++_i) \
;         __builtin_amdgcn_global_load_lds((const unsigned*)((const char*)(gbase) + (voff)[_i]), (LAS unsigned*)(lds + (bufoff) + ldsw + _i * 8192), 16, 0, 0); } while (0)
; #define PG8_LDA(dst, b, h) do { _Pragma("unroll") for (int m = 0; m < 4; ++m) _Pragma("unroll") for (int k = 0; k < 2; ++k) dst[m][k] = *(const LAS bf16x8*)(lds + PG8_SA(b, h) + aoff + m * 2048 + k * 1024); } while (0)
; #define PG8_LDB(dst, b, h) do { _Pragma("unroll") for (int n = 0; n < 2; ++n) _Pragma("unroll") for (int k = 0; k < 2; ++k) dst[n][k] = *(const LAS bf16x8*)(lds + PG8_SB(b, h) + boff + n * 2048 + k * 1024); } while (0)
; #define PG8_MMA(ai, bj, At, Bt) do { __builtin_amdgcn_s_setprio(1); _Pragma("unroll") for (int m = 0; m < 4; ++m) _Pragma("unroll") for (int n = 0; n < 2; ++n) _Pragma("unroll") for (int k = 0; k < 2; ++k) \
;         acc[ai][bj][m][n] = __builtin_amdgcn_mfma_f32_16x16x32_bf16(Bt[n][k], At[m][k], acc[ai][bj][m][n], 0, 0, 0); __builtin_amdgcn_s_setprio(0); } while (0)
; #define PG8_WAIT_L(n) asm volatile("s_waitcnt lgkmcnt(" #n ")" ::: "memory")
; #define PG8_BAR __builtin_amdgcn_s_barrier()
; #define PG8_SCHED __builtin_amdgcn_sched_barrier(0)
; template <class Epi>
; DEVINL void gemm_phase(LAS unsigned char* lds, const Gemm g, const Order& S, const Epi& E) {
;     ...
;         for (int t = 0; t < nt; t += 2) {
;             const bool last = (t == nt - 2);
;             const char* a1 = cA + (size_t)(t + 1) * kstep;
;             const char* a2 = last ? nA : cA + (size_t)(t + 2) * kstep; const char* b2 = last ? nB : cB + (size_t)(t + 2) * kstep;
;             const char* a3 = a2 + kstep; const char* b3 = b2 + kstep;
;             PG8_LDB(B0, 0, 0); PG8_SCHED; PG8_LDA(At, 0, 0); PG8_STAGE(PG8_SA(1, 1), a1 + hstepA, voffA);
;             PG8_WAIT_L(8); PG8_BAR; PG8_WAIT_L(0); PG8_MMA(0, 0, At, B0); PG8_BAR; PG8_SCHED;
;             PG8_LDB(B1, 0, 1); PG8_STAGE(PG8_SB(0, 0), b2, voffB);
;             PG8_BAR; PG8_WAIT_L(0); PG8_MMA(0, 1, At, B1); PG8_BAR;
;             PG8_LDA(At, 0, 1); PG8_STAGE(PG8_SA(0, 0), a2, voffA);
;             PG8_BAR; PG8_WAIT_L(0); PG8_MMA(1, 0, At, B0); PG8_BAR; PG8_SCHED;
.LBB0_802:
	ds_read_b128 v[150:153], v147
	ds_read_b128 v[154:157], v147 offset:1024
	ds_read_b128 v[158:161], v147 offset:2048
	ds_read_b128 v[162:165], v147 offset:3072
	s_add_i32 s65, s38, 2
	s_add_u32 s4, s16, 0x100
	s_addc_u32 s5, s17, 0
	s_cmp_eq_u32 s49, s38
	s_cselect_b32 s38, s58, s59
	s_cselect_b32 s41, s13, s5
	s_cselect_b32 s40, s12, s4
	s_cselect_b32 s39, s11, s64
	v_lshl_add_u64 v[198:199], s[16:17], 0, v[136:137]
	s_add_i32 m0, s31, 0xc000
	ds_read_b128 v[166:169], v148
	ds_read_b128 v[170:173], v148 offset:1024
	ds_read_b128 v[174:177], v148 offset:2048
	ds_read_b128 v[178:181], v148 offset:3072
	ds_read_b128 v[182:185], v148 offset:4096
	ds_read_b128 v[186:189], v148 offset:5120
	ds_read_b128 v[190:193], v148 offset:6144
	ds_read_b128 v[194:197], v148 offset:7168
	global_load_lds_dwordx4 v[198:199], off
	v_lshl_add_u64 v[198:199], s[16:17], 0, v[138:139]
	s_add_i32 m0, s31, 0xe000
	s_nop 0
	global_load_lds_dwordx4 v[198:199], off
	s_waitcnt lgkmcnt(8)
	s_barrier
	s_waitcnt lgkmcnt(0)
	s_setprio 1
	s_waitcnt lgkmcnt(0)
	v_mfma_f32_16x16x32_bf16 v[120:123], v[150:153], v[166:169], v[120:123]
	v_mfma_f32_16x16x32_bf16 v[120:123], v[154:157], v[170:173], v[120:123]
	v_mfma_f32_16x16x32_bf16 v[124:127], v[158:161], v[166:169], v[124:127]
	v_mfma_f32_16x16x32_bf16 v[124:127], v[162:165], v[170:173], v[124:127]
	v_mfma_f32_16x16x32_bf16 v[104:107], v[158:161], v[174:177], v[104:107]
	v_mfma_f32_16x16x32_bf16 v[104:107], v[162:165], v[178:181], v[104:107]
	v_mfma_f32_16x16x32_bf16 v[108:111], v[150:153], v[174:177], v[108:111]
	v_mfma_f32_16x16x32_bf16 v[108:111], v[154:157], v[178:181], v[108:111]
	v_mfma_f32_16x16x32_bf16 v[92:95], v[150:153], v[182:185], v[92:95]
	v_mfma_f32_16x16x32_bf16 v[92:95], v[154:157], v[186:189], v[92:95]
	v_mfma_f32_16x16x32_bf16 v[88:91], v[158:161], v[182:185], v[88:91]
	v_mfma_f32_16x16x32_bf16 v[88:91], v[162:165], v[186:189], v[88:91]
	v_mfma_f32_16x16x32_bf16 v[72:75], v[158:161], v[190:193], v[72:75]
	v_mfma_f32_16x16x32_bf16 v[72:75], v[162:165], v[194:197], v[72:75]
	v_mfma_f32_16x16x32_bf16 v[76:79], v[150:153], v[190:193], v[76:79]
	v_mfma_f32_16x16x32_bf16 v[76:79], v[154:157], v[194:197], v[76:79]
	s_setprio 0
	s_barrier
	s_add_i32 s2, s52, s28
	v_lshl_add_u64 v[218:219], s[38:39], 0, v[132:133]
	s_mov_b32 m0, s2
	ds_read_b128 v[198:201], v149
	ds_read_b128 v[202:205], v149 offset:1024
	ds_read_b128 v[206:209], v149 offset:2048
	ds_read_b128 v[210:213], v149 offset:3072
	global_load_lds_dwordx4 v[218:219], off
	v_lshl_add_u64 v[220:221], s[38:39], 0, v[128:129]
	s_add_i32 m0, s2, 0x2000
	s_nop 0
	global_load_lds_dwordx4 v[220:221], off
	s_barrier
	s_waitcnt lgkmcnt(0)
	s_setprio 1
	s_waitcnt lgkmcnt(0)
	v_mfma_f32_16x16x32_bf16 v[116:119], v[198:201], v[166:169], v[116:119]
	v_mfma_f32_16x16x32_bf16 v[116:119], v[202:205], v[170:173], v[116:119]
	v_mfma_f32_16x16x32_bf16 v[112:115], v[206:209], v[166:169], v[112:115]
	v_mfma_f32_16x16x32_bf16 v[112:115], v[210:213], v[170:173], v[112:115]
	v_mfma_f32_16x16x32_bf16 v[96:99], v[206:209], v[174:177], v[96:99]
	v_mfma_f32_16x16x32_bf16 v[96:99], v[210:213], v[178:181], v[96:99]
	v_mfma_f32_16x16x32_bf16 v[100:103], v[198:201], v[174:177], v[100:103]
	v_mfma_f32_16x16x32_bf16 v[100:103], v[202:205], v[178:181], v[100:103]
	v_mfma_f32_16x16x32_bf16 v[84:87], v[198:201], v[182:185], v[84:87]
	v_mfma_f32_16x16x32_bf16 v[84:87], v[202:205], v[186:189], v[84:87]
	v_mfma_f32_16x16x32_bf16 v[80:83], v[206:209], v[182:185], v[80:83]
	v_mfma_f32_16x16x32_bf16 v[80:83], v[210:213], v[186:189], v[80:83]
	v_mfma_f32_16x16x32_bf16 v[64:67], v[206:209], v[190:193], v[64:67]
	v_mfma_f32_16x16x32_bf16 v[64:67], v[210:213], v[194:197], v[64:67]
	v_mfma_f32_16x16x32_bf16 v[68:71], v[198:201], v[190:193], v[68:71]
	v_mfma_f32_16x16x32_bf16 v[68:71], v[202:205], v[194:197], v[68:71]
	s_setprio 0
	s_mov_b32 m0, s31
	v_lshl_add_u64 v[222:223], s[40:41], 0, v[134:135]
	s_barrier
	ds_read_b128 v[166:169], v148 offset:16384
	ds_read_b128 v[170:173], v148 offset:17408
	ds_read_b128 v[174:177], v148 offset:18432
	ds_read_b128 v[178:181], v148 offset:19456
	ds_read_b128 v[182:185], v148 offset:20480
	ds_read_b128 v[186:189], v148 offset:21504
	ds_read_b128 v[190:193], v148 offset:22528
	ds_read_b128 v[194:197], v148 offset:23552
	global_load_lds_dwordx4 v[222:223], off
	v_lshl_add_u64 v[224:225], s[40:41], 0, v[130:131]
	s_mov_b32 m0, s42
	s_nop 0
	global_load_lds_dwordx4 v[224:225], off
	s_barrier
	s_waitcnt lgkmcnt(0)
	s_setprio 1
	s_waitcnt lgkmcnt(0)
	v_mfma_f32_16x16x32_bf16 v[60:63], v[150:153], v[166:169], v[60:63]
	v_mfma_f32_16x16x32_bf16 v[60:63], v[154:157], v[170:173], v[60:63]
	v_mfma_f32_16x16x32_bf16 v[56:59], v[158:161], v[166:169], v[56:59]
	v_mfma_f32_16x16x32_bf16 v[56:59], v[162:165], v[170:173], v[56:59]
	v_mfma_f32_16x16x32_bf16 v[40:43], v[158:161], v[174:177], v[40:43]
	v_mfma_f32_16x16x32_bf16 v[40:43], v[162:165], v[178:181], v[40:43]
	v_mfma_f32_16x16x32_bf16 v[44:47], v[150:153], v[174:177], v[44:47]
	v_mfma_f32_16x16x32_bf16 v[44:47], v[154:157], v[178:181], v[44:47]
	v_mfma_f32_16x16x32_bf16 v[28:31], v[150:153], v[182:185], v[28:31]
	v_mfma_f32_16x16x32_bf16 v[28:31], v[154:157], v[186:189], v[28:31]
	v_mfma_f32_16x16x32_bf16 v[24:27], v[158:161], v[182:185], v[24:27]
	v_mfma_f32_16x16x32_bf16 v[24:27], v[162:165], v[186:189], v[24:27]
	v_mfma_f32_16x16x32_bf16 v[8:11], v[158:161], v[190:193], v[8:11]
	v_mfma_f32_16x16x32_bf16 v[8:11], v[162:165], v[194:197], v[8:11]
	v_mfma_f32_16x16x32_bf16 v[12:15], v[150:153], v[190:193], v[12:15]
	v_mfma_f32_16x16x32_bf16 v[12:15], v[154:157], v[194:197], v[12:15]
	s_setprio 0
	s_barrier
; #define PG8_STAGE(bufoff, gbase, voff) do { _Pragma("unroll") for (int _i = 0; _i < 2; ++_i) \
;         __builtin_amdgcn_global_load_lds((const unsigned*)((const char*)(gbase) + (voff)[_i]), (LAS unsigned*)(lds + (bufoff) + ldsw + _i * 8192), 16, 0, 0); } while (0)
; #define PG8_LDA(dst, b, h) do { _Pragma("unroll") for (int m = 0; m < 4; ++m) _Pragma("unroll") for (int k = 0; k < 2; ++k) dst[m][k] = *(const LAS bf16x8*)(lds + PG8_SA(b, h) + aoff + m * 2048 + k * 1024); } while (0)
; #define PG8_LDB(dst, b, h) do { _Pragma("unroll") for (int n = 0; n < 2; ++n) _Pragma("unroll") for (int k = 0; k < 2; ++k) dst[n][k] = *(const LAS bf16x8*)(lds + PG8_SB(b, h) + boff + n * 2048 + k * 1024); } while (0)
; #define PG8_MMA(ai, bj, At, Bt) do { __builtin_amdgcn_s_setprio(1); _Pragma("unroll") for (int m = 0; m < 4; ++m) _Pragma("unroll") for (int n = 0; n < 2; ++n) _Pragma("unroll") for (int k = 0; k < 2; ++k) \
;         acc[ai][bj][m][n] = __builtin_amdgcn_mfma_f32_16x16x32_bf16(Bt[n][k], At[m][k], acc[ai][bj][m][n], 0, 0, 0); __builtin_amdgcn_s_setprio(0); } while (0)
; #define PG8_WAIT_V(n) asm volatile("s_waitcnt vmcnt(" #n ")" ::: "memory")
; #define PG8_WAIT_L(n) asm volatile("s_waitcnt lgkmcnt(" #n ")" ::: "memory")
; #define PG8_BAR __builtin_amdgcn_s_barrier()
; #define PG8_SCHED __builtin_amdgcn_sched_barrier(0)
; template <class Epi>
; DEVINL void gemm_phase(LAS unsigned char* lds, const Gemm g, const Order& S, const Epi& E) {
;     ...
;             PG8_STAGE(PG8_SB(0, 1), b2 + hstepB, voffB);
;             PG8_WAIT_V(6); PG8_BAR; PG8_MMA(1, 1, At, B1); PG8_BAR;
;             PG8_LDB(B0, 1, 0); PG8_SCHED; PG8_LDA(At, 1, 0); PG8_STAGE(PG8_SA(0, 1), a2 + hstepA, voffA);
;             PG8_WAIT_L(8); PG8_BAR; PG8_WAIT_L(0); PG8_MMA(0, 0, At, B0); PG8_BAR; PG8_SCHED;
;             PG8_LDB(B1, 1, 1); PG8_STAGE(PG8_SB(1, 0), b3, voffB);
	s_add_u32 s2, s38, 0x20000
	s_addc_u32 s3, s39, 0
	s_add_i32 s16, s53, s28
	v_lshl_add_u64 v[150:151], s[2:3], 0, v[132:133]
	s_mov_b32 m0, s16
	s_nop 0
	global_load_lds_dwordx4 v[150:151], off
	v_lshl_add_u64 v[150:151], s[2:3], 0, v[128:129]
	s_add_i32 m0, s16, 0x2000
	s_nop 0
	global_load_lds_dwordx4 v[150:151], off
	s_waitcnt vmcnt(6)
	s_barrier
	s_setprio 1
	v_mfma_f32_16x16x32_bf16 v[52:55], v[198:201], v[166:169], v[52:55]
	v_mfma_f32_16x16x32_bf16 v[52:55], v[202:205], v[170:173], v[52:55]
	v_mfma_f32_16x16x32_bf16 v[48:51], v[206:209], v[166:169], v[48:51]
	v_mfma_f32_16x16x32_bf16 v[48:51], v[210:213], v[170:173], v[48:51]
	v_mfma_f32_16x16x32_bf16 v[32:35], v[206:209], v[174:177], v[32:35]
	v_mfma_f32_16x16x32_bf16 v[32:35], v[210:213], v[178:181], v[32:35]
	v_mfma_f32_16x16x32_bf16 v[36:39], v[198:201], v[174:177], v[36:39]
	v_mfma_f32_16x16x32_bf16 v[36:39], v[202:205], v[178:181], v[36:39]
	v_mfma_f32_16x16x32_bf16 v[20:23], v[198:201], v[182:185], v[20:23]
	v_mfma_f32_16x16x32_bf16 v[20:23], v[202:205], v[186:189], v[20:23]
	v_mfma_f32_16x16x32_bf16 v[16:19], v[206:209], v[182:185], v[16:19]
	v_mfma_f32_16x16x32_bf16 v[16:19], v[210:213], v[186:189], v[16:19]
	v_mfma_f32_16x16x32_bf16 v[0:3], v[206:209], v[190:193], v[0:3]
	v_mfma_f32_16x16x32_bf16 v[0:3], v[210:213], v[194:197], v[0:3]
	v_mfma_f32_16x16x32_bf16 v[4:7], v[198:201], v[190:193], v[4:7]
	v_mfma_f32_16x16x32_bf16 v[4:7], v[202:205], v[194:197], v[4:7]
	s_setprio 0
	s_add_i32 s16, 16, 0x18000
	v_add_u32_e32 v162, s16, v145
	s_barrier
	ds_read_b128 v[150:153], v162
	ds_read_b128 v[154:157], v162 offset:1024
	ds_read_b128 v[158:161], v162 offset:2048
	ds_read_b128 v[162:165], v162 offset:3072
	s_add_u32 s2, s40, 0x30000
	s_addc_u32 s3, s41, 0
	s_mov_b32 m0, s43
	v_lshl_add_u64 v[198:199], s[2:3], 0, v[134:135]
	ds_read_b128 v[166:169], v148 offset:32768
	ds_read_b128 v[170:173], v148 offset:33792
	ds_read_b128 v[174:177], v148 offset:34816
	ds_read_b128 v[178:181], v148 offset:35840
	ds_read_b128 v[182:185], v148 offset:36864
	ds_read_b128 v[186:189], v148 offset:37888
	ds_read_b128 v[190:193], v148 offset:38912
	ds_read_b128 v[194:197], v148 offset:39936
	global_load_lds_dwordx4 v[198:199], off
	v_lshl_add_u64 v[198:199], s[2:3], 0, v[130:131]
	s_mov_b32 m0, s44
	s_nop 0
	global_load_lds_dwordx4 v[198:199], off
	s_waitcnt lgkmcnt(8)
	s_barrier
	s_waitcnt lgkmcnt(0)
	s_setprio 1
	s_waitcnt lgkmcnt(0)
	v_mfma_f32_16x16x32_bf16 v[120:123], v[150:153], v[166:169], v[120:123]
	v_mfma_f32_16x16x32_bf16 v[120:123], v[154:157], v[170:173], v[120:123]
	v_mfma_f32_16x16x32_bf16 v[124:127], v[158:161], v[166:169], v[124:127]
	v_mfma_f32_16x16x32_bf16 v[124:127], v[162:165], v[170:173], v[124:127]
	v_mfma_f32_16x16x32_bf16 v[104:107], v[158:161], v[174:177], v[104:107]
	v_mfma_f32_16x16x32_bf16 v[104:107], v[162:165], v[178:181], v[104:107]
	v_mfma_f32_16x16x32_bf16 v[108:111], v[150:153], v[174:177], v[108:111]
	v_mfma_f32_16x16x32_bf16 v[108:111], v[154:157], v[178:181], v[108:111]
	v_mfma_f32_16x16x32_bf16 v[92:95], v[150:153], v[182:185], v[92:95]
	v_mfma_f32_16x16x32_bf16 v[92:95], v[154:157], v[186:189], v[92:95]
	v_mfma_f32_16x16x32_bf16 v[88:91], v[158:161], v[182:185], v[88:91]
	v_mfma_f32_16x16x32_bf16 v[88:91], v[162:165], v[186:189], v[88:91]
	v_mfma_f32_16x16x32_bf16 v[72:75], v[158:161], v[190:193], v[72:75]
	v_mfma_f32_16x16x32_bf16 v[72:75], v[162:165], v[194:197], v[72:75]
	v_mfma_f32_16x16x32_bf16 v[76:79], v[150:153], v[190:193], v[76:79]
	v_mfma_f32_16x16x32_bf16 v[76:79], v[154:157], v[194:197], v[76:79]
	s_setprio 0
	s_barrier
	s_add_i32 s17, 16, 0x1c000
	s_add_i32 s2, s16, s28
	v_add_u32_e32 v210, s17, v145
	v_lshl_add_u64 v[218:219], v[218:219], 0, s[6:7]
	s_mov_b32 m0, s2
	ds_read_b128 v[198:201], v210
	ds_read_b128 v[202:205], v210 offset:1024
	ds_read_b128 v[206:209], v210 offset:2048
	ds_read_b128 v[210:213], v210 offset:3072
	global_load_lds_dwordx4 v[218:219], off
	v_lshl_add_u64 v[218:219], v[220:221], 0, s[6:7]
	s_add_i32 m0, s2, 0x2000
	s_nop 0
	global_load_lds_dwordx4 v[218:219], off
	s_barrier
; #define PG8_STAGE(bufoff, gbase, voff) do { _Pragma("unroll") for (int _i = 0; _i < 2; ++_i) \
;         __builtin_amdgcn_global_load_lds((const unsigned*)((const char*)(gbase) + (voff)[_i]), (LAS unsigned*)(lds + (bufoff) + ldsw + _i * 8192), 16, 0, 0); } while (0)
; #define PG8_LDA(dst, b, h) do { _Pragma("unroll") for (int m = 0; m < 4; ++m) _Pragma("unroll") for (int k = 0; k < 2; ++k) dst[m][k] = *(const LAS bf16x8*)(lds + PG8_SA(b, h) + aoff + m * 2048 + k * 1024); } while (0)
; #define PG8_MMA(ai, bj, At, Bt) do { __builtin_amdgcn_s_setprio(1); _Pragma("unroll") for (int m = 0; m < 4; ++m) _Pragma("unroll") for (int n = 0; n < 2; ++n) _Pragma("unroll") for (int k = 0; k < 2; ++k) \
;         acc[ai][bj][m][n] = __builtin_amdgcn_mfma_f32_16x16x32_bf16(Bt[n][k], At[m][k], acc[ai][bj][m][n], 0, 0, 0); __builtin_amdgcn_s_setprio(0); } while (0)
; #define PG8_WAIT_V(n) asm volatile("s_waitcnt vmcnt(" #n ")" ::: "memory")
; #define PG8_WAIT_L(n) asm volatile("s_waitcnt lgkmcnt(" #n ")" ::: "memory")
; #define PG8_BAR __builtin_amdgcn_s_barrier()
; #define PG8_SCHED __builtin_amdgcn_sched_barrier(0)
; template <class Epi>
; DEVINL void gemm_phase(LAS unsigned char* lds, const Gemm g, const Order& S, const Epi& E) {
;     ...
;             PG8_BAR; PG8_WAIT_L(0); PG8_MMA(0, 1, At, B1); PG8_BAR;
;             PG8_LDA(At, 1, 1); PG8_STAGE(PG8_SA(1, 0), a3, voffA);
;             PG8_BAR; PG8_WAIT_L(0); PG8_MMA(1, 0, At, B0); PG8_BAR; PG8_SCHED;
;             PG8_STAGE(PG8_SB(1, 1), b3 + hstepB, voffB);
;             PG8_WAIT_V(6); PG8_BAR; PG8_MMA(1, 1, At, B1); PG8_BAR;
	s_waitcnt lgkmcnt(0)
	s_setprio 1
	s_waitcnt lgkmcnt(0)
	v_mfma_f32_16x16x32_bf16 v[116:119], v[198:201], v[166:169], v[116:119]
	v_mfma_f32_16x16x32_bf16 v[116:119], v[202:205], v[170:173], v[116:119]
	v_mfma_f32_16x16x32_bf16 v[112:115], v[206:209], v[166:169], v[112:115]
	v_mfma_f32_16x16x32_bf16 v[112:115], v[210:213], v[170:173], v[112:115]
	v_mfma_f32_16x16x32_bf16 v[96:99], v[206:209], v[174:177], v[96:99]
	v_mfma_f32_16x16x32_bf16 v[96:99], v[210:213], v[178:181], v[96:99]
	v_mfma_f32_16x16x32_bf16 v[100:103], v[198:201], v[174:177], v[100:103]
	v_mfma_f32_16x16x32_bf16 v[100:103], v[202:205], v[178:181], v[100:103]
	v_mfma_f32_16x16x32_bf16 v[84:87], v[198:201], v[182:185], v[84:87]
	v_mfma_f32_16x16x32_bf16 v[84:87], v[202:205], v[186:189], v[84:87]
	v_mfma_f32_16x16x32_bf16 v[80:83], v[206:209], v[182:185], v[80:83]
	v_mfma_f32_16x16x32_bf16 v[80:83], v[210:213], v[186:189], v[80:83]
	v_mfma_f32_16x16x32_bf16 v[64:67], v[206:209], v[190:193], v[64:67]
	v_mfma_f32_16x16x32_bf16 v[64:67], v[210:213], v[194:197], v[64:67]
	v_mfma_f32_16x16x32_bf16 v[68:71], v[198:201], v[190:193], v[68:71]
	v_mfma_f32_16x16x32_bf16 v[68:71], v[202:205], v[194:197], v[68:71]
	s_setprio 0
	s_mov_b32 m0, s47
	v_lshl_add_u64 v[218:219], v[222:223], 0, s[6:7]
	s_barrier
	ds_read_b128 v[166:169], v148 offset:49152
	ds_read_b128 v[170:173], v148 offset:50176
	ds_read_b128 v[174:177], v148 offset:51200
	ds_read_b128 v[178:181], v148 offset:52224
	ds_read_b128 v[182:185], v148 offset:53248
	ds_read_b128 v[186:189], v148 offset:54272
	ds_read_b128 v[190:193], v148 offset:55296
	ds_read_b128 v[194:197], v148 offset:56320
	global_load_lds_dwordx4 v[218:219], off
	v_lshl_add_u64 v[218:219], v[224:225], 0, s[6:7]
	s_mov_b32 m0, s48
	s_nop 0
	global_load_lds_dwordx4 v[218:219], off
	s_barrier
	s_waitcnt lgkmcnt(0)
	s_setprio 1
	s_waitcnt lgkmcnt(0)
	v_mfma_f32_16x16x32_bf16 v[60:63], v[150:153], v[166:169], v[60:63]
	v_mfma_f32_16x16x32_bf16 v[60:63], v[154:157], v[170:173], v[60:63]
	v_mfma_f32_16x16x32_bf16 v[56:59], v[158:161], v[166:169], v[56:59]
	v_mfma_f32_16x16x32_bf16 v[56:59], v[162:165], v[170:173], v[56:59]
	v_mfma_f32_16x16x32_bf16 v[40:43], v[158:161], v[174:177], v[40:43]
	v_mfma_f32_16x16x32_bf16 v[40:43], v[162:165], v[178:181], v[40:43]
	v_mfma_f32_16x16x32_bf16 v[44:47], v[150:153], v[174:177], v[44:47]
	v_mfma_f32_16x16x32_bf16 v[44:47], v[154:157], v[178:181], v[44:47]
	v_mfma_f32_16x16x32_bf16 v[28:31], v[150:153], v[182:185], v[28:31]
	v_mfma_f32_16x16x32_bf16 v[28:31], v[154:157], v[186:189], v[28:31]
	v_mfma_f32_16x16x32_bf16 v[24:27], v[158:161], v[182:185], v[24:27]
	v_mfma_f32_16x16x32_bf16 v[24:27], v[162:165], v[186:189], v[24:27]
	v_mfma_f32_16x16x32_bf16 v[8:11], v[158:161], v[190:193], v[8:11]
	v_mfma_f32_16x16x32_bf16 v[8:11], v[162:165], v[194:197], v[8:11]
	v_mfma_f32_16x16x32_bf16 v[12:15], v[150:153], v[190:193], v[12:15]
	v_mfma_f32_16x16x32_bf16 v[12:15], v[154:157], v[194:197], v[12:15]
	s_setprio 0
	s_barrier
	s_add_u32 s2, s38, 0x20080
	s_addc_u32 s3, s39, 0
	s_add_i32 s16, s17, s28
	v_lshl_add_u64 v[150:151], s[2:3], 0, v[132:133]
	s_mov_b32 m0, s16
	s_nop 0
	global_load_lds_dwordx4 v[150:151], off
	v_lshl_add_u64 v[150:151], s[2:3], 0, v[128:129]
	s_add_i32 m0, s16, 0x2000
	s_nop 0
	global_load_lds_dwordx4 v[150:151], off
	s_waitcnt vmcnt(6)
	s_barrier
	s_setprio 1
	v_mfma_f32_16x16x32_bf16 v[52:55], v[198:201], v[166:169], v[52:55]
	v_mfma_f32_16x16x32_bf16 v[52:55], v[202:205], v[170:173], v[52:55]
	v_mfma_f32_16x16x32_bf16 v[48:51], v[206:209], v[166:169], v[48:51]
	v_mfma_f32_16x16x32_bf16 v[48:51], v[210:213], v[170:173], v[48:51]
	v_mfma_f32_16x16x32_bf16 v[32:35], v[206:209], v[174:177], v[32:35]
	v_mfma_f32_16x16x32_bf16 v[32:35], v[210:213], v[178:181], v[32:35]
	v_mfma_f32_16x16x32_bf16 v[36:39], v[198:201], v[174:177], v[36:39]
	v_mfma_f32_16x16x32_bf16 v[36:39], v[202:205], v[178:181], v[36:39]
	v_mfma_f32_16x16x32_bf16 v[20:23], v[198:201], v[182:185], v[20:23]
	v_mfma_f32_16x16x32_bf16 v[20:23], v[202:205], v[186:189], v[20:23]
	v_mfma_f32_16x16x32_bf16 v[16:19], v[206:209], v[182:185], v[16:19]
	v_mfma_f32_16x16x32_bf16 v[16:19], v[210:213], v[186:189], v[16:19]
	v_mfma_f32_16x16x32_bf16 v[0:3], v[206:209], v[190:193], v[0:3]
	v_mfma_f32_16x16x32_bf16 v[0:3], v[210:213], v[194:197], v[0:3]
	v_mfma_f32_16x16x32_bf16 v[4:7], v[198:201], v[190:193], v[4:7]
	v_mfma_f32_16x16x32_bf16 v[4:7], v[202:205], v[194:197], v[4:7]
	s_setprio 0
	s_add_u32 s59, s59, 0x100
	s_addc_u32 s64, s64, 0
	s_cmp_ge_i32 s65, s46
	s_mov_b64 s[16:17], s[4:5]
	s_mov_b32 s38, s65
	s_barrier
	s_cbranch_scc0 .LBB0_802
	s_branch .LBB0_795

; #define PG8_STAGE(bufoff, gbase, voff) do { _Pragma("unroll") for (int _i = 0; _i < 2; ++_i) \
;         __builtin_amdgcn_global_load_lds((const unsigned*)((const char*)(gbase) + (voff)[_i]), (LAS unsigned*)(lds + (bufoff) + ldsw + _i * 8192), 16, 0, 0); } while (0)
; #define PG8_LDA(dst, b, h) do { _Pragma("unroll") for (int m = 0; m < 4; ++m) _Pragma("unroll") for (int k = 0; k < 2; ++k) dst[m][k] = *(const LAS bf16x8*)(lds + PG8_SA(b, h) + aoff + m * 2048 + k * 1024); } while (0)
; #define PG8_LDB(dst, b, h) do { _Pragma("unroll") for (int n = 0; n < 2; ++n) _Pragma("unroll") for (int k = 0; k < 2; ++k) dst[n][k] = *(const LAS bf16x8*)(lds + PG8_SB(b, h) + boff + n * 2048 + k * 1024); } while (0)
; #define PG8_MMA(ai, bj, At, Bt) do { __builtin_amdgcn_s_setprio(1); _Pragma("unroll") for (int m = 0; m < 4; ++m) _Pragma("unroll") for (int n = 0; n < 2; ++n) _Pragma("unroll") for (int k = 0; k < 2; ++k) \
;         acc[ai][bj][m][n] = __builtin_amdgcn_mfma_f32_16x16x32_bf16(Bt[n][k], At[m][k], acc[ai][bj][m][n], 0, 0, 0); __builtin_amdgcn_s_setprio(0); } while (0)
; #define PG8_WAIT_L(n) asm volatile("s_waitcnt lgkmcnt(" #n ")" ::: "memory")
; #define PG8_BAR __builtin_amdgcn_s_barrier()
; #define PG8_SCHED __builtin_amdgcn_sched_barrier(0)
; template <class Epi>
; DEVINL void gemm_phase(LAS unsigned char* lds, const Gemm g, const Order& S, const Epi& E) {
;     ...
;         const char* nA = has_next ? (const char*)g.A + (size_t)nxt.pm * tstepA : cA; const char* nB = has_next ? (const char*)g.Bt + (size_t)nxt.pn * tstepB : cB;
;         for (int t = 0; t < nt; t += 2) {
;             const bool last = (t == nt - 2);
;             const char* a1 = cA + (size_t)(t + 1) * kstep;
;             const char* a2 = last ? nA : cA + (size_t)(t + 2) * kstep; const char* b2 = last ? nB : cB + (size_t)(t + 2) * kstep;
;             const char* a3 = a2 + kstep; const char* b3 = b2 + kstep;
;             PG8_LDB(B0, 0, 0); PG8_SCHED; PG8_LDA(At, 0, 0); PG8_STAGE(PG8_SA(1, 1), a1 + hstepA, voffA);
;             PG8_WAIT_L(8); PG8_BAR; PG8_WAIT_L(0); PG8_MMA(0, 0, At, B0); PG8_BAR; PG8_SCHED;
;             PG8_LDB(B1, 0, 1); PG8_STAGE(PG8_SB(0, 0), b2, voffB);
;             PG8_BAR; PG8_WAIT_L(0); PG8_MMA(0, 1, At, B1); PG8_BAR;
;             PG8_LDA(At, 0, 1); PG8_STAGE(PG8_SA(0, 0), a2, voffA);
;             PG8_BAR; PG8_WAIT_L(0); PG8_MMA(1, 0, At, B0); PG8_BAR; PG8_SCHED;
.LBB0_825:
	ds_read_b128 v[150:153], v147
	ds_read_b128 v[154:157], v147 offset:1024
	ds_read_b128 v[158:161], v147 offset:2048
	ds_read_b128 v[162:165], v147 offset:3072
	s_add_i32 s68, s42, 2
	s_add_u32 s4, s38, 0x100
	s_addc_u32 s5, s39, 0
	s_cmp_eq_u32 s53, s42
	s_cselect_b32 s42, s65, s66
	s_cselect_b32 s45, s15, s5
	s_cselect_b32 s44, s14, s4
	s_cselect_b32 s43, s13, s67
	v_lshl_add_u64 v[198:199], s[38:39], 0, v[136:137]
	s_add_i32 m0, s31, 0xc000
	ds_read_b128 v[166:169], v148
	ds_read_b128 v[170:173], v148 offset:1024
	ds_read_b128 v[174:177], v148 offset:2048
	ds_read_b128 v[178:181], v148 offset:3072
	ds_read_b128 v[182:185], v148 offset:4096
	ds_read_b128 v[186:189], v148 offset:5120
	ds_read_b128 v[190:193], v148 offset:6144
	ds_read_b128 v[194:197], v148 offset:7168
	global_load_lds_dwordx4 v[198:199], off
	v_lshl_add_u64 v[198:199], s[38:39], 0, v[138:139]
	s_add_i32 m0, s31, 0xe000
	s_nop 0
	global_load_lds_dwordx4 v[198:199], off
	s_waitcnt lgkmcnt(8)
	s_barrier
	s_waitcnt lgkmcnt(0)
	s_setprio 1
	s_waitcnt lgkmcnt(0)
	v_mfma_f32_16x16x32_bf16 v[120:123], v[150:153], v[166:169], v[120:123]
	v_mfma_f32_16x16x32_bf16 v[120:123], v[154:157], v[170:173], v[120:123]
	v_mfma_f32_16x16x32_bf16 v[124:127], v[158:161], v[166:169], v[124:127]
	v_mfma_f32_16x16x32_bf16 v[124:127], v[162:165], v[170:173], v[124:127]
	v_mfma_f32_16x16x32_bf16 v[104:107], v[158:161], v[174:177], v[104:107]
	v_mfma_f32_16x16x32_bf16 v[104:107], v[162:165], v[178:181], v[104:107]
	v_mfma_f32_16x16x32_bf16 v[108:111], v[150:153], v[174:177], v[108:111]
	v_mfma_f32_16x16x32_bf16 v[108:111], v[154:157], v[178:181], v[108:111]
	v_mfma_f32_16x16x32_bf16 v[92:95], v[150:153], v[182:185], v[92:95]
	v_mfma_f32_16x16x32_bf16 v[92:95], v[154:157], v[186:189], v[92:95]
	v_mfma_f32_16x16x32_bf16 v[88:91], v[158:161], v[182:185], v[88:91]
	v_mfma_f32_16x16x32_bf16 v[88:91], v[162:165], v[186:189], v[88:91]
	v_mfma_f32_16x16x32_bf16 v[72:75], v[158:161], v[190:193], v[72:75]
	v_mfma_f32_16x16x32_bf16 v[72:75], v[162:165], v[194:197], v[72:75]
	v_mfma_f32_16x16x32_bf16 v[76:79], v[150:153], v[190:193], v[76:79]
	v_mfma_f32_16x16x32_bf16 v[76:79], v[154:157], v[194:197], v[76:79]
	s_setprio 0
	s_barrier
	s_add_i32 s2, s57, s30
	v_lshl_add_u64 v[218:219], s[42:43], 0, v[130:131]
	s_mov_b32 m0, s2
	ds_read_b128 v[198:201], v149
	ds_read_b128 v[202:205], v149 offset:1024
	ds_read_b128 v[206:209], v149 offset:2048
	ds_read_b128 v[210:213], v149 offset:3072
	global_load_lds_dwordx4 v[218:219], off
	v_lshl_add_u64 v[220:221], s[42:43], 0, v[134:135]
	s_add_i32 m0, s2, 0x2000
	s_nop 0
	global_load_lds_dwordx4 v[220:221], off
	s_barrier
	s_waitcnt lgkmcnt(0)
	s_setprio 1
	s_waitcnt lgkmcnt(0)
	v_mfma_f32_16x16x32_bf16 v[116:119], v[198:201], v[166:169], v[116:119]
	v_mfma_f32_16x16x32_bf16 v[116:119], v[202:205], v[170:173], v[116:119]
	v_mfma_f32_16x16x32_bf16 v[112:115], v[206:209], v[166:169], v[112:115]
	v_mfma_f32_16x16x32_bf16 v[112:115], v[210:213], v[170:173], v[112:115]
	v_mfma_f32_16x16x32_bf16 v[96:99], v[206:209], v[174:177], v[96:99]
	v_mfma_f32_16x16x32_bf16 v[96:99], v[210:213], v[178:181], v[96:99]
	v_mfma_f32_16x16x32_bf16 v[100:103], v[198:201], v[174:177], v[100:103]
	v_mfma_f32_16x16x32_bf16 v[100:103], v[202:205], v[178:181], v[100:103]
	v_mfma_f32_16x16x32_bf16 v[84:87], v[198:201], v[182:185], v[84:87]
	v_mfma_f32_16x16x32_bf16 v[84:87], v[202:205], v[186:189], v[84:87]
	v_mfma_f32_16x16x32_bf16 v[80:83], v[206:209], v[182:185], v[80:83]
	v_mfma_f32_16x16x32_bf16 v[80:83], v[210:213], v[186:189], v[80:83]
	v_mfma_f32_16x16x32_bf16 v[64:67], v[206:209], v[190:193], v[64:67]
	v_mfma_f32_16x16x32_bf16 v[64:67], v[210:213], v[194:197], v[64:67]
	v_mfma_f32_16x16x32_bf16 v[68:71], v[198:201], v[190:193], v[68:71]
	v_mfma_f32_16x16x32_bf16 v[68:71], v[202:205], v[194:197], v[68:71]
	s_setprio 0
	s_mov_b32 m0, s31
	v_lshl_add_u64 v[222:223], s[44:45], 0, v[128:129]
	s_barrier
	ds_read_b128 v[166:169], v148 offset:16384
	ds_read_b128 v[170:173], v148 offset:17408
	ds_read_b128 v[174:177], v148 offset:18432
	ds_read_b128 v[178:181], v148 offset:19456
	ds_read_b128 v[182:185], v148 offset:20480
	ds_read_b128 v[186:189], v148 offset:21504
	ds_read_b128 v[190:193], v148 offset:22528
	ds_read_b128 v[194:197], v148 offset:23552
	global_load_lds_dwordx4 v[222:223], off
	v_lshl_add_u64 v[224:225], s[44:45], 0, v[132:133]
	s_mov_b32 m0, s46
	s_nop 0
	global_load_lds_dwordx4 v[224:225], off
	s_barrier
	s_waitcnt lgkmcnt(0)
	s_setprio 1
	s_waitcnt lgkmcnt(0)
	v_mfma_f32_16x16x32_bf16 v[60:63], v[150:153], v[166:169], v[60:63]
	v_mfma_f32_16x16x32_bf16 v[60:63], v[154:157], v[170:173], v[60:63]
	v_mfma_f32_16x16x32_bf16 v[56:59], v[158:161], v[166:169], v[56:59]
	v_mfma_f32_16x16x32_bf16 v[56:59], v[162:165], v[170:173], v[56:59]
	v_mfma_f32_16x16x32_bf16 v[40:43], v[158:161], v[174:177], v[40:43]
	v_mfma_f32_16x16x32_bf16 v[40:43], v[162:165], v[178:181], v[40:43]
	v_mfma_f32_16x16x32_bf16 v[44:47], v[150:153], v[174:177], v[44:47]
	v_mfma_f32_16x16x32_bf16 v[44:47], v[154:157], v[178:181], v[44:47]
	v_mfma_f32_16x16x32_bf16 v[28:31], v[150:153], v[182:185], v[28:31]
	v_mfma_f32_16x16x32_bf16 v[28:31], v[154:157], v[186:189], v[28:31]
	v_mfma_f32_16x16x32_bf16 v[24:27], v[158:161], v[182:185], v[24:27]
	v_mfma_f32_16x16x32_bf16 v[24:27], v[162:165], v[186:189], v[24:27]
	v_mfma_f32_16x16x32_bf16 v[8:11], v[158:161], v[190:193], v[8:11]
	v_mfma_f32_16x16x32_bf16 v[8:11], v[162:165], v[194:197], v[8:11]
	v_mfma_f32_16x16x32_bf16 v[12:15], v[150:153], v[190:193], v[12:15]
	v_mfma_f32_16x16x32_bf16 v[12:15], v[154:157], v[194:197], v[12:15]
	s_setprio 0
	s_barrier
; #define PG8_STAGE(bufoff, gbase, voff) do { _Pragma("unroll") for (int _i = 0; _i < 2; ++_i) \
;         __builtin_amdgcn_global_load_lds((const unsigned*)((const char*)(gbase) + (voff)[_i]), (LAS unsigned*)(lds + (bufoff) + ldsw + _i * 8192), 16, 0, 0); } while (0)
; #define PG8_LDA(dst, b, h) do { _Pragma("unroll") for (int m = 0; m < 4; ++m) _Pragma("unroll") for (int k = 0; k < 2; ++k) dst[m][k] = *(const LAS bf16x8*)(lds + PG8_SA(b, h) + aoff + m * 2048 + k * 1024); } while (0)
; #define PG8_LDB(dst, b, h) do { _Pragma("unroll") for (int n = 0; n < 2; ++n) _Pragma("unroll") for (int k = 0; k < 2; ++k) dst[n][k] = *(const LAS bf16x8*)(lds + PG8_SB(b, h) + boff + n * 2048 + k * 1024); } while (0)
; #define PG8_MMA(ai, bj, At, Bt) do { __builtin_amdgcn_s_setprio(1); _Pragma("unroll") for (int m = 0; m < 4; ++m) _Pragma("unroll") for (int n = 0; n < 2; ++n) _Pragma("unroll") for (int k = 0; k < 2; ++k) \
;         acc[ai][bj][m][n] = __builtin_amdgcn_mfma_f32_16x16x32_bf16(Bt[n][k], At[m][k], acc[ai][bj][m][n], 0, 0, 0); __builtin_amdgcn_s_setprio(0); } while (0)
; #define PG8_WAIT_V(n) asm volatile("s_waitcnt vmcnt(" #n ")" ::: "memory")
; #define PG8_WAIT_L(n) asm volatile("s_waitcnt lgkmcnt(" #n ")" ::: "memory")
; #define PG8_BAR __builtin_amdgcn_s_barrier()
; #define PG8_SCHED __builtin_amdgcn_sched_barrier(0)
; template <class Epi>
; DEVINL void gemm_phase(LAS unsigned char* lds, const Gemm g, const Order& S, const Epi& E) {
;     ...
;             PG8_STAGE(PG8_SB(0, 1), b2 + hstepB, voffB);
;             PG8_WAIT_V(6); PG8_BAR; PG8_MMA(1, 1, At, B1); PG8_BAR;
;             PG8_LDB(B0, 1, 0); PG8_SCHED; PG8_LDA(At, 1, 0); PG8_STAGE(PG8_SA(0, 1), a2 + hstepA, voffA);
;             PG8_WAIT_L(8); PG8_BAR; PG8_WAIT_L(0); PG8_MMA(0, 0, At, B0); PG8_BAR; PG8_SCHED;
;             PG8_LDB(B1, 1, 1); PG8_STAGE(PG8_SB(1, 0), b3, voffB);
	s_add_u32 s2, s42, 0x10000
	s_addc_u32 s3, s43, 0
	s_add_i32 s38, s58, s30
	v_lshl_add_u64 v[150:151], s[2:3], 0, v[130:131]
	s_mov_b32 m0, s38
	s_nop 0
	global_load_lds_dwordx4 v[150:151], off
	v_lshl_add_u64 v[150:151], s[2:3], 0, v[134:135]
	s_add_i32 m0, s38, 0x2000
	s_nop 0
	global_load_lds_dwordx4 v[150:151], off
	s_waitcnt vmcnt(6)
	s_barrier
	s_setprio 1
	v_mfma_f32_16x16x32_bf16 v[52:55], v[198:201], v[166:169], v[52:55]
	v_mfma_f32_16x16x32_bf16 v[52:55], v[202:205], v[170:173], v[52:55]
	v_mfma_f32_16x16x32_bf16 v[48:51], v[206:209], v[166:169], v[48:51]
	v_mfma_f32_16x16x32_bf16 v[48:51], v[210:213], v[170:173], v[48:51]
	v_mfma_f32_16x16x32_bf16 v[32:35], v[206:209], v[174:177], v[32:35]
	v_mfma_f32_16x16x32_bf16 v[32:35], v[210:213], v[178:181], v[32:35]
	v_mfma_f32_16x16x32_bf16 v[36:39], v[198:201], v[174:177], v[36:39]
	v_mfma_f32_16x16x32_bf16 v[36:39], v[202:205], v[178:181], v[36:39]
	v_mfma_f32_16x16x32_bf16 v[20:23], v[198:201], v[182:185], v[20:23]
	v_mfma_f32_16x16x32_bf16 v[20:23], v[202:205], v[186:189], v[20:23]
	v_mfma_f32_16x16x32_bf16 v[16:19], v[206:209], v[182:185], v[16:19]
	v_mfma_f32_16x16x32_bf16 v[16:19], v[210:213], v[186:189], v[16:19]
	v_mfma_f32_16x16x32_bf16 v[0:3], v[206:209], v[190:193], v[0:3]
	v_mfma_f32_16x16x32_bf16 v[0:3], v[210:213], v[194:197], v[0:3]
	v_mfma_f32_16x16x32_bf16 v[4:7], v[198:201], v[190:193], v[4:7]
	v_mfma_f32_16x16x32_bf16 v[4:7], v[202:205], v[194:197], v[4:7]
	s_setprio 0
	s_add_i32 s38, 16, 0x18000
	v_add_u32_e32 v162, s38, v145
	s_barrier
	ds_read_b128 v[150:153], v162
	ds_read_b128 v[154:157], v162 offset:1024
	ds_read_b128 v[158:161], v162 offset:2048
	ds_read_b128 v[162:165], v162 offset:3072
	s_add_u32 s2, s44, 0x30000
	s_addc_u32 s3, s45, 0
	s_mov_b32 m0, s47
	v_lshl_add_u64 v[198:199], s[2:3], 0, v[128:129]
	ds_read_b128 v[166:169], v148 offset:32768
	ds_read_b128 v[170:173], v148 offset:33792
	ds_read_b128 v[174:177], v148 offset:34816
	ds_read_b128 v[178:181], v148 offset:35840
	ds_read_b128 v[182:185], v148 offset:36864
	ds_read_b128 v[186:189], v148 offset:37888
	ds_read_b128 v[190:193], v148 offset:38912
	ds_read_b128 v[194:197], v148 offset:39936
	global_load_lds_dwordx4 v[198:199], off
	v_lshl_add_u64 v[198:199], s[2:3], 0, v[132:133]
	s_mov_b32 m0, s48
	s_nop 0
	global_load_lds_dwordx4 v[198:199], off
	s_waitcnt lgkmcnt(8)
	s_barrier
	s_waitcnt lgkmcnt(0)
	s_setprio 1
	s_waitcnt lgkmcnt(0)
	v_mfma_f32_16x16x32_bf16 v[120:123], v[150:153], v[166:169], v[120:123]
	v_mfma_f32_16x16x32_bf16 v[120:123], v[154:157], v[170:173], v[120:123]
	v_mfma_f32_16x16x32_bf16 v[124:127], v[158:161], v[166:169], v[124:127]
	v_mfma_f32_16x16x32_bf16 v[124:127], v[162:165], v[170:173], v[124:127]
	v_mfma_f32_16x16x32_bf16 v[104:107], v[158:161], v[174:177], v[104:107]
	v_mfma_f32_16x16x32_bf16 v[104:107], v[162:165], v[178:181], v[104:107]
	v_mfma_f32_16x16x32_bf16 v[108:111], v[150:153], v[174:177], v[108:111]
	v_mfma_f32_16x16x32_bf16 v[108:111], v[154:157], v[178:181], v[108:111]
	v_mfma_f32_16x16x32_bf16 v[92:95], v[150:153], v[182:185], v[92:95]
	v_mfma_f32_16x16x32_bf16 v[92:95], v[154:157], v[186:189], v[92:95]
	v_mfma_f32_16x16x32_bf16 v[88:91], v[158:161], v[182:185], v[88:91]
	v_mfma_f32_16x16x32_bf16 v[88:91], v[162:165], v[186:189], v[88:91]
	v_mfma_f32_16x16x32_bf16 v[72:75], v[158:161], v[190:193], v[72:75]
	v_mfma_f32_16x16x32_bf16 v[72:75], v[162:165], v[194:197], v[72:75]
	v_mfma_f32_16x16x32_bf16 v[76:79], v[150:153], v[190:193], v[76:79]
	v_mfma_f32_16x16x32_bf16 v[76:79], v[154:157], v[194:197], v[76:79]
	s_setprio 0
	s_barrier
	s_add_i32 s39, 16, 0x1c000
	s_add_i32 s2, s38, s30
	v_add_u32_e32 v210, s39, v145
	v_lshl_add_u64 v[218:219], v[218:219], 0, s[8:9]
	s_mov_b32 m0, s2
	ds_read_b128 v[198:201], v210
	ds_read_b128 v[202:205], v210 offset:1024
	ds_read_b128 v[206:209], v210 offset:2048
	ds_read_b128 v[210:213], v210 offset:3072
	global_load_lds_dwordx4 v[218:219], off
	v_lshl_add_u64 v[218:219], v[220:221], 0, s[8:9]
	s_add_i32 m0, s2, 0x2000
	s_nop 0
	global_load_lds_dwordx4 v[218:219], off
	s_barrier
; #define PG8_STAGE(bufoff, gbase, voff) do { _Pragma("unroll") for (int _i = 0; _i < 2; ++_i) \
;         __builtin_amdgcn_global_load_lds((const unsigned*)((const char*)(gbase) + (voff)[_i]), (LAS unsigned*)(lds + (bufoff) + ldsw + _i * 8192), 16, 0, 0); } while (0)
; #define PG8_LDA(dst, b, h) do { _Pragma("unroll") for (int m = 0; m < 4; ++m) _Pragma("unroll") for (int k = 0; k < 2; ++k) dst[m][k] = *(const LAS bf16x8*)(lds + PG8_SA(b, h) + aoff + m * 2048 + k * 1024); } while (0)
; #define PG8_MMA(ai, bj, At, Bt) do { __builtin_amdgcn_s_setprio(1); _Pragma("unroll") for (int m = 0; m < 4; ++m) _Pragma("unroll") for (int n = 0; n < 2; ++n) _Pragma("unroll") for (int k = 0; k < 2; ++k) \
;         acc[ai][bj][m][n] = __builtin_amdgcn_mfma_f32_16x16x32_bf16(Bt[n][k], At[m][k], acc[ai][bj][m][n], 0, 0, 0); __builtin_amdgcn_s_setprio(0); } while (0)
; #define PG8_WAIT_V(n) asm volatile("s_waitcnt vmcnt(" #n ")" ::: "memory")
; #define PG8_WAIT_L(n) asm volatile("s_waitcnt lgkmcnt(" #n ")" ::: "memory")
; #define PG8_BAR __builtin_amdgcn_s_barrier()
; #define PG8_SCHED __builtin_amdgcn_sched_barrier(0)
; template <class Epi>
; DEVINL void gemm_phase(LAS unsigned char* lds, const Gemm g, const Order& S, const Epi& E) {
;     ...
;             PG8_BAR; PG8_WAIT_L(0); PG8_MMA(0, 1, At, B1); PG8_BAR;
;             PG8_LDA(At, 1, 1); PG8_STAGE(PG8_SA(1, 0), a3, voffA);
;             PG8_BAR; PG8_WAIT_L(0); PG8_MMA(1, 0, At, B0); PG8_BAR; PG8_SCHED;
;             PG8_STAGE(PG8_SB(1, 1), b3 + hstepB, voffB);
;             PG8_WAIT_V(6); PG8_BAR; PG8_MMA(1, 1, At, B1); PG8_BAR;
	s_waitcnt lgkmcnt(0)
	s_setprio 1
	s_waitcnt lgkmcnt(0)
	v_mfma_f32_16x16x32_bf16 v[116:119], v[198:201], v[166:169], v[116:119]
	v_mfma_f32_16x16x32_bf16 v[116:119], v[202:205], v[170:173], v[116:119]
	v_mfma_f32_16x16x32_bf16 v[112:115], v[206:209], v[166:169], v[112:115]
	v_mfma_f32_16x16x32_bf16 v[112:115], v[210:213], v[170:173], v[112:115]
	v_mfma_f32_16x16x32_bf16 v[96:99], v[206:209], v[174:177], v[96:99]
	v_mfma_f32_16x16x32_bf16 v[96:99], v[210:213], v[178:181], v[96:99]
	v_mfma_f32_16x16x32_bf16 v[100:103], v[198:201], v[174:177], v[100:103]
	v_mfma_f32_16x16x32_bf16 v[100:103], v[202:205], v[178:181], v[100:103]
	v_mfma_f32_16x16x32_bf16 v[84:87], v[198:201], v[182:185], v[84:87]
	v_mfma_f32_16x16x32_bf16 v[84:87], v[202:205], v[186:189], v[84:87]
	v_mfma_f32_16x16x32_bf16 v[80:83], v[206:209], v[182:185], v[80:83]
	v_mfma_f32_16x16x32_bf16 v[80:83], v[210:213], v[186:189], v[80:83]
	v_mfma_f32_16x16x32_bf16 v[64:67], v[206:209], v[190:193], v[64:67]
	v_mfma_f32_16x16x32_bf16 v[64:67], v[210:213], v[194:197], v[64:67]
	v_mfma_f32_16x16x32_bf16 v[68:71], v[198:201], v[190:193], v[68:71]
	v_mfma_f32_16x16x32_bf16 v[68:71], v[202:205], v[194:197], v[68:71]
	s_setprio 0
	s_mov_b32 m0, s50
	v_lshl_add_u64 v[218:219], v[222:223], 0, s[8:9]
	s_barrier
	ds_read_b128 v[166:169], v148 offset:49152
	ds_read_b128 v[170:173], v148 offset:50176
	ds_read_b128 v[174:177], v148 offset:51200
	ds_read_b128 v[178:181], v148 offset:52224
	ds_read_b128 v[182:185], v148 offset:53248
	ds_read_b128 v[186:189], v148 offset:54272
	ds_read_b128 v[190:193], v148 offset:55296
	ds_read_b128 v[194:197], v148 offset:56320
	global_load_lds_dwordx4 v[218:219], off
	v_lshl_add_u64 v[218:219], v[224:225], 0, s[8:9]
	s_mov_b32 m0, s51
	s_nop 0
	global_load_lds_dwordx4 v[218:219], off
	s_barrier
	s_waitcnt lgkmcnt(0)
	s_setprio 1
	s_waitcnt lgkmcnt(0)
	v_mfma_f32_16x16x32_bf16 v[60:63], v[150:153], v[166:169], v[60:63]
	v_mfma_f32_16x16x32_bf16 v[60:63], v[154:157], v[170:173], v[60:63]
	v_mfma_f32_16x16x32_bf16 v[56:59], v[158:161], v[166:169], v[56:59]
	v_mfma_f32_16x16x32_bf16 v[56:59], v[162:165], v[170:173], v[56:59]
	v_mfma_f32_16x16x32_bf16 v[40:43], v[158:161], v[174:177], v[40:43]
	v_mfma_f32_16x16x32_bf16 v[40:43], v[162:165], v[178:181], v[40:43]
	v_mfma_f32_16x16x32_bf16 v[44:47], v[150:153], v[174:177], v[44:47]
	v_mfma_f32_16x16x32_bf16 v[44:47], v[154:157], v[178:181], v[44:47]
	v_mfma_f32_16x16x32_bf16 v[28:31], v[150:153], v[182:185], v[28:31]
	v_mfma_f32_16x16x32_bf16 v[28:31], v[154:157], v[186:189], v[28:31]
	v_mfma_f32_16x16x32_bf16 v[24:27], v[158:161], v[182:185], v[24:27]
	v_mfma_f32_16x16x32_bf16 v[24:27], v[162:165], v[186:189], v[24:27]
	v_mfma_f32_16x16x32_bf16 v[8:11], v[158:161], v[190:193], v[8:11]
	v_mfma_f32_16x16x32_bf16 v[8:11], v[162:165], v[194:197], v[8:11]
	v_mfma_f32_16x16x32_bf16 v[12:15], v[150:153], v[190:193], v[12:15]
	v_mfma_f32_16x16x32_bf16 v[12:15], v[154:157], v[194:197], v[12:15]
	s_setprio 0
	s_barrier
	s_add_u32 s2, s42, 0x10080
	s_addc_u32 s3, s43, 0
	s_add_i32 s38, s39, s30
	v_lshl_add_u64 v[150:151], s[2:3], 0, v[130:131]
	s_mov_b32 m0, s38
	s_nop 0
	global_load_lds_dwordx4 v[150:151], off
	v_lshl_add_u64 v[150:151], s[2:3], 0, v[134:135]
	s_add_i32 m0, s38, 0x2000
	s_nop 0
	global_load_lds_dwordx4 v[150:151], off
	s_waitcnt vmcnt(6)
	s_barrier
	s_setprio 1
	v_mfma_f32_16x16x32_bf16 v[52:55], v[198:201], v[166:169], v[52:55]
	v_mfma_f32_16x16x32_bf16 v[52:55], v[202:205], v[170:173], v[52:55]
	v_mfma_f32_16x16x32_bf16 v[48:51], v[206:209], v[166:169], v[48:51]
	v_mfma_f32_16x16x32_bf16 v[48:51], v[210:213], v[170:173], v[48:51]
	v_mfma_f32_16x16x32_bf16 v[32:35], v[206:209], v[174:177], v[32:35]
	v_mfma_f32_16x16x32_bf16 v[32:35], v[210:213], v[178:181], v[32:35]
	v_mfma_f32_16x16x32_bf16 v[36:39], v[198:201], v[174:177], v[36:39]
	v_mfma_f32_16x16x32_bf16 v[36:39], v[202:205], v[178:181], v[36:39]
	v_mfma_f32_16x16x32_bf16 v[20:23], v[198:201], v[182:185], v[20:23]
	v_mfma_f32_16x16x32_bf16 v[20:23], v[202:205], v[186:189], v[20:23]
	v_mfma_f32_16x16x32_bf16 v[16:19], v[206:209], v[182:185], v[16:19]
	v_mfma_f32_16x16x32_bf16 v[16:19], v[210:213], v[186:189], v[16:19]
	v_mfma_f32_16x16x32_bf16 v[0:3], v[206:209], v[190:193], v[0:3]
	v_mfma_f32_16x16x32_bf16 v[0:3], v[210:213], v[194:197], v[0:3]
	v_mfma_f32_16x16x32_bf16 v[4:7], v[198:201], v[190:193], v[4:7]
	v_mfma_f32_16x16x32_bf16 v[4:7], v[202:205], v[194:197], v[4:7]
	s_setprio 0
	s_add_u32 s66, s66, 0x100
	s_addc_u32 s67, s67, 0
	s_cmp_ge_i32 s68, s49
	s_mov_b64 s[38:39], s[4:5]
	s_mov_b32 s42, s68
	s_barrier
	s_cbranch_scc0 .LBB0_825
	s_branch .LBB0_814

; #define PG8_STAGE(bufoff, gbase, voff) do { _Pragma("unroll") for (int _i = 0; _i < 2; ++_i) \
;         __builtin_amdgcn_global_load_lds((const unsigned*)((const char*)(gbase) + (voff)[_i]), (LAS unsigned*)(lds + (bufoff) + ldsw + _i * 8192), 16, 0, 0); } while (0)
; #define PG8_LDA(dst, b, h) do { _Pragma("unroll") for (int m = 0; m < 4; ++m) _Pragma("unroll") for (int k = 0; k < 2; ++k) dst[m][k] = *(const LAS bf16x8*)(lds + PG8_SA(b, h) + aoff + m * 2048 + k * 1024); } while (0)
; #define PG8_LDB(dst, b, h) do { _Pragma("unroll") for (int n = 0; n < 2; ++n) _Pragma("unroll") for (int k = 0; k < 2; ++k) dst[n][k] = *(const LAS bf16x8*)(lds + PG8_SB(b, h) + boff + n * 2048 + k * 1024); } while (0)
; #define PG8_MMA(ai, bj, At, Bt) do { __builtin_amdgcn_s_setprio(1); _Pragma("unroll") for (int m = 0; m < 4; ++m) _Pragma("unroll") for (int n = 0; n < 2; ++n) _Pragma("unroll") for (int k = 0; k < 2; ++k) \
;         acc[ai][bj][m][n] = __builtin_amdgcn_mfma_f32_16x16x32_bf16(Bt[n][k], At[m][k], acc[ai][bj][m][n], 0, 0, 0); __builtin_amdgcn_s_setprio(0); } while (0)
; #define PG8_WAIT_L(n) asm volatile("s_waitcnt lgkmcnt(" #n ")" ::: "memory")
; #define PG8_BAR __builtin_amdgcn_s_barrier()
; #define PG8_SCHED __builtin_amdgcn_sched_barrier(0)
; template <class Epi>
; DEVINL void gemm_phase(LAS unsigned char* lds, const Gemm g, const Order& S, const Epi& E) {
;     ...
;         const char* nA = has_next ? (const char*)g.A + (size_t)nxt.pm * tstepA : cA; const char* nB = has_next ? (const char*)g.Bt + (size_t)nxt.pn * tstepB : cB;
;         for (int t = 0; t < nt; t += 2) {
;             const bool last = (t == nt - 2);
;             const char* a1 = cA + (size_t)(t + 1) * kstep;
;             const char* a2 = last ? nA : cA + (size_t)(t + 2) * kstep; const char* b2 = last ? nB : cB + (size_t)(t + 2) * kstep;
;             const char* a3 = a2 + kstep; const char* b3 = b2 + kstep;
;             PG8_LDB(B0, 0, 0); PG8_SCHED; PG8_LDA(At, 0, 0); PG8_STAGE(PG8_SA(1, 1), a1 + hstepA, voffA);
;             PG8_WAIT_L(8); PG8_BAR; PG8_WAIT_L(0); PG8_MMA(0, 0, At, B0); PG8_BAR; PG8_SCHED;
;             PG8_LDB(B1, 0, 1); PG8_STAGE(PG8_SB(0, 0), b2, voffB);
;             PG8_BAR; PG8_WAIT_L(0); PG8_MMA(0, 1, At, B1); PG8_BAR;
;             PG8_LDA(At, 0, 1); PG8_STAGE(PG8_SA(0, 0), a2, voffA);
;             PG8_BAR; PG8_WAIT_L(0); PG8_MMA(1, 0, At, B0); PG8_BAR; PG8_SCHED;
.LBB0_848:
	ds_read_b128 v[150:153], v147
	ds_read_b128 v[154:157], v147 offset:1024
	ds_read_b128 v[158:161], v147 offset:2048
	ds_read_b128 v[162:165], v147 offset:3072
	s_add_i32 s67, s44, 2
	s_add_u32 s2, s4, 0xffff0080
	s_addc_u32 s3, s5, -1
	s_cmp_eq_u32 s25, s44
	s_cselect_b32 s44, s16, s65
	s_cselect_b32 s47, s13, s3
	s_cselect_b32 s46, s64, s2
	s_cselect_b32 s45, s17, s66
	v_lshl_add_u64 v[198:199], s[4:5], 0, v[136:137]
	s_add_i32 m0, s9, 0xc000
	ds_read_b128 v[166:169], v148
	ds_read_b128 v[170:173], v148 offset:1024
	ds_read_b128 v[174:177], v148 offset:2048
	ds_read_b128 v[178:181], v148 offset:3072
	ds_read_b128 v[182:185], v148 offset:4096
	ds_read_b128 v[186:189], v148 offset:5120
	ds_read_b128 v[190:193], v148 offset:6144
	ds_read_b128 v[194:197], v148 offset:7168
	global_load_lds_dwordx4 v[198:199], off
	v_lshl_add_u64 v[198:199], s[4:5], 0, v[138:139]
	s_add_i32 m0, s9, 0xe000
	s_nop 0
	global_load_lds_dwordx4 v[198:199], off
	s_waitcnt lgkmcnt(8)
	s_barrier
	s_waitcnt lgkmcnt(0)
	s_setprio 1
	s_waitcnt lgkmcnt(0)
	v_mfma_f32_16x16x32_bf16 v[120:123], v[150:153], v[166:169], v[120:123]
	v_mfma_f32_16x16x32_bf16 v[120:123], v[154:157], v[170:173], v[120:123]
	v_mfma_f32_16x16x32_bf16 v[124:127], v[158:161], v[166:169], v[124:127]
	v_mfma_f32_16x16x32_bf16 v[124:127], v[162:165], v[170:173], v[124:127]
	v_mfma_f32_16x16x32_bf16 v[104:107], v[158:161], v[174:177], v[104:107]
	v_mfma_f32_16x16x32_bf16 v[104:107], v[162:165], v[178:181], v[104:107]
	v_mfma_f32_16x16x32_bf16 v[108:111], v[150:153], v[174:177], v[108:111]
	v_mfma_f32_16x16x32_bf16 v[108:111], v[154:157], v[178:181], v[108:111]
	v_mfma_f32_16x16x32_bf16 v[92:95], v[150:153], v[182:185], v[92:95]
	v_mfma_f32_16x16x32_bf16 v[92:95], v[154:157], v[186:189], v[92:95]
	v_mfma_f32_16x16x32_bf16 v[88:91], v[158:161], v[182:185], v[88:91]
	v_mfma_f32_16x16x32_bf16 v[88:91], v[162:165], v[186:189], v[88:91]
	v_mfma_f32_16x16x32_bf16 v[72:75], v[158:161], v[190:193], v[72:75]
	v_mfma_f32_16x16x32_bf16 v[72:75], v[162:165], v[194:197], v[72:75]
	v_mfma_f32_16x16x32_bf16 v[76:79], v[150:153], v[190:193], v[76:79]
	v_mfma_f32_16x16x32_bf16 v[76:79], v[154:157], v[194:197], v[76:79]
	s_setprio 0
	s_barrier
	s_add_i32 s2, s56, s30
	v_lshl_add_u64 v[218:219], s[44:45], 0, v[130:131]
	s_mov_b32 m0, s2
	ds_read_b128 v[198:201], v149
	ds_read_b128 v[202:205], v149 offset:1024
	ds_read_b128 v[206:209], v149 offset:2048
	ds_read_b128 v[210:213], v149 offset:3072
	global_load_lds_dwordx4 v[218:219], off
	v_lshl_add_u64 v[220:221], s[44:45], 0, v[134:135]
	s_add_i32 m0, s2, 0x2000
	s_nop 0
	global_load_lds_dwordx4 v[220:221], off
	s_barrier
	s_waitcnt lgkmcnt(0)
	s_setprio 1
	s_waitcnt lgkmcnt(0)
	v_mfma_f32_16x16x32_bf16 v[116:119], v[198:201], v[166:169], v[116:119]
	v_mfma_f32_16x16x32_bf16 v[116:119], v[202:205], v[170:173], v[116:119]
	v_mfma_f32_16x16x32_bf16 v[112:115], v[206:209], v[166:169], v[112:115]
	v_mfma_f32_16x16x32_bf16 v[112:115], v[210:213], v[170:173], v[112:115]
	v_mfma_f32_16x16x32_bf16 v[96:99], v[206:209], v[174:177], v[96:99]
	v_mfma_f32_16x16x32_bf16 v[96:99], v[210:213], v[178:181], v[96:99]
	v_mfma_f32_16x16x32_bf16 v[100:103], v[198:201], v[174:177], v[100:103]
	v_mfma_f32_16x16x32_bf16 v[100:103], v[202:205], v[178:181], v[100:103]
	v_mfma_f32_16x16x32_bf16 v[84:87], v[198:201], v[182:185], v[84:87]
	v_mfma_f32_16x16x32_bf16 v[84:87], v[202:205], v[186:189], v[84:87]
	v_mfma_f32_16x16x32_bf16 v[80:83], v[206:209], v[182:185], v[80:83]
	v_mfma_f32_16x16x32_bf16 v[80:83], v[210:213], v[186:189], v[80:83]
	v_mfma_f32_16x16x32_bf16 v[64:67], v[206:209], v[190:193], v[64:67]
	v_mfma_f32_16x16x32_bf16 v[64:67], v[210:213], v[194:197], v[64:67]
	v_mfma_f32_16x16x32_bf16 v[68:71], v[198:201], v[190:193], v[68:71]
	v_mfma_f32_16x16x32_bf16 v[68:71], v[202:205], v[194:197], v[68:71]
	s_setprio 0
	s_mov_b32 m0, s9
	v_lshl_add_u64 v[222:223], s[46:47], 0, v[128:129]
	s_barrier
	ds_read_b128 v[166:169], v148 offset:16384
	ds_read_b128 v[170:173], v148 offset:17408
	ds_read_b128 v[174:177], v148 offset:18432
	ds_read_b128 v[178:181], v148 offset:19456
	ds_read_b128 v[182:185], v148 offset:20480
	ds_read_b128 v[186:189], v148 offset:21504
	ds_read_b128 v[190:193], v148 offset:22528
	ds_read_b128 v[194:197], v148 offset:23552
	global_load_lds_dwordx4 v[222:223], off
	v_lshl_add_u64 v[224:225], s[46:47], 0, v[132:133]
	s_mov_b32 m0, s31
	s_nop 0
	global_load_lds_dwordx4 v[224:225], off
	s_barrier
	s_waitcnt lgkmcnt(0)
	s_setprio 1
	s_waitcnt lgkmcnt(0)
	v_mfma_f32_16x16x32_bf16 v[60:63], v[150:153], v[166:169], v[60:63]
	v_mfma_f32_16x16x32_bf16 v[60:63], v[154:157], v[170:173], v[60:63]
	v_mfma_f32_16x16x32_bf16 v[56:59], v[158:161], v[166:169], v[56:59]
	v_mfma_f32_16x16x32_bf16 v[56:59], v[162:165], v[170:173], v[56:59]
	v_mfma_f32_16x16x32_bf16 v[40:43], v[158:161], v[174:177], v[40:43]
	v_mfma_f32_16x16x32_bf16 v[40:43], v[162:165], v[178:181], v[40:43]
	v_mfma_f32_16x16x32_bf16 v[44:47], v[150:153], v[174:177], v[44:47]
	v_mfma_f32_16x16x32_bf16 v[44:47], v[154:157], v[178:181], v[44:47]
	v_mfma_f32_16x16x32_bf16 v[28:31], v[150:153], v[182:185], v[28:31]
	v_mfma_f32_16x16x32_bf16 v[28:31], v[154:157], v[186:189], v[28:31]
	v_mfma_f32_16x16x32_bf16 v[24:27], v[158:161], v[182:185], v[24:27]
	v_mfma_f32_16x16x32_bf16 v[24:27], v[162:165], v[186:189], v[24:27]
	v_mfma_f32_16x16x32_bf16 v[8:11], v[158:161], v[190:193], v[8:11]
	v_mfma_f32_16x16x32_bf16 v[8:11], v[162:165], v[194:197], v[8:11]
	v_mfma_f32_16x16x32_bf16 v[12:15], v[150:153], v[190:193], v[12:15]
	v_mfma_f32_16x16x32_bf16 v[12:15], v[154:157], v[194:197], v[12:15]
	s_setprio 0
	s_barrier
; #define PG8_STAGE(bufoff, gbase, voff) do { _Pragma("unroll") for (int _i = 0; _i < 2; ++_i) \
;         __builtin_amdgcn_global_load_lds((const unsigned*)((const char*)(gbase) + (voff)[_i]), (LAS unsigned*)(lds + (bufoff) + ldsw + _i * 8192), 16, 0, 0); } while (0)
; #define PG8_LDA(dst, b, h) do { _Pragma("unroll") for (int m = 0; m < 4; ++m) _Pragma("unroll") for (int k = 0; k < 2; ++k) dst[m][k] = *(const LAS bf16x8*)(lds + PG8_SA(b, h) + aoff + m * 2048 + k * 1024); } while (0)
; #define PG8_LDB(dst, b, h) do { _Pragma("unroll") for (int n = 0; n < 2; ++n) _Pragma("unroll") for (int k = 0; k < 2; ++k) dst[n][k] = *(const LAS bf16x8*)(lds + PG8_SB(b, h) + boff + n * 2048 + k * 1024); } while (0)
; #define PG8_MMA(ai, bj, At, Bt) do { __builtin_amdgcn_s_setprio(1); _Pragma("unroll") for (int m = 0; m < 4; ++m) _Pragma("unroll") for (int n = 0; n < 2; ++n) _Pragma("unroll") for (int k = 0; k < 2; ++k) \
;         acc[ai][bj][m][n] = __builtin_amdgcn_mfma_f32_16x16x32_bf16(Bt[n][k], At[m][k], acc[ai][bj][m][n], 0, 0, 0); __builtin_amdgcn_s_setprio(0); } while (0)
; #define PG8_WAIT_V(n) asm volatile("s_waitcnt vmcnt(" #n ")" ::: "memory")
; #define PG8_WAIT_L(n) asm volatile("s_waitcnt lgkmcnt(" #n ")" ::: "memory")
; #define PG8_BAR __builtin_amdgcn_s_barrier()
; #define PG8_SCHED __builtin_amdgcn_sched_barrier(0)
; template <class Epi>
; DEVINL void gemm_phase(LAS unsigned char* lds, const Gemm g, const Order& S, const Epi& E) {
;     ...
;             PG8_STAGE(PG8_SB(0, 1), b2 + hstepB, voffB);
;             PG8_WAIT_V(6); PG8_BAR; PG8_MMA(1, 1, At, B1); PG8_BAR;
;             PG8_LDB(B0, 1, 0); PG8_SCHED; PG8_LDA(At, 1, 0); PG8_STAGE(PG8_SA(0, 1), a2 + hstepA, voffA);
;             PG8_WAIT_L(8); PG8_BAR; PG8_WAIT_L(0); PG8_MMA(0, 0, At, B0); PG8_BAR; PG8_SCHED;
;             PG8_LDB(B1, 1, 1); PG8_STAGE(PG8_SB(1, 0), b3, voffB);
	s_add_u32 s2, s44, 0x30000
	s_addc_u32 s3, s45, 0
	s_add_i32 s68, s57, s30
	v_lshl_add_u64 v[150:151], s[2:3], 0, v[130:131]
	s_mov_b32 m0, s68
	s_nop 0
	global_load_lds_dwordx4 v[150:151], off
	v_lshl_add_u64 v[150:151], s[2:3], 0, v[134:135]
	s_add_i32 m0, s68, 0x2000
	s_nop 0
	global_load_lds_dwordx4 v[150:151], off
	s_waitcnt vmcnt(6)
	s_barrier
	s_setprio 1
	v_mfma_f32_16x16x32_bf16 v[52:55], v[198:201], v[166:169], v[52:55]
	v_mfma_f32_16x16x32_bf16 v[52:55], v[202:205], v[170:173], v[52:55]
	v_mfma_f32_16x16x32_bf16 v[48:51], v[206:209], v[166:169], v[48:51]
	v_mfma_f32_16x16x32_bf16 v[48:51], v[210:213], v[170:173], v[48:51]
	v_mfma_f32_16x16x32_bf16 v[32:35], v[206:209], v[174:177], v[32:35]
	v_mfma_f32_16x16x32_bf16 v[32:35], v[210:213], v[178:181], v[32:35]
	v_mfma_f32_16x16x32_bf16 v[36:39], v[198:201], v[174:177], v[36:39]
	v_mfma_f32_16x16x32_bf16 v[36:39], v[202:205], v[178:181], v[36:39]
	v_mfma_f32_16x16x32_bf16 v[20:23], v[198:201], v[182:185], v[20:23]
	v_mfma_f32_16x16x32_bf16 v[20:23], v[202:205], v[186:189], v[20:23]
	v_mfma_f32_16x16x32_bf16 v[16:19], v[206:209], v[182:185], v[16:19]
	v_mfma_f32_16x16x32_bf16 v[16:19], v[210:213], v[186:189], v[16:19]
	v_mfma_f32_16x16x32_bf16 v[0:3], v[206:209], v[190:193], v[0:3]
	v_mfma_f32_16x16x32_bf16 v[0:3], v[210:213], v[194:197], v[0:3]
	v_mfma_f32_16x16x32_bf16 v[4:7], v[198:201], v[190:193], v[4:7]
	v_mfma_f32_16x16x32_bf16 v[4:7], v[202:205], v[194:197], v[4:7]
	s_setprio 0
	s_add_i32 s68, 16, 0x18000
	v_add_u32_e32 v162, s68, v145
	s_barrier
	ds_read_b128 v[150:153], v162
	ds_read_b128 v[154:157], v162 offset:1024
	ds_read_b128 v[158:161], v162 offset:2048
	ds_read_b128 v[162:165], v162 offset:3072
	s_add_u32 s2, s46, 0x10000
	s_addc_u32 s3, s47, 0
	s_mov_b32 m0, s48
	v_lshl_add_u64 v[198:199], s[2:3], 0, v[128:129]
	ds_read_b128 v[166:169], v148 offset:32768
	ds_read_b128 v[170:173], v148 offset:33792
	ds_read_b128 v[174:177], v148 offset:34816
	ds_read_b128 v[178:181], v148 offset:35840
	ds_read_b128 v[182:185], v148 offset:36864
	ds_read_b128 v[186:189], v148 offset:37888
	ds_read_b128 v[190:193], v148 offset:38912
	ds_read_b128 v[194:197], v148 offset:39936
	global_load_lds_dwordx4 v[198:199], off
	v_lshl_add_u64 v[198:199], s[2:3], 0, v[132:133]
	s_mov_b32 m0, s49
	s_nop 0
	global_load_lds_dwordx4 v[198:199], off
	s_waitcnt lgkmcnt(8)
	s_barrier
	s_waitcnt lgkmcnt(0)
	s_setprio 1
	s_waitcnt lgkmcnt(0)
	v_mfma_f32_16x16x32_bf16 v[120:123], v[150:153], v[166:169], v[120:123]
	v_mfma_f32_16x16x32_bf16 v[120:123], v[154:157], v[170:173], v[120:123]
	v_mfma_f32_16x16x32_bf16 v[124:127], v[158:161], v[166:169], v[124:127]
	v_mfma_f32_16x16x32_bf16 v[124:127], v[162:165], v[170:173], v[124:127]
	v_mfma_f32_16x16x32_bf16 v[104:107], v[158:161], v[174:177], v[104:107]
	v_mfma_f32_16x16x32_bf16 v[104:107], v[162:165], v[178:181], v[104:107]
	v_mfma_f32_16x16x32_bf16 v[108:111], v[150:153], v[174:177], v[108:111]
	v_mfma_f32_16x16x32_bf16 v[108:111], v[154:157], v[178:181], v[108:111]
	v_mfma_f32_16x16x32_bf16 v[92:95], v[150:153], v[182:185], v[92:95]
	v_mfma_f32_16x16x32_bf16 v[92:95], v[154:157], v[186:189], v[92:95]
	v_mfma_f32_16x16x32_bf16 v[88:91], v[158:161], v[182:185], v[88:91]
	v_mfma_f32_16x16x32_bf16 v[88:91], v[162:165], v[186:189], v[88:91]
	v_mfma_f32_16x16x32_bf16 v[72:75], v[158:161], v[190:193], v[72:75]
	v_mfma_f32_16x16x32_bf16 v[72:75], v[162:165], v[194:197], v[72:75]
	v_mfma_f32_16x16x32_bf16 v[76:79], v[150:153], v[190:193], v[76:79]
	v_mfma_f32_16x16x32_bf16 v[76:79], v[154:157], v[194:197], v[76:79]
	s_setprio 0
	s_barrier
	s_add_i32 s46, 16, 0x1c000
	s_add_i32 s2, s68, s30
	v_add_u32_e32 v210, s46, v145
	v_lshl_add_u64 v[218:219], v[218:219], 0, s[6:7]
	s_mov_b32 m0, s2
	ds_read_b128 v[198:201], v210
	ds_read_b128 v[202:205], v210 offset:1024
	ds_read_b128 v[206:209], v210 offset:2048
	ds_read_b128 v[210:213], v210 offset:3072
	global_load_lds_dwordx4 v[218:219], off
	v_lshl_add_u64 v[218:219], v[220:221], 0, s[6:7]
	s_add_i32 m0, s2, 0x2000
	s_nop 0
	global_load_lds_dwordx4 v[218:219], off
	s_barrier
; #define PG8_STAGE(bufoff, gbase, voff) do { _Pragma("unroll") for (int _i = 0; _i < 2; ++_i) \
;         __builtin_amdgcn_global_load_lds((const unsigned*)((const char*)(gbase) + (voff)[_i]), (LAS unsigned*)(lds + (bufoff) + ldsw + _i * 8192), 16, 0, 0); } while (0)
; #define PG8_LDA(dst, b, h) do { _Pragma("unroll") for (int m = 0; m < 4; ++m) _Pragma("unroll") for (int k = 0; k < 2; ++k) dst[m][k] = *(const LAS bf16x8*)(lds + PG8_SA(b, h) + aoff + m * 2048 + k * 1024); } while (0)
; #define PG8_MMA(ai, bj, At, Bt) do { __builtin_amdgcn_s_setprio(1); _Pragma("unroll") for (int m = 0; m < 4; ++m) _Pragma("unroll") for (int n = 0; n < 2; ++n) _Pragma("unroll") for (int k = 0; k < 2; ++k) \
;         acc[ai][bj][m][n] = __builtin_amdgcn_mfma_f32_16x16x32_bf16(Bt[n][k], At[m][k], acc[ai][bj][m][n], 0, 0, 0); __builtin_amdgcn_s_setprio(0); } while (0)
; #define PG8_WAIT_V(n) asm volatile("s_waitcnt vmcnt(" #n ")" ::: "memory")
; #define PG8_WAIT_L(n) asm volatile("s_waitcnt lgkmcnt(" #n ")" ::: "memory")
; #define PG8_BAR __builtin_amdgcn_s_barrier()
; #define PG8_SCHED __builtin_amdgcn_sched_barrier(0)
; template <class Epi>
; DEVINL void gemm_phase(LAS unsigned char* lds, const Gemm g, const Order& S, const Epi& E) {
;     ...
;             PG8_BAR; PG8_WAIT_L(0); PG8_MMA(0, 1, At, B1); PG8_BAR;
;             PG8_LDA(At, 1, 1); PG8_STAGE(PG8_SA(1, 0), a3, voffA);
;             PG8_BAR; PG8_WAIT_L(0); PG8_MMA(1, 0, At, B0); PG8_BAR; PG8_SCHED;
;             PG8_STAGE(PG8_SB(1, 1), b3 + hstepB, voffB);
;             PG8_WAIT_V(6); PG8_BAR; PG8_MMA(1, 1, At, B1); PG8_BAR;
	s_waitcnt lgkmcnt(0)
	s_setprio 1
	s_waitcnt lgkmcnt(0)
	v_mfma_f32_16x16x32_bf16 v[116:119], v[198:201], v[166:169], v[116:119]
	v_mfma_f32_16x16x32_bf16 v[116:119], v[202:205], v[170:173], v[116:119]
	v_mfma_f32_16x16x32_bf16 v[112:115], v[206:209], v[166:169], v[112:115]
	v_mfma_f32_16x16x32_bf16 v[112:115], v[210:213], v[170:173], v[112:115]
	v_mfma_f32_16x16x32_bf16 v[96:99], v[206:209], v[174:177], v[96:99]
	v_mfma_f32_16x16x32_bf16 v[96:99], v[210:213], v[178:181], v[96:99]
	v_mfma_f32_16x16x32_bf16 v[100:103], v[198:201], v[174:177], v[100:103]
	v_mfma_f32_16x16x32_bf16 v[100:103], v[202:205], v[178:181], v[100:103]
	v_mfma_f32_16x16x32_bf16 v[84:87], v[198:201], v[182:185], v[84:87]
	v_mfma_f32_16x16x32_bf16 v[84:87], v[202:205], v[186:189], v[84:87]
	v_mfma_f32_16x16x32_bf16 v[80:83], v[206:209], v[182:185], v[80:83]
	v_mfma_f32_16x16x32_bf16 v[80:83], v[210:213], v[186:189], v[80:83]
	v_mfma_f32_16x16x32_bf16 v[64:67], v[206:209], v[190:193], v[64:67]
	v_mfma_f32_16x16x32_bf16 v[64:67], v[210:213], v[194:197], v[64:67]
	v_mfma_f32_16x16x32_bf16 v[68:71], v[198:201], v[190:193], v[68:71]
	v_mfma_f32_16x16x32_bf16 v[68:71], v[202:205], v[194:197], v[68:71]
	s_setprio 0
	s_mov_b32 m0, s52
	v_lshl_add_u64 v[218:219], v[222:223], 0, s[6:7]
	s_barrier
	ds_read_b128 v[166:169], v148 offset:49152
	ds_read_b128 v[170:173], v148 offset:50176
	ds_read_b128 v[174:177], v148 offset:51200
	ds_read_b128 v[178:181], v148 offset:52224
	ds_read_b128 v[182:185], v148 offset:53248
	ds_read_b128 v[186:189], v148 offset:54272
	ds_read_b128 v[190:193], v148 offset:55296
	ds_read_b128 v[194:197], v148 offset:56320
	global_load_lds_dwordx4 v[218:219], off
	v_lshl_add_u64 v[218:219], v[224:225], 0, s[6:7]
	s_mov_b32 m0, s53
	s_nop 0
	global_load_lds_dwordx4 v[218:219], off
	s_barrier
	s_waitcnt lgkmcnt(0)
	s_setprio 1
	s_waitcnt lgkmcnt(0)
	v_mfma_f32_16x16x32_bf16 v[60:63], v[150:153], v[166:169], v[60:63]
	v_mfma_f32_16x16x32_bf16 v[60:63], v[154:157], v[170:173], v[60:63]
	v_mfma_f32_16x16x32_bf16 v[56:59], v[158:161], v[166:169], v[56:59]
	v_mfma_f32_16x16x32_bf16 v[56:59], v[162:165], v[170:173], v[56:59]
	v_mfma_f32_16x16x32_bf16 v[40:43], v[158:161], v[174:177], v[40:43]
	v_mfma_f32_16x16x32_bf16 v[40:43], v[162:165], v[178:181], v[40:43]
	v_mfma_f32_16x16x32_bf16 v[44:47], v[150:153], v[174:177], v[44:47]
	v_mfma_f32_16x16x32_bf16 v[44:47], v[154:157], v[178:181], v[44:47]
	v_mfma_f32_16x16x32_bf16 v[28:31], v[150:153], v[182:185], v[28:31]
	v_mfma_f32_16x16x32_bf16 v[28:31], v[154:157], v[186:189], v[28:31]
	v_mfma_f32_16x16x32_bf16 v[24:27], v[158:161], v[182:185], v[24:27]
	v_mfma_f32_16x16x32_bf16 v[24:27], v[162:165], v[186:189], v[24:27]
	v_mfma_f32_16x16x32_bf16 v[8:11], v[158:161], v[190:193], v[8:11]
	v_mfma_f32_16x16x32_bf16 v[8:11], v[162:165], v[194:197], v[8:11]
	v_mfma_f32_16x16x32_bf16 v[12:15], v[150:153], v[190:193], v[12:15]
	v_mfma_f32_16x16x32_bf16 v[12:15], v[154:157], v[194:197], v[12:15]
	s_setprio 0
	s_barrier
	s_add_u32 s2, s44, 0x30080
	s_addc_u32 s3, s45, 0
	s_add_i32 s44, s46, s30
	v_lshl_add_u64 v[150:151], s[2:3], 0, v[130:131]
	s_mov_b32 m0, s44
	s_nop 0
	global_load_lds_dwordx4 v[150:151], off
	v_lshl_add_u64 v[150:151], s[2:3], 0, v[134:135]
	s_add_i32 m0, s44, 0x2000
	s_nop 0
	global_load_lds_dwordx4 v[150:151], off
	s_waitcnt vmcnt(6)
	s_barrier
	s_setprio 1
	v_mfma_f32_16x16x32_bf16 v[52:55], v[198:201], v[166:169], v[52:55]
	v_mfma_f32_16x16x32_bf16 v[52:55], v[202:205], v[170:173], v[52:55]
	v_mfma_f32_16x16x32_bf16 v[48:51], v[206:209], v[166:169], v[48:51]
	v_mfma_f32_16x16x32_bf16 v[48:51], v[210:213], v[170:173], v[48:51]
	v_mfma_f32_16x16x32_bf16 v[32:35], v[206:209], v[174:177], v[32:35]
	v_mfma_f32_16x16x32_bf16 v[32:35], v[210:213], v[178:181], v[32:35]
	v_mfma_f32_16x16x32_bf16 v[36:39], v[198:201], v[174:177], v[36:39]
	v_mfma_f32_16x16x32_bf16 v[36:39], v[202:205], v[178:181], v[36:39]
	v_mfma_f32_16x16x32_bf16 v[20:23], v[198:201], v[182:185], v[20:23]
	v_mfma_f32_16x16x32_bf16 v[20:23], v[202:205], v[186:189], v[20:23]
	v_mfma_f32_16x16x32_bf16 v[16:19], v[206:209], v[182:185], v[16:19]
	v_mfma_f32_16x16x32_bf16 v[16:19], v[210:213], v[186:189], v[16:19]
	v_mfma_f32_16x16x32_bf16 v[0:3], v[206:209], v[190:193], v[0:3]
	v_mfma_f32_16x16x32_bf16 v[0:3], v[210:213], v[194:197], v[0:3]
	v_mfma_f32_16x16x32_bf16 v[4:7], v[198:201], v[190:193], v[4:7]
	v_mfma_f32_16x16x32_bf16 v[4:7], v[202:205], v[194:197], v[4:7]
	s_setprio 0
	s_add_u32 s4, s4, 0x100
	s_addc_u32 s5, s5, 0
	s_add_u32 s65, s65, 0x100
	s_addc_u32 s66, s66, 0
	s_cmp_ge_i32 s67, s51
	s_mov_b32 s44, s67
	s_barrier
	s_cbranch_scc0 .LBB0_848
	s_branch .LBB0_837

; #define PG8_STAGE(bufoff, gbase, voff) do { _Pragma("unroll") for (int _i = 0; _i < 2; ++_i) \
;         __builtin_amdgcn_global_load_lds((const unsigned*)((const char*)(gbase) + (voff)[_i]), (LAS unsigned*)(lds + (bufoff) + ldsw + _i * 8192), 16, 0, 0); } while (0)
; #define PG8_LDA(dst, b, h) do { _Pragma("unroll") for (int m = 0; m < 4; ++m) _Pragma("unroll") for (int k = 0; k < 2; ++k) dst[m][k] = *(const LAS bf16x8*)(lds + PG8_SA(b, h) + aoff + m * 2048 + k * 1024); } while (0)
; #define PG8_LDB(dst, b, h) do { _Pragma("unroll") for (int n = 0; n < 2; ++n) _Pragma("unroll") for (int k = 0; k < 2; ++k) dst[n][k] = *(const LAS bf16x8*)(lds + PG8_SB(b, h) + boff + n * 2048 + k * 1024); } while (0)
; #define PG8_MMA(ai, bj, At, Bt) do { __builtin_amdgcn_s_setprio(1); _Pragma("unroll") for (int m = 0; m < 4; ++m) _Pragma("unroll") for (int n = 0; n < 2; ++n) _Pragma("unroll") for (int k = 0; k < 2; ++k) \
;         acc[ai][bj][m][n] = __builtin_amdgcn_mfma_f32_16x16x32_bf16(Bt[n][k], At[m][k], acc[ai][bj][m][n], 0, 0, 0); __builtin_amdgcn_s_setprio(0); } while (0)
; #define PG8_WAIT_L(n) asm volatile("s_waitcnt lgkmcnt(" #n ")" ::: "memory")
; #define PG8_BAR __builtin_amdgcn_s_barrier()
; #define PG8_SCHED __builtin_amdgcn_sched_barrier(0)
; template <class Epi>
; DEVINL void gemm_phase(LAS unsigned char* lds, const Gemm g, const Order& S, const Epi& E) {
;     ...
;         const char* nA = has_next ? (const char*)g.A + (size_t)nxt.pm * tstepA : cA; const char* nB = has_next ? (const char*)g.Bt + (size_t)nxt.pn * tstepB : cB;
;         for (int t = 0; t < nt; t += 2) {
;             const bool last = (t == nt - 2);
;             const char* a1 = cA + (size_t)(t + 1) * kstep;
;             const char* a2 = last ? nA : cA + (size_t)(t + 2) * kstep; const char* b2 = last ? nB : cB + (size_t)(t + 2) * kstep;
;             const char* a3 = a2 + kstep; const char* b3 = b2 + kstep;
;             PG8_LDB(B0, 0, 0); PG8_SCHED; PG8_LDA(At, 0, 0); PG8_STAGE(PG8_SA(1, 1), a1 + hstepA, voffA);
;             PG8_WAIT_L(8); PG8_BAR; PG8_WAIT_L(0); PG8_MMA(0, 0, At, B0); PG8_BAR; PG8_SCHED;
;             PG8_LDB(B1, 0, 1); PG8_STAGE(PG8_SB(0, 0), b2, voffB);
;             PG8_BAR; PG8_WAIT_L(0); PG8_MMA(0, 1, At, B1); PG8_BAR;
;             PG8_LDA(At, 0, 1); PG8_STAGE(PG8_SA(0, 0), a2, voffA);
;             PG8_BAR; PG8_WAIT_L(0); PG8_MMA(1, 0, At, B0); PG8_BAR; PG8_SCHED;
.LBB0_986:
	ds_read_b128 v[150:153], v147
	ds_read_b128 v[154:157], v147 offset:1024
	ds_read_b128 v[158:161], v147 offset:2048
	ds_read_b128 v[162:165], v147 offset:3072
	s_add_i32 s69, s46, 2
	s_add_u32 s2, s4, 0xffff0080
	s_addc_u32 s3, s5, -1
	s_cmp_eq_u32 s54, s46
	s_cselect_b32 s46, s66, s67
	s_cselect_b32 s49, s11, s3
	s_cselect_b32 s48, s13, s2
	s_cselect_b32 s47, s65, s68
	v_lshl_add_u64 v[198:199], s[4:5], 0, v[136:137]
	s_add_i32 m0, s30, 0xc000
	ds_read_b128 v[166:169], v148
	ds_read_b128 v[170:173], v148 offset:1024
	ds_read_b128 v[174:177], v148 offset:2048
	ds_read_b128 v[178:181], v148 offset:3072
	ds_read_b128 v[182:185], v148 offset:4096
	ds_read_b128 v[186:189], v148 offset:5120
	ds_read_b128 v[190:193], v148 offset:6144
	ds_read_b128 v[194:197], v148 offset:7168
	global_load_lds_dwordx4 v[198:199], off
	v_lshl_add_u64 v[198:199], s[4:5], 0, v[138:139]
	s_add_i32 m0, s30, 0xe000
	s_nop 0
	global_load_lds_dwordx4 v[198:199], off
	s_waitcnt lgkmcnt(8)
	s_barrier
	s_waitcnt lgkmcnt(0)
	s_setprio 1
	s_waitcnt lgkmcnt(0)
	v_mfma_f32_16x16x32_bf16 v[124:127], v[150:153], v[166:169], v[124:127]
	v_mfma_f32_16x16x32_bf16 v[124:127], v[154:157], v[170:173], v[124:127]
	v_mfma_f32_16x16x32_bf16 v[120:123], v[158:161], v[166:169], v[120:123]
	v_mfma_f32_16x16x32_bf16 v[120:123], v[162:165], v[170:173], v[120:123]
	v_mfma_f32_16x16x32_bf16 v[112:115], v[158:161], v[174:177], v[112:115]
	v_mfma_f32_16x16x32_bf16 v[112:115], v[162:165], v[178:181], v[112:115]
	v_mfma_f32_16x16x32_bf16 v[116:119], v[150:153], v[174:177], v[116:119]
	v_mfma_f32_16x16x32_bf16 v[116:119], v[154:157], v[178:181], v[116:119]
	v_mfma_f32_16x16x32_bf16 v[108:111], v[150:153], v[182:185], v[108:111]
	v_mfma_f32_16x16x32_bf16 v[108:111], v[154:157], v[186:189], v[108:111]
	v_mfma_f32_16x16x32_bf16 v[104:107], v[158:161], v[182:185], v[104:107]
	v_mfma_f32_16x16x32_bf16 v[104:107], v[162:165], v[186:189], v[104:107]
	v_mfma_f32_16x16x32_bf16 v[96:99], v[158:161], v[190:193], v[96:99]
	v_mfma_f32_16x16x32_bf16 v[96:99], v[162:165], v[194:197], v[96:99]
	v_mfma_f32_16x16x32_bf16 v[100:103], v[150:153], v[190:193], v[100:103]
	v_mfma_f32_16x16x32_bf16 v[100:103], v[154:157], v[194:197], v[100:103]
	s_setprio 0
	s_barrier
	s_add_i32 s2, s58, s29
	v_lshl_add_u64 v[218:219], s[46:47], 0, v[130:131]
	s_mov_b32 m0, s2
	ds_read_b128 v[198:201], v149
	ds_read_b128 v[202:205], v149 offset:1024
	ds_read_b128 v[206:209], v149 offset:2048
	ds_read_b128 v[210:213], v149 offset:3072
	global_load_lds_dwordx4 v[218:219], off
	v_lshl_add_u64 v[220:221], s[46:47], 0, v[134:135]
	s_add_i32 m0, s2, 0x2000
	s_nop 0
	global_load_lds_dwordx4 v[220:221], off
	s_barrier
	s_waitcnt lgkmcnt(0)
	s_setprio 1
	s_waitcnt lgkmcnt(0)
	v_mfma_f32_16x16x32_bf16 v[60:63], v[198:201], v[166:169], v[60:63]
	v_mfma_f32_16x16x32_bf16 v[60:63], v[202:205], v[170:173], v[60:63]
	v_mfma_f32_16x16x32_bf16 v[56:59], v[206:209], v[166:169], v[56:59]
	v_mfma_f32_16x16x32_bf16 v[56:59], v[210:213], v[170:173], v[56:59]
	v_mfma_f32_16x16x32_bf16 v[48:51], v[206:209], v[174:177], v[48:51]
	v_mfma_f32_16x16x32_bf16 v[48:51], v[210:213], v[178:181], v[48:51]
	v_mfma_f32_16x16x32_bf16 v[52:55], v[198:201], v[174:177], v[52:55]
	v_mfma_f32_16x16x32_bf16 v[52:55], v[202:205], v[178:181], v[52:55]
	v_mfma_f32_16x16x32_bf16 v[44:47], v[198:201], v[182:185], v[44:47]
	v_mfma_f32_16x16x32_bf16 v[44:47], v[202:205], v[186:189], v[44:47]
	v_mfma_f32_16x16x32_bf16 v[40:43], v[206:209], v[182:185], v[40:43]
	v_mfma_f32_16x16x32_bf16 v[40:43], v[210:213], v[186:189], v[40:43]
	v_mfma_f32_16x16x32_bf16 v[32:35], v[206:209], v[190:193], v[32:35]
	v_mfma_f32_16x16x32_bf16 v[32:35], v[210:213], v[194:197], v[32:35]
	v_mfma_f32_16x16x32_bf16 v[36:39], v[198:201], v[190:193], v[36:39]
	v_mfma_f32_16x16x32_bf16 v[36:39], v[202:205], v[194:197], v[36:39]
	s_setprio 0
	s_mov_b32 m0, s30
	v_lshl_add_u64 v[222:223], s[48:49], 0, v[128:129]
	s_barrier
	ds_read_b128 v[166:169], v148 offset:16384
	ds_read_b128 v[170:173], v148 offset:17408
	ds_read_b128 v[174:177], v148 offset:18432
	ds_read_b128 v[178:181], v148 offset:19456
	ds_read_b128 v[182:185], v148 offset:20480
	ds_read_b128 v[186:189], v148 offset:21504
	ds_read_b128 v[190:193], v148 offset:22528
	ds_read_b128 v[194:197], v148 offset:23552
	global_load_lds_dwordx4 v[222:223], off
	v_lshl_add_u64 v[224:225], s[48:49], 0, v[132:133]
	s_mov_b32 m0, s31
	s_nop 0
	global_load_lds_dwordx4 v[224:225], off
	s_barrier
	s_waitcnt lgkmcnt(0)
	s_setprio 1
	s_waitcnt lgkmcnt(0)
	v_mfma_f32_16x16x32_bf16 v[92:95], v[150:153], v[166:169], v[92:95]
	v_mfma_f32_16x16x32_bf16 v[92:95], v[154:157], v[170:173], v[92:95]
	v_mfma_f32_16x16x32_bf16 v[88:91], v[158:161], v[166:169], v[88:91]
	v_mfma_f32_16x16x32_bf16 v[88:91], v[162:165], v[170:173], v[88:91]
	v_mfma_f32_16x16x32_bf16 v[80:83], v[158:161], v[174:177], v[80:83]
	v_mfma_f32_16x16x32_bf16 v[80:83], v[162:165], v[178:181], v[80:83]
	v_mfma_f32_16x16x32_bf16 v[84:87], v[150:153], v[174:177], v[84:87]
	v_mfma_f32_16x16x32_bf16 v[84:87], v[154:157], v[178:181], v[84:87]
	v_mfma_f32_16x16x32_bf16 v[76:79], v[150:153], v[182:185], v[76:79]
	v_mfma_f32_16x16x32_bf16 v[76:79], v[154:157], v[186:189], v[76:79]
	v_mfma_f32_16x16x32_bf16 v[72:75], v[158:161], v[182:185], v[72:75]
	v_mfma_f32_16x16x32_bf16 v[72:75], v[162:165], v[186:189], v[72:75]
	v_mfma_f32_16x16x32_bf16 v[64:67], v[158:161], v[190:193], v[64:67]
	v_mfma_f32_16x16x32_bf16 v[64:67], v[162:165], v[194:197], v[64:67]
	v_mfma_f32_16x16x32_bf16 v[68:71], v[150:153], v[190:193], v[68:71]
	v_mfma_f32_16x16x32_bf16 v[68:71], v[154:157], v[194:197], v[68:71]
	s_setprio 0
	s_barrier
; #define PG8_STAGE(bufoff, gbase, voff) do { _Pragma("unroll") for (int _i = 0; _i < 2; ++_i) \
;         __builtin_amdgcn_global_load_lds((const unsigned*)((const char*)(gbase) + (voff)[_i]), (LAS unsigned*)(lds + (bufoff) + ldsw + _i * 8192), 16, 0, 0); } while (0)
; #define PG8_LDA(dst, b, h) do { _Pragma("unroll") for (int m = 0; m < 4; ++m) _Pragma("unroll") for (int k = 0; k < 2; ++k) dst[m][k] = *(const LAS bf16x8*)(lds + PG8_SA(b, h) + aoff + m * 2048 + k * 1024); } while (0)
; #define PG8_LDB(dst, b, h) do { _Pragma("unroll") for (int n = 0; n < 2; ++n) _Pragma("unroll") for (int k = 0; k < 2; ++k) dst[n][k] = *(const LAS bf16x8*)(lds + PG8_SB(b, h) + boff + n * 2048 + k * 1024); } while (0)
; #define PG8_MMA(ai, bj, At, Bt) do { __builtin_amdgcn_s_setprio(1); _Pragma("unroll") for (int m = 0; m < 4; ++m) _Pragma("unroll") for (int n = 0; n < 2; ++n) _Pragma("unroll") for (int k = 0; k < 2; ++k) \
;         acc[ai][bj][m][n] = __builtin_amdgcn_mfma_f32_16x16x32_bf16(Bt[n][k], At[m][k], acc[ai][bj][m][n], 0, 0, 0); __builtin_amdgcn_s_setprio(0); } while (0)
; #define PG8_WAIT_V(n) asm volatile("s_waitcnt vmcnt(" #n ")" ::: "memory")
; #define PG8_WAIT_L(n) asm volatile("s_waitcnt lgkmcnt(" #n ")" ::: "memory")
; #define PG8_BAR __builtin_amdgcn_s_barrier()
; #define PG8_SCHED __builtin_amdgcn_sched_barrier(0)
; template <class Epi>
; DEVINL void gemm_phase(LAS unsigned char* lds, const Gemm g, const Order& S, const Epi& E) {
;     ...
;             PG8_STAGE(PG8_SB(0, 1), b2 + hstepB, voffB);
;             PG8_WAIT_V(6); PG8_BAR; PG8_MMA(1, 1, At, B1); PG8_BAR;
;             PG8_LDB(B0, 1, 0); PG8_SCHED; PG8_LDA(At, 1, 0); PG8_STAGE(PG8_SA(0, 1), a2 + hstepA, voffA);
;             PG8_WAIT_L(8); PG8_BAR; PG8_WAIT_L(0); PG8_MMA(0, 0, At, B0); PG8_BAR; PG8_SCHED;
;             PG8_LDB(B1, 1, 1); PG8_STAGE(PG8_SB(1, 0), b3, voffB);
	s_add_u32 s2, s46, 0x10000
	s_addc_u32 s3, s47, 0
	s_add_i32 s70, s59, s29
	v_lshl_add_u64 v[150:151], s[2:3], 0, v[130:131]
	s_mov_b32 m0, s70
	s_nop 0
	global_load_lds_dwordx4 v[150:151], off
	v_lshl_add_u64 v[150:151], s[2:3], 0, v[134:135]
	s_add_i32 m0, s70, 0x2000
	s_nop 0
	global_load_lds_dwordx4 v[150:151], off
	s_waitcnt vmcnt(6)
	s_barrier
	s_setprio 1
	v_mfma_f32_16x16x32_bf16 v[28:31], v[198:201], v[166:169], v[28:31]
	v_mfma_f32_16x16x32_bf16 v[28:31], v[202:205], v[170:173], v[28:31]
	v_mfma_f32_16x16x32_bf16 v[24:27], v[206:209], v[166:169], v[24:27]
	v_mfma_f32_16x16x32_bf16 v[24:27], v[210:213], v[170:173], v[24:27]
	v_mfma_f32_16x16x32_bf16 v[16:19], v[206:209], v[174:177], v[16:19]
	v_mfma_f32_16x16x32_bf16 v[16:19], v[210:213], v[178:181], v[16:19]
	v_mfma_f32_16x16x32_bf16 v[20:23], v[198:201], v[174:177], v[20:23]
	v_mfma_f32_16x16x32_bf16 v[20:23], v[202:205], v[178:181], v[20:23]
	v_mfma_f32_16x16x32_bf16 v[12:15], v[198:201], v[182:185], v[12:15]
	v_mfma_f32_16x16x32_bf16 v[12:15], v[202:205], v[186:189], v[12:15]
	v_mfma_f32_16x16x32_bf16 v[8:11], v[206:209], v[182:185], v[8:11]
	v_mfma_f32_16x16x32_bf16 v[8:11], v[210:213], v[186:189], v[8:11]
	v_mfma_f32_16x16x32_bf16 v[0:3], v[206:209], v[190:193], v[0:3]
	v_mfma_f32_16x16x32_bf16 v[0:3], v[210:213], v[194:197], v[0:3]
	v_mfma_f32_16x16x32_bf16 v[4:7], v[198:201], v[190:193], v[4:7]
	v_mfma_f32_16x16x32_bf16 v[4:7], v[202:205], v[194:197], v[4:7]
	s_setprio 0
	s_add_i32 s70, 16, 0x18000
	v_add_u32_e32 v162, s70, v145
	s_barrier
	ds_read_b128 v[150:153], v162
	ds_read_b128 v[154:157], v162 offset:1024
	ds_read_b128 v[158:161], v162 offset:2048
	ds_read_b128 v[162:165], v162 offset:3072
	s_add_u32 s2, s48, 0x10000
	s_addc_u32 s3, s49, 0
	s_mov_b32 m0, s45
	v_lshl_add_u64 v[198:199], s[2:3], 0, v[128:129]
	ds_read_b128 v[166:169], v148 offset:32768
	ds_read_b128 v[170:173], v148 offset:33792
	ds_read_b128 v[174:177], v148 offset:34816
	ds_read_b128 v[178:181], v148 offset:35840
	ds_read_b128 v[182:185], v148 offset:36864
	ds_read_b128 v[186:189], v148 offset:37888
	ds_read_b128 v[190:193], v148 offset:38912
	ds_read_b128 v[194:197], v148 offset:39936
	global_load_lds_dwordx4 v[198:199], off
	v_lshl_add_u64 v[198:199], s[2:3], 0, v[132:133]
	s_mov_b32 m0, s50
	s_nop 0
	global_load_lds_dwordx4 v[198:199], off
	s_waitcnt lgkmcnt(8)
	s_barrier
	s_waitcnt lgkmcnt(0)
	s_setprio 1
	s_waitcnt lgkmcnt(0)
	v_mfma_f32_16x16x32_bf16 v[124:127], v[150:153], v[166:169], v[124:127]
	v_mfma_f32_16x16x32_bf16 v[124:127], v[154:157], v[170:173], v[124:127]
	v_mfma_f32_16x16x32_bf16 v[120:123], v[158:161], v[166:169], v[120:123]
	v_mfma_f32_16x16x32_bf16 v[120:123], v[162:165], v[170:173], v[120:123]
	v_mfma_f32_16x16x32_bf16 v[112:115], v[158:161], v[174:177], v[112:115]
	v_mfma_f32_16x16x32_bf16 v[112:115], v[162:165], v[178:181], v[112:115]
	v_mfma_f32_16x16x32_bf16 v[116:119], v[150:153], v[174:177], v[116:119]
	v_mfma_f32_16x16x32_bf16 v[116:119], v[154:157], v[178:181], v[116:119]
	v_mfma_f32_16x16x32_bf16 v[108:111], v[150:153], v[182:185], v[108:111]
	v_mfma_f32_16x16x32_bf16 v[108:111], v[154:157], v[186:189], v[108:111]
	v_mfma_f32_16x16x32_bf16 v[104:107], v[158:161], v[182:185], v[104:107]
	v_mfma_f32_16x16x32_bf16 v[104:107], v[162:165], v[186:189], v[104:107]
	v_mfma_f32_16x16x32_bf16 v[96:99], v[158:161], v[190:193], v[96:99]
	v_mfma_f32_16x16x32_bf16 v[96:99], v[162:165], v[194:197], v[96:99]
	v_mfma_f32_16x16x32_bf16 v[100:103], v[150:153], v[190:193], v[100:103]
	v_mfma_f32_16x16x32_bf16 v[100:103], v[154:157], v[194:197], v[100:103]
	s_setprio 0
	s_barrier
	s_add_i32 s48, 16, 0x1c000
	s_add_i32 s2, s70, s29
	v_add_u32_e32 v210, s48, v145
	v_lshl_add_u64 v[218:219], v[218:219], 0, s[6:7]
	s_mov_b32 m0, s2
	ds_read_b128 v[198:201], v210
	ds_read_b128 v[202:205], v210 offset:1024
	ds_read_b128 v[206:209], v210 offset:2048
	ds_read_b128 v[210:213], v210 offset:3072
	global_load_lds_dwordx4 v[218:219], off
	v_lshl_add_u64 v[218:219], v[220:221], 0, s[6:7]
	s_add_i32 m0, s2, 0x2000
	s_nop 0
	global_load_lds_dwordx4 v[218:219], off
	s_barrier
; #define PG8_STAGE(bufoff, gbase, voff) do { _Pragma("unroll") for (int _i = 0; _i < 2; ++_i) \
;         __builtin_amdgcn_global_load_lds((const unsigned*)((const char*)(gbase) + (voff)[_i]), (LAS unsigned*)(lds + (bufoff) + ldsw + _i * 8192), 16, 0, 0); } while (0)
; #define PG8_LDA(dst, b, h) do { _Pragma("unroll") for (int m = 0; m < 4; ++m) _Pragma("unroll") for (int k = 0; k < 2; ++k) dst[m][k] = *(const LAS bf16x8*)(lds + PG8_SA(b, h) + aoff + m * 2048 + k * 1024); } while (0)
; #define PG8_MMA(ai, bj, At, Bt) do { __builtin_amdgcn_s_setprio(1); _Pragma("unroll") for (int m = 0; m < 4; ++m) _Pragma("unroll") for (int n = 0; n < 2; ++n) _Pragma("unroll") for (int k = 0; k < 2; ++k) \
;         acc[ai][bj][m][n] = __builtin_amdgcn_mfma_f32_16x16x32_bf16(Bt[n][k], At[m][k], acc[ai][bj][m][n], 0, 0, 0); __builtin_amdgcn_s_setprio(0); } while (0)
; #define PG8_WAIT_V(n) asm volatile("s_waitcnt vmcnt(" #n ")" ::: "memory")
; #define PG8_WAIT_L(n) asm volatile("s_waitcnt lgkmcnt(" #n ")" ::: "memory")
; #define PG8_BAR __builtin_amdgcn_s_barrier()
; #define PG8_SCHED __builtin_amdgcn_sched_barrier(0)
; template <class Epi>
; DEVINL void gemm_phase(LAS unsigned char* lds, const Gemm g, const Order& S, const Epi& E) {
;     ...
;             PG8_BAR; PG8_WAIT_L(0); PG8_MMA(0, 1, At, B1); PG8_BAR;
;             PG8_LDA(At, 1, 1); PG8_STAGE(PG8_SA(1, 0), a3, voffA);
;             PG8_BAR; PG8_WAIT_L(0); PG8_MMA(1, 0, At, B0); PG8_BAR; PG8_SCHED;
;             PG8_STAGE(PG8_SB(1, 1), b3 + hstepB, voffB);
;             PG8_WAIT_V(6); PG8_BAR; PG8_MMA(1, 1, At, B1); PG8_BAR;
	s_waitcnt lgkmcnt(0)
	s_setprio 1
	s_waitcnt lgkmcnt(0)
	v_mfma_f32_16x16x32_bf16 v[60:63], v[198:201], v[166:169], v[60:63]
	v_mfma_f32_16x16x32_bf16 v[60:63], v[202:205], v[170:173], v[60:63]
	v_mfma_f32_16x16x32_bf16 v[56:59], v[206:209], v[166:169], v[56:59]
	v_mfma_f32_16x16x32_bf16 v[56:59], v[210:213], v[170:173], v[56:59]
	v_mfma_f32_16x16x32_bf16 v[48:51], v[206:209], v[174:177], v[48:51]
	v_mfma_f32_16x16x32_bf16 v[48:51], v[210:213], v[178:181], v[48:51]
	v_mfma_f32_16x16x32_bf16 v[52:55], v[198:201], v[174:177], v[52:55]
	v_mfma_f32_16x16x32_bf16 v[52:55], v[202:205], v[178:181], v[52:55]
	v_mfma_f32_16x16x32_bf16 v[44:47], v[198:201], v[182:185], v[44:47]
	v_mfma_f32_16x16x32_bf16 v[44:47], v[202:205], v[186:189], v[44:47]
	v_mfma_f32_16x16x32_bf16 v[40:43], v[206:209], v[182:185], v[40:43]
	v_mfma_f32_16x16x32_bf16 v[40:43], v[210:213], v[186:189], v[40:43]
	v_mfma_f32_16x16x32_bf16 v[32:35], v[206:209], v[190:193], v[32:35]
	v_mfma_f32_16x16x32_bf16 v[32:35], v[210:213], v[194:197], v[32:35]
	v_mfma_f32_16x16x32_bf16 v[36:39], v[198:201], v[190:193], v[36:39]
	v_mfma_f32_16x16x32_bf16 v[36:39], v[202:205], v[194:197], v[36:39]
	s_setprio 0
	s_mov_b32 m0, s52
	v_lshl_add_u64 v[218:219], v[222:223], 0, s[6:7]
	s_barrier
	ds_read_b128 v[166:169], v148 offset:49152
	ds_read_b128 v[170:173], v148 offset:50176
	ds_read_b128 v[174:177], v148 offset:51200
	ds_read_b128 v[178:181], v148 offset:52224
	ds_read_b128 v[182:185], v148 offset:53248
	ds_read_b128 v[186:189], v148 offset:54272
	ds_read_b128 v[190:193], v148 offset:55296
	ds_read_b128 v[194:197], v148 offset:56320
	global_load_lds_dwordx4 v[218:219], off
	v_lshl_add_u64 v[218:219], v[224:225], 0, s[6:7]
	s_mov_b32 m0, s53
	s_nop 0
	global_load_lds_dwordx4 v[218:219], off
	s_barrier
	s_waitcnt lgkmcnt(0)
	s_setprio 1
	s_waitcnt lgkmcnt(0)
	v_mfma_f32_16x16x32_bf16 v[92:95], v[150:153], v[166:169], v[92:95]
	v_mfma_f32_16x16x32_bf16 v[92:95], v[154:157], v[170:173], v[92:95]
	v_mfma_f32_16x16x32_bf16 v[88:91], v[158:161], v[166:169], v[88:91]
	v_mfma_f32_16x16x32_bf16 v[88:91], v[162:165], v[170:173], v[88:91]
	v_mfma_f32_16x16x32_bf16 v[80:83], v[158:161], v[174:177], v[80:83]
	v_mfma_f32_16x16x32_bf16 v[80:83], v[162:165], v[178:181], v[80:83]
	v_mfma_f32_16x16x32_bf16 v[84:87], v[150:153], v[174:177], v[84:87]
	v_mfma_f32_16x16x32_bf16 v[84:87], v[154:157], v[178:181], v[84:87]
	v_mfma_f32_16x16x32_bf16 v[76:79], v[150:153], v[182:185], v[76:79]
	v_mfma_f32_16x16x32_bf16 v[76:79], v[154:157], v[186:189], v[76:79]
	v_mfma_f32_16x16x32_bf16 v[72:75], v[158:161], v[182:185], v[72:75]
	v_mfma_f32_16x16x32_bf16 v[72:75], v[162:165], v[186:189], v[72:75]
	v_mfma_f32_16x16x32_bf16 v[64:67], v[158:161], v[190:193], v[64:67]
	v_mfma_f32_16x16x32_bf16 v[64:67], v[162:165], v[194:197], v[64:67]
	v_mfma_f32_16x16x32_bf16 v[68:71], v[150:153], v[190:193], v[68:71]
	v_mfma_f32_16x16x32_bf16 v[68:71], v[154:157], v[194:197], v[68:71]
	s_setprio 0
	s_barrier
	s_add_u32 s2, s46, 0x10080
	s_addc_u32 s3, s47, 0
	s_add_i32 s46, s48, s29
	v_lshl_add_u64 v[150:151], s[2:3], 0, v[130:131]
	s_mov_b32 m0, s46
	s_nop 0
	global_load_lds_dwordx4 v[150:151], off
	v_lshl_add_u64 v[150:151], s[2:3], 0, v[134:135]
	s_add_i32 m0, s46, 0x2000
	s_nop 0
	global_load_lds_dwordx4 v[150:151], off
	s_waitcnt vmcnt(6)
	s_barrier
	s_setprio 1
	v_mfma_f32_16x16x32_bf16 v[28:31], v[198:201], v[166:169], v[28:31]
	v_mfma_f32_16x16x32_bf16 v[28:31], v[202:205], v[170:173], v[28:31]
	v_mfma_f32_16x16x32_bf16 v[24:27], v[206:209], v[166:169], v[24:27]
	v_mfma_f32_16x16x32_bf16 v[24:27], v[210:213], v[170:173], v[24:27]
	v_mfma_f32_16x16x32_bf16 v[16:19], v[206:209], v[174:177], v[16:19]
	v_mfma_f32_16x16x32_bf16 v[16:19], v[210:213], v[178:181], v[16:19]
	v_mfma_f32_16x16x32_bf16 v[20:23], v[198:201], v[174:177], v[20:23]
	v_mfma_f32_16x16x32_bf16 v[20:23], v[202:205], v[178:181], v[20:23]
	v_mfma_f32_16x16x32_bf16 v[12:15], v[198:201], v[182:185], v[12:15]
	v_mfma_f32_16x16x32_bf16 v[12:15], v[202:205], v[186:189], v[12:15]
	v_mfma_f32_16x16x32_bf16 v[8:11], v[206:209], v[182:185], v[8:11]
	v_mfma_f32_16x16x32_bf16 v[8:11], v[210:213], v[186:189], v[8:11]
	v_mfma_f32_16x16x32_bf16 v[0:3], v[206:209], v[190:193], v[0:3]
	v_mfma_f32_16x16x32_bf16 v[0:3], v[210:213], v[194:197], v[0:3]
	v_mfma_f32_16x16x32_bf16 v[4:7], v[198:201], v[190:193], v[4:7]
	v_mfma_f32_16x16x32_bf16 v[4:7], v[202:205], v[194:197], v[4:7]
	s_setprio 0
	s_add_u32 s4, s4, 0x100
	s_addc_u32 s5, s5, 0
	s_add_u32 s67, s67, 0x100
	s_addc_u32 s68, s68, 0
	s_cmp_ge_i32 s69, s51
	s_mov_b32 s46, s69
	s_barrier
	s_cbranch_scc0 .LBB0_986
	v_readlane_b32 s66, v251, 56
	v_readlane_b32 s67, v251, 57
	s_branch .LBB0_977

; #define PG8_STAGE(bufoff, gbase, voff) do { _Pragma("unroll") for (int _i = 0; _i < 2; ++_i) \
;         __builtin_amdgcn_global_load_lds((const unsigned*)((const char*)(gbase) + (voff)[_i]), (LAS unsigned*)(lds + (bufoff) + ldsw + _i * 8192), 16, 0, 0); } while (0)
; #define PG8_LDA(dst, b, h) do { _Pragma("unroll") for (int m = 0; m < 4; ++m) _Pragma("unroll") for (int k = 0; k < 2; ++k) dst[m][k] = *(const LAS bf16x8*)(lds + PG8_SA(b, h) + aoff + m * 2048 + k * 1024); } while (0)
; #define PG8_LDB(dst, b, h) do { _Pragma("unroll") for (int n = 0; n < 2; ++n) _Pragma("unroll") for (int k = 0; k < 2; ++k) dst[n][k] = *(const LAS bf16x8*)(lds + PG8_SB(b, h) + boff + n * 2048 + k * 1024); } while (0)
; #define PG8_MMA(ai, bj, At, Bt) do { __builtin_amdgcn_s_setprio(1); _Pragma("unroll") for (int m = 0; m < 4; ++m) _Pragma("unroll") for (int n = 0; n < 2; ++n) _Pragma("unroll") for (int k = 0; k < 2; ++k) \
;         acc[ai][bj][m][n] = __builtin_amdgcn_mfma_f32_16x16x32_bf16(Bt[n][k], At[m][k], acc[ai][bj][m][n], 0, 0, 0); __builtin_amdgcn_s_setprio(0); } while (0)
; #define PG8_WAIT_L(n) asm volatile("s_waitcnt lgkmcnt(" #n ")" ::: "memory")
; #define PG8_BAR __builtin_amdgcn_s_barrier()
; #define PG8_SCHED __builtin_amdgcn_sched_barrier(0)
; template <class Epi>
; DEVINL void gemm_phase(LAS unsigned char* lds, const Gemm g, const Order& S, const Epi& E) {
;     ...
;         const char* nA = has_next ? (const char*)g.A + (size_t)nxt.pm * tstepA : cA; const char* nB = has_next ? (const char*)g.Bt + (size_t)nxt.pn * tstepB : cB;
;         for (int t = 0; t < nt; t += 2) {
;             const bool last = (t == nt - 2);
;             const char* a1 = cA + (size_t)(t + 1) * kstep;
;             const char* a2 = last ? nA : cA + (size_t)(t + 2) * kstep; const char* b2 = last ? nB : cB + (size_t)(t + 2) * kstep;
;             const char* a3 = a2 + kstep; const char* b3 = b2 + kstep;
;             PG8_LDB(B0, 0, 0); PG8_SCHED; PG8_LDA(At, 0, 0); PG8_STAGE(PG8_SA(1, 1), a1 + hstepA, voffA);
;             PG8_WAIT_L(8); PG8_BAR; PG8_WAIT_L(0); PG8_MMA(0, 0, At, B0); PG8_BAR; PG8_SCHED;
;             PG8_LDB(B1, 0, 1); PG8_STAGE(PG8_SB(0, 0), b2, voffB);
;             PG8_BAR; PG8_WAIT_L(0); PG8_MMA(0, 1, At, B1); PG8_BAR;
;             PG8_LDA(At, 0, 1); PG8_STAGE(PG8_SA(0, 0), a2, voffA);
;             PG8_BAR; PG8_WAIT_L(0); PG8_MMA(1, 0, At, B0); PG8_BAR; PG8_SCHED;
.LBB0_1008:
	ds_read_b128 v[150:153], v147
	ds_read_b128 v[154:157], v147 offset:1024
	ds_read_b128 v[158:161], v147 offset:2048
	ds_read_b128 v[162:165], v147 offset:3072
	s_add_i32 s68, s46, 2
	s_add_u32 s47, s4, 0xffff0080
	s_addc_u32 s48, s5, -1
	s_cmp_eq_u32 s26, s46
	s_cselect_b32 s46, s13, s66
	s_cselect_b32 s49, s2, s48
	s_cselect_b32 s48, s3, s47
	s_cselect_b32 s47, s11, s67
	v_lshl_add_u64 v[198:199], s[4:5], 0, v[136:137]
	s_add_i32 m0, s45, 0xc000
	ds_read_b128 v[166:169], v148
	ds_read_b128 v[170:173], v148 offset:1024
	ds_read_b128 v[174:177], v148 offset:2048
	ds_read_b128 v[178:181], v148 offset:3072
	ds_read_b128 v[182:185], v148 offset:4096
	ds_read_b128 v[186:189], v148 offset:5120
	ds_read_b128 v[190:193], v148 offset:6144
	ds_read_b128 v[194:197], v148 offset:7168
	global_load_lds_dwordx4 v[198:199], off
	v_lshl_add_u64 v[198:199], s[4:5], 0, v[138:139]
	s_add_i32 m0, s45, 0xe000
	s_nop 0
	global_load_lds_dwordx4 v[198:199], off
	s_waitcnt lgkmcnt(8)
	s_barrier
	s_waitcnt lgkmcnt(0)
	s_setprio 1
	s_waitcnt lgkmcnt(0)
	v_mfma_f32_16x16x32_bf16 v[124:127], v[150:153], v[166:169], v[124:127]
	v_mfma_f32_16x16x32_bf16 v[124:127], v[154:157], v[170:173], v[124:127]
	v_mfma_f32_16x16x32_bf16 v[120:123], v[158:161], v[166:169], v[120:123]
	v_mfma_f32_16x16x32_bf16 v[120:123], v[162:165], v[170:173], v[120:123]
	v_mfma_f32_16x16x32_bf16 v[112:115], v[158:161], v[174:177], v[112:115]
	v_mfma_f32_16x16x32_bf16 v[112:115], v[162:165], v[178:181], v[112:115]
	v_mfma_f32_16x16x32_bf16 v[116:119], v[150:153], v[174:177], v[116:119]
	v_mfma_f32_16x16x32_bf16 v[116:119], v[154:157], v[178:181], v[116:119]
	v_mfma_f32_16x16x32_bf16 v[108:111], v[150:153], v[182:185], v[108:111]
	v_mfma_f32_16x16x32_bf16 v[108:111], v[154:157], v[186:189], v[108:111]
	v_mfma_f32_16x16x32_bf16 v[104:107], v[158:161], v[182:185], v[104:107]
	v_mfma_f32_16x16x32_bf16 v[104:107], v[162:165], v[186:189], v[104:107]
	v_mfma_f32_16x16x32_bf16 v[96:99], v[158:161], v[190:193], v[96:99]
	v_mfma_f32_16x16x32_bf16 v[96:99], v[162:165], v[194:197], v[96:99]
	v_mfma_f32_16x16x32_bf16 v[100:103], v[150:153], v[190:193], v[100:103]
	v_mfma_f32_16x16x32_bf16 v[100:103], v[154:157], v[194:197], v[100:103]
	s_setprio 0
	s_barrier
	s_add_i32 s69, s59, s31
	v_lshl_add_u64 v[218:219], s[46:47], 0, v[130:131]
	s_mov_b32 m0, s69
	ds_read_b128 v[198:201], v149
	ds_read_b128 v[202:205], v149 offset:1024
	ds_read_b128 v[206:209], v149 offset:2048
	ds_read_b128 v[210:213], v149 offset:3072
	global_load_lds_dwordx4 v[218:219], off
	v_lshl_add_u64 v[220:221], s[46:47], 0, v[134:135]
	s_add_i32 m0, s69, 0x2000
	s_nop 0
	global_load_lds_dwordx4 v[220:221], off
	s_barrier
	s_waitcnt lgkmcnt(0)
	s_setprio 1
	s_waitcnt lgkmcnt(0)
	v_mfma_f32_16x16x32_bf16 v[60:63], v[198:201], v[166:169], v[60:63]
	v_mfma_f32_16x16x32_bf16 v[60:63], v[202:205], v[170:173], v[60:63]
	v_mfma_f32_16x16x32_bf16 v[56:59], v[206:209], v[166:169], v[56:59]
	v_mfma_f32_16x16x32_bf16 v[56:59], v[210:213], v[170:173], v[56:59]
	v_mfma_f32_16x16x32_bf16 v[48:51], v[206:209], v[174:177], v[48:51]
	v_mfma_f32_16x16x32_bf16 v[48:51], v[210:213], v[178:181], v[48:51]
	v_mfma_f32_16x16x32_bf16 v[52:55], v[198:201], v[174:177], v[52:55]
	v_mfma_f32_16x16x32_bf16 v[52:55], v[202:205], v[178:181], v[52:55]
	v_mfma_f32_16x16x32_bf16 v[44:47], v[198:201], v[182:185], v[44:47]
	v_mfma_f32_16x16x32_bf16 v[44:47], v[202:205], v[186:189], v[44:47]
	v_mfma_f32_16x16x32_bf16 v[40:43], v[206:209], v[182:185], v[40:43]
	v_mfma_f32_16x16x32_bf16 v[40:43], v[210:213], v[186:189], v[40:43]
	v_mfma_f32_16x16x32_bf16 v[32:35], v[206:209], v[190:193], v[32:35]
	v_mfma_f32_16x16x32_bf16 v[32:35], v[210:213], v[194:197], v[32:35]
	v_mfma_f32_16x16x32_bf16 v[36:39], v[198:201], v[190:193], v[36:39]
	v_mfma_f32_16x16x32_bf16 v[36:39], v[202:205], v[194:197], v[36:39]
	s_setprio 0
	s_mov_b32 m0, s45
	v_lshl_add_u64 v[222:223], s[48:49], 0, v[128:129]
	s_barrier
	ds_read_b128 v[166:169], v148 offset:16384
	ds_read_b128 v[170:173], v148 offset:17408
	ds_read_b128 v[174:177], v148 offset:18432
	ds_read_b128 v[178:181], v148 offset:19456
	ds_read_b128 v[182:185], v148 offset:20480
	ds_read_b128 v[186:189], v148 offset:21504
	ds_read_b128 v[190:193], v148 offset:22528
	ds_read_b128 v[194:197], v148 offset:23552
	global_load_lds_dwordx4 v[222:223], off
	v_lshl_add_u64 v[224:225], s[48:49], 0, v[132:133]
	s_mov_b32 m0, s50
	s_nop 0
	global_load_lds_dwordx4 v[224:225], off
	s_barrier
	s_waitcnt lgkmcnt(0)
	s_setprio 1
	s_waitcnt lgkmcnt(0)
	v_mfma_f32_16x16x32_bf16 v[92:95], v[150:153], v[166:169], v[92:95]
	v_mfma_f32_16x16x32_bf16 v[92:95], v[154:157], v[170:173], v[92:95]
	v_mfma_f32_16x16x32_bf16 v[88:91], v[158:161], v[166:169], v[88:91]
	v_mfma_f32_16x16x32_bf16 v[88:91], v[162:165], v[170:173], v[88:91]
	v_mfma_f32_16x16x32_bf16 v[80:83], v[158:161], v[174:177], v[80:83]
	v_mfma_f32_16x16x32_bf16 v[80:83], v[162:165], v[178:181], v[80:83]
	v_mfma_f32_16x16x32_bf16 v[84:87], v[150:153], v[174:177], v[84:87]
	v_mfma_f32_16x16x32_bf16 v[84:87], v[154:157], v[178:181], v[84:87]
	v_mfma_f32_16x16x32_bf16 v[76:79], v[150:153], v[182:185], v[76:79]
	v_mfma_f32_16x16x32_bf16 v[76:79], v[154:157], v[186:189], v[76:79]
	v_mfma_f32_16x16x32_bf16 v[72:75], v[158:161], v[182:185], v[72:75]
	v_mfma_f32_16x16x32_bf16 v[72:75], v[162:165], v[186:189], v[72:75]
	v_mfma_f32_16x16x32_bf16 v[64:67], v[158:161], v[190:193], v[64:67]
	v_mfma_f32_16x16x32_bf16 v[64:67], v[162:165], v[194:197], v[64:67]
	v_mfma_f32_16x16x32_bf16 v[68:71], v[150:153], v[190:193], v[68:71]
	v_mfma_f32_16x16x32_bf16 v[68:71], v[154:157], v[194:197], v[68:71]
	s_setprio 0
	s_barrier
; #define PG8_STAGE(bufoff, gbase, voff) do { _Pragma("unroll") for (int _i = 0; _i < 2; ++_i) \
;         __builtin_amdgcn_global_load_lds((const unsigned*)((const char*)(gbase) + (voff)[_i]), (LAS unsigned*)(lds + (bufoff) + ldsw + _i * 8192), 16, 0, 0); } while (0)
; #define PG8_LDA(dst, b, h) do { _Pragma("unroll") for (int m = 0; m < 4; ++m) _Pragma("unroll") for (int k = 0; k < 2; ++k) dst[m][k] = *(const LAS bf16x8*)(lds + PG8_SA(b, h) + aoff + m * 2048 + k * 1024); } while (0)
; #define PG8_LDB(dst, b, h) do { _Pragma("unroll") for (int n = 0; n < 2; ++n) _Pragma("unroll") for (int k = 0; k < 2; ++k) dst[n][k] = *(const LAS bf16x8*)(lds + PG8_SB(b, h) + boff + n * 2048 + k * 1024); } while (0)
; #define PG8_MMA(ai, bj, At, Bt) do { __builtin_amdgcn_s_setprio(1); _Pragma("unroll") for (int m = 0; m < 4; ++m) _Pragma("unroll") for (int n = 0; n < 2; ++n) _Pragma("unroll") for (int k = 0; k < 2; ++k) \
;         acc[ai][bj][m][n] = __builtin_amdgcn_mfma_f32_16x16x32_bf16(Bt[n][k], At[m][k], acc[ai][bj][m][n], 0, 0, 0); __builtin_amdgcn_s_setprio(0); } while (0)
; #define PG8_WAIT_V(n) asm volatile("s_waitcnt vmcnt(" #n ")" ::: "memory")
; #define PG8_WAIT_L(n) asm volatile("s_waitcnt lgkmcnt(" #n ")" ::: "memory")
; #define PG8_BAR __builtin_amdgcn_s_barrier()
; #define PG8_SCHED __builtin_amdgcn_sched_barrier(0)
; template <class Epi>
; DEVINL void gemm_phase(LAS unsigned char* lds, const Gemm g, const Order& S, const Epi& E) {
;     ...
;             PG8_STAGE(PG8_SB(0, 1), b2 + hstepB, voffB);
;             PG8_WAIT_V(6); PG8_BAR; PG8_MMA(1, 1, At, B1); PG8_BAR;
;             PG8_LDB(B0, 1, 0); PG8_SCHED; PG8_LDA(At, 1, 0); PG8_STAGE(PG8_SA(0, 1), a2 + hstepA, voffA);
;             PG8_WAIT_L(8); PG8_BAR; PG8_WAIT_L(0); PG8_MMA(0, 0, At, B0); PG8_BAR; PG8_SCHED;
;             PG8_LDB(B1, 1, 1); PG8_STAGE(PG8_SB(1, 0), b3, voffB);
	s_add_u32 s70, s46, 0x10000
	s_addc_u32 s71, s47, 0
	s_add_i32 s69, s64, s31
	v_lshl_add_u64 v[150:151], s[70:71], 0, v[130:131]
	s_mov_b32 m0, s69
	s_nop 0
	global_load_lds_dwordx4 v[150:151], off
	v_lshl_add_u64 v[150:151], s[70:71], 0, v[134:135]
	s_add_i32 m0, s69, 0x2000
	s_nop 0
	global_load_lds_dwordx4 v[150:151], off
	s_waitcnt vmcnt(6)
	s_barrier
	s_setprio 1
	v_mfma_f32_16x16x32_bf16 v[28:31], v[198:201], v[166:169], v[28:31]
	v_mfma_f32_16x16x32_bf16 v[28:31], v[202:205], v[170:173], v[28:31]
	v_mfma_f32_16x16x32_bf16 v[24:27], v[206:209], v[166:169], v[24:27]
	v_mfma_f32_16x16x32_bf16 v[24:27], v[210:213], v[170:173], v[24:27]
	v_mfma_f32_16x16x32_bf16 v[16:19], v[206:209], v[174:177], v[16:19]
	v_mfma_f32_16x16x32_bf16 v[16:19], v[210:213], v[178:181], v[16:19]
	v_mfma_f32_16x16x32_bf16 v[20:23], v[198:201], v[174:177], v[20:23]
	v_mfma_f32_16x16x32_bf16 v[20:23], v[202:205], v[178:181], v[20:23]
	v_mfma_f32_16x16x32_bf16 v[12:15], v[198:201], v[182:185], v[12:15]
	v_mfma_f32_16x16x32_bf16 v[12:15], v[202:205], v[186:189], v[12:15]
	v_mfma_f32_16x16x32_bf16 v[8:11], v[206:209], v[182:185], v[8:11]
	v_mfma_f32_16x16x32_bf16 v[8:11], v[210:213], v[186:189], v[8:11]
	v_mfma_f32_16x16x32_bf16 v[0:3], v[206:209], v[190:193], v[0:3]
	v_mfma_f32_16x16x32_bf16 v[0:3], v[210:213], v[194:197], v[0:3]
	v_mfma_f32_16x16x32_bf16 v[4:7], v[198:201], v[190:193], v[4:7]
	v_mfma_f32_16x16x32_bf16 v[4:7], v[202:205], v[194:197], v[4:7]
	s_setprio 0
	s_add_i32 s69, 16, 0x18000
	v_add_u32_e32 v162, s69, v145
	s_barrier
	ds_read_b128 v[150:153], v162
	ds_read_b128 v[154:157], v162 offset:1024
	ds_read_b128 v[158:161], v162 offset:2048
	ds_read_b128 v[162:165], v162 offset:3072
	s_add_u32 s48, s48, 0x10000
	s_addc_u32 s49, s49, 0
	s_mov_b32 m0, s51
	v_lshl_add_u64 v[198:199], s[48:49], 0, v[128:129]
	ds_read_b128 v[166:169], v148 offset:32768
	ds_read_b128 v[170:173], v148 offset:33792
	ds_read_b128 v[174:177], v148 offset:34816
	ds_read_b128 v[178:181], v148 offset:35840
	ds_read_b128 v[182:185], v148 offset:36864
	ds_read_b128 v[186:189], v148 offset:37888
	ds_read_b128 v[190:193], v148 offset:38912
	ds_read_b128 v[194:197], v148 offset:39936
	global_load_lds_dwordx4 v[198:199], off
	v_lshl_add_u64 v[198:199], s[48:49], 0, v[132:133]
	s_mov_b32 m0, s52
	s_nop 0
	global_load_lds_dwordx4 v[198:199], off
	s_waitcnt lgkmcnt(8)
	s_barrier
	s_waitcnt lgkmcnt(0)
	s_setprio 1
	s_waitcnt lgkmcnt(0)
	v_mfma_f32_16x16x32_bf16 v[124:127], v[150:153], v[166:169], v[124:127]
	v_mfma_f32_16x16x32_bf16 v[124:127], v[154:157], v[170:173], v[124:127]
	v_mfma_f32_16x16x32_bf16 v[120:123], v[158:161], v[166:169], v[120:123]
	v_mfma_f32_16x16x32_bf16 v[120:123], v[162:165], v[170:173], v[120:123]
	v_mfma_f32_16x16x32_bf16 v[112:115], v[158:161], v[174:177], v[112:115]
	v_mfma_f32_16x16x32_bf16 v[112:115], v[162:165], v[178:181], v[112:115]
	v_mfma_f32_16x16x32_bf16 v[116:119], v[150:153], v[174:177], v[116:119]
	v_mfma_f32_16x16x32_bf16 v[116:119], v[154:157], v[178:181], v[116:119]
	v_mfma_f32_16x16x32_bf16 v[108:111], v[150:153], v[182:185], v[108:111]
	v_mfma_f32_16x16x32_bf16 v[108:111], v[154:157], v[186:189], v[108:111]
	v_mfma_f32_16x16x32_bf16 v[104:107], v[158:161], v[182:185], v[104:107]
	v_mfma_f32_16x16x32_bf16 v[104:107], v[162:165], v[186:189], v[104:107]
	v_mfma_f32_16x16x32_bf16 v[96:99], v[158:161], v[190:193], v[96:99]
	v_mfma_f32_16x16x32_bf16 v[96:99], v[162:165], v[194:197], v[96:99]
	v_mfma_f32_16x16x32_bf16 v[100:103], v[150:153], v[190:193], v[100:103]
	v_mfma_f32_16x16x32_bf16 v[100:103], v[154:157], v[194:197], v[100:103]
	s_setprio 0
	s_barrier
	s_add_i32 s48, 16, 0x1c000
	s_add_i32 s49, s69, s31
	v_add_u32_e32 v210, s48, v145
	v_lshl_add_u64 v[218:219], v[218:219], 0, s[6:7]
	s_mov_b32 m0, s49
	ds_read_b128 v[198:201], v210
	ds_read_b128 v[202:205], v210 offset:1024
	ds_read_b128 v[206:209], v210 offset:2048
	ds_read_b128 v[210:213], v210 offset:3072
	global_load_lds_dwordx4 v[218:219], off
	v_lshl_add_u64 v[218:219], v[220:221], 0, s[6:7]
	s_add_i32 m0, s49, 0x2000
	s_nop 0
	global_load_lds_dwordx4 v[218:219], off
	s_barrier
; #define PG8_STAGE(bufoff, gbase, voff) do { _Pragma("unroll") for (int _i = 0; _i < 2; ++_i) \
;         __builtin_amdgcn_global_load_lds((const unsigned*)((const char*)(gbase) + (voff)[_i]), (LAS unsigned*)(lds + (bufoff) + ldsw + _i * 8192), 16, 0, 0); } while (0)
; #define PG8_LDA(dst, b, h) do { _Pragma("unroll") for (int m = 0; m < 4; ++m) _Pragma("unroll") for (int k = 0; k < 2; ++k) dst[m][k] = *(const LAS bf16x8*)(lds + PG8_SA(b, h) + aoff + m * 2048 + k * 1024); } while (0)
; #define PG8_MMA(ai, bj, At, Bt) do { __builtin_amdgcn_s_setprio(1); _Pragma("unroll") for (int m = 0; m < 4; ++m) _Pragma("unroll") for (int n = 0; n < 2; ++n) _Pragma("unroll") for (int k = 0; k < 2; ++k) \
;         acc[ai][bj][m][n] = __builtin_amdgcn_mfma_f32_16x16x32_bf16(Bt[n][k], At[m][k], acc[ai][bj][m][n], 0, 0, 0); __builtin_amdgcn_s_setprio(0); } while (0)
; #define PG8_WAIT_V(n) asm volatile("s_waitcnt vmcnt(" #n ")" ::: "memory")
; #define PG8_WAIT_L(n) asm volatile("s_waitcnt lgkmcnt(" #n ")" ::: "memory")
; #define PG8_BAR __builtin_amdgcn_s_barrier()
; #define PG8_SCHED __builtin_amdgcn_sched_barrier(0)
; template <class Epi>
; DEVINL void gemm_phase(LAS unsigned char* lds, const Gemm g, const Order& S, const Epi& E) {
;     ...
;             PG8_BAR; PG8_WAIT_L(0); PG8_MMA(0, 1, At, B1); PG8_BAR;
;             PG8_LDA(At, 1, 1); PG8_STAGE(PG8_SA(1, 0), a3, voffA);
;             PG8_BAR; PG8_WAIT_L(0); PG8_MMA(1, 0, At, B0); PG8_BAR; PG8_SCHED;
;             PG8_STAGE(PG8_SB(1, 1), b3 + hstepB, voffB);
;             PG8_WAIT_V(6); PG8_BAR; PG8_MMA(1, 1, At, B1); PG8_BAR;
	s_waitcnt lgkmcnt(0)
	s_setprio 1
	s_waitcnt lgkmcnt(0)
	v_mfma_f32_16x16x32_bf16 v[60:63], v[198:201], v[166:169], v[60:63]
	v_mfma_f32_16x16x32_bf16 v[60:63], v[202:205], v[170:173], v[60:63]
	v_mfma_f32_16x16x32_bf16 v[56:59], v[206:209], v[166:169], v[56:59]
	v_mfma_f32_16x16x32_bf16 v[56:59], v[210:213], v[170:173], v[56:59]
	v_mfma_f32_16x16x32_bf16 v[48:51], v[206:209], v[174:177], v[48:51]
	v_mfma_f32_16x16x32_bf16 v[48:51], v[210:213], v[178:181], v[48:51]
	v_mfma_f32_16x16x32_bf16 v[52:55], v[198:201], v[174:177], v[52:55]
	v_mfma_f32_16x16x32_bf16 v[52:55], v[202:205], v[178:181], v[52:55]
	v_mfma_f32_16x16x32_bf16 v[44:47], v[198:201], v[182:185], v[44:47]
	v_mfma_f32_16x16x32_bf16 v[44:47], v[202:205], v[186:189], v[44:47]
	v_mfma_f32_16x16x32_bf16 v[40:43], v[206:209], v[182:185], v[40:43]
	v_mfma_f32_16x16x32_bf16 v[40:43], v[210:213], v[186:189], v[40:43]
	v_mfma_f32_16x16x32_bf16 v[32:35], v[206:209], v[190:193], v[32:35]
	v_mfma_f32_16x16x32_bf16 v[32:35], v[210:213], v[194:197], v[32:35]
	v_mfma_f32_16x16x32_bf16 v[36:39], v[198:201], v[190:193], v[36:39]
	v_mfma_f32_16x16x32_bf16 v[36:39], v[202:205], v[194:197], v[36:39]
	s_setprio 0
	s_mov_b32 m0, s54
	v_lshl_add_u64 v[218:219], v[222:223], 0, s[6:7]
	s_barrier
	ds_read_b128 v[166:169], v148 offset:49152
	ds_read_b128 v[170:173], v148 offset:50176
	ds_read_b128 v[174:177], v148 offset:51200
	ds_read_b128 v[178:181], v148 offset:52224
	ds_read_b128 v[182:185], v148 offset:53248
	ds_read_b128 v[186:189], v148 offset:54272
	ds_read_b128 v[190:193], v148 offset:55296
	ds_read_b128 v[194:197], v148 offset:56320
	global_load_lds_dwordx4 v[218:219], off
	v_lshl_add_u64 v[218:219], v[224:225], 0, s[6:7]
	s_mov_b32 m0, s55
	s_nop 0
	global_load_lds_dwordx4 v[218:219], off
	s_barrier
	s_waitcnt lgkmcnt(0)
	s_setprio 1
	s_waitcnt lgkmcnt(0)
	v_mfma_f32_16x16x32_bf16 v[92:95], v[150:153], v[166:169], v[92:95]
	v_mfma_f32_16x16x32_bf16 v[92:95], v[154:157], v[170:173], v[92:95]
	v_mfma_f32_16x16x32_bf16 v[88:91], v[158:161], v[166:169], v[88:91]
	v_mfma_f32_16x16x32_bf16 v[88:91], v[162:165], v[170:173], v[88:91]
	v_mfma_f32_16x16x32_bf16 v[80:83], v[158:161], v[174:177], v[80:83]
	v_mfma_f32_16x16x32_bf16 v[80:83], v[162:165], v[178:181], v[80:83]
	v_mfma_f32_16x16x32_bf16 v[84:87], v[150:153], v[174:177], v[84:87]
	v_mfma_f32_16x16x32_bf16 v[84:87], v[154:157], v[178:181], v[84:87]
	v_mfma_f32_16x16x32_bf16 v[76:79], v[150:153], v[182:185], v[76:79]
	v_mfma_f32_16x16x32_bf16 v[76:79], v[154:157], v[186:189], v[76:79]
	v_mfma_f32_16x16x32_bf16 v[72:75], v[158:161], v[182:185], v[72:75]
	v_mfma_f32_16x16x32_bf16 v[72:75], v[162:165], v[186:189], v[72:75]
	v_mfma_f32_16x16x32_bf16 v[64:67], v[158:161], v[190:193], v[64:67]
	v_mfma_f32_16x16x32_bf16 v[64:67], v[162:165], v[194:197], v[64:67]
	v_mfma_f32_16x16x32_bf16 v[68:71], v[150:153], v[190:193], v[68:71]
	v_mfma_f32_16x16x32_bf16 v[68:71], v[154:157], v[194:197], v[68:71]
	s_setprio 0
	s_barrier
	s_add_u32 s46, s46, 0x10080
	s_addc_u32 s47, s47, 0
	s_add_i32 s48, s48, s31
	v_lshl_add_u64 v[150:151], s[46:47], 0, v[130:131]
	s_mov_b32 m0, s48
	s_nop 0
	global_load_lds_dwordx4 v[150:151], off
	v_lshl_add_u64 v[150:151], s[46:47], 0, v[134:135]
	s_add_i32 m0, s48, 0x2000
	s_nop 0
	global_load_lds_dwordx4 v[150:151], off
	s_waitcnt vmcnt(6)
	s_barrier
	s_setprio 1
	v_mfma_f32_16x16x32_bf16 v[28:31], v[198:201], v[166:169], v[28:31]
	v_mfma_f32_16x16x32_bf16 v[28:31], v[202:205], v[170:173], v[28:31]
	v_mfma_f32_16x16x32_bf16 v[24:27], v[206:209], v[166:169], v[24:27]
	v_mfma_f32_16x16x32_bf16 v[24:27], v[210:213], v[170:173], v[24:27]
	v_mfma_f32_16x16x32_bf16 v[16:19], v[206:209], v[174:177], v[16:19]
	v_mfma_f32_16x16x32_bf16 v[16:19], v[210:213], v[178:181], v[16:19]
	v_mfma_f32_16x16x32_bf16 v[20:23], v[198:201], v[174:177], v[20:23]
	v_mfma_f32_16x16x32_bf16 v[20:23], v[202:205], v[178:181], v[20:23]
	v_mfma_f32_16x16x32_bf16 v[12:15], v[198:201], v[182:185], v[12:15]
	v_mfma_f32_16x16x32_bf16 v[12:15], v[202:205], v[186:189], v[12:15]
	v_mfma_f32_16x16x32_bf16 v[8:11], v[206:209], v[182:185], v[8:11]
	v_mfma_f32_16x16x32_bf16 v[8:11], v[210:213], v[186:189], v[8:11]
	v_mfma_f32_16x16x32_bf16 v[0:3], v[206:209], v[190:193], v[0:3]
	v_mfma_f32_16x16x32_bf16 v[0:3], v[210:213], v[194:197], v[0:3]
	v_mfma_f32_16x16x32_bf16 v[4:7], v[198:201], v[190:193], v[4:7]
	v_mfma_f32_16x16x32_bf16 v[4:7], v[202:205], v[194:197], v[4:7]
	s_setprio 0
	s_add_u32 s4, s4, 0x100
	s_addc_u32 s5, s5, 0
	s_add_u32 s66, s66, 0x100
	s_addc_u32 s67, s67, 0
	s_cmp_ge_i32 s68, s53
	s_mov_b32 s46, s68
	s_barrier
	s_cbranch_scc0 .LBB0_1008
	s_branch .LBB0_999

; #define PG8_STAGE(bufoff, gbase, voff) do { _Pragma("unroll") for (int _i = 0; _i < 2; ++_i) \
;         __builtin_amdgcn_global_load_lds((const unsigned*)((const char*)(gbase) + (voff)[_i]), (LAS unsigned*)(lds + (bufoff) + ldsw + _i * 8192), 16, 0, 0); } while (0)
; #define PG8_LDA(dst, b, h) do { _Pragma("unroll") for (int m = 0; m < 4; ++m) _Pragma("unroll") for (int k = 0; k < 2; ++k) dst[m][k] = *(const LAS bf16x8*)(lds + PG8_SA(b, h) + aoff + m * 2048 + k * 1024); } while (0)
; #define PG8_LDB(dst, b, h) do { _Pragma("unroll") for (int n = 0; n < 2; ++n) _Pragma("unroll") for (int k = 0; k < 2; ++k) dst[n][k] = *(const LAS bf16x8*)(lds + PG8_SB(b, h) + boff + n * 2048 + k * 1024); } while (0)
; #define PG8_MMA(ai, bj, At, Bt) do { __builtin_amdgcn_s_setprio(1); _Pragma("unroll") for (int m = 0; m < 4; ++m) _Pragma("unroll") for (int n = 0; n < 2; ++n) _Pragma("unroll") for (int k = 0; k < 2; ++k) \
;         acc[ai][bj][m][n] = __builtin_amdgcn_mfma_f32_16x16x32_bf16(Bt[n][k], At[m][k], acc[ai][bj][m][n], 0, 0, 0); __builtin_amdgcn_s_setprio(0); } while (0)
; #define PG8_WAIT_L(n) asm volatile("s_waitcnt lgkmcnt(" #n ")" ::: "memory")
; #define PG8_BAR __builtin_amdgcn_s_barrier()
; #define PG8_SCHED __builtin_amdgcn_sched_barrier(0)
; template <class Epi>
; DEVINL void gemm_phase(LAS unsigned char* lds, const Gemm g, const Order& S, const Epi& E) {
;     ...
;         const char* nA = has_next ? (const char*)g.A + (size_t)nxt.pm * tstepA : cA; const char* nB = has_next ? (const char*)g.Bt + (size_t)nxt.pn * tstepB : cB;
;         for (int t = 0; t < nt; t += 2) {
;             const bool last = (t == nt - 2);
;             const char* a1 = cA + (size_t)(t + 1) * kstep;
;             const char* a2 = last ? nA : cA + (size_t)(t + 2) * kstep; const char* b2 = last ? nB : cB + (size_t)(t + 2) * kstep;
;             const char* a3 = a2 + kstep; const char* b3 = b2 + kstep;
;             PG8_LDB(B0, 0, 0); PG8_SCHED; PG8_LDA(At, 0, 0); PG8_STAGE(PG8_SA(1, 1), a1 + hstepA, voffA);
;             PG8_WAIT_L(8); PG8_BAR; PG8_WAIT_L(0); PG8_MMA(0, 0, At, B0); PG8_BAR; PG8_SCHED;
;             PG8_LDB(B1, 0, 1); PG8_STAGE(PG8_SB(0, 0), b2, voffB);
;             PG8_BAR; PG8_WAIT_L(0); PG8_MMA(0, 1, At, B1); PG8_BAR;
;             PG8_LDA(At, 0, 1); PG8_STAGE(PG8_SA(0, 0), a2, voffA);
;             PG8_BAR; PG8_WAIT_L(0); PG8_MMA(1, 0, At, B0); PG8_BAR; PG8_SCHED;
.LBB0_1029:
	ds_read_b128 v[150:153], v147
	ds_read_b128 v[154:157], v147 offset:1024
	ds_read_b128 v[158:161], v147 offset:2048
	ds_read_b128 v[162:165], v147 offset:3072
	s_add_i32 s70, s48, 2
	s_add_u32 s49, s4, 0xffff0080
	s_addc_u32 s50, s5, -1
	s_cmp_eq_u32 s57, s48
	s_cselect_b32 s48, s13, s68
	s_cselect_b32 s51, s2, s50
	s_cselect_b32 s50, s3, s49
	s_cselect_b32 s49, s11, s69
	v_lshl_add_u64 v[198:199], s[4:5], 0, v[136:137]
	s_add_i32 m0, s31, 0xc000
	ds_read_b128 v[166:169], v148
	ds_read_b128 v[170:173], v148 offset:1024
	ds_read_b128 v[174:177], v148 offset:2048
	ds_read_b128 v[178:181], v148 offset:3072
	ds_read_b128 v[182:185], v148 offset:4096
	ds_read_b128 v[186:189], v148 offset:5120
	ds_read_b128 v[190:193], v148 offset:6144
	ds_read_b128 v[194:197], v148 offset:7168
	global_load_lds_dwordx4 v[198:199], off
	v_lshl_add_u64 v[198:199], s[4:5], 0, v[138:139]
	s_add_i32 m0, s31, 0xe000
	s_nop 0
	global_load_lds_dwordx4 v[198:199], off
	s_waitcnt lgkmcnt(8)
	s_barrier
	s_waitcnt lgkmcnt(0)
	s_setprio 1
	s_waitcnt lgkmcnt(0)
	v_mfma_f32_16x16x32_bf16 v[124:127], v[150:153], v[166:169], v[124:127]
	v_mfma_f32_16x16x32_bf16 v[124:127], v[154:157], v[170:173], v[124:127]
	v_mfma_f32_16x16x32_bf16 v[120:123], v[158:161], v[166:169], v[120:123]
	v_mfma_f32_16x16x32_bf16 v[120:123], v[162:165], v[170:173], v[120:123]
	v_mfma_f32_16x16x32_bf16 v[112:115], v[158:161], v[174:177], v[112:115]
	v_mfma_f32_16x16x32_bf16 v[112:115], v[162:165], v[178:181], v[112:115]
	v_mfma_f32_16x16x32_bf16 v[116:119], v[150:153], v[174:177], v[116:119]
	v_mfma_f32_16x16x32_bf16 v[116:119], v[154:157], v[178:181], v[116:119]
	v_mfma_f32_16x16x32_bf16 v[108:111], v[150:153], v[182:185], v[108:111]
	v_mfma_f32_16x16x32_bf16 v[108:111], v[154:157], v[186:189], v[108:111]
	v_mfma_f32_16x16x32_bf16 v[104:107], v[158:161], v[182:185], v[104:107]
	v_mfma_f32_16x16x32_bf16 v[104:107], v[162:165], v[186:189], v[104:107]
	v_mfma_f32_16x16x32_bf16 v[96:99], v[158:161], v[190:193], v[96:99]
	v_mfma_f32_16x16x32_bf16 v[96:99], v[162:165], v[194:197], v[96:99]
	v_mfma_f32_16x16x32_bf16 v[100:103], v[150:153], v[190:193], v[100:103]
	v_mfma_f32_16x16x32_bf16 v[100:103], v[154:157], v[194:197], v[100:103]
	s_setprio 0
	s_barrier
	s_add_i32 s71, s65, s30
	v_lshl_add_u64 v[218:219], s[48:49], 0, v[130:131]
	s_mov_b32 m0, s71
	ds_read_b128 v[198:201], v149
	ds_read_b128 v[202:205], v149 offset:1024
	ds_read_b128 v[206:209], v149 offset:2048
	ds_read_b128 v[210:213], v149 offset:3072
	global_load_lds_dwordx4 v[218:219], off
	v_lshl_add_u64 v[220:221], s[48:49], 0, v[134:135]
	s_add_i32 m0, s71, 0x2000
	s_nop 0
	global_load_lds_dwordx4 v[220:221], off
	s_barrier
	s_waitcnt lgkmcnt(0)
	s_setprio 1
	s_waitcnt lgkmcnt(0)
	v_mfma_f32_16x16x32_bf16 v[60:63], v[198:201], v[166:169], v[60:63]
	v_mfma_f32_16x16x32_bf16 v[60:63], v[202:205], v[170:173], v[60:63]
	v_mfma_f32_16x16x32_bf16 v[56:59], v[206:209], v[166:169], v[56:59]
	v_mfma_f32_16x16x32_bf16 v[56:59], v[210:213], v[170:173], v[56:59]
	v_mfma_f32_16x16x32_bf16 v[48:51], v[206:209], v[174:177], v[48:51]
	v_mfma_f32_16x16x32_bf16 v[48:51], v[210:213], v[178:181], v[48:51]
	v_mfma_f32_16x16x32_bf16 v[52:55], v[198:201], v[174:177], v[52:55]
	v_mfma_f32_16x16x32_bf16 v[52:55], v[202:205], v[178:181], v[52:55]
	v_mfma_f32_16x16x32_bf16 v[44:47], v[198:201], v[182:185], v[44:47]
	v_mfma_f32_16x16x32_bf16 v[44:47], v[202:205], v[186:189], v[44:47]
	v_mfma_f32_16x16x32_bf16 v[40:43], v[206:209], v[182:185], v[40:43]
	v_mfma_f32_16x16x32_bf16 v[40:43], v[210:213], v[186:189], v[40:43]
	v_mfma_f32_16x16x32_bf16 v[32:35], v[206:209], v[190:193], v[32:35]
	v_mfma_f32_16x16x32_bf16 v[32:35], v[210:213], v[194:197], v[32:35]
	v_mfma_f32_16x16x32_bf16 v[36:39], v[198:201], v[190:193], v[36:39]
	v_mfma_f32_16x16x32_bf16 v[36:39], v[202:205], v[194:197], v[36:39]
	s_setprio 0
	s_mov_b32 m0, s31
	v_lshl_add_u64 v[222:223], s[50:51], 0, v[128:129]
	s_barrier
	ds_read_b128 v[166:169], v148 offset:16384
	ds_read_b128 v[170:173], v148 offset:17408
	ds_read_b128 v[174:177], v148 offset:18432
	ds_read_b128 v[178:181], v148 offset:19456
	ds_read_b128 v[182:185], v148 offset:20480
	ds_read_b128 v[186:189], v148 offset:21504
	ds_read_b128 v[190:193], v148 offset:22528
	ds_read_b128 v[194:197], v148 offset:23552
	global_load_lds_dwordx4 v[222:223], off
	v_lshl_add_u64 v[224:225], s[50:51], 0, v[132:133]
	s_mov_b32 m0, s47
	s_nop 0
	global_load_lds_dwordx4 v[224:225], off
	s_barrier
	s_waitcnt lgkmcnt(0)
	s_setprio 1
	s_waitcnt lgkmcnt(0)
	v_mfma_f32_16x16x32_bf16 v[92:95], v[150:153], v[166:169], v[92:95]
	v_mfma_f32_16x16x32_bf16 v[92:95], v[154:157], v[170:173], v[92:95]
	v_mfma_f32_16x16x32_bf16 v[88:91], v[158:161], v[166:169], v[88:91]
	v_mfma_f32_16x16x32_bf16 v[88:91], v[162:165], v[170:173], v[88:91]
	v_mfma_f32_16x16x32_bf16 v[80:83], v[158:161], v[174:177], v[80:83]
	v_mfma_f32_16x16x32_bf16 v[80:83], v[162:165], v[178:181], v[80:83]
	v_mfma_f32_16x16x32_bf16 v[84:87], v[150:153], v[174:177], v[84:87]
	v_mfma_f32_16x16x32_bf16 v[84:87], v[154:157], v[178:181], v[84:87]
	v_mfma_f32_16x16x32_bf16 v[76:79], v[150:153], v[182:185], v[76:79]
	v_mfma_f32_16x16x32_bf16 v[76:79], v[154:157], v[186:189], v[76:79]
	v_mfma_f32_16x16x32_bf16 v[72:75], v[158:161], v[182:185], v[72:75]
	v_mfma_f32_16x16x32_bf16 v[72:75], v[162:165], v[186:189], v[72:75]
	v_mfma_f32_16x16x32_bf16 v[64:67], v[158:161], v[190:193], v[64:67]
	v_mfma_f32_16x16x32_bf16 v[64:67], v[162:165], v[194:197], v[64:67]
	v_mfma_f32_16x16x32_bf16 v[68:71], v[150:153], v[190:193], v[68:71]
	v_mfma_f32_16x16x32_bf16 v[68:71], v[154:157], v[194:197], v[68:71]
	s_setprio 0
	s_barrier
; #define PG8_STAGE(bufoff, gbase, voff) do { _Pragma("unroll") for (int _i = 0; _i < 2; ++_i) \
;         __builtin_amdgcn_global_load_lds((const unsigned*)((const char*)(gbase) + (voff)[_i]), (LAS unsigned*)(lds + (bufoff) + ldsw + _i * 8192), 16, 0, 0); } while (0)
; #define PG8_LDA(dst, b, h) do { _Pragma("unroll") for (int m = 0; m < 4; ++m) _Pragma("unroll") for (int k = 0; k < 2; ++k) dst[m][k] = *(const LAS bf16x8*)(lds + PG8_SA(b, h) + aoff + m * 2048 + k * 1024); } while (0)
; #define PG8_LDB(dst, b, h) do { _Pragma("unroll") for (int n = 0; n < 2; ++n) _Pragma("unroll") for (int k = 0; k < 2; ++k) dst[n][k] = *(const LAS bf16x8*)(lds + PG8_SB(b, h) + boff + n * 2048 + k * 1024); } while (0)
; #define PG8_MMA(ai, bj, At, Bt) do { __builtin_amdgcn_s_setprio(1); _Pragma("unroll") for (int m = 0; m < 4; ++m) _Pragma("unroll") for (int n = 0; n < 2; ++n) _Pragma("unroll") for (int k = 0; k < 2; ++k) \
;         acc[ai][bj][m][n] = __builtin_amdgcn_mfma_f32_16x16x32_bf16(Bt[n][k], At[m][k], acc[ai][bj][m][n], 0, 0, 0); __builtin_amdgcn_s_setprio(0); } while (0)
; #define PG8_WAIT_V(n) asm volatile("s_waitcnt vmcnt(" #n ")" ::: "memory")
; #define PG8_WAIT_L(n) asm volatile("s_waitcnt lgkmcnt(" #n ")" ::: "memory")
; #define PG8_BAR __builtin_amdgcn_s_barrier()
; #define PG8_SCHED __builtin_amdgcn_sched_barrier(0)
; template <class Epi>
; DEVINL void gemm_phase(LAS unsigned char* lds, const Gemm g, const Order& S, const Epi& E) {
;     ...
;             PG8_STAGE(PG8_SB(0, 1), b2 + hstepB, voffB);
;             PG8_WAIT_V(6); PG8_BAR; PG8_MMA(1, 1, At, B1); PG8_BAR;
;             PG8_LDB(B0, 1, 0); PG8_SCHED; PG8_LDA(At, 1, 0); PG8_STAGE(PG8_SA(0, 1), a2 + hstepA, voffA);
;             PG8_WAIT_L(8); PG8_BAR; PG8_WAIT_L(0); PG8_MMA(0, 0, At, B0); PG8_BAR; PG8_SCHED;
;             PG8_LDB(B1, 1, 1); PG8_STAGE(PG8_SB(1, 0), b3, voffB);
	s_add_u32 s72, s48, 0x10000
	s_addc_u32 s73, s49, 0
	s_add_i32 s71, s66, s30
	v_lshl_add_u64 v[150:151], s[72:73], 0, v[130:131]
	s_mov_b32 m0, s71
	s_nop 0
	global_load_lds_dwordx4 v[150:151], off
	v_lshl_add_u64 v[150:151], s[72:73], 0, v[134:135]
	s_add_i32 m0, s71, 0x2000
	s_nop 0
	global_load_lds_dwordx4 v[150:151], off
	s_waitcnt vmcnt(6)
	s_barrier
	s_setprio 1
	v_mfma_f32_16x16x32_bf16 v[28:31], v[198:201], v[166:169], v[28:31]
	v_mfma_f32_16x16x32_bf16 v[28:31], v[202:205], v[170:173], v[28:31]
	v_mfma_f32_16x16x32_bf16 v[24:27], v[206:209], v[166:169], v[24:27]
	v_mfma_f32_16x16x32_bf16 v[24:27], v[210:213], v[170:173], v[24:27]
	v_mfma_f32_16x16x32_bf16 v[16:19], v[206:209], v[174:177], v[16:19]
	v_mfma_f32_16x16x32_bf16 v[16:19], v[210:213], v[178:181], v[16:19]
	v_mfma_f32_16x16x32_bf16 v[20:23], v[198:201], v[174:177], v[20:23]
	v_mfma_f32_16x16x32_bf16 v[20:23], v[202:205], v[178:181], v[20:23]
	v_mfma_f32_16x16x32_bf16 v[12:15], v[198:201], v[182:185], v[12:15]
	v_mfma_f32_16x16x32_bf16 v[12:15], v[202:205], v[186:189], v[12:15]
	v_mfma_f32_16x16x32_bf16 v[8:11], v[206:209], v[182:185], v[8:11]
	v_mfma_f32_16x16x32_bf16 v[8:11], v[210:213], v[186:189], v[8:11]
	v_mfma_f32_16x16x32_bf16 v[0:3], v[206:209], v[190:193], v[0:3]
	v_mfma_f32_16x16x32_bf16 v[0:3], v[210:213], v[194:197], v[0:3]
	v_mfma_f32_16x16x32_bf16 v[4:7], v[198:201], v[190:193], v[4:7]
	v_mfma_f32_16x16x32_bf16 v[4:7], v[202:205], v[194:197], v[4:7]
	s_setprio 0
	s_add_i32 s71, 16, 0x18000
	v_add_u32_e32 v162, s71, v145
	s_barrier
	ds_read_b128 v[150:153], v162
	ds_read_b128 v[154:157], v162 offset:1024
	ds_read_b128 v[158:161], v162 offset:2048
	ds_read_b128 v[162:165], v162 offset:3072
	s_add_u32 s50, s50, 0x10000
	s_addc_u32 s51, s51, 0
	s_mov_b32 m0, s52
	v_lshl_add_u64 v[198:199], s[50:51], 0, v[128:129]
	ds_read_b128 v[166:169], v148 offset:32768
	ds_read_b128 v[170:173], v148 offset:33792
	ds_read_b128 v[174:177], v148 offset:34816
	ds_read_b128 v[178:181], v148 offset:35840
	ds_read_b128 v[182:185], v148 offset:36864
	ds_read_b128 v[186:189], v148 offset:37888
	ds_read_b128 v[190:193], v148 offset:38912
	ds_read_b128 v[194:197], v148 offset:39936
	global_load_lds_dwordx4 v[198:199], off
	v_lshl_add_u64 v[198:199], s[50:51], 0, v[132:133]
	s_mov_b32 m0, s53
	s_nop 0
	global_load_lds_dwordx4 v[198:199], off
	s_waitcnt lgkmcnt(8)
	s_barrier
	s_waitcnt lgkmcnt(0)
	s_setprio 1
	s_waitcnt lgkmcnt(0)
	v_mfma_f32_16x16x32_bf16 v[124:127], v[150:153], v[166:169], v[124:127]
	v_mfma_f32_16x16x32_bf16 v[124:127], v[154:157], v[170:173], v[124:127]
	v_mfma_f32_16x16x32_bf16 v[120:123], v[158:161], v[166:169], v[120:123]
	v_mfma_f32_16x16x32_bf16 v[120:123], v[162:165], v[170:173], v[120:123]
	v_mfma_f32_16x16x32_bf16 v[112:115], v[158:161], v[174:177], v[112:115]
	v_mfma_f32_16x16x32_bf16 v[112:115], v[162:165], v[178:181], v[112:115]
	v_mfma_f32_16x16x32_bf16 v[116:119], v[150:153], v[174:177], v[116:119]
	v_mfma_f32_16x16x32_bf16 v[116:119], v[154:157], v[178:181], v[116:119]
	v_mfma_f32_16x16x32_bf16 v[108:111], v[150:153], v[182:185], v[108:111]
	v_mfma_f32_16x16x32_bf16 v[108:111], v[154:157], v[186:189], v[108:111]
	v_mfma_f32_16x16x32_bf16 v[104:107], v[158:161], v[182:185], v[104:107]
	v_mfma_f32_16x16x32_bf16 v[104:107], v[162:165], v[186:189], v[104:107]
	v_mfma_f32_16x16x32_bf16 v[96:99], v[158:161], v[190:193], v[96:99]
	v_mfma_f32_16x16x32_bf16 v[96:99], v[162:165], v[194:197], v[96:99]
	v_mfma_f32_16x16x32_bf16 v[100:103], v[150:153], v[190:193], v[100:103]
	v_mfma_f32_16x16x32_bf16 v[100:103], v[154:157], v[194:197], v[100:103]
	s_setprio 0
	s_barrier
	s_add_i32 s50, 16, 0x1c000
	s_add_i32 s51, s71, s30
	v_add_u32_e32 v210, s50, v145
	v_lshl_add_u64 v[218:219], v[218:219], 0, s[6:7]
	s_mov_b32 m0, s51
	ds_read_b128 v[198:201], v210
	ds_read_b128 v[202:205], v210 offset:1024
	ds_read_b128 v[206:209], v210 offset:2048
	ds_read_b128 v[210:213], v210 offset:3072
	global_load_lds_dwordx4 v[218:219], off
	v_lshl_add_u64 v[218:219], v[220:221], 0, s[6:7]
	s_add_i32 m0, s51, 0x2000
	s_nop 0
	global_load_lds_dwordx4 v[218:219], off
	s_barrier
; #define PG8_STAGE(bufoff, gbase, voff) do { _Pragma("unroll") for (int _i = 0; _i < 2; ++_i) \
;         __builtin_amdgcn_global_load_lds((const unsigned*)((const char*)(gbase) + (voff)[_i]), (LAS unsigned*)(lds + (bufoff) + ldsw + _i * 8192), 16, 0, 0); } while (0)
; #define PG8_LDA(dst, b, h) do { _Pragma("unroll") for (int m = 0; m < 4; ++m) _Pragma("unroll") for (int k = 0; k < 2; ++k) dst[m][k] = *(const LAS bf16x8*)(lds + PG8_SA(b, h) + aoff + m * 2048 + k * 1024); } while (0)
; #define PG8_MMA(ai, bj, At, Bt) do { __builtin_amdgcn_s_setprio(1); _Pragma("unroll") for (int m = 0; m < 4; ++m) _Pragma("unroll") for (int n = 0; n < 2; ++n) _Pragma("unroll") for (int k = 0; k < 2; ++k) \
;         acc[ai][bj][m][n] = __builtin_amdgcn_mfma_f32_16x16x32_bf16(Bt[n][k], At[m][k], acc[ai][bj][m][n], 0, 0, 0); __builtin_amdgcn_s_setprio(0); } while (0)
; #define PG8_WAIT_V(n) asm volatile("s_waitcnt vmcnt(" #n ")" ::: "memory")
; #define PG8_WAIT_L(n) asm volatile("s_waitcnt lgkmcnt(" #n ")" ::: "memory")
; #define PG8_BAR __builtin_amdgcn_s_barrier()
; #define PG8_SCHED __builtin_amdgcn_sched_barrier(0)
; template <class Epi>
; DEVINL void gemm_phase(LAS unsigned char* lds, const Gemm g, const Order& S, const Epi& E) {
;     ...
;             PG8_BAR; PG8_WAIT_L(0); PG8_MMA(0, 1, At, B1); PG8_BAR;
;             PG8_LDA(At, 1, 1); PG8_STAGE(PG8_SA(1, 0), a3, voffA);
;             PG8_BAR; PG8_WAIT_L(0); PG8_MMA(1, 0, At, B0); PG8_BAR; PG8_SCHED;
;             PG8_STAGE(PG8_SB(1, 1), b3 + hstepB, voffB);
;             PG8_WAIT_V(6); PG8_BAR; PG8_MMA(1, 1, At, B1); PG8_BAR;
	s_waitcnt lgkmcnt(0)
	s_setprio 1
	s_waitcnt lgkmcnt(0)
	v_mfma_f32_16x16x32_bf16 v[60:63], v[198:201], v[166:169], v[60:63]
	v_mfma_f32_16x16x32_bf16 v[60:63], v[202:205], v[170:173], v[60:63]
	v_mfma_f32_16x16x32_bf16 v[56:59], v[206:209], v[166:169], v[56:59]
	v_mfma_f32_16x16x32_bf16 v[56:59], v[210:213], v[170:173], v[56:59]
	v_mfma_f32_16x16x32_bf16 v[48:51], v[206:209], v[174:177], v[48:51]
	v_mfma_f32_16x16x32_bf16 v[48:51], v[210:213], v[178:181], v[48:51]
	v_mfma_f32_16x16x32_bf16 v[52:55], v[198:201], v[174:177], v[52:55]
	v_mfma_f32_16x16x32_bf16 v[52:55], v[202:205], v[178:181], v[52:55]
	v_mfma_f32_16x16x32_bf16 v[44:47], v[198:201], v[182:185], v[44:47]
	v_mfma_f32_16x16x32_bf16 v[44:47], v[202:205], v[186:189], v[44:47]
	v_mfma_f32_16x16x32_bf16 v[40:43], v[206:209], v[182:185], v[40:43]
	v_mfma_f32_16x16x32_bf16 v[40:43], v[210:213], v[186:189], v[40:43]
	v_mfma_f32_16x16x32_bf16 v[32:35], v[206:209], v[190:193], v[32:35]
	v_mfma_f32_16x16x32_bf16 v[32:35], v[210:213], v[194:197], v[32:35]
	v_mfma_f32_16x16x32_bf16 v[36:39], v[198:201], v[190:193], v[36:39]
	v_mfma_f32_16x16x32_bf16 v[36:39], v[202:205], v[194:197], v[36:39]
	s_setprio 0
	s_mov_b32 m0, s55
	v_lshl_add_u64 v[218:219], v[222:223], 0, s[6:7]
	s_barrier
	ds_read_b128 v[166:169], v148 offset:49152
	ds_read_b128 v[170:173], v148 offset:50176
	ds_read_b128 v[174:177], v148 offset:51200
	ds_read_b128 v[178:181], v148 offset:52224
	ds_read_b128 v[182:185], v148 offset:53248
	ds_read_b128 v[186:189], v148 offset:54272
	ds_read_b128 v[190:193], v148 offset:55296
	ds_read_b128 v[194:197], v148 offset:56320
	global_load_lds_dwordx4 v[218:219], off
	v_lshl_add_u64 v[218:219], v[224:225], 0, s[6:7]
	s_mov_b32 m0, s56
	s_nop 0
	global_load_lds_dwordx4 v[218:219], off
	s_barrier
	s_waitcnt lgkmcnt(0)
	s_setprio 1
	s_waitcnt lgkmcnt(0)
	v_mfma_f32_16x16x32_bf16 v[92:95], v[150:153], v[166:169], v[92:95]
	v_mfma_f32_16x16x32_bf16 v[92:95], v[154:157], v[170:173], v[92:95]
	v_mfma_f32_16x16x32_bf16 v[88:91], v[158:161], v[166:169], v[88:91]
	v_mfma_f32_16x16x32_bf16 v[88:91], v[162:165], v[170:173], v[88:91]
	v_mfma_f32_16x16x32_bf16 v[80:83], v[158:161], v[174:177], v[80:83]
	v_mfma_f32_16x16x32_bf16 v[80:83], v[162:165], v[178:181], v[80:83]
	v_mfma_f32_16x16x32_bf16 v[84:87], v[150:153], v[174:177], v[84:87]
	v_mfma_f32_16x16x32_bf16 v[84:87], v[154:157], v[178:181], v[84:87]
	v_mfma_f32_16x16x32_bf16 v[76:79], v[150:153], v[182:185], v[76:79]
	v_mfma_f32_16x16x32_bf16 v[76:79], v[154:157], v[186:189], v[76:79]
	v_mfma_f32_16x16x32_bf16 v[72:75], v[158:161], v[182:185], v[72:75]
	v_mfma_f32_16x16x32_bf16 v[72:75], v[162:165], v[186:189], v[72:75]
	v_mfma_f32_16x16x32_bf16 v[64:67], v[158:161], v[190:193], v[64:67]
	v_mfma_f32_16x16x32_bf16 v[64:67], v[162:165], v[194:197], v[64:67]
	v_mfma_f32_16x16x32_bf16 v[68:71], v[150:153], v[190:193], v[68:71]
	v_mfma_f32_16x16x32_bf16 v[68:71], v[154:157], v[194:197], v[68:71]
	s_setprio 0
	s_barrier
	s_add_u32 s48, s48, 0x10080
	s_addc_u32 s49, s49, 0
	s_add_i32 s50, s50, s30
	v_lshl_add_u64 v[150:151], s[48:49], 0, v[130:131]
	s_mov_b32 m0, s50
	s_nop 0
	global_load_lds_dwordx4 v[150:151], off
	v_lshl_add_u64 v[150:151], s[48:49], 0, v[134:135]
	s_add_i32 m0, s50, 0x2000
	s_nop 0
	global_load_lds_dwordx4 v[150:151], off
	s_waitcnt vmcnt(6)
	s_barrier
	s_setprio 1
	v_mfma_f32_16x16x32_bf16 v[28:31], v[198:201], v[166:169], v[28:31]
	v_mfma_f32_16x16x32_bf16 v[28:31], v[202:205], v[170:173], v[28:31]
	v_mfma_f32_16x16x32_bf16 v[24:27], v[206:209], v[166:169], v[24:27]
	v_mfma_f32_16x16x32_bf16 v[24:27], v[210:213], v[170:173], v[24:27]
	v_mfma_f32_16x16x32_bf16 v[16:19], v[206:209], v[174:177], v[16:19]
	v_mfma_f32_16x16x32_bf16 v[16:19], v[210:213], v[178:181], v[16:19]
	v_mfma_f32_16x16x32_bf16 v[20:23], v[198:201], v[174:177], v[20:23]
	v_mfma_f32_16x16x32_bf16 v[20:23], v[202:205], v[178:181], v[20:23]
	v_mfma_f32_16x16x32_bf16 v[12:15], v[198:201], v[182:185], v[12:15]
	v_mfma_f32_16x16x32_bf16 v[12:15], v[202:205], v[186:189], v[12:15]
	v_mfma_f32_16x16x32_bf16 v[8:11], v[206:209], v[182:185], v[8:11]
	v_mfma_f32_16x16x32_bf16 v[8:11], v[210:213], v[186:189], v[8:11]
	v_mfma_f32_16x16x32_bf16 v[0:3], v[206:209], v[190:193], v[0:3]
	v_mfma_f32_16x16x32_bf16 v[0:3], v[210:213], v[194:197], v[0:3]
	v_mfma_f32_16x16x32_bf16 v[4:7], v[198:201], v[190:193], v[4:7]
	v_mfma_f32_16x16x32_bf16 v[4:7], v[202:205], v[194:197], v[4:7]
	s_setprio 0
	s_add_u32 s4, s4, 0x100
	s_addc_u32 s5, s5, 0
	s_add_u32 s68, s68, 0x100
	s_addc_u32 s69, s69, 0
	s_cmp_ge_i32 s70, s54
	s_mov_b32 s48, s70
	s_barrier
	s_cbranch_scc0 .LBB0_1029
	s_branch .LBB0_1020

; #define PG8_STAGE(bufoff, gbase, voff) do { _Pragma("unroll") for (int _i = 0; _i < 2; ++_i) \
;         __builtin_amdgcn_global_load_lds((const unsigned*)((const char*)(gbase) + (voff)[_i]), (LAS unsigned*)(lds + (bufoff) + ldsw + _i * 8192), 16, 0, 0); } while (0)
; #define PG8_LDA(dst, b, h) do { _Pragma("unroll") for (int m = 0; m < 4; ++m) _Pragma("unroll") for (int k = 0; k < 2; ++k) dst[m][k] = *(const LAS bf16x8*)(lds + PG8_SA(b, h) + aoff + m * 2048 + k * 1024); } while (0)
; #define PG8_LDB(dst, b, h) do { _Pragma("unroll") for (int n = 0; n < 2; ++n) _Pragma("unroll") for (int k = 0; k < 2; ++k) dst[n][k] = *(const LAS bf16x8*)(lds + PG8_SB(b, h) + boff + n * 2048 + k * 1024); } while (0)
; #define PG8_MMA(ai, bj, At, Bt) do { __builtin_amdgcn_s_setprio(1); _Pragma("unroll") for (int m = 0; m < 4; ++m) _Pragma("unroll") for (int n = 0; n < 2; ++n) _Pragma("unroll") for (int k = 0; k < 2; ++k) \
;         acc[ai][bj][m][n] = __builtin_amdgcn_mfma_f32_16x16x32_bf16(Bt[n][k], At[m][k], acc[ai][bj][m][n], 0, 0, 0); __builtin_amdgcn_s_setprio(0); } while (0)
; #define PG8_WAIT_L(n) asm volatile("s_waitcnt lgkmcnt(" #n ")" ::: "memory")
; #define PG8_BAR __builtin_amdgcn_s_barrier()
; #define PG8_SCHED __builtin_amdgcn_sched_barrier(0)
; template <class Epi>
; DEVINL void gemm_phase(LAS unsigned char* lds, const Gemm g, const Order& S, const Epi& E) {
;     ...
;         const char* nA = has_next ? (const char*)g.A + (size_t)nxt.pm * tstepA : cA; const char* nB = has_next ? (const char*)g.Bt + (size_t)nxt.pn * tstepB : cB;
;         for (int t = 0; t < nt; t += 2) {
;             const bool last = (t == nt - 2);
;             const char* a1 = cA + (size_t)(t + 1) * kstep;
;             const char* a2 = last ? nA : cA + (size_t)(t + 2) * kstep; const char* b2 = last ? nB : cB + (size_t)(t + 2) * kstep;
;             const char* a3 = a2 + kstep; const char* b3 = b2 + kstep;
;             PG8_LDB(B0, 0, 0); PG8_SCHED; PG8_LDA(At, 0, 0); PG8_STAGE(PG8_SA(1, 1), a1 + hstepA, voffA);
;             PG8_WAIT_L(8); PG8_BAR; PG8_WAIT_L(0); PG8_MMA(0, 0, At, B0); PG8_BAR; PG8_SCHED;
;             PG8_LDB(B1, 0, 1); PG8_STAGE(PG8_SB(0, 0), b2, voffB);
;             PG8_BAR; PG8_WAIT_L(0); PG8_MMA(0, 1, At, B1); PG8_BAR;
;             PG8_LDA(At, 0, 1); PG8_STAGE(PG8_SA(0, 0), a2, voffA);
;             PG8_BAR; PG8_WAIT_L(0); PG8_MMA(1, 0, At, B0); PG8_BAR; PG8_SCHED;
.LBB0_1186:
	ds_read_b128 v[128:131], v159
	ds_read_b128 v[148:151], v159 offset:1024
	ds_read_b128 v[152:155], v159 offset:2048
	ds_read_b128 v[162:165], v159 offset:3072
	s_add_i32 s66, s30, 2
	s_add_u32 s31, s10, 0xfffc0080
	s_addc_u32 s40, s11, -1
	s_cmp_eq_u32 s53, s30
	s_cselect_b32 s30, s17, s64
	s_cselect_b32 s41, s2, s40
	s_cselect_b32 s40, s3, s31
	s_cselect_b32 s31, s13, s65
	v_lshl_add_u64 v[198:199], s[10:11], 0, v[140:141]
	s_add_i32 m0, s29, 0xc000
	ds_read_b128 v[166:169], v160
	ds_read_b128 v[170:173], v160 offset:1024
	ds_read_b128 v[174:177], v160 offset:2048
	ds_read_b128 v[178:181], v160 offset:3072
	ds_read_b128 v[182:185], v160 offset:4096
	ds_read_b128 v[186:189], v160 offset:5120
	ds_read_b128 v[190:193], v160 offset:6144
	ds_read_b128 v[194:197], v160 offset:7168
	global_load_lds_dwordx4 v[198:199], off
	v_lshl_add_u64 v[198:199], s[10:11], 0, v[142:143]
	s_add_i32 m0, s29, 0xe000
	s_nop 0
	global_load_lds_dwordx4 v[198:199], off
	s_waitcnt lgkmcnt(8)
	s_barrier
	s_waitcnt lgkmcnt(0)
	s_setprio 1
	s_waitcnt lgkmcnt(0)
	v_mfma_f32_16x16x32_bf16 v[124:127], v[128:131], v[166:169], v[124:127]
	v_mfma_f32_16x16x32_bf16 v[124:127], v[148:151], v[170:173], v[124:127]
	v_mfma_f32_16x16x32_bf16 v[120:123], v[152:155], v[166:169], v[120:123]
	v_mfma_f32_16x16x32_bf16 v[120:123], v[162:165], v[170:173], v[120:123]
	v_mfma_f32_16x16x32_bf16 v[104:107], v[152:155], v[174:177], v[104:107]
	v_mfma_f32_16x16x32_bf16 v[104:107], v[162:165], v[178:181], v[104:107]
	v_mfma_f32_16x16x32_bf16 v[108:111], v[128:131], v[174:177], v[108:111]
	v_mfma_f32_16x16x32_bf16 v[108:111], v[148:151], v[178:181], v[108:111]
	v_mfma_f32_16x16x32_bf16 v[92:95], v[128:131], v[182:185], v[92:95]
	v_mfma_f32_16x16x32_bf16 v[92:95], v[148:151], v[186:189], v[92:95]
	v_mfma_f32_16x16x32_bf16 v[88:91], v[152:155], v[182:185], v[88:91]
	v_mfma_f32_16x16x32_bf16 v[88:91], v[162:165], v[186:189], v[88:91]
	v_mfma_f32_16x16x32_bf16 v[72:75], v[152:155], v[190:193], v[72:75]
	v_mfma_f32_16x16x32_bf16 v[72:75], v[162:165], v[194:197], v[72:75]
	v_mfma_f32_16x16x32_bf16 v[76:79], v[128:131], v[190:193], v[76:79]
	v_mfma_f32_16x16x32_bf16 v[76:79], v[148:151], v[194:197], v[76:79]
	s_setprio 0
	s_barrier
	s_add_i32 s67, s57, s46
	v_lshl_add_u64 v[218:219], s[30:31], 0, v[134:135]
	s_mov_b32 m0, s67
	ds_read_b128 v[198:201], v161
	ds_read_b128 v[202:205], v161 offset:1024
	ds_read_b128 v[206:209], v161 offset:2048
	ds_read_b128 v[210:213], v161 offset:3072
	global_load_lds_dwordx4 v[218:219], off
	v_lshl_add_u64 v[220:221], s[30:31], 0, v[138:139]
	s_add_i32 m0, s67, 0x2000
	s_nop 0
	global_load_lds_dwordx4 v[220:221], off
	s_barrier
	s_waitcnt lgkmcnt(0)
	s_setprio 1
	s_waitcnt lgkmcnt(0)
	v_mfma_f32_16x16x32_bf16 v[116:119], v[198:201], v[166:169], v[116:119]
	v_mfma_f32_16x16x32_bf16 v[116:119], v[202:205], v[170:173], v[116:119]
	v_mfma_f32_16x16x32_bf16 v[112:115], v[206:209], v[166:169], v[112:115]
	v_mfma_f32_16x16x32_bf16 v[112:115], v[210:213], v[170:173], v[112:115]
	v_mfma_f32_16x16x32_bf16 v[96:99], v[206:209], v[174:177], v[96:99]
	v_mfma_f32_16x16x32_bf16 v[96:99], v[210:213], v[178:181], v[96:99]
	v_mfma_f32_16x16x32_bf16 v[100:103], v[198:201], v[174:177], v[100:103]
	v_mfma_f32_16x16x32_bf16 v[100:103], v[202:205], v[178:181], v[100:103]
	v_mfma_f32_16x16x32_bf16 v[84:87], v[198:201], v[182:185], v[84:87]
	v_mfma_f32_16x16x32_bf16 v[84:87], v[202:205], v[186:189], v[84:87]
	v_mfma_f32_16x16x32_bf16 v[80:83], v[206:209], v[182:185], v[80:83]
	v_mfma_f32_16x16x32_bf16 v[80:83], v[210:213], v[186:189], v[80:83]
	v_mfma_f32_16x16x32_bf16 v[64:67], v[206:209], v[190:193], v[64:67]
	v_mfma_f32_16x16x32_bf16 v[64:67], v[210:213], v[194:197], v[64:67]
	v_mfma_f32_16x16x32_bf16 v[68:71], v[198:201], v[190:193], v[68:71]
	v_mfma_f32_16x16x32_bf16 v[68:71], v[202:205], v[194:197], v[68:71]
	s_setprio 0
	s_mov_b32 m0, s29
	v_lshl_add_u64 v[222:223], s[40:41], 0, v[132:133]
	s_barrier
	ds_read_b128 v[166:169], v160 offset:16384
	ds_read_b128 v[170:173], v160 offset:17408
	ds_read_b128 v[174:177], v160 offset:18432
	ds_read_b128 v[178:181], v160 offset:19456
	ds_read_b128 v[182:185], v160 offset:20480
	ds_read_b128 v[186:189], v160 offset:21504
	ds_read_b128 v[190:193], v160 offset:22528
	ds_read_b128 v[194:197], v160 offset:23552
	global_load_lds_dwordx4 v[222:223], off
	v_lshl_add_u64 v[224:225], s[40:41], 0, v[136:137]
	s_mov_b32 m0, s47
	s_nop 0
	global_load_lds_dwordx4 v[224:225], off
	s_barrier
	s_waitcnt lgkmcnt(0)
	s_setprio 1
	s_waitcnt lgkmcnt(0)
	v_mfma_f32_16x16x32_bf16 v[60:63], v[128:131], v[166:169], v[60:63]
	v_mfma_f32_16x16x32_bf16 v[60:63], v[148:151], v[170:173], v[60:63]
	v_mfma_f32_16x16x32_bf16 v[56:59], v[152:155], v[166:169], v[56:59]
	v_mfma_f32_16x16x32_bf16 v[56:59], v[162:165], v[170:173], v[56:59]
	v_mfma_f32_16x16x32_bf16 v[40:43], v[152:155], v[174:177], v[40:43]
	v_mfma_f32_16x16x32_bf16 v[40:43], v[162:165], v[178:181], v[40:43]
	v_mfma_f32_16x16x32_bf16 v[44:47], v[128:131], v[174:177], v[44:47]
	v_mfma_f32_16x16x32_bf16 v[44:47], v[148:151], v[178:181], v[44:47]
	v_mfma_f32_16x16x32_bf16 v[28:31], v[128:131], v[182:185], v[28:31]
	v_mfma_f32_16x16x32_bf16 v[28:31], v[148:151], v[186:189], v[28:31]
	v_mfma_f32_16x16x32_bf16 v[24:27], v[152:155], v[182:185], v[24:27]
	v_mfma_f32_16x16x32_bf16 v[24:27], v[162:165], v[186:189], v[24:27]
	v_mfma_f32_16x16x32_bf16 v[8:11], v[152:155], v[190:193], v[8:11]
	v_mfma_f32_16x16x32_bf16 v[8:11], v[162:165], v[194:197], v[8:11]
	v_mfma_f32_16x16x32_bf16 v[12:15], v[128:131], v[190:193], v[12:15]
	v_mfma_f32_16x16x32_bf16 v[12:15], v[148:151], v[194:197], v[12:15]
	s_setprio 0
	s_barrier
; #define PG8_STAGE(bufoff, gbase, voff) do { _Pragma("unroll") for (int _i = 0; _i < 2; ++_i) \
;         __builtin_amdgcn_global_load_lds((const unsigned*)((const char*)(gbase) + (voff)[_i]), (LAS unsigned*)(lds + (bufoff) + ldsw + _i * 8192), 16, 0, 0); } while (0)
; #define PG8_LDA(dst, b, h) do { _Pragma("unroll") for (int m = 0; m < 4; ++m) _Pragma("unroll") for (int k = 0; k < 2; ++k) dst[m][k] = *(const LAS bf16x8*)(lds + PG8_SA(b, h) + aoff + m * 2048 + k * 1024); } while (0)
; #define PG8_LDB(dst, b, h) do { _Pragma("unroll") for (int n = 0; n < 2; ++n) _Pragma("unroll") for (int k = 0; k < 2; ++k) dst[n][k] = *(const LAS bf16x8*)(lds + PG8_SB(b, h) + boff + n * 2048 + k * 1024); } while (0)
; #define PG8_MMA(ai, bj, At, Bt) do { __builtin_amdgcn_s_setprio(1); _Pragma("unroll") for (int m = 0; m < 4; ++m) _Pragma("unroll") for (int n = 0; n < 2; ++n) _Pragma("unroll") for (int k = 0; k < 2; ++k) \
;         acc[ai][bj][m][n] = __builtin_amdgcn_mfma_f32_16x16x32_bf16(Bt[n][k], At[m][k], acc[ai][bj][m][n], 0, 0, 0); __builtin_amdgcn_s_setprio(0); } while (0)
; #define PG8_WAIT_V(n) asm volatile("s_waitcnt vmcnt(" #n ")" ::: "memory")
; #define PG8_WAIT_L(n) asm volatile("s_waitcnt lgkmcnt(" #n ")" ::: "memory")
; #define PG8_BAR __builtin_amdgcn_s_barrier()
; #define PG8_SCHED __builtin_amdgcn_sched_barrier(0)
; template <class Epi>
; DEVINL void gemm_phase(LAS unsigned char* lds, const Gemm g, const Order& S, const Epi& E) {
;     ...
;             PG8_STAGE(PG8_SB(0, 1), b2 + hstepB, voffB);
;             PG8_WAIT_V(6); PG8_BAR; PG8_MMA(1, 1, At, B1); PG8_BAR;
;             PG8_LDB(B0, 1, 0); PG8_SCHED; PG8_LDA(At, 1, 0); PG8_STAGE(PG8_SA(0, 1), a2 + hstepA, voffA);
;             PG8_WAIT_L(8); PG8_BAR; PG8_WAIT_L(0); PG8_MMA(0, 0, At, B0); PG8_BAR; PG8_SCHED;
;             PG8_LDB(B1, 1, 1); PG8_STAGE(PG8_SB(1, 0), b3, voffB);
	s_add_u32 s68, s30, 0x40000
	s_addc_u32 s69, s31, 0
	s_add_i32 s67, s58, s46
	v_lshl_add_u64 v[128:129], s[68:69], 0, v[134:135]
	s_mov_b32 m0, s67
	s_nop 0
	global_load_lds_dwordx4 v[128:129], off
	v_lshl_add_u64 v[128:129], s[68:69], 0, v[138:139]
	s_add_i32 m0, s67, 0x2000
	s_nop 0
	global_load_lds_dwordx4 v[128:129], off
	s_waitcnt vmcnt(6)
	s_barrier
	s_setprio 1
	v_mfma_f32_16x16x32_bf16 v[52:55], v[198:201], v[166:169], v[52:55]
	v_mfma_f32_16x16x32_bf16 v[52:55], v[202:205], v[170:173], v[52:55]
	v_mfma_f32_16x16x32_bf16 v[48:51], v[206:209], v[166:169], v[48:51]
	v_mfma_f32_16x16x32_bf16 v[48:51], v[210:213], v[170:173], v[48:51]
	v_mfma_f32_16x16x32_bf16 v[32:35], v[206:209], v[174:177], v[32:35]
	v_mfma_f32_16x16x32_bf16 v[32:35], v[210:213], v[178:181], v[32:35]
	v_mfma_f32_16x16x32_bf16 v[36:39], v[198:201], v[174:177], v[36:39]
	v_mfma_f32_16x16x32_bf16 v[36:39], v[202:205], v[178:181], v[36:39]
	v_mfma_f32_16x16x32_bf16 v[20:23], v[198:201], v[182:185], v[20:23]
	v_mfma_f32_16x16x32_bf16 v[20:23], v[202:205], v[186:189], v[20:23]
	v_mfma_f32_16x16x32_bf16 v[16:19], v[206:209], v[182:185], v[16:19]
	v_mfma_f32_16x16x32_bf16 v[16:19], v[210:213], v[186:189], v[16:19]
	v_mfma_f32_16x16x32_bf16 v[0:3], v[206:209], v[190:193], v[0:3]
	v_mfma_f32_16x16x32_bf16 v[0:3], v[210:213], v[194:197], v[0:3]
	v_mfma_f32_16x16x32_bf16 v[4:7], v[198:201], v[190:193], v[4:7]
	v_mfma_f32_16x16x32_bf16 v[4:7], v[202:205], v[194:197], v[4:7]
	s_setprio 0
	s_add_i32 s67, 16, 0x18000
	v_add_u32_e32 v162, s67, v157
	s_barrier
	ds_read_b128 v[128:131], v162
	ds_read_b128 v[148:151], v162 offset:1024
	ds_read_b128 v[152:155], v162 offset:2048
	ds_read_b128 v[162:165], v162 offset:3072
	s_add_u32 s40, s40, 0x40000
	s_addc_u32 s41, s41, 0
	s_mov_b32 m0, s48
	v_lshl_add_u64 v[198:199], s[40:41], 0, v[132:133]
	ds_read_b128 v[166:169], v160 offset:32768
	ds_read_b128 v[170:173], v160 offset:33792
	ds_read_b128 v[174:177], v160 offset:34816
	ds_read_b128 v[178:181], v160 offset:35840
	ds_read_b128 v[182:185], v160 offset:36864
	ds_read_b128 v[186:189], v160 offset:37888
	ds_read_b128 v[190:193], v160 offset:38912
	ds_read_b128 v[194:197], v160 offset:39936
	global_load_lds_dwordx4 v[198:199], off
	v_lshl_add_u64 v[198:199], s[40:41], 0, v[136:137]
	s_mov_b32 m0, s49
	s_nop 0
	global_load_lds_dwordx4 v[198:199], off
	s_waitcnt lgkmcnt(8)
	s_barrier
	s_waitcnt lgkmcnt(0)
	s_setprio 1
	s_waitcnt lgkmcnt(0)
	v_mfma_f32_16x16x32_bf16 v[124:127], v[128:131], v[166:169], v[124:127]
	v_mfma_f32_16x16x32_bf16 v[124:127], v[148:151], v[170:173], v[124:127]
	v_mfma_f32_16x16x32_bf16 v[120:123], v[152:155], v[166:169], v[120:123]
	v_mfma_f32_16x16x32_bf16 v[120:123], v[162:165], v[170:173], v[120:123]
	v_mfma_f32_16x16x32_bf16 v[104:107], v[152:155], v[174:177], v[104:107]
	v_mfma_f32_16x16x32_bf16 v[104:107], v[162:165], v[178:181], v[104:107]
	v_mfma_f32_16x16x32_bf16 v[108:111], v[128:131], v[174:177], v[108:111]
	v_mfma_f32_16x16x32_bf16 v[108:111], v[148:151], v[178:181], v[108:111]
	v_mfma_f32_16x16x32_bf16 v[92:95], v[128:131], v[182:185], v[92:95]
	v_mfma_f32_16x16x32_bf16 v[92:95], v[148:151], v[186:189], v[92:95]
	v_mfma_f32_16x16x32_bf16 v[88:91], v[152:155], v[182:185], v[88:91]
	v_mfma_f32_16x16x32_bf16 v[88:91], v[162:165], v[186:189], v[88:91]
	v_mfma_f32_16x16x32_bf16 v[72:75], v[152:155], v[190:193], v[72:75]
	v_mfma_f32_16x16x32_bf16 v[72:75], v[162:165], v[194:197], v[72:75]
	v_mfma_f32_16x16x32_bf16 v[76:79], v[128:131], v[190:193], v[76:79]
	v_mfma_f32_16x16x32_bf16 v[76:79], v[148:151], v[194:197], v[76:79]
	s_setprio 0
	s_barrier
	s_add_i32 s40, 16, 0x1c000
	s_add_i32 s41, s67, s46
	v_add_u32_e32 v210, s40, v157
	v_lshl_add_u64 v[218:219], v[218:219], 0, s[6:7]
	s_mov_b32 m0, s41
	ds_read_b128 v[198:201], v210
	ds_read_b128 v[202:205], v210 offset:1024
	ds_read_b128 v[206:209], v210 offset:2048
	ds_read_b128 v[210:213], v210 offset:3072
	global_load_lds_dwordx4 v[218:219], off
	v_lshl_add_u64 v[218:219], v[220:221], 0, s[6:7]
	s_add_i32 m0, s41, 0x2000
	s_nop 0
	global_load_lds_dwordx4 v[218:219], off
	s_barrier
; #define PG8_STAGE(bufoff, gbase, voff) do { _Pragma("unroll") for (int _i = 0; _i < 2; ++_i) \
;         __builtin_amdgcn_global_load_lds((const unsigned*)((const char*)(gbase) + (voff)[_i]), (LAS unsigned*)(lds + (bufoff) + ldsw + _i * 8192), 16, 0, 0); } while (0)
; #define PG8_LDA(dst, b, h) do { _Pragma("unroll") for (int m = 0; m < 4; ++m) _Pragma("unroll") for (int k = 0; k < 2; ++k) dst[m][k] = *(const LAS bf16x8*)(lds + PG8_SA(b, h) + aoff + m * 2048 + k * 1024); } while (0)
; #define PG8_MMA(ai, bj, At, Bt) do { __builtin_amdgcn_s_setprio(1); _Pragma("unroll") for (int m = 0; m < 4; ++m) _Pragma("unroll") for (int n = 0; n < 2; ++n) _Pragma("unroll") for (int k = 0; k < 2; ++k) \
;         acc[ai][bj][m][n] = __builtin_amdgcn_mfma_f32_16x16x32_bf16(Bt[n][k], At[m][k], acc[ai][bj][m][n], 0, 0, 0); __builtin_amdgcn_s_setprio(0); } while (0)
; #define PG8_WAIT_V(n) asm volatile("s_waitcnt vmcnt(" #n ")" ::: "memory")
; #define PG8_WAIT_L(n) asm volatile("s_waitcnt lgkmcnt(" #n ")" ::: "memory")
; #define PG8_BAR __builtin_amdgcn_s_barrier()
; #define PG8_SCHED __builtin_amdgcn_sched_barrier(0)
; template <class Epi>
; DEVINL void gemm_phase(LAS unsigned char* lds, const Gemm g, const Order& S, const Epi& E) {
;     ...
;             PG8_BAR; PG8_WAIT_L(0); PG8_MMA(0, 1, At, B1); PG8_BAR;
;             PG8_LDA(At, 1, 1); PG8_STAGE(PG8_SA(1, 0), a3, voffA);
;             PG8_BAR; PG8_WAIT_L(0); PG8_MMA(1, 0, At, B0); PG8_BAR; PG8_SCHED;
;             PG8_STAGE(PG8_SB(1, 1), b3 + hstepB, voffB);
;             PG8_WAIT_V(6); PG8_BAR; PG8_MMA(1, 1, At, B1); PG8_BAR;
	s_waitcnt lgkmcnt(0)
	s_setprio 1
	s_waitcnt lgkmcnt(0)
	v_mfma_f32_16x16x32_bf16 v[116:119], v[198:201], v[166:169], v[116:119]
	v_mfma_f32_16x16x32_bf16 v[116:119], v[202:205], v[170:173], v[116:119]
	v_mfma_f32_16x16x32_bf16 v[112:115], v[206:209], v[166:169], v[112:115]
	v_mfma_f32_16x16x32_bf16 v[112:115], v[210:213], v[170:173], v[112:115]
	v_mfma_f32_16x16x32_bf16 v[96:99], v[206:209], v[174:177], v[96:99]
	v_mfma_f32_16x16x32_bf16 v[96:99], v[210:213], v[178:181], v[96:99]
	v_mfma_f32_16x16x32_bf16 v[100:103], v[198:201], v[174:177], v[100:103]
	v_mfma_f32_16x16x32_bf16 v[100:103], v[202:205], v[178:181], v[100:103]
	v_mfma_f32_16x16x32_bf16 v[84:87], v[198:201], v[182:185], v[84:87]
	v_mfma_f32_16x16x32_bf16 v[84:87], v[202:205], v[186:189], v[84:87]
	v_mfma_f32_16x16x32_bf16 v[80:83], v[206:209], v[182:185], v[80:83]
	v_mfma_f32_16x16x32_bf16 v[80:83], v[210:213], v[186:189], v[80:83]
	v_mfma_f32_16x16x32_bf16 v[64:67], v[206:209], v[190:193], v[64:67]
	v_mfma_f32_16x16x32_bf16 v[64:67], v[210:213], v[194:197], v[64:67]
	v_mfma_f32_16x16x32_bf16 v[68:71], v[198:201], v[190:193], v[68:71]
	v_mfma_f32_16x16x32_bf16 v[68:71], v[202:205], v[194:197], v[68:71]
	s_setprio 0
	s_mov_b32 m0, s51
	v_lshl_add_u64 v[218:219], v[222:223], 0, s[6:7]
	s_barrier
	ds_read_b128 v[166:169], v160 offset:49152
	ds_read_b128 v[170:173], v160 offset:50176
	ds_read_b128 v[174:177], v160 offset:51200
	ds_read_b128 v[178:181], v160 offset:52224
	ds_read_b128 v[182:185], v160 offset:53248
	ds_read_b128 v[186:189], v160 offset:54272
	ds_read_b128 v[190:193], v160 offset:55296
	ds_read_b128 v[194:197], v160 offset:56320
	global_load_lds_dwordx4 v[218:219], off
	v_lshl_add_u64 v[218:219], v[224:225], 0, s[6:7]
	s_mov_b32 m0, s52
	s_nop 0
	global_load_lds_dwordx4 v[218:219], off
	s_barrier
	s_waitcnt lgkmcnt(0)
	s_setprio 1
	s_waitcnt lgkmcnt(0)
	v_mfma_f32_16x16x32_bf16 v[60:63], v[128:131], v[166:169], v[60:63]
	v_mfma_f32_16x16x32_bf16 v[60:63], v[148:151], v[170:173], v[60:63]
	v_mfma_f32_16x16x32_bf16 v[56:59], v[152:155], v[166:169], v[56:59]
	v_mfma_f32_16x16x32_bf16 v[56:59], v[162:165], v[170:173], v[56:59]
	v_mfma_f32_16x16x32_bf16 v[40:43], v[152:155], v[174:177], v[40:43]
	v_mfma_f32_16x16x32_bf16 v[40:43], v[162:165], v[178:181], v[40:43]
	v_mfma_f32_16x16x32_bf16 v[44:47], v[128:131], v[174:177], v[44:47]
	v_mfma_f32_16x16x32_bf16 v[44:47], v[148:151], v[178:181], v[44:47]
	v_mfma_f32_16x16x32_bf16 v[28:31], v[128:131], v[182:185], v[28:31]
	v_mfma_f32_16x16x32_bf16 v[28:31], v[148:151], v[186:189], v[28:31]
	v_mfma_f32_16x16x32_bf16 v[24:27], v[152:155], v[182:185], v[24:27]
	v_mfma_f32_16x16x32_bf16 v[24:27], v[162:165], v[186:189], v[24:27]
	v_mfma_f32_16x16x32_bf16 v[8:11], v[152:155], v[190:193], v[8:11]
	v_mfma_f32_16x16x32_bf16 v[8:11], v[162:165], v[194:197], v[8:11]
	v_mfma_f32_16x16x32_bf16 v[12:15], v[128:131], v[190:193], v[12:15]
	v_mfma_f32_16x16x32_bf16 v[12:15], v[148:151], v[194:197], v[12:15]
	s_setprio 0
	s_barrier
	s_add_u32 s30, s30, 0x40080
	s_addc_u32 s31, s31, 0
	s_add_i32 s40, s40, s46
	v_lshl_add_u64 v[128:129], s[30:31], 0, v[134:135]
	s_mov_b32 m0, s40
	s_nop 0
	global_load_lds_dwordx4 v[128:129], off
	v_lshl_add_u64 v[128:129], s[30:31], 0, v[138:139]
	s_add_i32 m0, s40, 0x2000
	s_nop 0
	global_load_lds_dwordx4 v[128:129], off
	s_waitcnt vmcnt(6)
	s_barrier
	s_setprio 1
	v_mfma_f32_16x16x32_bf16 v[52:55], v[198:201], v[166:169], v[52:55]
	v_mfma_f32_16x16x32_bf16 v[52:55], v[202:205], v[170:173], v[52:55]
	v_mfma_f32_16x16x32_bf16 v[48:51], v[206:209], v[166:169], v[48:51]
	v_mfma_f32_16x16x32_bf16 v[48:51], v[210:213], v[170:173], v[48:51]
	v_mfma_f32_16x16x32_bf16 v[32:35], v[206:209], v[174:177], v[32:35]
	v_mfma_f32_16x16x32_bf16 v[32:35], v[210:213], v[178:181], v[32:35]
	v_mfma_f32_16x16x32_bf16 v[36:39], v[198:201], v[174:177], v[36:39]
	v_mfma_f32_16x16x32_bf16 v[36:39], v[202:205], v[178:181], v[36:39]
	v_mfma_f32_16x16x32_bf16 v[20:23], v[198:201], v[182:185], v[20:23]
	v_mfma_f32_16x16x32_bf16 v[20:23], v[202:205], v[186:189], v[20:23]
	v_mfma_f32_16x16x32_bf16 v[16:19], v[206:209], v[182:185], v[16:19]
	v_mfma_f32_16x16x32_bf16 v[16:19], v[210:213], v[186:189], v[16:19]
	v_mfma_f32_16x16x32_bf16 v[0:3], v[206:209], v[190:193], v[0:3]
	v_mfma_f32_16x16x32_bf16 v[0:3], v[210:213], v[194:197], v[0:3]
	v_mfma_f32_16x16x32_bf16 v[4:7], v[198:201], v[190:193], v[4:7]
	v_mfma_f32_16x16x32_bf16 v[4:7], v[202:205], v[194:197], v[4:7]
	s_setprio 0
	s_add_u32 s10, s10, 0x100
	s_addc_u32 s11, s11, 0
	s_add_u32 s64, s64, 0x100
	s_addc_u32 s65, s65, 0
	s_cmp_ge_i32 s66, s50
	s_mov_b32 s30, s66
	s_barrier
	s_cbranch_scc0 .LBB0_1186
	s_branch .LBB0_1177

; #define PG8_STAGE(bufoff, gbase, voff) do { _Pragma("unroll") for (int _i = 0; _i < 2; ++_i) \
;         __builtin_amdgcn_global_load_lds((const unsigned*)((const char*)(gbase) + (voff)[_i]), (LAS unsigned*)(lds + (bufoff) + ldsw + _i * 8192), 16, 0, 0); } while (0)
; #define PG8_LDA(dst, b, h) do { _Pragma("unroll") for (int m = 0; m < 4; ++m) _Pragma("unroll") for (int k = 0; k < 2; ++k) dst[m][k] = *(const LAS bf16x8*)(lds + PG8_SA(b, h) + aoff + m * 2048 + k * 1024); } while (0)
; #define PG8_LDB(dst, b, h) do { _Pragma("unroll") for (int n = 0; n < 2; ++n) _Pragma("unroll") for (int k = 0; k < 2; ++k) dst[n][k] = *(const LAS bf16x8*)(lds + PG8_SB(b, h) + boff + n * 2048 + k * 1024); } while (0)
; #define PG8_MMA(ai, bj, At, Bt) do { __builtin_amdgcn_s_setprio(1); _Pragma("unroll") for (int m = 0; m < 4; ++m) _Pragma("unroll") for (int n = 0; n < 2; ++n) _Pragma("unroll") for (int k = 0; k < 2; ++k) \
;         acc[ai][bj][m][n] = __builtin_amdgcn_mfma_f32_16x16x32_bf16(Bt[n][k], At[m][k], acc[ai][bj][m][n], 0, 0, 0); __builtin_amdgcn_s_setprio(0); } while (0)
; #define PG8_WAIT_L(n) asm volatile("s_waitcnt lgkmcnt(" #n ")" ::: "memory")
; #define PG8_BAR __builtin_amdgcn_s_barrier()
; #define PG8_SCHED __builtin_amdgcn_sched_barrier(0)
; template <class Epi>
; DEVINL void gemm_phase(LAS unsigned char* lds, const Gemm g, const Order& S, const Epi& E) {
;     ...
;             PG8_LDB(B0, 0, 0); PG8_SCHED; PG8_LDA(At, 0, 0); PG8_STAGE(PG8_SA(1, 1), a1 + hstepA, voffA);
;             PG8_WAIT_L(8); PG8_BAR; PG8_WAIT_L(0); PG8_MMA(0, 0, At, B0); PG8_BAR; PG8_SCHED;
;             PG8_LDB(B1, 0, 1); PG8_STAGE(PG8_SB(0, 0), b2, voffB);
;             PG8_BAR; PG8_WAIT_L(0); PG8_MMA(0, 1, At, B1); PG8_BAR;
;             PG8_LDA(At, 0, 1); PG8_STAGE(PG8_SA(0, 0), a2, voffA);
;             PG8_BAR; PG8_WAIT_L(0); PG8_MMA(1, 0, At, B0); PG8_BAR; PG8_SCHED;
.LBB0_1259:
	ds_read_b128 v[128:131], v183
	ds_read_b128 v[132:135], v183 offset:1024
	ds_read_b128 v[136:139], v183 offset:2048
	ds_read_b128 v[140:143], v183 offset:3072
	s_add_i32 s68, s40, 2
	s_add_u32 s41, s8, 0xfffc0080
	s_addc_u32 s42, s9, -1
	s_cmp_eq_u32 s55, s40
	s_cselect_b32 s40, s25, s66
	s_cselect_b32 s43, s2, s42
	s_cselect_b32 s42, s3, s41
	s_cselect_b32 s41, s17, s67
	v_lshl_add_u64 v[198:199], s[8:9], 0, v[160:161]
	s_add_i32 m0, s31, 0xc000
	ds_read_b128 v[144:147], v184
	ds_read_b128 v[148:151], v184 offset:1024
	ds_read_b128 v[168:171], v184 offset:2048
	ds_read_b128 v[172:175], v184 offset:3072
	ds_read_b128 v[176:179], v184 offset:4096
	ds_read_b128 v[186:189], v184 offset:5120
	ds_read_b128 v[190:193], v184 offset:6144
	ds_read_b128 v[194:197], v184 offset:7168
	global_load_lds_dwordx4 v[198:199], off
	v_lshl_add_u64 v[198:199], s[8:9], 0, v[162:163]
	s_add_i32 m0, s31, 0xe000
	s_nop 0
	global_load_lds_dwordx4 v[198:199], off
	s_waitcnt lgkmcnt(8)
	s_barrier
	s_waitcnt lgkmcnt(0)
	s_setprio 1
	s_waitcnt lgkmcnt(0)
	v_mfma_f32_16x16x32_bf16 v[116:119], v[128:131], v[144:147], v[116:119]
	v_mfma_f32_16x16x32_bf16 v[116:119], v[132:135], v[148:151], v[116:119]
	v_mfma_f32_16x16x32_bf16 v[124:127], v[136:139], v[144:147], v[124:127]
	v_mfma_f32_16x16x32_bf16 v[124:127], v[140:143], v[148:151], v[124:127]
	v_mfma_f32_16x16x32_bf16 v[104:107], v[136:139], v[168:171], v[104:107]
	v_mfma_f32_16x16x32_bf16 v[104:107], v[140:143], v[172:175], v[104:107]
	v_mfma_f32_16x16x32_bf16 v[108:111], v[128:131], v[168:171], v[108:111]
	v_mfma_f32_16x16x32_bf16 v[108:111], v[132:135], v[172:175], v[108:111]
	v_mfma_f32_16x16x32_bf16 v[92:95], v[128:131], v[176:179], v[92:95]
	v_mfma_f32_16x16x32_bf16 v[92:95], v[132:135], v[186:189], v[92:95]
	v_mfma_f32_16x16x32_bf16 v[88:91], v[136:139], v[176:179], v[88:91]
	v_mfma_f32_16x16x32_bf16 v[88:91], v[140:143], v[186:189], v[88:91]
	v_mfma_f32_16x16x32_bf16 v[72:75], v[136:139], v[190:193], v[72:75]
	v_mfma_f32_16x16x32_bf16 v[72:75], v[140:143], v[194:197], v[72:75]
	v_mfma_f32_16x16x32_bf16 v[76:79], v[128:131], v[190:193], v[76:79]
	v_mfma_f32_16x16x32_bf16 v[76:79], v[132:135], v[194:197], v[76:79]
	s_setprio 0
	s_barrier
	s_add_i32 s69, s59, s48
	v_lshl_add_u64 v[218:219], s[40:41], 0, v[154:155]
	s_mov_b32 m0, s69
	ds_read_b128 v[198:201], v185
	ds_read_b128 v[202:205], v185 offset:1024
	ds_read_b128 v[206:209], v185 offset:2048
	ds_read_b128 v[210:213], v185 offset:3072
	global_load_lds_dwordx4 v[218:219], off
	v_lshl_add_u64 v[220:221], s[40:41], 0, v[158:159]
	s_add_i32 m0, s69, 0x2000
	s_nop 0
	global_load_lds_dwordx4 v[220:221], off
	s_barrier
	s_waitcnt lgkmcnt(0)
	s_setprio 1
	s_waitcnt lgkmcnt(0)
	v_mfma_f32_16x16x32_bf16 v[120:123], v[198:201], v[144:147], v[120:123]
	v_mfma_f32_16x16x32_bf16 v[120:123], v[202:205], v[148:151], v[120:123]
	v_mfma_f32_16x16x32_bf16 v[112:115], v[206:209], v[144:147], v[112:115]
	v_mfma_f32_16x16x32_bf16 v[112:115], v[210:213], v[148:151], v[112:115]
	v_mfma_f32_16x16x32_bf16 v[96:99], v[206:209], v[168:171], v[96:99]
	v_mfma_f32_16x16x32_bf16 v[96:99], v[210:213], v[172:175], v[96:99]
	v_mfma_f32_16x16x32_bf16 v[100:103], v[198:201], v[168:171], v[100:103]
	v_mfma_f32_16x16x32_bf16 v[100:103], v[202:205], v[172:175], v[100:103]
	v_mfma_f32_16x16x32_bf16 v[84:87], v[198:201], v[176:179], v[84:87]
	v_mfma_f32_16x16x32_bf16 v[84:87], v[202:205], v[186:189], v[84:87]
	v_mfma_f32_16x16x32_bf16 v[80:83], v[206:209], v[176:179], v[80:83]
	v_mfma_f32_16x16x32_bf16 v[80:83], v[210:213], v[186:189], v[80:83]
	v_mfma_f32_16x16x32_bf16 v[64:67], v[206:209], v[190:193], v[64:67]
	v_mfma_f32_16x16x32_bf16 v[64:67], v[210:213], v[194:197], v[64:67]
	v_mfma_f32_16x16x32_bf16 v[68:71], v[198:201], v[190:193], v[68:71]
	v_mfma_f32_16x16x32_bf16 v[68:71], v[202:205], v[194:197], v[68:71]
	s_setprio 0
	s_mov_b32 m0, s31
	v_lshl_add_u64 v[222:223], s[42:43], 0, v[152:153]
	s_barrier
	ds_read_b128 v[144:147], v184 offset:16384
	ds_read_b128 v[148:151], v184 offset:17408
	ds_read_b128 v[168:171], v184 offset:18432
	ds_read_b128 v[172:175], v184 offset:19456
	ds_read_b128 v[176:179], v184 offset:20480
	ds_read_b128 v[186:189], v184 offset:21504
	ds_read_b128 v[190:193], v184 offset:22528
	ds_read_b128 v[194:197], v184 offset:23552
	global_load_lds_dwordx4 v[222:223], off
	v_lshl_add_u64 v[224:225], s[42:43], 0, v[156:157]
	s_mov_b32 m0, s49
	s_nop 0
	global_load_lds_dwordx4 v[224:225], off
	s_barrier
	s_waitcnt lgkmcnt(0)
	s_setprio 1
	s_waitcnt lgkmcnt(0)
	v_mfma_f32_16x16x32_bf16 v[60:63], v[128:131], v[144:147], v[60:63]
	v_mfma_f32_16x16x32_bf16 v[60:63], v[132:135], v[148:151], v[60:63]
	v_mfma_f32_16x16x32_bf16 v[56:59], v[136:139], v[144:147], v[56:59]
	v_mfma_f32_16x16x32_bf16 v[56:59], v[140:143], v[148:151], v[56:59]
	v_mfma_f32_16x16x32_bf16 v[40:43], v[136:139], v[168:171], v[40:43]
	v_mfma_f32_16x16x32_bf16 v[40:43], v[140:143], v[172:175], v[40:43]
	v_mfma_f32_16x16x32_bf16 v[44:47], v[128:131], v[168:171], v[44:47]
	v_mfma_f32_16x16x32_bf16 v[44:47], v[132:135], v[172:175], v[44:47]
	v_mfma_f32_16x16x32_bf16 v[28:31], v[128:131], v[176:179], v[28:31]
	v_mfma_f32_16x16x32_bf16 v[28:31], v[132:135], v[186:189], v[28:31]
	v_mfma_f32_16x16x32_bf16 v[24:27], v[136:139], v[176:179], v[24:27]
	v_mfma_f32_16x16x32_bf16 v[24:27], v[140:143], v[186:189], v[24:27]
	v_mfma_f32_16x16x32_bf16 v[8:11], v[136:139], v[190:193], v[8:11]
	v_mfma_f32_16x16x32_bf16 v[8:11], v[140:143], v[194:197], v[8:11]
	v_mfma_f32_16x16x32_bf16 v[12:15], v[128:131], v[190:193], v[12:15]
	v_mfma_f32_16x16x32_bf16 v[12:15], v[132:135], v[194:197], v[12:15]
	s_setprio 0
	s_barrier
; #define PG8_STAGE(bufoff, gbase, voff) do { _Pragma("unroll") for (int _i = 0; _i < 2; ++_i) \
;         __builtin_amdgcn_global_load_lds((const unsigned*)((const char*)(gbase) + (voff)[_i]), (LAS unsigned*)(lds + (bufoff) + ldsw + _i * 8192), 16, 0, 0); } while (0)
; #define PG8_LDA(dst, b, h) do { _Pragma("unroll") for (int m = 0; m < 4; ++m) _Pragma("unroll") for (int k = 0; k < 2; ++k) dst[m][k] = *(const LAS bf16x8*)(lds + PG8_SA(b, h) + aoff + m * 2048 + k * 1024); } while (0)
; #define PG8_LDB(dst, b, h) do { _Pragma("unroll") for (int n = 0; n < 2; ++n) _Pragma("unroll") for (int k = 0; k < 2; ++k) dst[n][k] = *(const LAS bf16x8*)(lds + PG8_SB(b, h) + boff + n * 2048 + k * 1024); } while (0)
; #define PG8_MMA(ai, bj, At, Bt) do { __builtin_amdgcn_s_setprio(1); _Pragma("unroll") for (int m = 0; m < 4; ++m) _Pragma("unroll") for (int n = 0; n < 2; ++n) _Pragma("unroll") for (int k = 0; k < 2; ++k) \
;         acc[ai][bj][m][n] = __builtin_amdgcn_mfma_f32_16x16x32_bf16(Bt[n][k], At[m][k], acc[ai][bj][m][n], 0, 0, 0); __builtin_amdgcn_s_setprio(0); } while (0)
; #define PG8_WAIT_V(n) asm volatile("s_waitcnt vmcnt(" #n ")" ::: "memory")
; #define PG8_WAIT_L(n) asm volatile("s_waitcnt lgkmcnt(" #n ")" ::: "memory")
; #define PG8_BAR __builtin_amdgcn_s_barrier()
; #define PG8_SCHED __builtin_amdgcn_sched_barrier(0)
; template <class Epi>
; DEVINL void gemm_phase(LAS unsigned char* lds, const Gemm g, const Order& S, const Epi& E) {
;     ...
;             PG8_STAGE(PG8_SB(0, 1), b2 + hstepB, voffB);
;             PG8_WAIT_V(6); PG8_BAR; PG8_MMA(1, 1, At, B1); PG8_BAR;
;             PG8_LDB(B0, 1, 0); PG8_SCHED; PG8_LDA(At, 1, 0); PG8_STAGE(PG8_SA(0, 1), a2 + hstepA, voffA);
;             PG8_WAIT_L(8); PG8_BAR; PG8_WAIT_L(0); PG8_MMA(0, 0, At, B0); PG8_BAR; PG8_SCHED;
;             PG8_LDB(B1, 1, 1); PG8_STAGE(PG8_SB(1, 0), b3, voffB);
	s_add_u32 s70, s40, 0x40000
	s_addc_u32 s71, s41, 0
	s_add_i32 s69, s64, s48
	v_lshl_add_u64 v[128:129], s[70:71], 0, v[154:155]
	s_mov_b32 m0, s69
	s_nop 0
	global_load_lds_dwordx4 v[128:129], off
	v_lshl_add_u64 v[128:129], s[70:71], 0, v[158:159]
	s_add_i32 m0, s69, 0x2000
	s_nop 0
	global_load_lds_dwordx4 v[128:129], off
	s_waitcnt vmcnt(6)
	s_barrier
	s_setprio 1
	v_mfma_f32_16x16x32_bf16 v[52:55], v[198:201], v[144:147], v[52:55]
	v_mfma_f32_16x16x32_bf16 v[52:55], v[202:205], v[148:151], v[52:55]
	v_mfma_f32_16x16x32_bf16 v[48:51], v[206:209], v[144:147], v[48:51]
	v_mfma_f32_16x16x32_bf16 v[48:51], v[210:213], v[148:151], v[48:51]
	v_mfma_f32_16x16x32_bf16 v[32:35], v[206:209], v[168:171], v[32:35]
	v_mfma_f32_16x16x32_bf16 v[32:35], v[210:213], v[172:175], v[32:35]
	v_mfma_f32_16x16x32_bf16 v[36:39], v[198:201], v[168:171], v[36:39]
	v_mfma_f32_16x16x32_bf16 v[36:39], v[202:205], v[172:175], v[36:39]
	v_mfma_f32_16x16x32_bf16 v[20:23], v[198:201], v[176:179], v[20:23]
	v_mfma_f32_16x16x32_bf16 v[20:23], v[202:205], v[186:189], v[20:23]
	v_mfma_f32_16x16x32_bf16 v[16:19], v[206:209], v[176:179], v[16:19]
	v_mfma_f32_16x16x32_bf16 v[16:19], v[210:213], v[186:189], v[16:19]
	v_mfma_f32_16x16x32_bf16 v[0:3], v[206:209], v[190:193], v[0:3]
	v_mfma_f32_16x16x32_bf16 v[0:3], v[210:213], v[194:197], v[0:3]
	v_mfma_f32_16x16x32_bf16 v[4:7], v[198:201], v[190:193], v[4:7]
	v_mfma_f32_16x16x32_bf16 v[4:7], v[202:205], v[194:197], v[4:7]
	s_setprio 0
	s_add_i32 s69, 16, 0x18000
	v_add_u32_e32 v140, s69, v181
	s_barrier
	ds_read_b128 v[128:131], v140
	ds_read_b128 v[132:135], v140 offset:1024
	ds_read_b128 v[136:139], v140 offset:2048
	ds_read_b128 v[140:143], v140 offset:3072
	s_add_u32 s42, s42, 0x40000
	s_addc_u32 s43, s43, 0
	s_mov_b32 m0, s50
	v_lshl_add_u64 v[198:199], s[42:43], 0, v[152:153]
	ds_read_b128 v[144:147], v184 offset:32768
	ds_read_b128 v[148:151], v184 offset:33792
	ds_read_b128 v[168:171], v184 offset:34816
	ds_read_b128 v[172:175], v184 offset:35840
	ds_read_b128 v[176:179], v184 offset:36864
	ds_read_b128 v[186:189], v184 offset:37888
	ds_read_b128 v[190:193], v184 offset:38912
	ds_read_b128 v[194:197], v184 offset:39936
	global_load_lds_dwordx4 v[198:199], off
	v_lshl_add_u64 v[198:199], s[42:43], 0, v[156:157]
	s_mov_b32 m0, s51
	s_nop 0
	global_load_lds_dwordx4 v[198:199], off
	s_waitcnt lgkmcnt(8)
	s_barrier
	s_waitcnt lgkmcnt(0)
	s_setprio 1
	s_waitcnt lgkmcnt(0)
	v_mfma_f32_16x16x32_bf16 v[116:119], v[128:131], v[144:147], v[116:119]
	v_mfma_f32_16x16x32_bf16 v[116:119], v[132:135], v[148:151], v[116:119]
	v_mfma_f32_16x16x32_bf16 v[124:127], v[136:139], v[144:147], v[124:127]
	v_mfma_f32_16x16x32_bf16 v[124:127], v[140:143], v[148:151], v[124:127]
	v_mfma_f32_16x16x32_bf16 v[104:107], v[136:139], v[168:171], v[104:107]
	v_mfma_f32_16x16x32_bf16 v[104:107], v[140:143], v[172:175], v[104:107]
	v_mfma_f32_16x16x32_bf16 v[108:111], v[128:131], v[168:171], v[108:111]
	v_mfma_f32_16x16x32_bf16 v[108:111], v[132:135], v[172:175], v[108:111]
	v_mfma_f32_16x16x32_bf16 v[92:95], v[128:131], v[176:179], v[92:95]
	v_mfma_f32_16x16x32_bf16 v[92:95], v[132:135], v[186:189], v[92:95]
	v_mfma_f32_16x16x32_bf16 v[88:91], v[136:139], v[176:179], v[88:91]
	v_mfma_f32_16x16x32_bf16 v[88:91], v[140:143], v[186:189], v[88:91]
	v_mfma_f32_16x16x32_bf16 v[72:75], v[136:139], v[190:193], v[72:75]
	v_mfma_f32_16x16x32_bf16 v[72:75], v[140:143], v[194:197], v[72:75]
	v_mfma_f32_16x16x32_bf16 v[76:79], v[128:131], v[190:193], v[76:79]
	v_mfma_f32_16x16x32_bf16 v[76:79], v[132:135], v[194:197], v[76:79]
	s_setprio 0
	s_barrier
	s_add_i32 s42, 16, 0x1c000
	s_add_i32 s43, s69, s48
	v_add_u32_e32 v210, s42, v181
	v_lshl_add_u64 v[218:219], v[218:219], 0, s[10:11]
	s_mov_b32 m0, s43
	ds_read_b128 v[198:201], v210
	ds_read_b128 v[202:205], v210 offset:1024
	ds_read_b128 v[206:209], v210 offset:2048
	ds_read_b128 v[210:213], v210 offset:3072
	global_load_lds_dwordx4 v[218:219], off
	v_lshl_add_u64 v[218:219], v[220:221], 0, s[10:11]
	s_add_i32 m0, s43, 0x2000
	s_nop 0
	global_load_lds_dwordx4 v[218:219], off
	s_barrier
; #define PG8_STAGE(bufoff, gbase, voff) do { _Pragma("unroll") for (int _i = 0; _i < 2; ++_i) \
;         __builtin_amdgcn_global_load_lds((const unsigned*)((const char*)(gbase) + (voff)[_i]), (LAS unsigned*)(lds + (bufoff) + ldsw + _i * 8192), 16, 0, 0); } while (0)
; #define PG8_LDA(dst, b, h) do { _Pragma("unroll") for (int m = 0; m < 4; ++m) _Pragma("unroll") for (int k = 0; k < 2; ++k) dst[m][k] = *(const LAS bf16x8*)(lds + PG8_SA(b, h) + aoff + m * 2048 + k * 1024); } while (0)
; #define PG8_MMA(ai, bj, At, Bt) do { __builtin_amdgcn_s_setprio(1); _Pragma("unroll") for (int m = 0; m < 4; ++m) _Pragma("unroll") for (int n = 0; n < 2; ++n) _Pragma("unroll") for (int k = 0; k < 2; ++k) \
;         acc[ai][bj][m][n] = __builtin_amdgcn_mfma_f32_16x16x32_bf16(Bt[n][k], At[m][k], acc[ai][bj][m][n], 0, 0, 0); __builtin_amdgcn_s_setprio(0); } while (0)
; #define PG8_WAIT_V(n) asm volatile("s_waitcnt vmcnt(" #n ")" ::: "memory")
; #define PG8_WAIT_L(n) asm volatile("s_waitcnt lgkmcnt(" #n ")" ::: "memory")
; #define PG8_BAR __builtin_amdgcn_s_barrier()
; #define PG8_SCHED __builtin_amdgcn_sched_barrier(0)
; template <class Epi>
; DEVINL void gemm_phase(LAS unsigned char* lds, const Gemm g, const Order& S, const Epi& E) {
;     ...
;             PG8_BAR; PG8_WAIT_L(0); PG8_MMA(0, 1, At, B1); PG8_BAR;
;             PG8_LDA(At, 1, 1); PG8_STAGE(PG8_SA(1, 0), a3, voffA);
;             PG8_BAR; PG8_WAIT_L(0); PG8_MMA(1, 0, At, B0); PG8_BAR; PG8_SCHED;
;             PG8_STAGE(PG8_SB(1, 1), b3 + hstepB, voffB);
;             PG8_WAIT_V(6); PG8_BAR; PG8_MMA(1, 1, At, B1); PG8_BAR;
	s_waitcnt lgkmcnt(0)
	s_setprio 1
	s_waitcnt lgkmcnt(0)
	v_mfma_f32_16x16x32_bf16 v[120:123], v[198:201], v[144:147], v[120:123]
	v_mfma_f32_16x16x32_bf16 v[120:123], v[202:205], v[148:151], v[120:123]
	v_mfma_f32_16x16x32_bf16 v[112:115], v[206:209], v[144:147], v[112:115]
	v_mfma_f32_16x16x32_bf16 v[112:115], v[210:213], v[148:151], v[112:115]
	v_mfma_f32_16x16x32_bf16 v[96:99], v[206:209], v[168:171], v[96:99]
	v_mfma_f32_16x16x32_bf16 v[96:99], v[210:213], v[172:175], v[96:99]
	v_mfma_f32_16x16x32_bf16 v[100:103], v[198:201], v[168:171], v[100:103]
	v_mfma_f32_16x16x32_bf16 v[100:103], v[202:205], v[172:175], v[100:103]
	v_mfma_f32_16x16x32_bf16 v[84:87], v[198:201], v[176:179], v[84:87]
	v_mfma_f32_16x16x32_bf16 v[84:87], v[202:205], v[186:189], v[84:87]
	v_mfma_f32_16x16x32_bf16 v[80:83], v[206:209], v[176:179], v[80:83]
	v_mfma_f32_16x16x32_bf16 v[80:83], v[210:213], v[186:189], v[80:83]
	v_mfma_f32_16x16x32_bf16 v[64:67], v[206:209], v[190:193], v[64:67]
	v_mfma_f32_16x16x32_bf16 v[64:67], v[210:213], v[194:197], v[64:67]
	v_mfma_f32_16x16x32_bf16 v[68:71], v[198:201], v[190:193], v[68:71]
	v_mfma_f32_16x16x32_bf16 v[68:71], v[202:205], v[194:197], v[68:71]
	s_setprio 0
	s_mov_b32 m0, s53
	v_lshl_add_u64 v[218:219], v[222:223], 0, s[10:11]
	s_barrier
	ds_read_b128 v[144:147], v184 offset:49152
	ds_read_b128 v[148:151], v184 offset:50176
	ds_read_b128 v[168:171], v184 offset:51200
	ds_read_b128 v[172:175], v184 offset:52224
	ds_read_b128 v[176:179], v184 offset:53248
	ds_read_b128 v[186:189], v184 offset:54272
	ds_read_b128 v[190:193], v184 offset:55296
	ds_read_b128 v[194:197], v184 offset:56320
	global_load_lds_dwordx4 v[218:219], off
	v_lshl_add_u64 v[218:219], v[224:225], 0, s[10:11]
	s_mov_b32 m0, s54
	s_nop 0
	global_load_lds_dwordx4 v[218:219], off
	s_barrier
	s_waitcnt lgkmcnt(0)
	s_setprio 1
	s_waitcnt lgkmcnt(0)
	v_mfma_f32_16x16x32_bf16 v[60:63], v[128:131], v[144:147], v[60:63]
	v_mfma_f32_16x16x32_bf16 v[60:63], v[132:135], v[148:151], v[60:63]
	v_mfma_f32_16x16x32_bf16 v[56:59], v[136:139], v[144:147], v[56:59]
	v_mfma_f32_16x16x32_bf16 v[56:59], v[140:143], v[148:151], v[56:59]
	v_mfma_f32_16x16x32_bf16 v[40:43], v[136:139], v[168:171], v[40:43]
	v_mfma_f32_16x16x32_bf16 v[40:43], v[140:143], v[172:175], v[40:43]
	v_mfma_f32_16x16x32_bf16 v[44:47], v[128:131], v[168:171], v[44:47]
	v_mfma_f32_16x16x32_bf16 v[44:47], v[132:135], v[172:175], v[44:47]
	v_mfma_f32_16x16x32_bf16 v[28:31], v[128:131], v[176:179], v[28:31]
	v_mfma_f32_16x16x32_bf16 v[28:31], v[132:135], v[186:189], v[28:31]
	v_mfma_f32_16x16x32_bf16 v[24:27], v[136:139], v[176:179], v[24:27]
	v_mfma_f32_16x16x32_bf16 v[24:27], v[140:143], v[186:189], v[24:27]
	v_mfma_f32_16x16x32_bf16 v[8:11], v[136:139], v[190:193], v[8:11]
	v_mfma_f32_16x16x32_bf16 v[8:11], v[140:143], v[194:197], v[8:11]
	v_mfma_f32_16x16x32_bf16 v[12:15], v[128:131], v[190:193], v[12:15]
	v_mfma_f32_16x16x32_bf16 v[12:15], v[132:135], v[194:197], v[12:15]
	s_setprio 0
	s_barrier
	s_add_u32 s40, s40, 0x40080
	s_addc_u32 s41, s41, 0
	s_add_i32 s42, s42, s48
	v_lshl_add_u64 v[128:129], s[40:41], 0, v[154:155]
	s_mov_b32 m0, s42
	s_nop 0
	global_load_lds_dwordx4 v[128:129], off
	v_lshl_add_u64 v[128:129], s[40:41], 0, v[158:159]
	s_add_i32 m0, s42, 0x2000
	s_nop 0
	global_load_lds_dwordx4 v[128:129], off
	s_waitcnt vmcnt(6)
	s_barrier
	s_setprio 1
	v_mfma_f32_16x16x32_bf16 v[52:55], v[198:201], v[144:147], v[52:55]
	v_mfma_f32_16x16x32_bf16 v[52:55], v[202:205], v[148:151], v[52:55]
	v_mfma_f32_16x16x32_bf16 v[48:51], v[206:209], v[144:147], v[48:51]
	v_mfma_f32_16x16x32_bf16 v[48:51], v[210:213], v[148:151], v[48:51]
	v_mfma_f32_16x16x32_bf16 v[32:35], v[206:209], v[168:171], v[32:35]
	v_mfma_f32_16x16x32_bf16 v[32:35], v[210:213], v[172:175], v[32:35]
	v_mfma_f32_16x16x32_bf16 v[36:39], v[198:201], v[168:171], v[36:39]
	v_mfma_f32_16x16x32_bf16 v[36:39], v[202:205], v[172:175], v[36:39]
	v_mfma_f32_16x16x32_bf16 v[20:23], v[198:201], v[176:179], v[20:23]
	v_mfma_f32_16x16x32_bf16 v[20:23], v[202:205], v[186:189], v[20:23]
	v_mfma_f32_16x16x32_bf16 v[16:19], v[206:209], v[176:179], v[16:19]
	v_mfma_f32_16x16x32_bf16 v[16:19], v[210:213], v[186:189], v[16:19]
	v_mfma_f32_16x16x32_bf16 v[0:3], v[206:209], v[190:193], v[0:3]
	v_mfma_f32_16x16x32_bf16 v[0:3], v[210:213], v[194:197], v[0:3]
	v_mfma_f32_16x16x32_bf16 v[4:7], v[198:201], v[190:193], v[4:7]
	v_mfma_f32_16x16x32_bf16 v[4:7], v[202:205], v[194:197], v[4:7]
	s_setprio 0
	s_add_u32 s8, s8, 0x100
	s_addc_u32 s9, s9, 0
	s_add_u32 s66, s66, 0x100
	s_addc_u32 s67, s67, 0
	s_cmp_ge_i32 s68, s52
	s_mov_b32 s40, s68
	s_barrier
	s_cbranch_scc0 .LBB0_1259
	s_branch .LBB0_1250

; #define PG8_STAGE(bufoff, gbase, voff) do { _Pragma("unroll") for (int _i = 0; _i < 2; ++_i) \
;         __builtin_amdgcn_global_load_lds((const unsigned*)((const char*)(gbase) + (voff)[_i]), (LAS unsigned*)(lds + (bufoff) + ldsw + _i * 8192), 16, 0, 0); } while (0)
; #define PG8_LDA(dst, b, h) do { _Pragma("unroll") for (int m = 0; m < 4; ++m) _Pragma("unroll") for (int k = 0; k < 2; ++k) dst[m][k] = *(const LAS bf16x8*)(lds + PG8_SA(b, h) + aoff + m * 2048 + k * 1024); } while (0)
; #define PG8_LDB(dst, b, h) do { _Pragma("unroll") for (int n = 0; n < 2; ++n) _Pragma("unroll") for (int k = 0; k < 2; ++k) dst[n][k] = *(const LAS bf16x8*)(lds + PG8_SB(b, h) + boff + n * 2048 + k * 1024); } while (0)
; #define PG8_MMA(ai, bj, At, Bt) do { __builtin_amdgcn_s_setprio(1); _Pragma("unroll") for (int m = 0; m < 4; ++m) _Pragma("unroll") for (int n = 0; n < 2; ++n) _Pragma("unroll") for (int k = 0; k < 2; ++k) \
;         acc[ai][bj][m][n] = __builtin_amdgcn_mfma_f32_16x16x32_bf16(Bt[n][k], At[m][k], acc[ai][bj][m][n], 0, 0, 0); __builtin_amdgcn_s_setprio(0); } while (0)
; #define PG8_WAIT_L(n) asm volatile("s_waitcnt lgkmcnt(" #n ")" ::: "memory")
; #define PG8_BAR __builtin_amdgcn_s_barrier()
; #define PG8_SCHED __builtin_amdgcn_sched_barrier(0)
; template <class Epi>
; DEVINL void gemm_phase(LAS unsigned char* lds, const Gemm g, const Order& S, const Epi& E) {
;     ...
;             PG8_LDB(B0, 0, 0); PG8_SCHED; PG8_LDA(At, 0, 0); PG8_STAGE(PG8_SA(1, 1), a1 + hstepA, voffA);
;             PG8_WAIT_L(8); PG8_BAR; PG8_WAIT_L(0); PG8_MMA(0, 0, At, B0); PG8_BAR; PG8_SCHED;
;             PG8_LDB(B1, 0, 1); PG8_STAGE(PG8_SB(0, 0), b2, voffB);
;             PG8_BAR; PG8_WAIT_L(0); PG8_MMA(0, 1, At, B1); PG8_BAR;
;             PG8_LDA(At, 0, 1); PG8_STAGE(PG8_SA(0, 0), a2, voffA);
;             PG8_BAR; PG8_WAIT_L(0); PG8_MMA(1, 0, At, B0); PG8_BAR; PG8_SCHED;
.LBB0_1332:
	ds_read_b128 v[150:153], v147
	ds_read_b128 v[154:157], v147 offset:1024
	ds_read_b128 v[158:161], v147 offset:2048
	ds_read_b128 v[162:165], v147 offset:3072
	s_add_i32 s71, s40, 2
	s_add_u32 s41, s8, 0xfff80080
	s_addc_u32 s42, s9, -1
	s_cmp_eq_u32 s55, s40
	s_cselect_b32 s40, s29, s69
	s_cselect_b32 s43, s2, s42
	s_cselect_b32 s42, s3, s41
	s_cselect_b32 s41, s27, s70
	v_lshl_add_u64 v[198:199], s[8:9], 0, v[136:137]
	s_add_i32 m0, s25, 0xc000
	ds_read_b128 v[166:169], v148
	ds_read_b128 v[170:173], v148 offset:1024
	ds_read_b128 v[174:177], v148 offset:2048
	ds_read_b128 v[178:181], v148 offset:3072
	ds_read_b128 v[182:185], v148 offset:4096
	ds_read_b128 v[186:189], v148 offset:5120
	ds_read_b128 v[190:193], v148 offset:6144
	ds_read_b128 v[194:197], v148 offset:7168
	global_load_lds_dwordx4 v[198:199], off
	v_lshl_add_u64 v[198:199], s[8:9], 0, v[138:139]
	s_add_i32 m0, s25, 0xe000
	s_nop 0
	global_load_lds_dwordx4 v[198:199], off
	s_waitcnt lgkmcnt(8)
	s_barrier
	s_waitcnt lgkmcnt(0)
	s_setprio 1
	s_waitcnt lgkmcnt(0)
	v_mfma_f32_16x16x32_bf16 v[120:123], v[150:153], v[166:169], v[120:123]
	v_mfma_f32_16x16x32_bf16 v[120:123], v[154:157], v[170:173], v[120:123]
	v_mfma_f32_16x16x32_bf16 v[124:127], v[158:161], v[166:169], v[124:127]
	v_mfma_f32_16x16x32_bf16 v[124:127], v[162:165], v[170:173], v[124:127]
	v_mfma_f32_16x16x32_bf16 v[104:107], v[158:161], v[174:177], v[104:107]
	v_mfma_f32_16x16x32_bf16 v[104:107], v[162:165], v[178:181], v[104:107]
	v_mfma_f32_16x16x32_bf16 v[108:111], v[150:153], v[174:177], v[108:111]
	v_mfma_f32_16x16x32_bf16 v[108:111], v[154:157], v[178:181], v[108:111]
	v_mfma_f32_16x16x32_bf16 v[92:95], v[150:153], v[182:185], v[92:95]
	v_mfma_f32_16x16x32_bf16 v[92:95], v[154:157], v[186:189], v[92:95]
	v_mfma_f32_16x16x32_bf16 v[88:91], v[158:161], v[182:185], v[88:91]
	v_mfma_f32_16x16x32_bf16 v[88:91], v[162:165], v[186:189], v[88:91]
	v_mfma_f32_16x16x32_bf16 v[72:75], v[158:161], v[190:193], v[72:75]
	v_mfma_f32_16x16x32_bf16 v[72:75], v[162:165], v[194:197], v[72:75]
	v_mfma_f32_16x16x32_bf16 v[76:79], v[150:153], v[190:193], v[76:79]
	v_mfma_f32_16x16x32_bf16 v[76:79], v[154:157], v[194:197], v[76:79]
	s_setprio 0
	s_barrier
	s_add_i32 s72, s59, s48
	v_lshl_add_u64 v[218:219], s[40:41], 0, v[130:131]
	s_mov_b32 m0, s72
	ds_read_b128 v[198:201], v149
	ds_read_b128 v[202:205], v149 offset:1024
	ds_read_b128 v[206:209], v149 offset:2048
	ds_read_b128 v[210:213], v149 offset:3072
	global_load_lds_dwordx4 v[218:219], off
	v_lshl_add_u64 v[220:221], s[40:41], 0, v[134:135]
	s_add_i32 m0, s72, 0x2000
	s_nop 0
	global_load_lds_dwordx4 v[220:221], off
	s_barrier
	s_waitcnt lgkmcnt(0)
	s_setprio 1
	s_waitcnt lgkmcnt(0)
	v_mfma_f32_16x16x32_bf16 v[116:119], v[198:201], v[166:169], v[116:119]
	v_mfma_f32_16x16x32_bf16 v[116:119], v[202:205], v[170:173], v[116:119]
	v_mfma_f32_16x16x32_bf16 v[112:115], v[206:209], v[166:169], v[112:115]
	v_mfma_f32_16x16x32_bf16 v[112:115], v[210:213], v[170:173], v[112:115]
	v_mfma_f32_16x16x32_bf16 v[96:99], v[206:209], v[174:177], v[96:99]
	v_mfma_f32_16x16x32_bf16 v[96:99], v[210:213], v[178:181], v[96:99]
	v_mfma_f32_16x16x32_bf16 v[100:103], v[198:201], v[174:177], v[100:103]
	v_mfma_f32_16x16x32_bf16 v[100:103], v[202:205], v[178:181], v[100:103]
	v_mfma_f32_16x16x32_bf16 v[84:87], v[198:201], v[182:185], v[84:87]
	v_mfma_f32_16x16x32_bf16 v[84:87], v[202:205], v[186:189], v[84:87]
	v_mfma_f32_16x16x32_bf16 v[80:83], v[206:209], v[182:185], v[80:83]
	v_mfma_f32_16x16x32_bf16 v[80:83], v[210:213], v[186:189], v[80:83]
	v_mfma_f32_16x16x32_bf16 v[64:67], v[206:209], v[190:193], v[64:67]
	v_mfma_f32_16x16x32_bf16 v[64:67], v[210:213], v[194:197], v[64:67]
	v_mfma_f32_16x16x32_bf16 v[68:71], v[198:201], v[190:193], v[68:71]
	v_mfma_f32_16x16x32_bf16 v[68:71], v[202:205], v[194:197], v[68:71]
	s_setprio 0
	s_mov_b32 m0, s25
	v_lshl_add_u64 v[222:223], s[42:43], 0, v[128:129]
	s_barrier
	ds_read_b128 v[166:169], v148 offset:16384
	ds_read_b128 v[170:173], v148 offset:17408
	ds_read_b128 v[174:177], v148 offset:18432
	ds_read_b128 v[178:181], v148 offset:19456
	ds_read_b128 v[182:185], v148 offset:20480
	ds_read_b128 v[186:189], v148 offset:21504
	ds_read_b128 v[190:193], v148 offset:22528
	ds_read_b128 v[194:197], v148 offset:23552
	global_load_lds_dwordx4 v[222:223], off
	v_lshl_add_u64 v[224:225], s[42:43], 0, v[132:133]
	s_mov_b32 m0, s49
	s_nop 0
	global_load_lds_dwordx4 v[224:225], off
	s_barrier
	s_waitcnt lgkmcnt(0)
	s_setprio 1
	s_waitcnt lgkmcnt(0)
	v_mfma_f32_16x16x32_bf16 v[60:63], v[150:153], v[166:169], v[60:63]
	v_mfma_f32_16x16x32_bf16 v[60:63], v[154:157], v[170:173], v[60:63]
	v_mfma_f32_16x16x32_bf16 v[56:59], v[158:161], v[166:169], v[56:59]
	v_mfma_f32_16x16x32_bf16 v[56:59], v[162:165], v[170:173], v[56:59]
	v_mfma_f32_16x16x32_bf16 v[40:43], v[158:161], v[174:177], v[40:43]
	v_mfma_f32_16x16x32_bf16 v[40:43], v[162:165], v[178:181], v[40:43]
	v_mfma_f32_16x16x32_bf16 v[44:47], v[150:153], v[174:177], v[44:47]
	v_mfma_f32_16x16x32_bf16 v[44:47], v[154:157], v[178:181], v[44:47]
	v_mfma_f32_16x16x32_bf16 v[28:31], v[150:153], v[182:185], v[28:31]
	v_mfma_f32_16x16x32_bf16 v[28:31], v[154:157], v[186:189], v[28:31]
	v_mfma_f32_16x16x32_bf16 v[24:27], v[158:161], v[182:185], v[24:27]
	v_mfma_f32_16x16x32_bf16 v[24:27], v[162:165], v[186:189], v[24:27]
	v_mfma_f32_16x16x32_bf16 v[8:11], v[158:161], v[190:193], v[8:11]
	v_mfma_f32_16x16x32_bf16 v[8:11], v[162:165], v[194:197], v[8:11]
	v_mfma_f32_16x16x32_bf16 v[12:15], v[150:153], v[190:193], v[12:15]
	v_mfma_f32_16x16x32_bf16 v[12:15], v[154:157], v[194:197], v[12:15]
	s_setprio 0
	s_barrier
; #define PG8_STAGE(bufoff, gbase, voff) do { _Pragma("unroll") for (int _i = 0; _i < 2; ++_i) \
;         __builtin_amdgcn_global_load_lds((const unsigned*)((const char*)(gbase) + (voff)[_i]), (LAS unsigned*)(lds + (bufoff) + ldsw + _i * 8192), 16, 0, 0); } while (0)
; #define PG8_LDA(dst, b, h) do { _Pragma("unroll") for (int m = 0; m < 4; ++m) _Pragma("unroll") for (int k = 0; k < 2; ++k) dst[m][k] = *(const LAS bf16x8*)(lds + PG8_SA(b, h) + aoff + m * 2048 + k * 1024); } while (0)
; #define PG8_LDB(dst, b, h) do { _Pragma("unroll") for (int n = 0; n < 2; ++n) _Pragma("unroll") for (int k = 0; k < 2; ++k) dst[n][k] = *(const LAS bf16x8*)(lds + PG8_SB(b, h) + boff + n * 2048 + k * 1024); } while (0)
; #define PG8_MMA(ai, bj, At, Bt) do { __builtin_amdgcn_s_setprio(1); _Pragma("unroll") for (int m = 0; m < 4; ++m) _Pragma("unroll") for (int n = 0; n < 2; ++n) _Pragma("unroll") for (int k = 0; k < 2; ++k) \
;         acc[ai][bj][m][n] = __builtin_amdgcn_mfma_f32_16x16x32_bf16(Bt[n][k], At[m][k], acc[ai][bj][m][n], 0, 0, 0); __builtin_amdgcn_s_setprio(0); } while (0)
; #define PG8_WAIT_V(n) asm volatile("s_waitcnt vmcnt(" #n ")" ::: "memory")
; #define PG8_WAIT_L(n) asm volatile("s_waitcnt lgkmcnt(" #n ")" ::: "memory")
; #define PG8_BAR __builtin_amdgcn_s_barrier()
; #define PG8_SCHED __builtin_amdgcn_sched_barrier(0)
; template <class Epi>
; DEVINL void gemm_phase(LAS unsigned char* lds, const Gemm g, const Order& S, const Epi& E) {
;     ...
;             PG8_STAGE(PG8_SB(0, 1), b2 + hstepB, voffB);
;             PG8_WAIT_V(6); PG8_BAR; PG8_MMA(1, 1, At, B1); PG8_BAR;
;             PG8_LDB(B0, 1, 0); PG8_SCHED; PG8_LDA(At, 1, 0); PG8_STAGE(PG8_SA(0, 1), a2 + hstepA, voffA);
;             PG8_WAIT_L(8); PG8_BAR; PG8_WAIT_L(0); PG8_MMA(0, 0, At, B0); PG8_BAR; PG8_SCHED;
;             PG8_LDB(B1, 1, 1); PG8_STAGE(PG8_SB(1, 0), b3, voffB);
	s_add_u32 s72, s40, 0x80000
	s_addc_u32 s73, s41, 0
	s_add_i32 s74, s64, s48
	v_lshl_add_u64 v[150:151], s[72:73], 0, v[130:131]
	s_mov_b32 m0, s74
	s_nop 0
	global_load_lds_dwordx4 v[150:151], off
	v_lshl_add_u64 v[150:151], s[72:73], 0, v[134:135]
	s_add_i32 m0, s74, 0x2000
	s_nop 0
	global_load_lds_dwordx4 v[150:151], off
	s_waitcnt vmcnt(6)
	s_barrier
	s_setprio 1
	v_mfma_f32_16x16x32_bf16 v[52:55], v[198:201], v[166:169], v[52:55]
	v_mfma_f32_16x16x32_bf16 v[52:55], v[202:205], v[170:173], v[52:55]
	v_mfma_f32_16x16x32_bf16 v[48:51], v[206:209], v[166:169], v[48:51]
	v_mfma_f32_16x16x32_bf16 v[48:51], v[210:213], v[170:173], v[48:51]
	v_mfma_f32_16x16x32_bf16 v[32:35], v[206:209], v[174:177], v[32:35]
	v_mfma_f32_16x16x32_bf16 v[32:35], v[210:213], v[178:181], v[32:35]
	v_mfma_f32_16x16x32_bf16 v[36:39], v[198:201], v[174:177], v[36:39]
	v_mfma_f32_16x16x32_bf16 v[36:39], v[202:205], v[178:181], v[36:39]
	v_mfma_f32_16x16x32_bf16 v[20:23], v[198:201], v[182:185], v[20:23]
	v_mfma_f32_16x16x32_bf16 v[20:23], v[202:205], v[186:189], v[20:23]
	v_mfma_f32_16x16x32_bf16 v[16:19], v[206:209], v[182:185], v[16:19]
	v_mfma_f32_16x16x32_bf16 v[16:19], v[210:213], v[186:189], v[16:19]
	v_mfma_f32_16x16x32_bf16 v[0:3], v[206:209], v[190:193], v[0:3]
	v_mfma_f32_16x16x32_bf16 v[0:3], v[210:213], v[194:197], v[0:3]
	v_mfma_f32_16x16x32_bf16 v[4:7], v[198:201], v[190:193], v[4:7]
	v_mfma_f32_16x16x32_bf16 v[4:7], v[202:205], v[194:197], v[4:7]
	s_setprio 0
	s_add_i32 s72, 16, 0x18000
	v_add_u32_e32 v162, s72, v145
	s_barrier
	ds_read_b128 v[150:153], v162
	ds_read_b128 v[154:157], v162 offset:1024
	ds_read_b128 v[158:161], v162 offset:2048
	ds_read_b128 v[162:165], v162 offset:3072
	s_add_u32 s42, s42, 0x80000
	s_addc_u32 s43, s43, 0
	s_mov_b32 m0, s50
	v_lshl_add_u64 v[198:199], s[42:43], 0, v[128:129]
	ds_read_b128 v[166:169], v148 offset:32768
	ds_read_b128 v[170:173], v148 offset:33792
	ds_read_b128 v[174:177], v148 offset:34816
	ds_read_b128 v[178:181], v148 offset:35840
	ds_read_b128 v[182:185], v148 offset:36864
	ds_read_b128 v[186:189], v148 offset:37888
	ds_read_b128 v[190:193], v148 offset:38912
	ds_read_b128 v[194:197], v148 offset:39936
	global_load_lds_dwordx4 v[198:199], off
	v_lshl_add_u64 v[198:199], s[42:43], 0, v[132:133]
	s_mov_b32 m0, s51
	s_nop 0
	global_load_lds_dwordx4 v[198:199], off
	s_waitcnt lgkmcnt(8)
	s_barrier
	s_waitcnt lgkmcnt(0)
	s_setprio 1
	s_waitcnt lgkmcnt(0)
	v_mfma_f32_16x16x32_bf16 v[120:123], v[150:153], v[166:169], v[120:123]
	v_mfma_f32_16x16x32_bf16 v[120:123], v[154:157], v[170:173], v[120:123]
	v_mfma_f32_16x16x32_bf16 v[124:127], v[158:161], v[166:169], v[124:127]
	v_mfma_f32_16x16x32_bf16 v[124:127], v[162:165], v[170:173], v[124:127]
	v_mfma_f32_16x16x32_bf16 v[104:107], v[158:161], v[174:177], v[104:107]
	v_mfma_f32_16x16x32_bf16 v[104:107], v[162:165], v[178:181], v[104:107]
	v_mfma_f32_16x16x32_bf16 v[108:111], v[150:153], v[174:177], v[108:111]
	v_mfma_f32_16x16x32_bf16 v[108:111], v[154:157], v[178:181], v[108:111]
	v_mfma_f32_16x16x32_bf16 v[92:95], v[150:153], v[182:185], v[92:95]
	v_mfma_f32_16x16x32_bf16 v[92:95], v[154:157], v[186:189], v[92:95]
	v_mfma_f32_16x16x32_bf16 v[88:91], v[158:161], v[182:185], v[88:91]
	v_mfma_f32_16x16x32_bf16 v[88:91], v[162:165], v[186:189], v[88:91]
	v_mfma_f32_16x16x32_bf16 v[72:75], v[158:161], v[190:193], v[72:75]
	v_mfma_f32_16x16x32_bf16 v[72:75], v[162:165], v[194:197], v[72:75]
	v_mfma_f32_16x16x32_bf16 v[76:79], v[150:153], v[190:193], v[76:79]
	v_mfma_f32_16x16x32_bf16 v[76:79], v[154:157], v[194:197], v[76:79]
	s_setprio 0
	s_barrier
	s_add_i32 s42, 16, 0x1c000
	s_add_i32 s43, s72, s48
	v_add_u32_e32 v210, s42, v145
	v_lshl_add_u64 v[218:219], v[218:219], 0, s[6:7]
	s_mov_b32 m0, s43
	ds_read_b128 v[198:201], v210
	ds_read_b128 v[202:205], v210 offset:1024
	ds_read_b128 v[206:209], v210 offset:2048
	ds_read_b128 v[210:213], v210 offset:3072
	global_load_lds_dwordx4 v[218:219], off
	v_lshl_add_u64 v[218:219], v[220:221], 0, s[6:7]
	s_add_i32 m0, s43, 0x2000
	s_nop 0
	global_load_lds_dwordx4 v[218:219], off
	s_barrier
; #define PG8_STAGE(bufoff, gbase, voff) do { _Pragma("unroll") for (int _i = 0; _i < 2; ++_i) \
;         __builtin_amdgcn_global_load_lds((const unsigned*)((const char*)(gbase) + (voff)[_i]), (LAS unsigned*)(lds + (bufoff) + ldsw + _i * 8192), 16, 0, 0); } while (0)
; #define PG8_LDA(dst, b, h) do { _Pragma("unroll") for (int m = 0; m < 4; ++m) _Pragma("unroll") for (int k = 0; k < 2; ++k) dst[m][k] = *(const LAS bf16x8*)(lds + PG8_SA(b, h) + aoff + m * 2048 + k * 1024); } while (0)
; #define PG8_MMA(ai, bj, At, Bt) do { __builtin_amdgcn_s_setprio(1); _Pragma("unroll") for (int m = 0; m < 4; ++m) _Pragma("unroll") for (int n = 0; n < 2; ++n) _Pragma("unroll") for (int k = 0; k < 2; ++k) \
;         acc[ai][bj][m][n] = __builtin_amdgcn_mfma_f32_16x16x32_bf16(Bt[n][k], At[m][k], acc[ai][bj][m][n], 0, 0, 0); __builtin_amdgcn_s_setprio(0); } while (0)
; #define PG8_WAIT_V(n) asm volatile("s_waitcnt vmcnt(" #n ")" ::: "memory")
; #define PG8_WAIT_L(n) asm volatile("s_waitcnt lgkmcnt(" #n ")" ::: "memory")
; #define PG8_BAR __builtin_amdgcn_s_barrier()
; #define PG8_SCHED __builtin_amdgcn_sched_barrier(0)
; template <class Epi>
; DEVINL void gemm_phase(LAS unsigned char* lds, const Gemm g, const Order& S, const Epi& E) {
;     ...
;             PG8_BAR; PG8_WAIT_L(0); PG8_MMA(0, 1, At, B1); PG8_BAR;
;             PG8_LDA(At, 1, 1); PG8_STAGE(PG8_SA(1, 0), a3, voffA);
;             PG8_BAR; PG8_WAIT_L(0); PG8_MMA(1, 0, At, B0); PG8_BAR; PG8_SCHED;
;             PG8_STAGE(PG8_SB(1, 1), b3 + hstepB, voffB);
;             PG8_WAIT_V(6); PG8_BAR; PG8_MMA(1, 1, At, B1); PG8_BAR;
	s_waitcnt lgkmcnt(0)
	s_setprio 1
	s_waitcnt lgkmcnt(0)
	v_mfma_f32_16x16x32_bf16 v[116:119], v[198:201], v[166:169], v[116:119]
	v_mfma_f32_16x16x32_bf16 v[116:119], v[202:205], v[170:173], v[116:119]
	v_mfma_f32_16x16x32_bf16 v[112:115], v[206:209], v[166:169], v[112:115]
	v_mfma_f32_16x16x32_bf16 v[112:115], v[210:213], v[170:173], v[112:115]
	v_mfma_f32_16x16x32_bf16 v[96:99], v[206:209], v[174:177], v[96:99]
	v_mfma_f32_16x16x32_bf16 v[96:99], v[210:213], v[178:181], v[96:99]
	v_mfma_f32_16x16x32_bf16 v[100:103], v[198:201], v[174:177], v[100:103]
	v_mfma_f32_16x16x32_bf16 v[100:103], v[202:205], v[178:181], v[100:103]
	v_mfma_f32_16x16x32_bf16 v[84:87], v[198:201], v[182:185], v[84:87]
	v_mfma_f32_16x16x32_bf16 v[84:87], v[202:205], v[186:189], v[84:87]
	v_mfma_f32_16x16x32_bf16 v[80:83], v[206:209], v[182:185], v[80:83]
	v_mfma_f32_16x16x32_bf16 v[80:83], v[210:213], v[186:189], v[80:83]
	v_mfma_f32_16x16x32_bf16 v[64:67], v[206:209], v[190:193], v[64:67]
	v_mfma_f32_16x16x32_bf16 v[64:67], v[210:213], v[194:197], v[64:67]
	v_mfma_f32_16x16x32_bf16 v[68:71], v[198:201], v[190:193], v[68:71]
	v_mfma_f32_16x16x32_bf16 v[68:71], v[202:205], v[194:197], v[68:71]
	s_setprio 0
	s_mov_b32 m0, s53
	v_lshl_add_u64 v[218:219], v[222:223], 0, s[6:7]
	s_barrier
	ds_read_b128 v[166:169], v148 offset:49152
	ds_read_b128 v[170:173], v148 offset:50176
	ds_read_b128 v[174:177], v148 offset:51200
	ds_read_b128 v[178:181], v148 offset:52224
	ds_read_b128 v[182:185], v148 offset:53248
	ds_read_b128 v[186:189], v148 offset:54272
	ds_read_b128 v[190:193], v148 offset:55296
	ds_read_b128 v[194:197], v148 offset:56320
	global_load_lds_dwordx4 v[218:219], off
	v_lshl_add_u64 v[218:219], v[224:225], 0, s[6:7]
	s_mov_b32 m0, s54
	s_nop 0
	global_load_lds_dwordx4 v[218:219], off
	s_barrier
	s_waitcnt lgkmcnt(0)
	s_setprio 1
	s_waitcnt lgkmcnt(0)
	v_mfma_f32_16x16x32_bf16 v[60:63], v[150:153], v[166:169], v[60:63]
	v_mfma_f32_16x16x32_bf16 v[60:63], v[154:157], v[170:173], v[60:63]
	v_mfma_f32_16x16x32_bf16 v[56:59], v[158:161], v[166:169], v[56:59]
	v_mfma_f32_16x16x32_bf16 v[56:59], v[162:165], v[170:173], v[56:59]
	v_mfma_f32_16x16x32_bf16 v[40:43], v[158:161], v[174:177], v[40:43]
	v_mfma_f32_16x16x32_bf16 v[40:43], v[162:165], v[178:181], v[40:43]
	v_mfma_f32_16x16x32_bf16 v[44:47], v[150:153], v[174:177], v[44:47]
	v_mfma_f32_16x16x32_bf16 v[44:47], v[154:157], v[178:181], v[44:47]
	v_mfma_f32_16x16x32_bf16 v[28:31], v[150:153], v[182:185], v[28:31]
	v_mfma_f32_16x16x32_bf16 v[28:31], v[154:157], v[186:189], v[28:31]
	v_mfma_f32_16x16x32_bf16 v[24:27], v[158:161], v[182:185], v[24:27]
	v_mfma_f32_16x16x32_bf16 v[24:27], v[162:165], v[186:189], v[24:27]
	v_mfma_f32_16x16x32_bf16 v[8:11], v[158:161], v[190:193], v[8:11]
	v_mfma_f32_16x16x32_bf16 v[8:11], v[162:165], v[194:197], v[8:11]
	v_mfma_f32_16x16x32_bf16 v[12:15], v[150:153], v[190:193], v[12:15]
	v_mfma_f32_16x16x32_bf16 v[12:15], v[154:157], v[194:197], v[12:15]
	s_setprio 0
	s_barrier
	s_add_u32 s40, s40, 0x80080
	s_addc_u32 s41, s41, 0
	s_add_i32 s42, s42, s48
	v_lshl_add_u64 v[150:151], s[40:41], 0, v[130:131]
	s_mov_b32 m0, s42
	s_nop 0
	global_load_lds_dwordx4 v[150:151], off
	v_lshl_add_u64 v[150:151], s[40:41], 0, v[134:135]
	s_add_i32 m0, s42, 0x2000
	s_nop 0
	global_load_lds_dwordx4 v[150:151], off
	s_waitcnt vmcnt(6)
	s_barrier
	s_setprio 1
	v_mfma_f32_16x16x32_bf16 v[52:55], v[198:201], v[166:169], v[52:55]
	v_mfma_f32_16x16x32_bf16 v[52:55], v[202:205], v[170:173], v[52:55]
	v_mfma_f32_16x16x32_bf16 v[48:51], v[206:209], v[166:169], v[48:51]
	v_mfma_f32_16x16x32_bf16 v[48:51], v[210:213], v[170:173], v[48:51]
	v_mfma_f32_16x16x32_bf16 v[32:35], v[206:209], v[174:177], v[32:35]
	v_mfma_f32_16x16x32_bf16 v[32:35], v[210:213], v[178:181], v[32:35]
	v_mfma_f32_16x16x32_bf16 v[36:39], v[198:201], v[174:177], v[36:39]
	v_mfma_f32_16x16x32_bf16 v[36:39], v[202:205], v[178:181], v[36:39]
	v_mfma_f32_16x16x32_bf16 v[20:23], v[198:201], v[182:185], v[20:23]
	v_mfma_f32_16x16x32_bf16 v[20:23], v[202:205], v[186:189], v[20:23]
	v_mfma_f32_16x16x32_bf16 v[16:19], v[206:209], v[182:185], v[16:19]
	v_mfma_f32_16x16x32_bf16 v[16:19], v[210:213], v[186:189], v[16:19]
	v_mfma_f32_16x16x32_bf16 v[0:3], v[206:209], v[190:193], v[0:3]
	v_mfma_f32_16x16x32_bf16 v[0:3], v[210:213], v[194:197], v[0:3]
	v_mfma_f32_16x16x32_bf16 v[4:7], v[198:201], v[190:193], v[4:7]
	v_mfma_f32_16x16x32_bf16 v[4:7], v[202:205], v[194:197], v[4:7]
	s_setprio 0
	s_add_u32 s8, s8, 0x100
	s_addc_u32 s9, s9, 0
	s_add_u32 s69, s69, 0x100
	s_addc_u32 s70, s70, 0
	s_cmp_ge_i32 s71, s52
	s_mov_b32 s40, s71
	s_barrier
	s_cbranch_scc0 .LBB0_1332
	s_branch .LBB0_1323

; #define PG8_STAGE(bufoff, gbase, voff) do { _Pragma("unroll") for (int _i = 0; _i < 2; ++_i) \
;         __builtin_amdgcn_global_load_lds((const unsigned*)((const char*)(gbase) + (voff)[_i]), (LAS unsigned*)(lds + (bufoff) + ldsw + _i * 8192), 16, 0, 0); } while (0)
; #define PG8_LDA(dst, b, h) do { _Pragma("unroll") for (int m = 0; m < 4; ++m) _Pragma("unroll") for (int k = 0; k < 2; ++k) dst[m][k] = *(const LAS bf16x8*)(lds + PG8_SA(b, h) + aoff + m * 2048 + k * 1024); } while (0)
; #define PG8_LDB(dst, b, h) do { _Pragma("unroll") for (int n = 0; n < 2; ++n) _Pragma("unroll") for (int k = 0; k < 2; ++k) dst[n][k] = *(const LAS bf16x8*)(lds + PG8_SB(b, h) + boff + n * 2048 + k * 1024); } while (0)
; #define PG8_MMA(ai, bj, At, Bt) do { __builtin_amdgcn_s_setprio(1); _Pragma("unroll") for (int m = 0; m < 4; ++m) _Pragma("unroll") for (int n = 0; n < 2; ++n) _Pragma("unroll") for (int k = 0; k < 2; ++k) \
;         acc[ai][bj][m][n] = __builtin_amdgcn_mfma_f32_16x16x32_bf16(Bt[n][k], At[m][k], acc[ai][bj][m][n], 0, 0, 0); __builtin_amdgcn_s_setprio(0); } while (0)
; #define PG8_WAIT_L(n) asm volatile("s_waitcnt lgkmcnt(" #n ")" ::: "memory")
; #define PG8_BAR __builtin_amdgcn_s_barrier()
; #define PG8_SCHED __builtin_amdgcn_sched_barrier(0)
; template <class Epi>
; DEVINL void gemm_phase(LAS unsigned char* lds, const Gemm g, const Order& S, const Epi& E) {
;     ...
;             PG8_LDB(B0, 0, 0); PG8_SCHED; PG8_LDA(At, 0, 0); PG8_STAGE(PG8_SA(1, 1), a1 + hstepA, voffA);
;             PG8_WAIT_L(8); PG8_BAR; PG8_WAIT_L(0); PG8_MMA(0, 0, At, B0); PG8_BAR; PG8_SCHED;
;             PG8_LDB(B1, 0, 1); PG8_STAGE(PG8_SB(0, 0), b2, voffB);
;             PG8_BAR; PG8_WAIT_L(0); PG8_MMA(0, 1, At, B1); PG8_BAR;
;             PG8_LDA(At, 0, 1); PG8_STAGE(PG8_SA(0, 0), a2, voffA);
;             PG8_BAR; PG8_WAIT_L(0); PG8_MMA(1, 0, At, B0); PG8_BAR; PG8_SCHED;
.LBB0_1492:
	ds_read_b128 v[150:153], v147
	ds_read_b128 v[154:157], v147 offset:1024
	ds_read_b128 v[158:161], v147 offset:2048
	ds_read_b128 v[162:165], v147 offset:3072
	s_add_i32 s74, s42, 2
	s_add_u32 s43, s8, 0xfff80080
	s_addc_u32 s44, s9, -1
	s_cmp_eq_u32 s57, s42
	s_cselect_b32 s42, s37, s72
	s_cselect_b32 s45, s2, s44
	s_cselect_b32 s44, s3, s43
	s_cselect_b32 s43, s31, s73
	v_lshl_add_u64 v[198:199], s[8:9], 0, v[136:137]
	s_add_i32 m0, s29, 0xc000
	ds_read_b128 v[166:169], v148
	ds_read_b128 v[170:173], v148 offset:1024
	ds_read_b128 v[174:177], v148 offset:2048
	ds_read_b128 v[178:181], v148 offset:3072
	ds_read_b128 v[182:185], v148 offset:4096
	ds_read_b128 v[186:189], v148 offset:5120
	ds_read_b128 v[190:193], v148 offset:6144
	ds_read_b128 v[194:197], v148 offset:7168
	global_load_lds_dwordx4 v[198:199], off
	v_lshl_add_u64 v[198:199], s[8:9], 0, v[138:139]
	s_add_i32 m0, s29, 0xe000
	s_nop 0
	global_load_lds_dwordx4 v[198:199], off
	s_waitcnt lgkmcnt(8)
	s_barrier
	s_waitcnt lgkmcnt(0)
	s_setprio 1
	s_waitcnt lgkmcnt(0)
	v_mfma_f32_16x16x32_bf16 v[120:123], v[150:153], v[166:169], v[120:123]
	v_mfma_f32_16x16x32_bf16 v[120:123], v[154:157], v[170:173], v[120:123]
	v_mfma_f32_16x16x32_bf16 v[124:127], v[158:161], v[166:169], v[124:127]
	v_mfma_f32_16x16x32_bf16 v[124:127], v[162:165], v[170:173], v[124:127]
	v_mfma_f32_16x16x32_bf16 v[104:107], v[158:161], v[174:177], v[104:107]
	v_mfma_f32_16x16x32_bf16 v[104:107], v[162:165], v[178:181], v[104:107]
	v_mfma_f32_16x16x32_bf16 v[108:111], v[150:153], v[174:177], v[108:111]
	v_mfma_f32_16x16x32_bf16 v[108:111], v[154:157], v[178:181], v[108:111]
	v_mfma_f32_16x16x32_bf16 v[92:95], v[150:153], v[182:185], v[92:95]
	v_mfma_f32_16x16x32_bf16 v[92:95], v[154:157], v[186:189], v[92:95]
	v_mfma_f32_16x16x32_bf16 v[88:91], v[158:161], v[182:185], v[88:91]
	v_mfma_f32_16x16x32_bf16 v[88:91], v[162:165], v[186:189], v[88:91]
	v_mfma_f32_16x16x32_bf16 v[72:75], v[158:161], v[190:193], v[72:75]
	v_mfma_f32_16x16x32_bf16 v[72:75], v[162:165], v[194:197], v[72:75]
	v_mfma_f32_16x16x32_bf16 v[76:79], v[150:153], v[190:193], v[76:79]
	v_mfma_f32_16x16x32_bf16 v[76:79], v[154:157], v[194:197], v[76:79]
	s_setprio 0
	s_barrier
	s_add_i32 s75, s65, s50
	v_lshl_add_u64 v[218:219], s[42:43], 0, v[130:131]
	s_mov_b32 m0, s75
	ds_read_b128 v[198:201], v149
	ds_read_b128 v[202:205], v149 offset:1024
	ds_read_b128 v[206:209], v149 offset:2048
	ds_read_b128 v[210:213], v149 offset:3072
	global_load_lds_dwordx4 v[218:219], off
	v_lshl_add_u64 v[220:221], s[42:43], 0, v[134:135]
	s_add_i32 m0, s75, 0x2000
	s_nop 0
	global_load_lds_dwordx4 v[220:221], off
	s_barrier
	s_waitcnt lgkmcnt(0)
	s_setprio 1
	s_waitcnt lgkmcnt(0)
	v_mfma_f32_16x16x32_bf16 v[116:119], v[198:201], v[166:169], v[116:119]
	v_mfma_f32_16x16x32_bf16 v[116:119], v[202:205], v[170:173], v[116:119]
	v_mfma_f32_16x16x32_bf16 v[112:115], v[206:209], v[166:169], v[112:115]
	v_mfma_f32_16x16x32_bf16 v[112:115], v[210:213], v[170:173], v[112:115]
	v_mfma_f32_16x16x32_bf16 v[96:99], v[206:209], v[174:177], v[96:99]
	v_mfma_f32_16x16x32_bf16 v[96:99], v[210:213], v[178:181], v[96:99]
	v_mfma_f32_16x16x32_bf16 v[100:103], v[198:201], v[174:177], v[100:103]
	v_mfma_f32_16x16x32_bf16 v[100:103], v[202:205], v[178:181], v[100:103]
	v_mfma_f32_16x16x32_bf16 v[84:87], v[198:201], v[182:185], v[84:87]
	v_mfma_f32_16x16x32_bf16 v[84:87], v[202:205], v[186:189], v[84:87]
	v_mfma_f32_16x16x32_bf16 v[80:83], v[206:209], v[182:185], v[80:83]
	v_mfma_f32_16x16x32_bf16 v[80:83], v[210:213], v[186:189], v[80:83]
	v_mfma_f32_16x16x32_bf16 v[64:67], v[206:209], v[190:193], v[64:67]
	v_mfma_f32_16x16x32_bf16 v[64:67], v[210:213], v[194:197], v[64:67]
	v_mfma_f32_16x16x32_bf16 v[68:71], v[198:201], v[190:193], v[68:71]
	v_mfma_f32_16x16x32_bf16 v[68:71], v[202:205], v[194:197], v[68:71]
	s_setprio 0
	s_mov_b32 m0, s29
	v_lshl_add_u64 v[222:223], s[44:45], 0, v[128:129]
	s_barrier
	ds_read_b128 v[166:169], v148 offset:16384
	ds_read_b128 v[170:173], v148 offset:17408
	ds_read_b128 v[174:177], v148 offset:18432
	ds_read_b128 v[178:181], v148 offset:19456
	ds_read_b128 v[182:185], v148 offset:20480
	ds_read_b128 v[186:189], v148 offset:21504
	ds_read_b128 v[190:193], v148 offset:22528
	ds_read_b128 v[194:197], v148 offset:23552
	global_load_lds_dwordx4 v[222:223], off
	v_lshl_add_u64 v[224:225], s[44:45], 0, v[132:133]
	s_mov_b32 m0, s51
	s_nop 0
	global_load_lds_dwordx4 v[224:225], off
	s_barrier
	s_waitcnt lgkmcnt(0)
	s_setprio 1
	s_waitcnt lgkmcnt(0)
	v_mfma_f32_16x16x32_bf16 v[60:63], v[150:153], v[166:169], v[60:63]
	v_mfma_f32_16x16x32_bf16 v[60:63], v[154:157], v[170:173], v[60:63]
	v_mfma_f32_16x16x32_bf16 v[56:59], v[158:161], v[166:169], v[56:59]
	v_mfma_f32_16x16x32_bf16 v[56:59], v[162:165], v[170:173], v[56:59]
	v_mfma_f32_16x16x32_bf16 v[40:43], v[158:161], v[174:177], v[40:43]
	v_mfma_f32_16x16x32_bf16 v[40:43], v[162:165], v[178:181], v[40:43]
	v_mfma_f32_16x16x32_bf16 v[44:47], v[150:153], v[174:177], v[44:47]
	v_mfma_f32_16x16x32_bf16 v[44:47], v[154:157], v[178:181], v[44:47]
	v_mfma_f32_16x16x32_bf16 v[28:31], v[150:153], v[182:185], v[28:31]
	v_mfma_f32_16x16x32_bf16 v[28:31], v[154:157], v[186:189], v[28:31]
	v_mfma_f32_16x16x32_bf16 v[24:27], v[158:161], v[182:185], v[24:27]
	v_mfma_f32_16x16x32_bf16 v[24:27], v[162:165], v[186:189], v[24:27]
	v_mfma_f32_16x16x32_bf16 v[8:11], v[158:161], v[190:193], v[8:11]
	v_mfma_f32_16x16x32_bf16 v[8:11], v[162:165], v[194:197], v[8:11]
	v_mfma_f32_16x16x32_bf16 v[12:15], v[150:153], v[190:193], v[12:15]
	v_mfma_f32_16x16x32_bf16 v[12:15], v[154:157], v[194:197], v[12:15]
	s_setprio 0
	s_barrier
; #define PG8_STAGE(bufoff, gbase, voff) do { _Pragma("unroll") for (int _i = 0; _i < 2; ++_i) \
;         __builtin_amdgcn_global_load_lds((const unsigned*)((const char*)(gbase) + (voff)[_i]), (LAS unsigned*)(lds + (bufoff) + ldsw + _i * 8192), 16, 0, 0); } while (0)
; #define PG8_LDA(dst, b, h) do { _Pragma("unroll") for (int m = 0; m < 4; ++m) _Pragma("unroll") for (int k = 0; k < 2; ++k) dst[m][k] = *(const LAS bf16x8*)(lds + PG8_SA(b, h) + aoff + m * 2048 + k * 1024); } while (0)
; #define PG8_LDB(dst, b, h) do { _Pragma("unroll") for (int n = 0; n < 2; ++n) _Pragma("unroll") for (int k = 0; k < 2; ++k) dst[n][k] = *(const LAS bf16x8*)(lds + PG8_SB(b, h) + boff + n * 2048 + k * 1024); } while (0)
; #define PG8_MMA(ai, bj, At, Bt) do { __builtin_amdgcn_s_setprio(1); _Pragma("unroll") for (int m = 0; m < 4; ++m) _Pragma("unroll") for (int n = 0; n < 2; ++n) _Pragma("unroll") for (int k = 0; k < 2; ++k) \
;         acc[ai][bj][m][n] = __builtin_amdgcn_mfma_f32_16x16x32_bf16(Bt[n][k], At[m][k], acc[ai][bj][m][n], 0, 0, 0); __builtin_amdgcn_s_setprio(0); } while (0)
; #define PG8_WAIT_V(n) asm volatile("s_waitcnt vmcnt(" #n ")" ::: "memory")
; #define PG8_WAIT_L(n) asm volatile("s_waitcnt lgkmcnt(" #n ")" ::: "memory")
; #define PG8_BAR __builtin_amdgcn_s_barrier()
; #define PG8_SCHED __builtin_amdgcn_sched_barrier(0)
; template <class Epi>
; DEVINL void gemm_phase(LAS unsigned char* lds, const Gemm g, const Order& S, const Epi& E) {
;     ...
;             PG8_STAGE(PG8_SB(0, 1), b2 + hstepB, voffB);
;             PG8_WAIT_V(6); PG8_BAR; PG8_MMA(1, 1, At, B1); PG8_BAR;
;             PG8_LDB(B0, 1, 0); PG8_SCHED; PG8_LDA(At, 1, 0); PG8_STAGE(PG8_SA(0, 1), a2 + hstepA, voffA);
;             PG8_WAIT_L(8); PG8_BAR; PG8_WAIT_L(0); PG8_MMA(0, 0, At, B0); PG8_BAR; PG8_SCHED;
;             PG8_LDB(B1, 1, 1); PG8_STAGE(PG8_SB(1, 0), b3, voffB);
	s_add_u32 s76, s42, 0x80000
	s_addc_u32 s77, s43, 0
	s_add_i32 s75, s66, s50
	v_lshl_add_u64 v[150:151], s[76:77], 0, v[130:131]
	s_mov_b32 m0, s75
	s_nop 0
	global_load_lds_dwordx4 v[150:151], off
	v_lshl_add_u64 v[150:151], s[76:77], 0, v[134:135]
	s_add_i32 m0, s75, 0x2000
	s_nop 0
	global_load_lds_dwordx4 v[150:151], off
	s_waitcnt vmcnt(6)
	s_barrier
	s_setprio 1
	v_mfma_f32_16x16x32_bf16 v[52:55], v[198:201], v[166:169], v[52:55]
	v_mfma_f32_16x16x32_bf16 v[52:55], v[202:205], v[170:173], v[52:55]
	v_mfma_f32_16x16x32_bf16 v[48:51], v[206:209], v[166:169], v[48:51]
	v_mfma_f32_16x16x32_bf16 v[48:51], v[210:213], v[170:173], v[48:51]
	v_mfma_f32_16x16x32_bf16 v[32:35], v[206:209], v[174:177], v[32:35]
	v_mfma_f32_16x16x32_bf16 v[32:35], v[210:213], v[178:181], v[32:35]
	v_mfma_f32_16x16x32_bf16 v[36:39], v[198:201], v[174:177], v[36:39]
	v_mfma_f32_16x16x32_bf16 v[36:39], v[202:205], v[178:181], v[36:39]
	v_mfma_f32_16x16x32_bf16 v[20:23], v[198:201], v[182:185], v[20:23]
	v_mfma_f32_16x16x32_bf16 v[20:23], v[202:205], v[186:189], v[20:23]
	v_mfma_f32_16x16x32_bf16 v[16:19], v[206:209], v[182:185], v[16:19]
	v_mfma_f32_16x16x32_bf16 v[16:19], v[210:213], v[186:189], v[16:19]
	v_mfma_f32_16x16x32_bf16 v[0:3], v[206:209], v[190:193], v[0:3]
	v_mfma_f32_16x16x32_bf16 v[0:3], v[210:213], v[194:197], v[0:3]
	v_mfma_f32_16x16x32_bf16 v[4:7], v[198:201], v[190:193], v[4:7]
	v_mfma_f32_16x16x32_bf16 v[4:7], v[202:205], v[194:197], v[4:7]
	s_setprio 0
	s_add_i32 s75, 16, 0x18000
	v_add_u32_e32 v162, s75, v145
	s_barrier
	ds_read_b128 v[150:153], v162
	ds_read_b128 v[154:157], v162 offset:1024
	ds_read_b128 v[158:161], v162 offset:2048
	ds_read_b128 v[162:165], v162 offset:3072
	s_add_u32 s44, s44, 0x80000
	s_addc_u32 s45, s45, 0
	s_mov_b32 m0, s52
	v_lshl_add_u64 v[198:199], s[44:45], 0, v[128:129]
	ds_read_b128 v[166:169], v148 offset:32768
	ds_read_b128 v[170:173], v148 offset:33792
	ds_read_b128 v[174:177], v148 offset:34816
	ds_read_b128 v[178:181], v148 offset:35840
	ds_read_b128 v[182:185], v148 offset:36864
	ds_read_b128 v[186:189], v148 offset:37888
	ds_read_b128 v[190:193], v148 offset:38912
	ds_read_b128 v[194:197], v148 offset:39936
	global_load_lds_dwordx4 v[198:199], off
	v_lshl_add_u64 v[198:199], s[44:45], 0, v[132:133]
	s_mov_b32 m0, s53
	s_nop 0
	global_load_lds_dwordx4 v[198:199], off
	s_waitcnt lgkmcnt(8)
	s_barrier
	s_waitcnt lgkmcnt(0)
	s_setprio 1
	s_waitcnt lgkmcnt(0)
	v_mfma_f32_16x16x32_bf16 v[120:123], v[150:153], v[166:169], v[120:123]
	v_mfma_f32_16x16x32_bf16 v[120:123], v[154:157], v[170:173], v[120:123]
	v_mfma_f32_16x16x32_bf16 v[124:127], v[158:161], v[166:169], v[124:127]
	v_mfma_f32_16x16x32_bf16 v[124:127], v[162:165], v[170:173], v[124:127]
	v_mfma_f32_16x16x32_bf16 v[104:107], v[158:161], v[174:177], v[104:107]
	v_mfma_f32_16x16x32_bf16 v[104:107], v[162:165], v[178:181], v[104:107]
	v_mfma_f32_16x16x32_bf16 v[108:111], v[150:153], v[174:177], v[108:111]
	v_mfma_f32_16x16x32_bf16 v[108:111], v[154:157], v[178:181], v[108:111]
	v_mfma_f32_16x16x32_bf16 v[92:95], v[150:153], v[182:185], v[92:95]
	v_mfma_f32_16x16x32_bf16 v[92:95], v[154:157], v[186:189], v[92:95]
	v_mfma_f32_16x16x32_bf16 v[88:91], v[158:161], v[182:185], v[88:91]
	v_mfma_f32_16x16x32_bf16 v[88:91], v[162:165], v[186:189], v[88:91]
	v_mfma_f32_16x16x32_bf16 v[72:75], v[158:161], v[190:193], v[72:75]
	v_mfma_f32_16x16x32_bf16 v[72:75], v[162:165], v[194:197], v[72:75]
	v_mfma_f32_16x16x32_bf16 v[76:79], v[150:153], v[190:193], v[76:79]
	v_mfma_f32_16x16x32_bf16 v[76:79], v[154:157], v[194:197], v[76:79]
	s_setprio 0
	s_barrier
	s_add_i32 s44, 16, 0x1c000
	s_add_i32 s45, s75, s50
	v_add_u32_e32 v210, s44, v145
	v_lshl_add_u64 v[218:219], v[218:219], 0, s[6:7]
	s_mov_b32 m0, s45
	ds_read_b128 v[198:201], v210
	ds_read_b128 v[202:205], v210 offset:1024
	ds_read_b128 v[206:209], v210 offset:2048
	ds_read_b128 v[210:213], v210 offset:3072
	global_load_lds_dwordx4 v[218:219], off
	v_lshl_add_u64 v[218:219], v[220:221], 0, s[6:7]
	s_add_i32 m0, s45, 0x2000
	s_nop 0
	global_load_lds_dwordx4 v[218:219], off
	s_barrier
; #define PG8_STAGE(bufoff, gbase, voff) do { _Pragma("unroll") for (int _i = 0; _i < 2; ++_i) \
;         __builtin_amdgcn_global_load_lds((const unsigned*)((const char*)(gbase) + (voff)[_i]), (LAS unsigned*)(lds + (bufoff) + ldsw + _i * 8192), 16, 0, 0); } while (0)
; #define PG8_LDA(dst, b, h) do { _Pragma("unroll") for (int m = 0; m < 4; ++m) _Pragma("unroll") for (int k = 0; k < 2; ++k) dst[m][k] = *(const LAS bf16x8*)(lds + PG8_SA(b, h) + aoff + m * 2048 + k * 1024); } while (0)
; #define PG8_MMA(ai, bj, At, Bt) do { __builtin_amdgcn_s_setprio(1); _Pragma("unroll") for (int m = 0; m < 4; ++m) _Pragma("unroll") for (int n = 0; n < 2; ++n) _Pragma("unroll") for (int k = 0; k < 2; ++k) \
;         acc[ai][bj][m][n] = __builtin_amdgcn_mfma_f32_16x16x32_bf16(Bt[n][k], At[m][k], acc[ai][bj][m][n], 0, 0, 0); __builtin_amdgcn_s_setprio(0); } while (0)
; #define PG8_WAIT_V(n) asm volatile("s_waitcnt vmcnt(" #n ")" ::: "memory")
; #define PG8_WAIT_L(n) asm volatile("s_waitcnt lgkmcnt(" #n ")" ::: "memory")
; #define PG8_BAR __builtin_amdgcn_s_barrier()
; #define PG8_SCHED __builtin_amdgcn_sched_barrier(0)
; template <class Epi>
; DEVINL void gemm_phase(LAS unsigned char* lds, const Gemm g, const Order& S, const Epi& E) {
;     ...
;             PG8_BAR; PG8_WAIT_L(0); PG8_MMA(0, 1, At, B1); PG8_BAR;
;             PG8_LDA(At, 1, 1); PG8_STAGE(PG8_SA(1, 0), a3, voffA);
;             PG8_BAR; PG8_WAIT_L(0); PG8_MMA(1, 0, At, B0); PG8_BAR; PG8_SCHED;
;             PG8_STAGE(PG8_SB(1, 1), b3 + hstepB, voffB);
;             PG8_WAIT_V(6); PG8_BAR; PG8_MMA(1, 1, At, B1); PG8_BAR;
	s_waitcnt lgkmcnt(0)
	s_setprio 1
	s_waitcnt lgkmcnt(0)
	v_mfma_f32_16x16x32_bf16 v[116:119], v[198:201], v[166:169], v[116:119]
	v_mfma_f32_16x16x32_bf16 v[116:119], v[202:205], v[170:173], v[116:119]
	v_mfma_f32_16x16x32_bf16 v[112:115], v[206:209], v[166:169], v[112:115]
	v_mfma_f32_16x16x32_bf16 v[112:115], v[210:213], v[170:173], v[112:115]
	v_mfma_f32_16x16x32_bf16 v[96:99], v[206:209], v[174:177], v[96:99]
	v_mfma_f32_16x16x32_bf16 v[96:99], v[210:213], v[178:181], v[96:99]
	v_mfma_f32_16x16x32_bf16 v[100:103], v[198:201], v[174:177], v[100:103]
	v_mfma_f32_16x16x32_bf16 v[100:103], v[202:205], v[178:181], v[100:103]
	v_mfma_f32_16x16x32_bf16 v[84:87], v[198:201], v[182:185], v[84:87]
	v_mfma_f32_16x16x32_bf16 v[84:87], v[202:205], v[186:189], v[84:87]
	v_mfma_f32_16x16x32_bf16 v[80:83], v[206:209], v[182:185], v[80:83]
	v_mfma_f32_16x16x32_bf16 v[80:83], v[210:213], v[186:189], v[80:83]
	v_mfma_f32_16x16x32_bf16 v[64:67], v[206:209], v[190:193], v[64:67]
	v_mfma_f32_16x16x32_bf16 v[64:67], v[210:213], v[194:197], v[64:67]
	v_mfma_f32_16x16x32_bf16 v[68:71], v[198:201], v[190:193], v[68:71]
	v_mfma_f32_16x16x32_bf16 v[68:71], v[202:205], v[194:197], v[68:71]
	s_setprio 0
	s_mov_b32 m0, s55
	v_lshl_add_u64 v[218:219], v[222:223], 0, s[6:7]
	s_barrier
	ds_read_b128 v[166:169], v148 offset:49152
	ds_read_b128 v[170:173], v148 offset:50176
	ds_read_b128 v[174:177], v148 offset:51200
	ds_read_b128 v[178:181], v148 offset:52224
	ds_read_b128 v[182:185], v148 offset:53248
	ds_read_b128 v[186:189], v148 offset:54272
	ds_read_b128 v[190:193], v148 offset:55296
	ds_read_b128 v[194:197], v148 offset:56320
	global_load_lds_dwordx4 v[218:219], off
	v_lshl_add_u64 v[218:219], v[224:225], 0, s[6:7]
	s_mov_b32 m0, s56
	s_nop 0
	global_load_lds_dwordx4 v[218:219], off
	s_barrier
	s_waitcnt lgkmcnt(0)
	s_setprio 1
	s_waitcnt lgkmcnt(0)
	v_mfma_f32_16x16x32_bf16 v[60:63], v[150:153], v[166:169], v[60:63]
	v_mfma_f32_16x16x32_bf16 v[60:63], v[154:157], v[170:173], v[60:63]
	v_mfma_f32_16x16x32_bf16 v[56:59], v[158:161], v[166:169], v[56:59]
	v_mfma_f32_16x16x32_bf16 v[56:59], v[162:165], v[170:173], v[56:59]
	v_mfma_f32_16x16x32_bf16 v[40:43], v[158:161], v[174:177], v[40:43]
	v_mfma_f32_16x16x32_bf16 v[40:43], v[162:165], v[178:181], v[40:43]
	v_mfma_f32_16x16x32_bf16 v[44:47], v[150:153], v[174:177], v[44:47]
	v_mfma_f32_16x16x32_bf16 v[44:47], v[154:157], v[178:181], v[44:47]
	v_mfma_f32_16x16x32_bf16 v[28:31], v[150:153], v[182:185], v[28:31]
	v_mfma_f32_16x16x32_bf16 v[28:31], v[154:157], v[186:189], v[28:31]
	v_mfma_f32_16x16x32_bf16 v[24:27], v[158:161], v[182:185], v[24:27]
	v_mfma_f32_16x16x32_bf16 v[24:27], v[162:165], v[186:189], v[24:27]
	v_mfma_f32_16x16x32_bf16 v[8:11], v[158:161], v[190:193], v[8:11]
	v_mfma_f32_16x16x32_bf16 v[8:11], v[162:165], v[194:197], v[8:11]
	v_mfma_f32_16x16x32_bf16 v[12:15], v[150:153], v[190:193], v[12:15]
	v_mfma_f32_16x16x32_bf16 v[12:15], v[154:157], v[194:197], v[12:15]
	s_setprio 0
	s_barrier
	s_add_u32 s42, s42, 0x80080
	s_addc_u32 s43, s43, 0
	s_add_i32 s44, s44, s50
	v_lshl_add_u64 v[150:151], s[42:43], 0, v[130:131]
	s_mov_b32 m0, s44
	s_nop 0
	global_load_lds_dwordx4 v[150:151], off
	v_lshl_add_u64 v[150:151], s[42:43], 0, v[134:135]
	s_add_i32 m0, s44, 0x2000
	s_nop 0
	global_load_lds_dwordx4 v[150:151], off
	s_waitcnt vmcnt(6)
	s_barrier
	s_setprio 1
	v_mfma_f32_16x16x32_bf16 v[52:55], v[198:201], v[166:169], v[52:55]
	v_mfma_f32_16x16x32_bf16 v[52:55], v[202:205], v[170:173], v[52:55]
	v_mfma_f32_16x16x32_bf16 v[48:51], v[206:209], v[166:169], v[48:51]
	v_mfma_f32_16x16x32_bf16 v[48:51], v[210:213], v[170:173], v[48:51]
	v_mfma_f32_16x16x32_bf16 v[32:35], v[206:209], v[174:177], v[32:35]
	v_mfma_f32_16x16x32_bf16 v[32:35], v[210:213], v[178:181], v[32:35]
	v_mfma_f32_16x16x32_bf16 v[36:39], v[198:201], v[174:177], v[36:39]
	v_mfma_f32_16x16x32_bf16 v[36:39], v[202:205], v[178:181], v[36:39]
	v_mfma_f32_16x16x32_bf16 v[20:23], v[198:201], v[182:185], v[20:23]
	v_mfma_f32_16x16x32_bf16 v[20:23], v[202:205], v[186:189], v[20:23]
	v_mfma_f32_16x16x32_bf16 v[16:19], v[206:209], v[182:185], v[16:19]
	v_mfma_f32_16x16x32_bf16 v[16:19], v[210:213], v[186:189], v[16:19]
	v_mfma_f32_16x16x32_bf16 v[0:3], v[206:209], v[190:193], v[0:3]
	v_mfma_f32_16x16x32_bf16 v[0:3], v[210:213], v[194:197], v[0:3]
	v_mfma_f32_16x16x32_bf16 v[4:7], v[198:201], v[190:193], v[4:7]
	v_mfma_f32_16x16x32_bf16 v[4:7], v[202:205], v[194:197], v[4:7]
	s_setprio 0
	s_add_u32 s8, s8, 0x100
	s_addc_u32 s9, s9, 0
	s_add_u32 s72, s72, 0x100
	s_addc_u32 s73, s73, 0
	s_cmp_ge_i32 s74, s54
	s_mov_b32 s42, s74
	s_barrier
	s_cbranch_scc0 .LBB0_1492
	v_readlane_b32 s75, v250, 1
	s_branch .LBB0_1483

; #define PG8_STAGE(bufoff, gbase, voff) do { _Pragma("unroll") for (int _i = 0; _i < 2; ++_i) \
;         __builtin_amdgcn_global_load_lds((const unsigned*)((const char*)(gbase) + (voff)[_i]), (LAS unsigned*)(lds + (bufoff) + ldsw + _i * 8192), 16, 0, 0); } while (0)
; #define PG8_LDA(dst, b, h) do { _Pragma("unroll") for (int m = 0; m < 4; ++m) _Pragma("unroll") for (int k = 0; k < 2; ++k) dst[m][k] = *(const LAS bf16x8*)(lds + PG8_SA(b, h) + aoff + m * 2048 + k * 1024); } while (0)
; #define PG8_LDB(dst, b, h) do { _Pragma("unroll") for (int n = 0; n < 2; ++n) _Pragma("unroll") for (int k = 0; k < 2; ++k) dst[n][k] = *(const LAS bf16x8*)(lds + PG8_SB(b, h) + boff + n * 2048 + k * 1024); } while (0)
; #define PG8_MMA(ai, bj, At, Bt) do { __builtin_amdgcn_s_setprio(1); _Pragma("unroll") for (int m = 0; m < 4; ++m) _Pragma("unroll") for (int n = 0; n < 2; ++n) _Pragma("unroll") for (int k = 0; k < 2; ++k) \
;         acc[ai][bj][m][n] = __builtin_amdgcn_mfma_f32_16x16x32_bf16(Bt[n][k], At[m][k], acc[ai][bj][m][n], 0, 0, 0); __builtin_amdgcn_s_setprio(0); } while (0)
; #define PG8_WAIT_L(n) asm volatile("s_waitcnt lgkmcnt(" #n ")" ::: "memory")
; #define PG8_BAR __builtin_amdgcn_s_barrier()
; #define PG8_SCHED __builtin_amdgcn_sched_barrier(0)
; template <class Epi>
; DEVINL void gemm_phase(LAS unsigned char* lds, const Gemm g, const Order& S, const Epi& E) {
;     ...
;             PG8_LDB(B0, 0, 0); PG8_SCHED; PG8_LDA(At, 0, 0); PG8_STAGE(PG8_SA(1, 1), a1 + hstepA, voffA);
;             PG8_WAIT_L(8); PG8_BAR; PG8_WAIT_L(0); PG8_MMA(0, 0, At, B0); PG8_BAR; PG8_SCHED;
;             PG8_LDB(B1, 0, 1); PG8_STAGE(PG8_SB(0, 0), b2, voffB);
;             PG8_BAR; PG8_WAIT_L(0); PG8_MMA(0, 1, At, B1); PG8_BAR;
;             PG8_LDA(At, 0, 1); PG8_STAGE(PG8_SA(0, 0), a2, voffA);
;             PG8_BAR; PG8_WAIT_L(0); PG8_MMA(1, 0, At, B0); PG8_BAR; PG8_SCHED;
.LBB0_1623:
	ds_read_b128 v[150:153], v147
	ds_read_b128 v[154:157], v147 offset:1024
	ds_read_b128 v[158:161], v147 offset:2048
	ds_read_b128 v[162:165], v147 offset:3072
	s_add_i32 s69, s38, 2
	s_add_u32 s39, s2, 0xfffc0080
	s_addc_u32 s40, s3, -1
	s_cmp_eq_u32 s52, s38
	s_cselect_b32 s38, s66, s67
	s_cselect_b32 s41, s27, s40
	s_cselect_b32 s40, s29, s39
	s_cselect_b32 s39, s65, s68
	v_lshl_add_u64 v[198:199], s[2:3], 0, v[136:137]
	s_add_i32 m0, s25, 0xc000
	ds_read_b128 v[166:169], v148
	ds_read_b128 v[170:173], v148 offset:1024
	ds_read_b128 v[174:177], v148 offset:2048
	ds_read_b128 v[178:181], v148 offset:3072
	ds_read_b128 v[182:185], v148 offset:4096
	ds_read_b128 v[186:189], v148 offset:5120
	ds_read_b128 v[190:193], v148 offset:6144
	ds_read_b128 v[194:197], v148 offset:7168
	global_load_lds_dwordx4 v[198:199], off
	v_lshl_add_u64 v[198:199], s[2:3], 0, v[138:139]
	s_add_i32 m0, s25, 0xe000
	s_nop 0
	global_load_lds_dwordx4 v[198:199], off
	s_waitcnt lgkmcnt(8)
	s_barrier
	s_waitcnt lgkmcnt(0)
	s_setprio 1
	s_waitcnt lgkmcnt(0)
	v_mfma_f32_16x16x32_bf16 v[120:123], v[150:153], v[166:169], v[120:123]
	v_mfma_f32_16x16x32_bf16 v[120:123], v[154:157], v[170:173], v[120:123]
	v_mfma_f32_16x16x32_bf16 v[124:127], v[158:161], v[166:169], v[124:127]
	v_mfma_f32_16x16x32_bf16 v[124:127], v[162:165], v[170:173], v[124:127]
	v_mfma_f32_16x16x32_bf16 v[104:107], v[158:161], v[174:177], v[104:107]
	v_mfma_f32_16x16x32_bf16 v[104:107], v[162:165], v[178:181], v[104:107]
	v_mfma_f32_16x16x32_bf16 v[108:111], v[150:153], v[174:177], v[108:111]
	v_mfma_f32_16x16x32_bf16 v[108:111], v[154:157], v[178:181], v[108:111]
	v_mfma_f32_16x16x32_bf16 v[92:95], v[150:153], v[182:185], v[92:95]
	v_mfma_f32_16x16x32_bf16 v[92:95], v[154:157], v[186:189], v[92:95]
	v_mfma_f32_16x16x32_bf16 v[88:91], v[158:161], v[182:185], v[88:91]
	v_mfma_f32_16x16x32_bf16 v[88:91], v[162:165], v[186:189], v[88:91]
	v_mfma_f32_16x16x32_bf16 v[72:75], v[158:161], v[190:193], v[72:75]
	v_mfma_f32_16x16x32_bf16 v[72:75], v[162:165], v[194:197], v[72:75]
	v_mfma_f32_16x16x32_bf16 v[76:79], v[150:153], v[190:193], v[76:79]
	v_mfma_f32_16x16x32_bf16 v[76:79], v[154:157], v[194:197], v[76:79]
	s_setprio 0
	s_barrier
	s_add_i32 s70, s58, s45
	v_lshl_add_u64 v[218:219], s[38:39], 0, v[130:131]
	s_mov_b32 m0, s70
	ds_read_b128 v[198:201], v149
	ds_read_b128 v[202:205], v149 offset:1024
	ds_read_b128 v[206:209], v149 offset:2048
	ds_read_b128 v[210:213], v149 offset:3072
	global_load_lds_dwordx4 v[218:219], off
	v_lshl_add_u64 v[220:221], s[38:39], 0, v[134:135]
	s_add_i32 m0, s70, 0x2000
	s_nop 0
	global_load_lds_dwordx4 v[220:221], off
	s_barrier
	s_waitcnt lgkmcnt(0)
	s_setprio 1
	s_waitcnt lgkmcnt(0)
	v_mfma_f32_16x16x32_bf16 v[116:119], v[198:201], v[166:169], v[116:119]
	v_mfma_f32_16x16x32_bf16 v[116:119], v[202:205], v[170:173], v[116:119]
	v_mfma_f32_16x16x32_bf16 v[112:115], v[206:209], v[166:169], v[112:115]
	v_mfma_f32_16x16x32_bf16 v[112:115], v[210:213], v[170:173], v[112:115]
	v_mfma_f32_16x16x32_bf16 v[96:99], v[206:209], v[174:177], v[96:99]
	v_mfma_f32_16x16x32_bf16 v[96:99], v[210:213], v[178:181], v[96:99]
	v_mfma_f32_16x16x32_bf16 v[100:103], v[198:201], v[174:177], v[100:103]
	v_mfma_f32_16x16x32_bf16 v[100:103], v[202:205], v[178:181], v[100:103]
	v_mfma_f32_16x16x32_bf16 v[84:87], v[198:201], v[182:185], v[84:87]
	v_mfma_f32_16x16x32_bf16 v[84:87], v[202:205], v[186:189], v[84:87]
	v_mfma_f32_16x16x32_bf16 v[80:83], v[206:209], v[182:185], v[80:83]
	v_mfma_f32_16x16x32_bf16 v[80:83], v[210:213], v[186:189], v[80:83]
	v_mfma_f32_16x16x32_bf16 v[64:67], v[206:209], v[190:193], v[64:67]
	v_mfma_f32_16x16x32_bf16 v[64:67], v[210:213], v[194:197], v[64:67]
	v_mfma_f32_16x16x32_bf16 v[68:71], v[198:201], v[190:193], v[68:71]
	v_mfma_f32_16x16x32_bf16 v[68:71], v[202:205], v[194:197], v[68:71]
	s_setprio 0
	s_mov_b32 m0, s25
	v_lshl_add_u64 v[222:223], s[40:41], 0, v[128:129]
	s_barrier
	ds_read_b128 v[166:169], v148 offset:16384
	ds_read_b128 v[170:173], v148 offset:17408
	ds_read_b128 v[174:177], v148 offset:18432
	ds_read_b128 v[178:181], v148 offset:19456
	ds_read_b128 v[182:185], v148 offset:20480
	ds_read_b128 v[186:189], v148 offset:21504
	ds_read_b128 v[190:193], v148 offset:22528
	ds_read_b128 v[194:197], v148 offset:23552
	global_load_lds_dwordx4 v[222:223], off
	v_lshl_add_u64 v[224:225], s[40:41], 0, v[132:133]
	s_mov_b32 m0, s46
	s_nop 0
	global_load_lds_dwordx4 v[224:225], off
	s_barrier
	s_waitcnt lgkmcnt(0)
	s_setprio 1
	s_waitcnt lgkmcnt(0)
	v_mfma_f32_16x16x32_bf16 v[60:63], v[150:153], v[166:169], v[60:63]
	v_mfma_f32_16x16x32_bf16 v[60:63], v[154:157], v[170:173], v[60:63]
	v_mfma_f32_16x16x32_bf16 v[56:59], v[158:161], v[166:169], v[56:59]
	v_mfma_f32_16x16x32_bf16 v[56:59], v[162:165], v[170:173], v[56:59]
	v_mfma_f32_16x16x32_bf16 v[40:43], v[158:161], v[174:177], v[40:43]
	v_mfma_f32_16x16x32_bf16 v[40:43], v[162:165], v[178:181], v[40:43]
	v_mfma_f32_16x16x32_bf16 v[44:47], v[150:153], v[174:177], v[44:47]
	v_mfma_f32_16x16x32_bf16 v[44:47], v[154:157], v[178:181], v[44:47]
	v_mfma_f32_16x16x32_bf16 v[28:31], v[150:153], v[182:185], v[28:31]
	v_mfma_f32_16x16x32_bf16 v[28:31], v[154:157], v[186:189], v[28:31]
	v_mfma_f32_16x16x32_bf16 v[24:27], v[158:161], v[182:185], v[24:27]
	v_mfma_f32_16x16x32_bf16 v[24:27], v[162:165], v[186:189], v[24:27]
	v_mfma_f32_16x16x32_bf16 v[8:11], v[158:161], v[190:193], v[8:11]
	v_mfma_f32_16x16x32_bf16 v[8:11], v[162:165], v[194:197], v[8:11]
	v_mfma_f32_16x16x32_bf16 v[12:15], v[150:153], v[190:193], v[12:15]
	v_mfma_f32_16x16x32_bf16 v[12:15], v[154:157], v[194:197], v[12:15]
	s_setprio 0
	s_barrier
; #define PG8_STAGE(bufoff, gbase, voff) do { _Pragma("unroll") for (int _i = 0; _i < 2; ++_i) \
;         __builtin_amdgcn_global_load_lds((const unsigned*)((const char*)(gbase) + (voff)[_i]), (LAS unsigned*)(lds + (bufoff) + ldsw + _i * 8192), 16, 0, 0); } while (0)
; #define PG8_LDA(dst, b, h) do { _Pragma("unroll") for (int m = 0; m < 4; ++m) _Pragma("unroll") for (int k = 0; k < 2; ++k) dst[m][k] = *(const LAS bf16x8*)(lds + PG8_SA(b, h) + aoff + m * 2048 + k * 1024); } while (0)
; #define PG8_LDB(dst, b, h) do { _Pragma("unroll") for (int n = 0; n < 2; ++n) _Pragma("unroll") for (int k = 0; k < 2; ++k) dst[n][k] = *(const LAS bf16x8*)(lds + PG8_SB(b, h) + boff + n * 2048 + k * 1024); } while (0)
; #define PG8_MMA(ai, bj, At, Bt) do { __builtin_amdgcn_s_setprio(1); _Pragma("unroll") for (int m = 0; m < 4; ++m) _Pragma("unroll") for (int n = 0; n < 2; ++n) _Pragma("unroll") for (int k = 0; k < 2; ++k) \
;         acc[ai][bj][m][n] = __builtin_amdgcn_mfma_f32_16x16x32_bf16(Bt[n][k], At[m][k], acc[ai][bj][m][n], 0, 0, 0); __builtin_amdgcn_s_setprio(0); } while (0)
; #define PG8_WAIT_V(n) asm volatile("s_waitcnt vmcnt(" #n ")" ::: "memory")
; #define PG8_WAIT_L(n) asm volatile("s_waitcnt lgkmcnt(" #n ")" ::: "memory")
; #define PG8_BAR __builtin_amdgcn_s_barrier()
; #define PG8_SCHED __builtin_amdgcn_sched_barrier(0)
; template <class Epi>
; DEVINL void gemm_phase(LAS unsigned char* lds, const Gemm g, const Order& S, const Epi& E) {
;     ...
;             PG8_STAGE(PG8_SB(0, 1), b2 + hstepB, voffB);
;             PG8_WAIT_V(6); PG8_BAR; PG8_MMA(1, 1, At, B1); PG8_BAR;
;             PG8_LDB(B0, 1, 0); PG8_SCHED; PG8_LDA(At, 1, 0); PG8_STAGE(PG8_SA(0, 1), a2 + hstepA, voffA);
;             PG8_WAIT_L(8); PG8_BAR; PG8_WAIT_L(0); PG8_MMA(0, 0, At, B0); PG8_BAR; PG8_SCHED;
;             PG8_LDB(B1, 1, 1); PG8_STAGE(PG8_SB(1, 0), b3, voffB);
	s_add_u32 s70, s38, 0x40000
	s_addc_u32 s71, s39, 0
	s_add_i32 s72, s59, s45
	v_lshl_add_u64 v[150:151], s[70:71], 0, v[130:131]
	s_mov_b32 m0, s72
	s_nop 0
	global_load_lds_dwordx4 v[150:151], off
	v_lshl_add_u64 v[150:151], s[70:71], 0, v[134:135]
	s_add_i32 m0, s72, 0x2000
	s_nop 0
	global_load_lds_dwordx4 v[150:151], off
	s_waitcnt vmcnt(6)
	s_barrier
	s_setprio 1
	v_mfma_f32_16x16x32_bf16 v[52:55], v[198:201], v[166:169], v[52:55]
	v_mfma_f32_16x16x32_bf16 v[52:55], v[202:205], v[170:173], v[52:55]
	v_mfma_f32_16x16x32_bf16 v[48:51], v[206:209], v[166:169], v[48:51]
	v_mfma_f32_16x16x32_bf16 v[48:51], v[210:213], v[170:173], v[48:51]
	v_mfma_f32_16x16x32_bf16 v[32:35], v[206:209], v[174:177], v[32:35]
	v_mfma_f32_16x16x32_bf16 v[32:35], v[210:213], v[178:181], v[32:35]
	v_mfma_f32_16x16x32_bf16 v[36:39], v[198:201], v[174:177], v[36:39]
	v_mfma_f32_16x16x32_bf16 v[36:39], v[202:205], v[178:181], v[36:39]
	v_mfma_f32_16x16x32_bf16 v[20:23], v[198:201], v[182:185], v[20:23]
	v_mfma_f32_16x16x32_bf16 v[20:23], v[202:205], v[186:189], v[20:23]
	v_mfma_f32_16x16x32_bf16 v[16:19], v[206:209], v[182:185], v[16:19]
	v_mfma_f32_16x16x32_bf16 v[16:19], v[210:213], v[186:189], v[16:19]
	v_mfma_f32_16x16x32_bf16 v[0:3], v[206:209], v[190:193], v[0:3]
	v_mfma_f32_16x16x32_bf16 v[0:3], v[210:213], v[194:197], v[0:3]
	v_mfma_f32_16x16x32_bf16 v[4:7], v[198:201], v[190:193], v[4:7]
	v_mfma_f32_16x16x32_bf16 v[4:7], v[202:205], v[194:197], v[4:7]
	s_setprio 0
	s_add_i32 s70, 16, 0x18000
	v_add_u32_e32 v162, s70, v145
	s_barrier
	ds_read_b128 v[150:153], v162
	ds_read_b128 v[154:157], v162 offset:1024
	ds_read_b128 v[158:161], v162 offset:2048
	ds_read_b128 v[162:165], v162 offset:3072
	s_add_u32 s40, s40, 0x40000
	s_addc_u32 s41, s41, 0
	s_mov_b32 m0, s47
	v_lshl_add_u64 v[198:199], s[40:41], 0, v[128:129]
	ds_read_b128 v[166:169], v148 offset:32768
	ds_read_b128 v[170:173], v148 offset:33792
	ds_read_b128 v[174:177], v148 offset:34816
	ds_read_b128 v[178:181], v148 offset:35840
	ds_read_b128 v[182:185], v148 offset:36864
	ds_read_b128 v[186:189], v148 offset:37888
	ds_read_b128 v[190:193], v148 offset:38912
	ds_read_b128 v[194:197], v148 offset:39936
	global_load_lds_dwordx4 v[198:199], off
	v_lshl_add_u64 v[198:199], s[40:41], 0, v[132:133]
	s_mov_b32 m0, s48
	s_nop 0
	global_load_lds_dwordx4 v[198:199], off
	s_waitcnt lgkmcnt(8)
	s_barrier
	s_waitcnt lgkmcnt(0)
	s_setprio 1
	s_waitcnt lgkmcnt(0)
	v_mfma_f32_16x16x32_bf16 v[120:123], v[150:153], v[166:169], v[120:123]
	v_mfma_f32_16x16x32_bf16 v[120:123], v[154:157], v[170:173], v[120:123]
	v_mfma_f32_16x16x32_bf16 v[124:127], v[158:161], v[166:169], v[124:127]
	v_mfma_f32_16x16x32_bf16 v[124:127], v[162:165], v[170:173], v[124:127]
	v_mfma_f32_16x16x32_bf16 v[104:107], v[158:161], v[174:177], v[104:107]
	v_mfma_f32_16x16x32_bf16 v[104:107], v[162:165], v[178:181], v[104:107]
	v_mfma_f32_16x16x32_bf16 v[108:111], v[150:153], v[174:177], v[108:111]
	v_mfma_f32_16x16x32_bf16 v[108:111], v[154:157], v[178:181], v[108:111]
	v_mfma_f32_16x16x32_bf16 v[92:95], v[150:153], v[182:185], v[92:95]
	v_mfma_f32_16x16x32_bf16 v[92:95], v[154:157], v[186:189], v[92:95]
	v_mfma_f32_16x16x32_bf16 v[88:91], v[158:161], v[182:185], v[88:91]
	v_mfma_f32_16x16x32_bf16 v[88:91], v[162:165], v[186:189], v[88:91]
	v_mfma_f32_16x16x32_bf16 v[72:75], v[158:161], v[190:193], v[72:75]
	v_mfma_f32_16x16x32_bf16 v[72:75], v[162:165], v[194:197], v[72:75]
	v_mfma_f32_16x16x32_bf16 v[76:79], v[150:153], v[190:193], v[76:79]
	v_mfma_f32_16x16x32_bf16 v[76:79], v[154:157], v[194:197], v[76:79]
	s_setprio 0
	s_barrier
	s_add_i32 s40, 16, 0x1c000
	s_add_i32 s41, s70, s45
	v_add_u32_e32 v210, s40, v145
	v_lshl_add_u64 v[218:219], v[218:219], 0, s[6:7]
	s_mov_b32 m0, s41
	ds_read_b128 v[198:201], v210
	ds_read_b128 v[202:205], v210 offset:1024
	ds_read_b128 v[206:209], v210 offset:2048
	ds_read_b128 v[210:213], v210 offset:3072
	global_load_lds_dwordx4 v[218:219], off
	v_lshl_add_u64 v[218:219], v[220:221], 0, s[6:7]
	s_add_i32 m0, s41, 0x2000
	s_nop 0
	global_load_lds_dwordx4 v[218:219], off
	s_barrier
; #define PG8_STAGE(bufoff, gbase, voff) do { _Pragma("unroll") for (int _i = 0; _i < 2; ++_i) \
;         __builtin_amdgcn_global_load_lds((const unsigned*)((const char*)(gbase) + (voff)[_i]), (LAS unsigned*)(lds + (bufoff) + ldsw + _i * 8192), 16, 0, 0); } while (0)
; #define PG8_LDA(dst, b, h) do { _Pragma("unroll") for (int m = 0; m < 4; ++m) _Pragma("unroll") for (int k = 0; k < 2; ++k) dst[m][k] = *(const LAS bf16x8*)(lds + PG8_SA(b, h) + aoff + m * 2048 + k * 1024); } while (0)
; #define PG8_MMA(ai, bj, At, Bt) do { __builtin_amdgcn_s_setprio(1); _Pragma("unroll") for (int m = 0; m < 4; ++m) _Pragma("unroll") for (int n = 0; n < 2; ++n) _Pragma("unroll") for (int k = 0; k < 2; ++k) \
;         acc[ai][bj][m][n] = __builtin_amdgcn_mfma_f32_16x16x32_bf16(Bt[n][k], At[m][k], acc[ai][bj][m][n], 0, 0, 0); __builtin_amdgcn_s_setprio(0); } while (0)
; #define PG8_WAIT_V(n) asm volatile("s_waitcnt vmcnt(" #n ")" ::: "memory")
; #define PG8_WAIT_L(n) asm volatile("s_waitcnt lgkmcnt(" #n ")" ::: "memory")
; #define PG8_BAR __builtin_amdgcn_s_barrier()
; #define PG8_SCHED __builtin_amdgcn_sched_barrier(0)
; template <class Epi>
; DEVINL void gemm_phase(LAS unsigned char* lds, const Gemm g, const Order& S, const Epi& E) {
;     ...
;             PG8_BAR; PG8_WAIT_L(0); PG8_MMA(0, 1, At, B1); PG8_BAR;
;             PG8_LDA(At, 1, 1); PG8_STAGE(PG8_SA(1, 0), a3, voffA);
;             PG8_BAR; PG8_WAIT_L(0); PG8_MMA(1, 0, At, B0); PG8_BAR; PG8_SCHED;
;             PG8_STAGE(PG8_SB(1, 1), b3 + hstepB, voffB);
;             PG8_WAIT_V(6); PG8_BAR; PG8_MMA(1, 1, At, B1); PG8_BAR;
	s_waitcnt lgkmcnt(0)
	s_setprio 1
	s_waitcnt lgkmcnt(0)
	v_mfma_f32_16x16x32_bf16 v[116:119], v[198:201], v[166:169], v[116:119]
	v_mfma_f32_16x16x32_bf16 v[116:119], v[202:205], v[170:173], v[116:119]
	v_mfma_f32_16x16x32_bf16 v[112:115], v[206:209], v[166:169], v[112:115]
	v_mfma_f32_16x16x32_bf16 v[112:115], v[210:213], v[170:173], v[112:115]
	v_mfma_f32_16x16x32_bf16 v[96:99], v[206:209], v[174:177], v[96:99]
	v_mfma_f32_16x16x32_bf16 v[96:99], v[210:213], v[178:181], v[96:99]
	v_mfma_f32_16x16x32_bf16 v[100:103], v[198:201], v[174:177], v[100:103]
	v_mfma_f32_16x16x32_bf16 v[100:103], v[202:205], v[178:181], v[100:103]
	v_mfma_f32_16x16x32_bf16 v[84:87], v[198:201], v[182:185], v[84:87]
	v_mfma_f32_16x16x32_bf16 v[84:87], v[202:205], v[186:189], v[84:87]
	v_mfma_f32_16x16x32_bf16 v[80:83], v[206:209], v[182:185], v[80:83]
	v_mfma_f32_16x16x32_bf16 v[80:83], v[210:213], v[186:189], v[80:83]
	v_mfma_f32_16x16x32_bf16 v[64:67], v[206:209], v[190:193], v[64:67]
	v_mfma_f32_16x16x32_bf16 v[64:67], v[210:213], v[194:197], v[64:67]
	v_mfma_f32_16x16x32_bf16 v[68:71], v[198:201], v[190:193], v[68:71]
	v_mfma_f32_16x16x32_bf16 v[68:71], v[202:205], v[194:197], v[68:71]
	s_setprio 0
	s_mov_b32 m0, s50
	v_lshl_add_u64 v[218:219], v[222:223], 0, s[6:7]
	s_barrier
	ds_read_b128 v[166:169], v148 offset:49152
	ds_read_b128 v[170:173], v148 offset:50176
	ds_read_b128 v[174:177], v148 offset:51200
	ds_read_b128 v[178:181], v148 offset:52224
	ds_read_b128 v[182:185], v148 offset:53248
	ds_read_b128 v[186:189], v148 offset:54272
	ds_read_b128 v[190:193], v148 offset:55296
	ds_read_b128 v[194:197], v148 offset:56320
	global_load_lds_dwordx4 v[218:219], off
	v_lshl_add_u64 v[218:219], v[224:225], 0, s[6:7]
	s_mov_b32 m0, s51
	s_nop 0
	global_load_lds_dwordx4 v[218:219], off
	s_barrier
	s_waitcnt lgkmcnt(0)
	s_setprio 1
	s_waitcnt lgkmcnt(0)
	v_mfma_f32_16x16x32_bf16 v[60:63], v[150:153], v[166:169], v[60:63]
	v_mfma_f32_16x16x32_bf16 v[60:63], v[154:157], v[170:173], v[60:63]
	v_mfma_f32_16x16x32_bf16 v[56:59], v[158:161], v[166:169], v[56:59]
	v_mfma_f32_16x16x32_bf16 v[56:59], v[162:165], v[170:173], v[56:59]
	v_mfma_f32_16x16x32_bf16 v[40:43], v[158:161], v[174:177], v[40:43]
	v_mfma_f32_16x16x32_bf16 v[40:43], v[162:165], v[178:181], v[40:43]
	v_mfma_f32_16x16x32_bf16 v[44:47], v[150:153], v[174:177], v[44:47]
	v_mfma_f32_16x16x32_bf16 v[44:47], v[154:157], v[178:181], v[44:47]
	v_mfma_f32_16x16x32_bf16 v[28:31], v[150:153], v[182:185], v[28:31]
	v_mfma_f32_16x16x32_bf16 v[28:31], v[154:157], v[186:189], v[28:31]
	v_mfma_f32_16x16x32_bf16 v[24:27], v[158:161], v[182:185], v[24:27]
	v_mfma_f32_16x16x32_bf16 v[24:27], v[162:165], v[186:189], v[24:27]
	v_mfma_f32_16x16x32_bf16 v[8:11], v[158:161], v[190:193], v[8:11]
	v_mfma_f32_16x16x32_bf16 v[8:11], v[162:165], v[194:197], v[8:11]
	v_mfma_f32_16x16x32_bf16 v[12:15], v[150:153], v[190:193], v[12:15]
	v_mfma_f32_16x16x32_bf16 v[12:15], v[154:157], v[194:197], v[12:15]
	s_setprio 0
	s_barrier
	s_add_u32 s38, s38, 0x40080
	s_addc_u32 s39, s39, 0
	s_add_i32 s40, s40, s45
	v_lshl_add_u64 v[150:151], s[38:39], 0, v[130:131]
	s_mov_b32 m0, s40
	s_nop 0
	global_load_lds_dwordx4 v[150:151], off
	v_lshl_add_u64 v[150:151], s[38:39], 0, v[134:135]
	s_add_i32 m0, s40, 0x2000
	s_nop 0
	global_load_lds_dwordx4 v[150:151], off
	s_waitcnt vmcnt(6)
	s_barrier
	s_setprio 1
	v_mfma_f32_16x16x32_bf16 v[52:55], v[198:201], v[166:169], v[52:55]
	v_mfma_f32_16x16x32_bf16 v[52:55], v[202:205], v[170:173], v[52:55]
	v_mfma_f32_16x16x32_bf16 v[48:51], v[206:209], v[166:169], v[48:51]
	v_mfma_f32_16x16x32_bf16 v[48:51], v[210:213], v[170:173], v[48:51]
	v_mfma_f32_16x16x32_bf16 v[32:35], v[206:209], v[174:177], v[32:35]
	v_mfma_f32_16x16x32_bf16 v[32:35], v[210:213], v[178:181], v[32:35]
	v_mfma_f32_16x16x32_bf16 v[36:39], v[198:201], v[174:177], v[36:39]
	v_mfma_f32_16x16x32_bf16 v[36:39], v[202:205], v[178:181], v[36:39]
	v_mfma_f32_16x16x32_bf16 v[20:23], v[198:201], v[182:185], v[20:23]
	v_mfma_f32_16x16x32_bf16 v[20:23], v[202:205], v[186:189], v[20:23]
	v_mfma_f32_16x16x32_bf16 v[16:19], v[206:209], v[182:185], v[16:19]
	v_mfma_f32_16x16x32_bf16 v[16:19], v[210:213], v[186:189], v[16:19]
	v_mfma_f32_16x16x32_bf16 v[0:3], v[206:209], v[190:193], v[0:3]
	v_mfma_f32_16x16x32_bf16 v[0:3], v[210:213], v[194:197], v[0:3]
	v_mfma_f32_16x16x32_bf16 v[4:7], v[198:201], v[190:193], v[4:7]
	v_mfma_f32_16x16x32_bf16 v[4:7], v[202:205], v[194:197], v[4:7]
	s_setprio 0
	s_add_u32 s2, s2, 0x100
	s_addc_u32 s3, s3, 0
	s_add_u32 s67, s67, 0x100
	s_addc_u32 s68, s68, 0
	s_cmp_ge_i32 s69, s49
	s_mov_b32 s38, s69
	s_barrier
	s_cbranch_scc0 .LBB0_1623
	s_branch .LBB0_1614

; #define PG8_STAGE(bufoff, gbase, voff) do { _Pragma("unroll") for (int _i = 0; _i < 2; ++_i) \
;         __builtin_amdgcn_global_load_lds((const unsigned*)((const char*)(gbase) + (voff)[_i]), (LAS unsigned*)(lds + (bufoff) + ldsw + _i * 8192), 16, 0, 0); } while (0)
; #define PG8_LDA(dst, b, h) do { _Pragma("unroll") for (int m = 0; m < 4; ++m) _Pragma("unroll") for (int k = 0; k < 2; ++k) dst[m][k] = *(const LAS bf16x8*)(lds + PG8_SA(b, h) + aoff + m * 2048 + k * 1024); } while (0)
; #define PG8_LDB(dst, b, h) do { _Pragma("unroll") for (int n = 0; n < 2; ++n) _Pragma("unroll") for (int k = 0; k < 2; ++k) dst[n][k] = *(const LAS bf16x8*)(lds + PG8_SB(b, h) + boff + n * 2048 + k * 1024); } while (0)
; #define PG8_MMA(ai, bj, At, Bt) do { __builtin_amdgcn_s_setprio(1); _Pragma("unroll") for (int m = 0; m < 4; ++m) _Pragma("unroll") for (int n = 0; n < 2; ++n) _Pragma("unroll") for (int k = 0; k < 2; ++k) \
;         acc[ai][bj][m][n] = __builtin_amdgcn_mfma_f32_16x16x32_bf16(Bt[n][k], At[m][k], acc[ai][bj][m][n], 0, 0, 0); __builtin_amdgcn_s_setprio(0); } while (0)
; #define PG8_WAIT_L(n) asm volatile("s_waitcnt lgkmcnt(" #n ")" ::: "memory")
; #define PG8_BAR __builtin_amdgcn_s_barrier()
; #define PG8_SCHED __builtin_amdgcn_sched_barrier(0)
; template <class Epi>
; DEVINL void gemm_phase(LAS unsigned char* lds, const Gemm g, const Order& S, const Epi& E) {
;     ...
;             PG8_LDB(B0, 0, 0); PG8_SCHED; PG8_LDA(At, 0, 0); PG8_STAGE(PG8_SA(1, 1), a1 + hstepA, voffA);
;             PG8_WAIT_L(8); PG8_BAR; PG8_WAIT_L(0); PG8_MMA(0, 0, At, B0); PG8_BAR; PG8_SCHED;
;             PG8_LDB(B1, 0, 1); PG8_STAGE(PG8_SB(0, 0), b2, voffB);
;             PG8_BAR; PG8_WAIT_L(0); PG8_MMA(0, 1, At, B1); PG8_BAR;
;             PG8_LDA(At, 0, 1); PG8_STAGE(PG8_SA(0, 0), a2, voffA);
;             PG8_BAR; PG8_WAIT_L(0); PG8_MMA(1, 0, At, B0); PG8_BAR; PG8_SCHED;
.LBB0_1775:
	ds_read_b128 v[152:155], v149
	ds_read_b128 v[156:159], v149 offset:1024
	ds_read_b128 v[160:163], v149 offset:2048
	ds_read_b128 v[164:167], v149 offset:3072
	s_add_i32 s55, s26, 2
	s_add_u32 s27, s24, 0xfff80080
	s_addc_u32 s28, s25, -1
	s_cmp_eq_u32 s44, s26
	s_cselect_b32 s26, s52, s53
	s_cselect_b32 s29, s9, s28
	s_cselect_b32 s28, s11, s27
	s_cselect_b32 s27, s51, s54
	v_lshl_add_u64 v[144:145], s[24:25], 0, v[136:137]
	s_add_i32 m0, s17, 0xc000
	ds_read_b128 v[168:171], v150
	ds_read_b128 v[172:175], v150 offset:1024
	ds_read_b128 v[176:179], v150 offset:2048
	ds_read_b128 v[180:183], v150 offset:3072
	ds_read_b128 v[184:187], v150 offset:4096
	ds_read_b128 v[188:191], v150 offset:5120
	ds_read_b128 v[192:195], v150 offset:6144
	ds_read_b128 v[196:199], v150 offset:7168
	global_load_lds_dwordx4 v[144:145], off
	v_lshl_add_u64 v[144:145], s[24:25], 0, v[138:139]
	s_add_i32 m0, s17, 0xe000
	s_nop 0
	global_load_lds_dwordx4 v[144:145], off
	s_waitcnt lgkmcnt(8)
	s_barrier
	s_waitcnt lgkmcnt(0)
	s_setprio 1
	s_waitcnt lgkmcnt(0)
	v_mfma_f32_16x16x32_bf16 v[124:127], v[152:155], v[168:171], v[124:127]
	v_mfma_f32_16x16x32_bf16 v[124:127], v[156:159], v[172:175], v[124:127]
	v_mfma_f32_16x16x32_bf16 v[116:119], v[160:163], v[168:171], v[116:119]
	v_mfma_f32_16x16x32_bf16 v[116:119], v[164:167], v[172:175], v[116:119]
	v_mfma_f32_16x16x32_bf16 v[100:103], v[160:163], v[176:179], v[100:103]
	v_mfma_f32_16x16x32_bf16 v[100:103], v[164:167], v[180:183], v[100:103]
	v_mfma_f32_16x16x32_bf16 v[108:111], v[152:155], v[176:179], v[108:111]
	v_mfma_f32_16x16x32_bf16 v[108:111], v[156:159], v[180:183], v[108:111]
	v_mfma_f32_16x16x32_bf16 v[92:95], v[152:155], v[184:187], v[92:95]
	v_mfma_f32_16x16x32_bf16 v[92:95], v[156:159], v[188:191], v[92:95]
	v_mfma_f32_16x16x32_bf16 v[84:87], v[160:163], v[184:187], v[84:87]
	v_mfma_f32_16x16x32_bf16 v[84:87], v[164:167], v[188:191], v[84:87]
	v_mfma_f32_16x16x32_bf16 v[68:71], v[160:163], v[192:195], v[68:71]
	v_mfma_f32_16x16x32_bf16 v[68:71], v[164:167], v[196:199], v[68:71]
	v_mfma_f32_16x16x32_bf16 v[76:79], v[152:155], v[192:195], v[76:79]
	v_mfma_f32_16x16x32_bf16 v[76:79], v[156:159], v[196:199], v[76:79]
	s_setprio 0
	s_barrier
	s_add_i32 s56, s47, s30
	v_lshl_add_u64 v[144:145], s[26:27], 0, v[132:133]
	s_mov_b32 m0, s56
	ds_read_b128 v[200:203], v151
	ds_read_b128 v[204:207], v151 offset:1024
	ds_read_b128 v[208:211], v151 offset:2048
	ds_read_b128 v[218:221], v151 offset:3072
	global_load_lds_dwordx4 v[144:145], off
	v_lshl_add_u64 v[212:213], s[26:27], 0, v[128:129]
	s_add_i32 m0, s56, 0x2000
	s_nop 0
	global_load_lds_dwordx4 v[212:213], off
	s_barrier
	s_waitcnt lgkmcnt(0)
	s_setprio 1
	s_waitcnt lgkmcnt(0)
	v_mfma_f32_16x16x32_bf16 v[120:123], v[200:203], v[168:171], v[120:123]
	v_mfma_f32_16x16x32_bf16 v[120:123], v[204:207], v[172:175], v[120:123]
	v_mfma_f32_16x16x32_bf16 v[112:115], v[208:211], v[168:171], v[112:115]
	v_mfma_f32_16x16x32_bf16 v[112:115], v[218:221], v[172:175], v[112:115]
	v_mfma_f32_16x16x32_bf16 v[96:99], v[208:211], v[176:179], v[96:99]
	v_mfma_f32_16x16x32_bf16 v[96:99], v[218:221], v[180:183], v[96:99]
	v_mfma_f32_16x16x32_bf16 v[104:107], v[200:203], v[176:179], v[104:107]
	v_mfma_f32_16x16x32_bf16 v[104:107], v[204:207], v[180:183], v[104:107]
	v_mfma_f32_16x16x32_bf16 v[88:91], v[200:203], v[184:187], v[88:91]
	v_mfma_f32_16x16x32_bf16 v[88:91], v[204:207], v[188:191], v[88:91]
	v_mfma_f32_16x16x32_bf16 v[80:83], v[208:211], v[184:187], v[80:83]
	v_mfma_f32_16x16x32_bf16 v[80:83], v[218:221], v[188:191], v[80:83]
	v_mfma_f32_16x16x32_bf16 v[64:67], v[208:211], v[192:195], v[64:67]
	v_mfma_f32_16x16x32_bf16 v[64:67], v[218:221], v[196:199], v[64:67]
	v_mfma_f32_16x16x32_bf16 v[72:75], v[200:203], v[192:195], v[72:75]
	v_mfma_f32_16x16x32_bf16 v[72:75], v[204:207], v[196:199], v[72:75]
	s_setprio 0
	s_mov_b32 m0, s17
	v_lshl_add_u64 v[222:223], s[28:29], 0, v[134:135]
	s_barrier
	ds_read_b128 v[168:171], v150 offset:16384
	ds_read_b128 v[172:175], v150 offset:17408
	ds_read_b128 v[176:179], v150 offset:18432
	ds_read_b128 v[180:183], v150 offset:19456
	ds_read_b128 v[184:187], v150 offset:20480
	ds_read_b128 v[188:191], v150 offset:21504
	ds_read_b128 v[192:195], v150 offset:22528
	ds_read_b128 v[196:199], v150 offset:23552
	global_load_lds_dwordx4 v[222:223], off
	v_lshl_add_u64 v[224:225], s[28:29], 0, v[130:131]
	s_mov_b32 m0, s37
	s_nop 0
	global_load_lds_dwordx4 v[224:225], off
	s_barrier
	s_waitcnt lgkmcnt(0)
	s_setprio 1
	s_waitcnt lgkmcnt(0)
	v_mfma_f32_16x16x32_bf16 v[60:63], v[152:155], v[168:171], v[60:63]
	v_mfma_f32_16x16x32_bf16 v[60:63], v[156:159], v[172:175], v[60:63]
	v_mfma_f32_16x16x32_bf16 v[52:55], v[160:163], v[168:171], v[52:55]
	v_mfma_f32_16x16x32_bf16 v[52:55], v[164:167], v[172:175], v[52:55]
	v_mfma_f32_16x16x32_bf16 v[36:39], v[160:163], v[176:179], v[36:39]
	v_mfma_f32_16x16x32_bf16 v[36:39], v[164:167], v[180:183], v[36:39]
	v_mfma_f32_16x16x32_bf16 v[44:47], v[152:155], v[176:179], v[44:47]
	v_mfma_f32_16x16x32_bf16 v[44:47], v[156:159], v[180:183], v[44:47]
	v_mfma_f32_16x16x32_bf16 v[28:31], v[152:155], v[184:187], v[28:31]
	v_mfma_f32_16x16x32_bf16 v[28:31], v[156:159], v[188:191], v[28:31]
	v_mfma_f32_16x16x32_bf16 v[20:23], v[160:163], v[184:187], v[20:23]
	v_mfma_f32_16x16x32_bf16 v[20:23], v[164:167], v[188:191], v[20:23]
	v_mfma_f32_16x16x32_bf16 v[4:7], v[160:163], v[192:195], v[4:7]
	v_mfma_f32_16x16x32_bf16 v[4:7], v[164:167], v[196:199], v[4:7]
	v_mfma_f32_16x16x32_bf16 v[12:15], v[152:155], v[192:195], v[12:15]
	v_mfma_f32_16x16x32_bf16 v[12:15], v[156:159], v[196:199], v[12:15]
	s_setprio 0
	s_barrier
; #define PG8_STAGE(bufoff, gbase, voff) do { _Pragma("unroll") for (int _i = 0; _i < 2; ++_i) \
;         __builtin_amdgcn_global_load_lds((const unsigned*)((const char*)(gbase) + (voff)[_i]), (LAS unsigned*)(lds + (bufoff) + ldsw + _i * 8192), 16, 0, 0); } while (0)
; #define PG8_LDA(dst, b, h) do { _Pragma("unroll") for (int m = 0; m < 4; ++m) _Pragma("unroll") for (int k = 0; k < 2; ++k) dst[m][k] = *(const LAS bf16x8*)(lds + PG8_SA(b, h) + aoff + m * 2048 + k * 1024); } while (0)
; #define PG8_LDB(dst, b, h) do { _Pragma("unroll") for (int n = 0; n < 2; ++n) _Pragma("unroll") for (int k = 0; k < 2; ++k) dst[n][k] = *(const LAS bf16x8*)(lds + PG8_SB(b, h) + boff + n * 2048 + k * 1024); } while (0)
; #define PG8_MMA(ai, bj, At, Bt) do { __builtin_amdgcn_s_setprio(1); _Pragma("unroll") for (int m = 0; m < 4; ++m) _Pragma("unroll") for (int n = 0; n < 2; ++n) _Pragma("unroll") for (int k = 0; k < 2; ++k) \
;         acc[ai][bj][m][n] = __builtin_amdgcn_mfma_f32_16x16x32_bf16(Bt[n][k], At[m][k], acc[ai][bj][m][n], 0, 0, 0); __builtin_amdgcn_s_setprio(0); } while (0)
; #define PG8_WAIT_V(n) asm volatile("s_waitcnt vmcnt(" #n ")" ::: "memory")
; #define PG8_WAIT_L(n) asm volatile("s_waitcnt lgkmcnt(" #n ")" ::: "memory")
; #define PG8_BAR __builtin_amdgcn_s_barrier()
; #define PG8_SCHED __builtin_amdgcn_sched_barrier(0)
; template <class Epi>
; DEVINL void gemm_phase(LAS unsigned char* lds, const Gemm g, const Order& S, const Epi& E) {
;     ...
;             PG8_STAGE(PG8_SB(0, 1), b2 + hstepB, voffB);
;             PG8_WAIT_V(6); PG8_BAR; PG8_MMA(1, 1, At, B1); PG8_BAR;
;             PG8_LDB(B0, 1, 0); PG8_SCHED; PG8_LDA(At, 1, 0); PG8_STAGE(PG8_SA(0, 1), a2 + hstepA, voffA);
;             PG8_WAIT_L(8); PG8_BAR; PG8_WAIT_L(0); PG8_MMA(0, 0, At, B0); PG8_BAR; PG8_SCHED;
;             PG8_LDB(B1, 1, 1); PG8_STAGE(PG8_SB(1, 0), b3, voffB);
	s_add_u32 s56, s26, 0x80000
	s_addc_u32 s57, s27, 0
	s_add_i32 s58, s48, s30
	v_lshl_add_u64 v[152:153], s[56:57], 0, v[132:133]
	s_mov_b32 m0, s58
	s_nop 0
	global_load_lds_dwordx4 v[152:153], off
	v_lshl_add_u64 v[152:153], s[56:57], 0, v[128:129]
	s_add_i32 m0, s58, 0x2000
	s_nop 0
	global_load_lds_dwordx4 v[152:153], off
	s_waitcnt vmcnt(6)
	s_barrier
	s_setprio 1
	v_mfma_f32_16x16x32_bf16 v[56:59], v[200:203], v[168:171], v[56:59]
	v_mfma_f32_16x16x32_bf16 v[56:59], v[204:207], v[172:175], v[56:59]
	v_mfma_f32_16x16x32_bf16 v[48:51], v[208:211], v[168:171], v[48:51]
	v_mfma_f32_16x16x32_bf16 v[48:51], v[218:221], v[172:175], v[48:51]
	v_mfma_f32_16x16x32_bf16 v[32:35], v[208:211], v[176:179], v[32:35]
	v_mfma_f32_16x16x32_bf16 v[32:35], v[218:221], v[180:183], v[32:35]
	v_mfma_f32_16x16x32_bf16 v[40:43], v[200:203], v[176:179], v[40:43]
	v_mfma_f32_16x16x32_bf16 v[40:43], v[204:207], v[180:183], v[40:43]
	v_mfma_f32_16x16x32_bf16 v[24:27], v[200:203], v[184:187], v[24:27]
	v_mfma_f32_16x16x32_bf16 v[24:27], v[204:207], v[188:191], v[24:27]
	v_mfma_f32_16x16x32_bf16 v[16:19], v[208:211], v[184:187], v[16:19]
	v_mfma_f32_16x16x32_bf16 v[16:19], v[218:221], v[188:191], v[16:19]
	v_mfma_f32_16x16x32_bf16 v[0:3], v[208:211], v[192:195], v[0:3]
	v_mfma_f32_16x16x32_bf16 v[0:3], v[218:221], v[196:199], v[0:3]
	v_mfma_f32_16x16x32_bf16 v[8:11], v[200:203], v[192:195], v[8:11]
	v_mfma_f32_16x16x32_bf16 v[8:11], v[204:207], v[196:199], v[8:11]
	s_setprio 0
	s_add_i32 s56, 16, 0x18000
	v_add_u32_e32 v164, s56, v147
	s_barrier
	ds_read_b128 v[152:155], v164
	ds_read_b128 v[156:159], v164 offset:1024
	ds_read_b128 v[160:163], v164 offset:2048
	ds_read_b128 v[164:167], v164 offset:3072
	s_add_u32 s28, s28, 0x80000
	s_addc_u32 s29, s29, 0
	s_mov_b32 m0, s38
	v_lshl_add_u64 v[200:201], s[28:29], 0, v[134:135]
	ds_read_b128 v[168:171], v150 offset:32768
	ds_read_b128 v[172:175], v150 offset:33792
	ds_read_b128 v[176:179], v150 offset:34816
	ds_read_b128 v[180:183], v150 offset:35840
	ds_read_b128 v[184:187], v150 offset:36864
	ds_read_b128 v[188:191], v150 offset:37888
	ds_read_b128 v[192:195], v150 offset:38912
	ds_read_b128 v[196:199], v150 offset:39936
	global_load_lds_dwordx4 v[200:201], off
	v_lshl_add_u64 v[200:201], s[28:29], 0, v[130:131]
	s_mov_b32 m0, s39
	s_nop 0
	global_load_lds_dwordx4 v[200:201], off
	s_waitcnt lgkmcnt(8)
	s_barrier
	s_waitcnt lgkmcnt(0)
	s_setprio 1
	s_waitcnt lgkmcnt(0)
	v_mfma_f32_16x16x32_bf16 v[124:127], v[152:155], v[168:171], v[124:127]
	v_mfma_f32_16x16x32_bf16 v[124:127], v[156:159], v[172:175], v[124:127]
	v_mfma_f32_16x16x32_bf16 v[116:119], v[160:163], v[168:171], v[116:119]
	v_mfma_f32_16x16x32_bf16 v[116:119], v[164:167], v[172:175], v[116:119]
	v_mfma_f32_16x16x32_bf16 v[100:103], v[160:163], v[176:179], v[100:103]
	v_mfma_f32_16x16x32_bf16 v[100:103], v[164:167], v[180:183], v[100:103]
	v_mfma_f32_16x16x32_bf16 v[108:111], v[152:155], v[176:179], v[108:111]
	v_mfma_f32_16x16x32_bf16 v[108:111], v[156:159], v[180:183], v[108:111]
	v_mfma_f32_16x16x32_bf16 v[92:95], v[152:155], v[184:187], v[92:95]
	v_mfma_f32_16x16x32_bf16 v[92:95], v[156:159], v[188:191], v[92:95]
	v_mfma_f32_16x16x32_bf16 v[84:87], v[160:163], v[184:187], v[84:87]
	v_mfma_f32_16x16x32_bf16 v[84:87], v[164:167], v[188:191], v[84:87]
	v_mfma_f32_16x16x32_bf16 v[68:71], v[160:163], v[192:195], v[68:71]
	v_mfma_f32_16x16x32_bf16 v[68:71], v[164:167], v[196:199], v[68:71]
	v_mfma_f32_16x16x32_bf16 v[76:79], v[152:155], v[192:195], v[76:79]
	v_mfma_f32_16x16x32_bf16 v[76:79], v[156:159], v[196:199], v[76:79]
	s_setprio 0
	s_barrier
	s_add_i32 s28, 16, 0x1c000
	s_add_i32 s29, s56, s30
	v_add_u32_e32 v214, s28, v147
	v_lshl_add_u64 v[144:145], v[144:145], 0, s[6:7]
	s_mov_b32 m0, s29
	ds_read_b128 v[200:203], v214
	ds_read_b128 v[204:207], v214 offset:1024
	ds_read_b128 v[208:211], v214 offset:2048
	ds_read_b128 v[218:221], v214 offset:3072
	global_load_lds_dwordx4 v[144:145], off
	v_lshl_add_u64 v[144:145], v[212:213], 0, s[6:7]
	s_add_i32 m0, s29, 0x2000
	s_nop 0
	global_load_lds_dwordx4 v[144:145], off
	s_barrier
; #define PG8_STAGE(bufoff, gbase, voff) do { _Pragma("unroll") for (int _i = 0; _i < 2; ++_i) \
;         __builtin_amdgcn_global_load_lds((const unsigned*)((const char*)(gbase) + (voff)[_i]), (LAS unsigned*)(lds + (bufoff) + ldsw + _i * 8192), 16, 0, 0); } while (0)
; #define PG8_LDA(dst, b, h) do { _Pragma("unroll") for (int m = 0; m < 4; ++m) _Pragma("unroll") for (int k = 0; k < 2; ++k) dst[m][k] = *(const LAS bf16x8*)(lds + PG8_SA(b, h) + aoff + m * 2048 + k * 1024); } while (0)
; #define PG8_MMA(ai, bj, At, Bt) do { __builtin_amdgcn_s_setprio(1); _Pragma("unroll") for (int m = 0; m < 4; ++m) _Pragma("unroll") for (int n = 0; n < 2; ++n) _Pragma("unroll") for (int k = 0; k < 2; ++k) \
;         acc[ai][bj][m][n] = __builtin_amdgcn_mfma_f32_16x16x32_bf16(Bt[n][k], At[m][k], acc[ai][bj][m][n], 0, 0, 0); __builtin_amdgcn_s_setprio(0); } while (0)
; #define PG8_WAIT_V(n) asm volatile("s_waitcnt vmcnt(" #n ")" ::: "memory")
; #define PG8_WAIT_L(n) asm volatile("s_waitcnt lgkmcnt(" #n ")" ::: "memory")
; #define PG8_BAR __builtin_amdgcn_s_barrier()
; #define PG8_SCHED __builtin_amdgcn_sched_barrier(0)
; template <class Epi>
; DEVINL void gemm_phase(LAS unsigned char* lds, const Gemm g, const Order& S, const Epi& E) {
;     ...
;             PG8_BAR; PG8_WAIT_L(0); PG8_MMA(0, 1, At, B1); PG8_BAR;
;             PG8_LDA(At, 1, 1); PG8_STAGE(PG8_SA(1, 0), a3, voffA);
;             PG8_BAR; PG8_WAIT_L(0); PG8_MMA(1, 0, At, B0); PG8_BAR; PG8_SCHED;
;             PG8_STAGE(PG8_SB(1, 1), b3 + hstepB, voffB);
;             PG8_WAIT_V(6); PG8_BAR; PG8_MMA(1, 1, At, B1); PG8_BAR;
	s_waitcnt lgkmcnt(0)
	s_setprio 1
	s_waitcnt lgkmcnt(0)
	v_mfma_f32_16x16x32_bf16 v[120:123], v[200:203], v[168:171], v[120:123]
	v_mfma_f32_16x16x32_bf16 v[120:123], v[204:207], v[172:175], v[120:123]
	v_mfma_f32_16x16x32_bf16 v[112:115], v[208:211], v[168:171], v[112:115]
	v_mfma_f32_16x16x32_bf16 v[112:115], v[218:221], v[172:175], v[112:115]
	v_mfma_f32_16x16x32_bf16 v[96:99], v[208:211], v[176:179], v[96:99]
	v_mfma_f32_16x16x32_bf16 v[96:99], v[218:221], v[180:183], v[96:99]
	v_mfma_f32_16x16x32_bf16 v[104:107], v[200:203], v[176:179], v[104:107]
	v_mfma_f32_16x16x32_bf16 v[104:107], v[204:207], v[180:183], v[104:107]
	v_mfma_f32_16x16x32_bf16 v[88:91], v[200:203], v[184:187], v[88:91]
	v_mfma_f32_16x16x32_bf16 v[88:91], v[204:207], v[188:191], v[88:91]
	v_mfma_f32_16x16x32_bf16 v[80:83], v[208:211], v[184:187], v[80:83]
	v_mfma_f32_16x16x32_bf16 v[80:83], v[218:221], v[188:191], v[80:83]
	v_mfma_f32_16x16x32_bf16 v[64:67], v[208:211], v[192:195], v[64:67]
	v_mfma_f32_16x16x32_bf16 v[64:67], v[218:221], v[196:199], v[64:67]
	v_mfma_f32_16x16x32_bf16 v[72:75], v[200:203], v[192:195], v[72:75]
	v_mfma_f32_16x16x32_bf16 v[72:75], v[204:207], v[196:199], v[72:75]
	s_setprio 0
	s_mov_b32 m0, s42
	v_lshl_add_u64 v[144:145], v[222:223], 0, s[6:7]
	s_barrier
	ds_read_b128 v[168:171], v150 offset:49152
	ds_read_b128 v[172:175], v150 offset:50176
	ds_read_b128 v[176:179], v150 offset:51200
	ds_read_b128 v[180:183], v150 offset:52224
	ds_read_b128 v[184:187], v150 offset:53248
	ds_read_b128 v[188:191], v150 offset:54272
	ds_read_b128 v[192:195], v150 offset:55296
	ds_read_b128 v[196:199], v150 offset:56320
	global_load_lds_dwordx4 v[144:145], off
	v_lshl_add_u64 v[144:145], v[224:225], 0, s[6:7]
	s_mov_b32 m0, s43
	s_nop 0
	global_load_lds_dwordx4 v[144:145], off
	s_barrier
	s_waitcnt lgkmcnt(0)
	s_setprio 1
	s_waitcnt lgkmcnt(0)
	v_mfma_f32_16x16x32_bf16 v[60:63], v[152:155], v[168:171], v[60:63]
	v_mfma_f32_16x16x32_bf16 v[60:63], v[156:159], v[172:175], v[60:63]
	v_mfma_f32_16x16x32_bf16 v[52:55], v[160:163], v[168:171], v[52:55]
	v_mfma_f32_16x16x32_bf16 v[52:55], v[164:167], v[172:175], v[52:55]
	v_mfma_f32_16x16x32_bf16 v[36:39], v[160:163], v[176:179], v[36:39]
	v_mfma_f32_16x16x32_bf16 v[36:39], v[164:167], v[180:183], v[36:39]
	v_mfma_f32_16x16x32_bf16 v[44:47], v[152:155], v[176:179], v[44:47]
	v_mfma_f32_16x16x32_bf16 v[44:47], v[156:159], v[180:183], v[44:47]
	v_mfma_f32_16x16x32_bf16 v[28:31], v[152:155], v[184:187], v[28:31]
	v_mfma_f32_16x16x32_bf16 v[28:31], v[156:159], v[188:191], v[28:31]
	v_mfma_f32_16x16x32_bf16 v[20:23], v[160:163], v[184:187], v[20:23]
	v_mfma_f32_16x16x32_bf16 v[20:23], v[164:167], v[188:191], v[20:23]
	v_mfma_f32_16x16x32_bf16 v[4:7], v[160:163], v[192:195], v[4:7]
	v_mfma_f32_16x16x32_bf16 v[4:7], v[164:167], v[196:199], v[4:7]
	v_mfma_f32_16x16x32_bf16 v[12:15], v[152:155], v[192:195], v[12:15]
	v_mfma_f32_16x16x32_bf16 v[12:15], v[156:159], v[196:199], v[12:15]
	s_setprio 0
	s_barrier
	s_add_u32 s26, s26, 0x80080
	s_addc_u32 s27, s27, 0
	s_add_i32 s28, s28, s30
	v_lshl_add_u64 v[144:145], s[26:27], 0, v[132:133]
	s_mov_b32 m0, s28
	s_nop 0
	global_load_lds_dwordx4 v[144:145], off
	v_lshl_add_u64 v[144:145], s[26:27], 0, v[128:129]
	s_add_i32 m0, s28, 0x2000
	s_nop 0
	global_load_lds_dwordx4 v[144:145], off
	s_waitcnt vmcnt(6)
	s_barrier
	s_setprio 1
	v_mfma_f32_16x16x32_bf16 v[56:59], v[200:203], v[168:171], v[56:59]
	v_mfma_f32_16x16x32_bf16 v[56:59], v[204:207], v[172:175], v[56:59]
	v_mfma_f32_16x16x32_bf16 v[48:51], v[208:211], v[168:171], v[48:51]
	v_mfma_f32_16x16x32_bf16 v[48:51], v[218:221], v[172:175], v[48:51]
	v_mfma_f32_16x16x32_bf16 v[32:35], v[208:211], v[176:179], v[32:35]
	v_mfma_f32_16x16x32_bf16 v[32:35], v[218:221], v[180:183], v[32:35]
	v_mfma_f32_16x16x32_bf16 v[40:43], v[200:203], v[176:179], v[40:43]
	v_mfma_f32_16x16x32_bf16 v[40:43], v[204:207], v[180:183], v[40:43]
	v_mfma_f32_16x16x32_bf16 v[24:27], v[200:203], v[184:187], v[24:27]
	v_mfma_f32_16x16x32_bf16 v[24:27], v[204:207], v[188:191], v[24:27]
	v_mfma_f32_16x16x32_bf16 v[16:19], v[208:211], v[184:187], v[16:19]
	v_mfma_f32_16x16x32_bf16 v[16:19], v[218:221], v[188:191], v[16:19]
	v_mfma_f32_16x16x32_bf16 v[0:3], v[208:211], v[192:195], v[0:3]
	v_mfma_f32_16x16x32_bf16 v[0:3], v[218:221], v[196:199], v[0:3]
	v_mfma_f32_16x16x32_bf16 v[8:11], v[200:203], v[192:195], v[8:11]
	v_mfma_f32_16x16x32_bf16 v[8:11], v[204:207], v[196:199], v[8:11]
	s_setprio 0
	s_add_u32 s24, s24, 0x100
	s_addc_u32 s25, s25, 0
	s_add_u32 s53, s53, 0x100
	s_addc_u32 s54, s54, 0
	s_cmp_ge_i32 s55, s41
	s_mov_b32 s26, s55
	s_barrier
	s_cbranch_scc0 .LBB0_1775
	s_branch .LBB0_1770

; #define PG8_STAGE(bufoff, gbase, voff) do { _Pragma("unroll") for (int _i = 0; _i < 2; ++_i) \
;         __builtin_amdgcn_global_load_lds((const unsigned*)((const char*)(gbase) + (voff)[_i]), (LAS unsigned*)(lds + (bufoff) + ldsw + _i * 8192), 16, 0, 0); } while (0)
; #define PG8_LDA(dst, b, h) do { _Pragma("unroll") for (int m = 0; m < 4; ++m) _Pragma("unroll") for (int k = 0; k < 2; ++k) dst[m][k] = *(const LAS bf16x8*)(lds + PG8_SA(b, h) + aoff + m * 2048 + k * 1024); } while (0)
; #define PG8_LDB(dst, b, h) do { _Pragma("unroll") for (int n = 0; n < 2; ++n) _Pragma("unroll") for (int k = 0; k < 2; ++k) dst[n][k] = *(const LAS bf16x8*)(lds + PG8_SB(b, h) + boff + n * 2048 + k * 1024); } while (0)
; #define PG8_MMA(ai, bj, At, Bt) do { __builtin_amdgcn_s_setprio(1); _Pragma("unroll") for (int m = 0; m < 4; ++m) _Pragma("unroll") for (int n = 0; n < 2; ++n) _Pragma("unroll") for (int k = 0; k < 2; ++k) \
;         acc[ai][bj][m][n] = __builtin_amdgcn_mfma_f32_16x16x32_bf16(Bt[n][k], At[m][k], acc[ai][bj][m][n], 0, 0, 0); __builtin_amdgcn_s_setprio(0); } while (0)
; #define PG8_WAIT_L(n) asm volatile("s_waitcnt lgkmcnt(" #n ")" ::: "memory")
; #define PG8_BAR __builtin_amdgcn_s_barrier()
; #define PG8_SCHED __builtin_amdgcn_sched_barrier(0)
; template <class Epi>
; DEVINL void gemm_phase(LAS unsigned char* lds, const Gemm g, const Order& S, const Epi& E) {
;     ...
;             PG8_LDB(B0, 0, 0); PG8_SCHED; PG8_LDA(At, 0, 0); PG8_STAGE(PG8_SA(1, 1), a1 + hstepA, voffA);
;             PG8_WAIT_L(8); PG8_BAR; PG8_WAIT_L(0); PG8_MMA(0, 0, At, B0); PG8_BAR; PG8_SCHED;
;             PG8_LDB(B1, 0, 1); PG8_STAGE(PG8_SB(0, 0), b2, voffB);
;             PG8_BAR; PG8_WAIT_L(0); PG8_MMA(0, 1, At, B1); PG8_BAR;
;             PG8_LDA(At, 0, 1); PG8_STAGE(PG8_SA(0, 0), a2, voffA);
;             PG8_BAR; PG8_WAIT_L(0); PG8_MMA(1, 0, At, B0); PG8_BAR; PG8_SCHED;
.LBB0_1852:
	ds_read_b128 v[150:153], v147
	ds_read_b128 v[154:157], v147 offset:1024
	ds_read_b128 v[158:161], v147 offset:2048
	ds_read_b128 v[162:165], v147 offset:3072
	s_add_i32 s61, s28, 2
	s_add_u32 s26, s24, 0x100
	s_addc_u32 s27, s25, 0
	s_cmp_eq_u32 s45, s28
	s_cselect_b32 s28, s4, s59
	s_cselect_b32 s31, s3, s27
	s_cselect_b32 s30, s2, s26
	s_cselect_b32 s29, s5, s60
	v_lshl_add_u64 v[198:199], s[24:25], 0, v[136:137]
	s_add_i32 m0, s38, 0xc000
	ds_read_b128 v[166:169], v148
	ds_read_b128 v[170:173], v148 offset:1024
	ds_read_b128 v[174:177], v148 offset:2048
	ds_read_b128 v[178:181], v148 offset:3072
	ds_read_b128 v[182:185], v148 offset:4096
	ds_read_b128 v[186:189], v148 offset:5120
	ds_read_b128 v[190:193], v148 offset:6144
	ds_read_b128 v[194:197], v148 offset:7168
	global_load_lds_dwordx4 v[198:199], off
	v_lshl_add_u64 v[198:199], s[24:25], 0, v[138:139]
	s_add_i32 m0, s38, 0xe000
	s_nop 0
	global_load_lds_dwordx4 v[198:199], off
	s_waitcnt lgkmcnt(8)
	s_barrier
	s_waitcnt lgkmcnt(0)
	s_setprio 1
	s_waitcnt lgkmcnt(0)
	v_mfma_f32_16x16x32_bf16 v[120:123], v[150:153], v[166:169], v[120:123]
	v_mfma_f32_16x16x32_bf16 v[120:123], v[154:157], v[170:173], v[120:123]
	v_mfma_f32_16x16x32_bf16 v[124:127], v[158:161], v[166:169], v[124:127]
	v_mfma_f32_16x16x32_bf16 v[124:127], v[162:165], v[170:173], v[124:127]
	v_mfma_f32_16x16x32_bf16 v[104:107], v[158:161], v[174:177], v[104:107]
	v_mfma_f32_16x16x32_bf16 v[104:107], v[162:165], v[178:181], v[104:107]
	v_mfma_f32_16x16x32_bf16 v[108:111], v[150:153], v[174:177], v[108:111]
	v_mfma_f32_16x16x32_bf16 v[108:111], v[154:157], v[178:181], v[108:111]
	v_mfma_f32_16x16x32_bf16 v[92:95], v[150:153], v[182:185], v[92:95]
	v_mfma_f32_16x16x32_bf16 v[92:95], v[154:157], v[186:189], v[92:95]
	v_mfma_f32_16x16x32_bf16 v[88:91], v[158:161], v[182:185], v[88:91]
	v_mfma_f32_16x16x32_bf16 v[88:91], v[162:165], v[186:189], v[88:91]
	v_mfma_f32_16x16x32_bf16 v[72:75], v[158:161], v[190:193], v[72:75]
	v_mfma_f32_16x16x32_bf16 v[72:75], v[162:165], v[194:197], v[72:75]
	v_mfma_f32_16x16x32_bf16 v[76:79], v[150:153], v[190:193], v[76:79]
	v_mfma_f32_16x16x32_bf16 v[76:79], v[154:157], v[194:197], v[76:79]
	s_setprio 0
	s_barrier
	s_add_i32 s24, s49, s37
	v_lshl_add_u64 v[218:219], s[28:29], 0, v[130:131]
	s_mov_b32 m0, s24
	ds_read_b128 v[198:201], v149
	ds_read_b128 v[202:205], v149 offset:1024
	ds_read_b128 v[206:209], v149 offset:2048
	ds_read_b128 v[210:213], v149 offset:3072
	global_load_lds_dwordx4 v[218:219], off
	v_lshl_add_u64 v[220:221], s[28:29], 0, v[134:135]
	s_add_i32 m0, s24, 0x2000
	s_nop 0
	global_load_lds_dwordx4 v[220:221], off
	s_barrier
	s_waitcnt lgkmcnt(0)
	s_setprio 1
	s_waitcnt lgkmcnt(0)
	v_mfma_f32_16x16x32_bf16 v[116:119], v[198:201], v[166:169], v[116:119]
	v_mfma_f32_16x16x32_bf16 v[116:119], v[202:205], v[170:173], v[116:119]
	v_mfma_f32_16x16x32_bf16 v[112:115], v[206:209], v[166:169], v[112:115]
	v_mfma_f32_16x16x32_bf16 v[112:115], v[210:213], v[170:173], v[112:115]
	v_mfma_f32_16x16x32_bf16 v[96:99], v[206:209], v[174:177], v[96:99]
	v_mfma_f32_16x16x32_bf16 v[96:99], v[210:213], v[178:181], v[96:99]
	v_mfma_f32_16x16x32_bf16 v[100:103], v[198:201], v[174:177], v[100:103]
	v_mfma_f32_16x16x32_bf16 v[100:103], v[202:205], v[178:181], v[100:103]
	v_mfma_f32_16x16x32_bf16 v[84:87], v[198:201], v[182:185], v[84:87]
	v_mfma_f32_16x16x32_bf16 v[84:87], v[202:205], v[186:189], v[84:87]
	v_mfma_f32_16x16x32_bf16 v[80:83], v[206:209], v[182:185], v[80:83]
	v_mfma_f32_16x16x32_bf16 v[80:83], v[210:213], v[186:189], v[80:83]
	v_mfma_f32_16x16x32_bf16 v[64:67], v[206:209], v[190:193], v[64:67]
	v_mfma_f32_16x16x32_bf16 v[64:67], v[210:213], v[194:197], v[64:67]
	v_mfma_f32_16x16x32_bf16 v[68:71], v[198:201], v[190:193], v[68:71]
	v_mfma_f32_16x16x32_bf16 v[68:71], v[202:205], v[194:197], v[68:71]
	s_setprio 0
	s_mov_b32 m0, s38
	v_lshl_add_u64 v[222:223], s[30:31], 0, v[128:129]
	s_barrier
	ds_read_b128 v[166:169], v148 offset:16384
	ds_read_b128 v[170:173], v148 offset:17408
	ds_read_b128 v[174:177], v148 offset:18432
	ds_read_b128 v[178:181], v148 offset:19456
	ds_read_b128 v[182:185], v148 offset:20480
	ds_read_b128 v[186:189], v148 offset:21504
	ds_read_b128 v[190:193], v148 offset:22528
	ds_read_b128 v[194:197], v148 offset:23552
	global_load_lds_dwordx4 v[222:223], off
	v_lshl_add_u64 v[224:225], s[30:31], 0, v[132:133]
	s_mov_b32 m0, s39
	s_nop 0
	global_load_lds_dwordx4 v[224:225], off
	s_barrier
	s_waitcnt lgkmcnt(0)
	s_setprio 1
	s_waitcnt lgkmcnt(0)
	v_mfma_f32_16x16x32_bf16 v[60:63], v[150:153], v[166:169], v[60:63]
	v_mfma_f32_16x16x32_bf16 v[60:63], v[154:157], v[170:173], v[60:63]
	v_mfma_f32_16x16x32_bf16 v[56:59], v[158:161], v[166:169], v[56:59]
	v_mfma_f32_16x16x32_bf16 v[56:59], v[162:165], v[170:173], v[56:59]
	v_mfma_f32_16x16x32_bf16 v[40:43], v[158:161], v[174:177], v[40:43]
	v_mfma_f32_16x16x32_bf16 v[40:43], v[162:165], v[178:181], v[40:43]
	v_mfma_f32_16x16x32_bf16 v[44:47], v[150:153], v[174:177], v[44:47]
	v_mfma_f32_16x16x32_bf16 v[44:47], v[154:157], v[178:181], v[44:47]
	v_mfma_f32_16x16x32_bf16 v[28:31], v[150:153], v[182:185], v[28:31]
	v_mfma_f32_16x16x32_bf16 v[28:31], v[154:157], v[186:189], v[28:31]
	v_mfma_f32_16x16x32_bf16 v[24:27], v[158:161], v[182:185], v[24:27]
	v_mfma_f32_16x16x32_bf16 v[24:27], v[162:165], v[186:189], v[24:27]
	v_mfma_f32_16x16x32_bf16 v[8:11], v[158:161], v[190:193], v[8:11]
	v_mfma_f32_16x16x32_bf16 v[8:11], v[162:165], v[194:197], v[8:11]
	v_mfma_f32_16x16x32_bf16 v[12:15], v[150:153], v[190:193], v[12:15]
	v_mfma_f32_16x16x32_bf16 v[12:15], v[154:157], v[194:197], v[12:15]
	s_setprio 0
	s_barrier
; #define PG8_STAGE(bufoff, gbase, voff) do { _Pragma("unroll") for (int _i = 0; _i < 2; ++_i) \
;         __builtin_amdgcn_global_load_lds((const unsigned*)((const char*)(gbase) + (voff)[_i]), (LAS unsigned*)(lds + (bufoff) + ldsw + _i * 8192), 16, 0, 0); } while (0)
; #define PG8_LDA(dst, b, h) do { _Pragma("unroll") for (int m = 0; m < 4; ++m) _Pragma("unroll") for (int k = 0; k < 2; ++k) dst[m][k] = *(const LAS bf16x8*)(lds + PG8_SA(b, h) + aoff + m * 2048 + k * 1024); } while (0)
; #define PG8_LDB(dst, b, h) do { _Pragma("unroll") for (int n = 0; n < 2; ++n) _Pragma("unroll") for (int k = 0; k < 2; ++k) dst[n][k] = *(const LAS bf16x8*)(lds + PG8_SB(b, h) + boff + n * 2048 + k * 1024); } while (0)
; #define PG8_MMA(ai, bj, At, Bt) do { __builtin_amdgcn_s_setprio(1); _Pragma("unroll") for (int m = 0; m < 4; ++m) _Pragma("unroll") for (int n = 0; n < 2; ++n) _Pragma("unroll") for (int k = 0; k < 2; ++k) \
;         acc[ai][bj][m][n] = __builtin_amdgcn_mfma_f32_16x16x32_bf16(Bt[n][k], At[m][k], acc[ai][bj][m][n], 0, 0, 0); __builtin_amdgcn_s_setprio(0); } while (0)
; #define PG8_WAIT_V(n) asm volatile("s_waitcnt vmcnt(" #n ")" ::: "memory")
; #define PG8_WAIT_L(n) asm volatile("s_waitcnt lgkmcnt(" #n ")" ::: "memory")
; #define PG8_BAR __builtin_amdgcn_s_barrier()
; #define PG8_SCHED __builtin_amdgcn_sched_barrier(0)
; template <class Epi>
; DEVINL void gemm_phase(LAS unsigned char* lds, const Gemm g, const Order& S, const Epi& E) {
;     ...
;             PG8_STAGE(PG8_SB(0, 1), b2 + hstepB, voffB);
;             PG8_WAIT_V(6); PG8_BAR; PG8_MMA(1, 1, At, B1); PG8_BAR;
;             PG8_LDB(B0, 1, 0); PG8_SCHED; PG8_LDA(At, 1, 0); PG8_STAGE(PG8_SA(0, 1), a2 + hstepA, voffA);
;             PG8_WAIT_L(8); PG8_BAR; PG8_WAIT_L(0); PG8_MMA(0, 0, At, B0); PG8_BAR; PG8_SCHED;
;             PG8_LDB(B1, 1, 1); PG8_STAGE(PG8_SB(1, 0), b3, voffB);
	s_add_u32 s24, s28, 0x158000
	s_addc_u32 s25, s29, 0
	s_add_i32 s62, s50, s37
	v_lshl_add_u64 v[150:151], s[24:25], 0, v[130:131]
	s_mov_b32 m0, s62
	s_nop 0
	global_load_lds_dwordx4 v[150:151], off
	v_lshl_add_u64 v[150:151], s[24:25], 0, v[134:135]
	s_add_i32 m0, s62, 0x2000
	s_nop 0
	global_load_lds_dwordx4 v[150:151], off
	s_waitcnt vmcnt(6)
	s_barrier
	s_setprio 1
	v_mfma_f32_16x16x32_bf16 v[52:55], v[198:201], v[166:169], v[52:55]
	v_mfma_f32_16x16x32_bf16 v[52:55], v[202:205], v[170:173], v[52:55]
	v_mfma_f32_16x16x32_bf16 v[48:51], v[206:209], v[166:169], v[48:51]
	v_mfma_f32_16x16x32_bf16 v[48:51], v[210:213], v[170:173], v[48:51]
	v_mfma_f32_16x16x32_bf16 v[32:35], v[206:209], v[174:177], v[32:35]
	v_mfma_f32_16x16x32_bf16 v[32:35], v[210:213], v[178:181], v[32:35]
	v_mfma_f32_16x16x32_bf16 v[36:39], v[198:201], v[174:177], v[36:39]
	v_mfma_f32_16x16x32_bf16 v[36:39], v[202:205], v[178:181], v[36:39]
	v_mfma_f32_16x16x32_bf16 v[20:23], v[198:201], v[182:185], v[20:23]
	v_mfma_f32_16x16x32_bf16 v[20:23], v[202:205], v[186:189], v[20:23]
	v_mfma_f32_16x16x32_bf16 v[16:19], v[206:209], v[182:185], v[16:19]
	v_mfma_f32_16x16x32_bf16 v[16:19], v[210:213], v[186:189], v[16:19]
	v_mfma_f32_16x16x32_bf16 v[0:3], v[206:209], v[190:193], v[0:3]
	v_mfma_f32_16x16x32_bf16 v[0:3], v[210:213], v[194:197], v[0:3]
	v_mfma_f32_16x16x32_bf16 v[4:7], v[198:201], v[190:193], v[4:7]
	v_mfma_f32_16x16x32_bf16 v[4:7], v[202:205], v[194:197], v[4:7]
	s_setprio 0
	s_add_i32 s62, 16, 0x18000
	v_add_u32_e32 v162, s62, v145
	s_barrier
	ds_read_b128 v[150:153], v162
	ds_read_b128 v[154:157], v162 offset:1024
	ds_read_b128 v[158:161], v162 offset:2048
	ds_read_b128 v[162:165], v162 offset:3072
	s_add_u32 s24, s30, 0x158000
	s_addc_u32 s25, s31, 0
	s_mov_b32 m0, s40
	v_lshl_add_u64 v[198:199], s[24:25], 0, v[128:129]
	ds_read_b128 v[166:169], v148 offset:32768
	ds_read_b128 v[170:173], v148 offset:33792
	ds_read_b128 v[174:177], v148 offset:34816
	ds_read_b128 v[178:181], v148 offset:35840
	ds_read_b128 v[182:185], v148 offset:36864
	ds_read_b128 v[186:189], v148 offset:37888
	ds_read_b128 v[190:193], v148 offset:38912
	ds_read_b128 v[194:197], v148 offset:39936
	global_load_lds_dwordx4 v[198:199], off
	v_lshl_add_u64 v[198:199], s[24:25], 0, v[132:133]
	s_mov_b32 m0, s41
	s_nop 0
	global_load_lds_dwordx4 v[198:199], off
	s_waitcnt lgkmcnt(8)
	s_barrier
	s_waitcnt lgkmcnt(0)
	s_setprio 1
	s_waitcnt lgkmcnt(0)
	v_mfma_f32_16x16x32_bf16 v[120:123], v[150:153], v[166:169], v[120:123]
	v_mfma_f32_16x16x32_bf16 v[120:123], v[154:157], v[170:173], v[120:123]
	v_mfma_f32_16x16x32_bf16 v[124:127], v[158:161], v[166:169], v[124:127]
	v_mfma_f32_16x16x32_bf16 v[124:127], v[162:165], v[170:173], v[124:127]
	v_mfma_f32_16x16x32_bf16 v[104:107], v[158:161], v[174:177], v[104:107]
	v_mfma_f32_16x16x32_bf16 v[104:107], v[162:165], v[178:181], v[104:107]
	v_mfma_f32_16x16x32_bf16 v[108:111], v[150:153], v[174:177], v[108:111]
	v_mfma_f32_16x16x32_bf16 v[108:111], v[154:157], v[178:181], v[108:111]
	v_mfma_f32_16x16x32_bf16 v[92:95], v[150:153], v[182:185], v[92:95]
	v_mfma_f32_16x16x32_bf16 v[92:95], v[154:157], v[186:189], v[92:95]
	v_mfma_f32_16x16x32_bf16 v[88:91], v[158:161], v[182:185], v[88:91]
	v_mfma_f32_16x16x32_bf16 v[88:91], v[162:165], v[186:189], v[88:91]
	v_mfma_f32_16x16x32_bf16 v[72:75], v[158:161], v[190:193], v[72:75]
	v_mfma_f32_16x16x32_bf16 v[72:75], v[162:165], v[194:197], v[72:75]
	v_mfma_f32_16x16x32_bf16 v[76:79], v[150:153], v[190:193], v[76:79]
	v_mfma_f32_16x16x32_bf16 v[76:79], v[154:157], v[194:197], v[76:79]
	s_setprio 0
	s_barrier
	s_add_i32 s30, 16, 0x1c000
	s_add_i32 s24, s62, s37
	v_add_u32_e32 v210, s30, v145
	v_lshl_add_u64 v[218:219], v[218:219], 0, s[6:7]
	s_mov_b32 m0, s24
	ds_read_b128 v[198:201], v210
	ds_read_b128 v[202:205], v210 offset:1024
	ds_read_b128 v[206:209], v210 offset:2048
	ds_read_b128 v[210:213], v210 offset:3072
	global_load_lds_dwordx4 v[218:219], off
	v_lshl_add_u64 v[218:219], v[220:221], 0, s[6:7]
	s_add_i32 m0, s24, 0x2000
	s_nop 0
	global_load_lds_dwordx4 v[218:219], off
	s_barrier
; #define PG8_STAGE(bufoff, gbase, voff) do { _Pragma("unroll") for (int _i = 0; _i < 2; ++_i) \
;         __builtin_amdgcn_global_load_lds((const unsigned*)((const char*)(gbase) + (voff)[_i]), (LAS unsigned*)(lds + (bufoff) + ldsw + _i * 8192), 16, 0, 0); } while (0)
; #define PG8_LDA(dst, b, h) do { _Pragma("unroll") for (int m = 0; m < 4; ++m) _Pragma("unroll") for (int k = 0; k < 2; ++k) dst[m][k] = *(const LAS bf16x8*)(lds + PG8_SA(b, h) + aoff + m * 2048 + k * 1024); } while (0)
; #define PG8_MMA(ai, bj, At, Bt) do { __builtin_amdgcn_s_setprio(1); _Pragma("unroll") for (int m = 0; m < 4; ++m) _Pragma("unroll") for (int n = 0; n < 2; ++n) _Pragma("unroll") for (int k = 0; k < 2; ++k) \
;         acc[ai][bj][m][n] = __builtin_amdgcn_mfma_f32_16x16x32_bf16(Bt[n][k], At[m][k], acc[ai][bj][m][n], 0, 0, 0); __builtin_amdgcn_s_setprio(0); } while (0)
; #define PG8_WAIT_V(n) asm volatile("s_waitcnt vmcnt(" #n ")" ::: "memory")
; #define PG8_WAIT_L(n) asm volatile("s_waitcnt lgkmcnt(" #n ")" ::: "memory")
; #define PG8_BAR __builtin_amdgcn_s_barrier()
; #define PG8_SCHED __builtin_amdgcn_sched_barrier(0)
; template <class Epi>
; DEVINL void gemm_phase(LAS unsigned char* lds, const Gemm g, const Order& S, const Epi& E) {
;     ...
;             PG8_BAR; PG8_WAIT_L(0); PG8_MMA(0, 1, At, B1); PG8_BAR;
;             PG8_LDA(At, 1, 1); PG8_STAGE(PG8_SA(1, 0), a3, voffA);
;             PG8_BAR; PG8_WAIT_L(0); PG8_MMA(1, 0, At, B0); PG8_BAR; PG8_SCHED;
;             PG8_STAGE(PG8_SB(1, 1), b3 + hstepB, voffB);
;             PG8_WAIT_V(6); PG8_BAR; PG8_MMA(1, 1, At, B1); PG8_BAR;
	s_waitcnt lgkmcnt(0)
	s_setprio 1
	s_waitcnt lgkmcnt(0)
	v_mfma_f32_16x16x32_bf16 v[116:119], v[198:201], v[166:169], v[116:119]
	v_mfma_f32_16x16x32_bf16 v[116:119], v[202:205], v[170:173], v[116:119]
	v_mfma_f32_16x16x32_bf16 v[112:115], v[206:209], v[166:169], v[112:115]
	v_mfma_f32_16x16x32_bf16 v[112:115], v[210:213], v[170:173], v[112:115]
	v_mfma_f32_16x16x32_bf16 v[96:99], v[206:209], v[174:177], v[96:99]
	v_mfma_f32_16x16x32_bf16 v[96:99], v[210:213], v[178:181], v[96:99]
	v_mfma_f32_16x16x32_bf16 v[100:103], v[198:201], v[174:177], v[100:103]
	v_mfma_f32_16x16x32_bf16 v[100:103], v[202:205], v[178:181], v[100:103]
	v_mfma_f32_16x16x32_bf16 v[84:87], v[198:201], v[182:185], v[84:87]
	v_mfma_f32_16x16x32_bf16 v[84:87], v[202:205], v[186:189], v[84:87]
	v_mfma_f32_16x16x32_bf16 v[80:83], v[206:209], v[182:185], v[80:83]
	v_mfma_f32_16x16x32_bf16 v[80:83], v[210:213], v[186:189], v[80:83]
	v_mfma_f32_16x16x32_bf16 v[64:67], v[206:209], v[190:193], v[64:67]
	v_mfma_f32_16x16x32_bf16 v[64:67], v[210:213], v[194:197], v[64:67]
	v_mfma_f32_16x16x32_bf16 v[68:71], v[198:201], v[190:193], v[68:71]
	v_mfma_f32_16x16x32_bf16 v[68:71], v[202:205], v[194:197], v[68:71]
	s_setprio 0
	s_mov_b32 m0, s43
	v_lshl_add_u64 v[218:219], v[222:223], 0, s[6:7]
	s_barrier
	ds_read_b128 v[166:169], v148 offset:49152
	ds_read_b128 v[170:173], v148 offset:50176
	ds_read_b128 v[174:177], v148 offset:51200
	ds_read_b128 v[178:181], v148 offset:52224
	ds_read_b128 v[182:185], v148 offset:53248
	ds_read_b128 v[186:189], v148 offset:54272
	ds_read_b128 v[190:193], v148 offset:55296
	ds_read_b128 v[194:197], v148 offset:56320
	global_load_lds_dwordx4 v[218:219], off
	v_lshl_add_u64 v[218:219], v[224:225], 0, s[6:7]
	s_mov_b32 m0, s44
	s_nop 0
	global_load_lds_dwordx4 v[218:219], off
	s_barrier
	s_waitcnt lgkmcnt(0)
	s_setprio 1
	s_waitcnt lgkmcnt(0)
	v_mfma_f32_16x16x32_bf16 v[60:63], v[150:153], v[166:169], v[60:63]
	v_mfma_f32_16x16x32_bf16 v[60:63], v[154:157], v[170:173], v[60:63]
	v_mfma_f32_16x16x32_bf16 v[56:59], v[158:161], v[166:169], v[56:59]
	v_mfma_f32_16x16x32_bf16 v[56:59], v[162:165], v[170:173], v[56:59]
	v_mfma_f32_16x16x32_bf16 v[40:43], v[158:161], v[174:177], v[40:43]
	v_mfma_f32_16x16x32_bf16 v[40:43], v[162:165], v[178:181], v[40:43]
	v_mfma_f32_16x16x32_bf16 v[44:47], v[150:153], v[174:177], v[44:47]
	v_mfma_f32_16x16x32_bf16 v[44:47], v[154:157], v[178:181], v[44:47]
	v_mfma_f32_16x16x32_bf16 v[28:31], v[150:153], v[182:185], v[28:31]
	v_mfma_f32_16x16x32_bf16 v[28:31], v[154:157], v[186:189], v[28:31]
	v_mfma_f32_16x16x32_bf16 v[24:27], v[158:161], v[182:185], v[24:27]
	v_mfma_f32_16x16x32_bf16 v[24:27], v[162:165], v[186:189], v[24:27]
	v_mfma_f32_16x16x32_bf16 v[8:11], v[158:161], v[190:193], v[8:11]
	v_mfma_f32_16x16x32_bf16 v[8:11], v[162:165], v[194:197], v[8:11]
	v_mfma_f32_16x16x32_bf16 v[12:15], v[150:153], v[190:193], v[12:15]
	v_mfma_f32_16x16x32_bf16 v[12:15], v[154:157], v[194:197], v[12:15]
	s_setprio 0
	s_barrier
	s_add_u32 s24, s28, 0x158080
	s_addc_u32 s25, s29, 0
	s_add_i32 s28, s30, s37
	v_lshl_add_u64 v[150:151], s[24:25], 0, v[130:131]
	s_mov_b32 m0, s28
	s_nop 0
	global_load_lds_dwordx4 v[150:151], off
	v_lshl_add_u64 v[150:151], s[24:25], 0, v[134:135]
	s_add_i32 m0, s28, 0x2000
	s_nop 0
	global_load_lds_dwordx4 v[150:151], off
	s_waitcnt vmcnt(6)
	s_barrier
	s_setprio 1
	v_mfma_f32_16x16x32_bf16 v[52:55], v[198:201], v[166:169], v[52:55]
	v_mfma_f32_16x16x32_bf16 v[52:55], v[202:205], v[170:173], v[52:55]
	v_mfma_f32_16x16x32_bf16 v[48:51], v[206:209], v[166:169], v[48:51]
	v_mfma_f32_16x16x32_bf16 v[48:51], v[210:213], v[170:173], v[48:51]
	v_mfma_f32_16x16x32_bf16 v[32:35], v[206:209], v[174:177], v[32:35]
	v_mfma_f32_16x16x32_bf16 v[32:35], v[210:213], v[178:181], v[32:35]
	v_mfma_f32_16x16x32_bf16 v[36:39], v[198:201], v[174:177], v[36:39]
	v_mfma_f32_16x16x32_bf16 v[36:39], v[202:205], v[178:181], v[36:39]
	v_mfma_f32_16x16x32_bf16 v[20:23], v[198:201], v[182:185], v[20:23]
	v_mfma_f32_16x16x32_bf16 v[20:23], v[202:205], v[186:189], v[20:23]
	v_mfma_f32_16x16x32_bf16 v[16:19], v[206:209], v[182:185], v[16:19]
	v_mfma_f32_16x16x32_bf16 v[16:19], v[210:213], v[186:189], v[16:19]
	v_mfma_f32_16x16x32_bf16 v[0:3], v[206:209], v[190:193], v[0:3]
	v_mfma_f32_16x16x32_bf16 v[0:3], v[210:213], v[194:197], v[0:3]
	v_mfma_f32_16x16x32_bf16 v[4:7], v[198:201], v[190:193], v[4:7]
	v_mfma_f32_16x16x32_bf16 v[4:7], v[202:205], v[194:197], v[4:7]
	s_setprio 0
	s_add_u32 s59, s59, 0x100
	s_addc_u32 s60, s60, 0
	s_cmp_ge_i32 s61, s42
	s_mov_b64 s[24:25], s[26:27]
	s_mov_b32 s28, s61
	s_barrier
	s_cbranch_scc0 .LBB0_1852
	s_branch .LBB0_1839
